# v024
# speedup vs baseline: 1.0346x; 1.0043x over previous
; #define STAGE_A(P, half, kt) do { const char* _u = Ab + ((size_t)(half) * 128 * lda + (size_t)(kt) * BK) * 2; \
;     _Pragma("unroll") for (int _i = 0; _i < 2; ++_i) \
;       __builtin_amdgcn_global_load_lds((const unsigned*)(_u + offA[_i]), \
;         (__attribute__((address_space(3))) unsigned*)((__attribute__((address_space(3))) char*)(P) + tidg * 16 + _i * 8192), 16, 0, 0); } while (0)
; #define STAGE_B(P, half, kt) do { const char* _u = Bb + ((size_t)(half) * 128 * ldb + (size_t)(kt) * BK) * 2; \
;     _Pragma("unroll") for (int _i = 0; _i < 2; ++_i) \
;       __builtin_amdgcn_global_load_lds((const unsigned*)(_u + offB[_i]), \
;         (__attribute__((address_space(3))) unsigned*)((__attribute__((address_space(3))) char*)(P) + tidg * 16 + _i * 8192), 16, 0, 0); } while (0)
; #define LDA(dst, b, h) _Pragma("unroll") for (int m = 0; m < 4; ++m) _Pragma("unroll") for (int k = 0; k < 2; ++k) \
;     dst[m][k] = *reinterpret_cast<const bf16x8*>((const char*)SA(b, h) + lds_byte(wr * 64 + m * 16 + fr, k * 32 + fq * 8))
; #define LDB(dst, b, h) _Pragma("unroll") for (int n = 0; n < 2; ++n) _Pragma("unroll") for (int k = 0; k < 2; ++k) \
;     dst[n][k] = *reinterpret_cast<const bf16x8*>((const char*)SB(b, h) + lds_byte(wc * 32 + n * 16 + fr, k * 32 + fq * 8))
; #define MMA(ai, bj, At_, Bt_) do { __builtin_amdgcn_s_setprio(1); \
;     _Pragma("unroll") for (int m = 0; m < 4; ++m) _Pragma("unroll") for (int n = 0; n < 2; ++n) _Pragma("unroll") for (int k = 0; k < 2; ++k) \
;       acc[ai][bj][m][n] = __builtin_amdgcn_mfma_f32_16x16x32_bf16(Bt_[n][k], At_[m][k], acc[ai][bj][m][n], 0, 0, 0); \
;     __builtin_amdgcn_s_setprio(0); } while (0)
; template <bool PF = true, class Epi, class KRF = KRFull>
; __device__ __forceinline__ void gemm_phase(const u16* __restrict__ A, int lda, const u16* __restrict__ Bt, int ldb, int K, int nM, int nN,
;                                            lds_u16* shm, Epi epi, KRF krf = KRFull(), bool flip = false) {
;     ...
;     for (int t = 0; t < nt - 2; t += 2) {
;       LDB(B0, 0, 0); SCHED; LDA(At, 0, 0); STAGE_A(SA(1, 1), 1, t + 1);
;       WAIT_L(8); BAR; WAIT_L(0); MMA(0, 0, At, B0); BAR; SCHED;
;       LDB(B1, 0, 1); STAGE_B(SB(0, 0), 0, t + 2);
;       BAR; WAIT_L(0); MMA(0, 1, At, B1); BAR;
;       LDA(At, 0, 1); STAGE_A(SA(0, 0), 0, t + 2);
;       BAR; WAIT_L(0); MMA(1, 0, At, B0); BAR; SCHED;
.LBB0_903:
	v_readfirstlane_b32 s3, v144
	ds_read_b128 v[158:161], v154
	ds_read_b128 v[162:165], v154 offset:1024
	ds_read_b128 v[166:169], v154 offset:2048
	ds_read_b128 v[170:173], v154 offset:3072
	v_add_u32_e32 v155, 0xc000, v144
	v_lshl_add_u64 v[174:175], v[134:135], 0, s[14:15]
	v_lshl_add_u64 v[156:157], v[174:175], 0, s[62:63]
	s_add_u32 m0, s3, 0xc000
	ds_read_b128 v[180:183], v142
	ds_read_b128 v[184:187], v142 offset:1024
	ds_read_b128 v[188:191], v141
	ds_read_b128 v[192:195], v141 offset:1024
	ds_read_b128 v[196:199], v140
	ds_read_b128 v[200:203], v140 offset:1024
	ds_read_b128 v[204:207], v139
	ds_read_b128 v[208:211], v139 offset:1024
	global_load_lds_dwordx4 v[156:157], off
	v_add_u32_e32 v156, 0xe000, v144
	v_lshl_add_u64 v[222:223], v[136:137], 0, s[14:15]
	v_lshl_add_u64 v[212:213], v[222:223], 0, s[62:63]
	s_add_u32 m0, s3, 0xe000
	s_nop 0
	global_load_lds_dwordx4 v[212:213], off
	s_waitcnt lgkmcnt(8)
	s_barrier
	s_waitcnt lgkmcnt(0)
	s_setprio 1
	s_waitcnt lgkmcnt(0)
	v_mfma_f32_16x16x32_bf16 v[124:127], v[158:161], v[180:183], v[124:127]
	v_mfma_f32_16x16x32_bf16 v[120:123], v[166:169], v[180:183], v[120:123]
	v_mfma_f32_16x16x32_bf16 v[116:119], v[158:161], v[188:191], v[116:119]
	v_mfma_f32_16x16x32_bf16 v[112:115], v[166:169], v[188:191], v[112:115]
	v_mfma_f32_16x16x32_bf16 v[108:111], v[158:161], v[196:199], v[108:111]
	v_mfma_f32_16x16x32_bf16 v[104:107], v[166:169], v[196:199], v[104:107]
	v_mfma_f32_16x16x32_bf16 v[100:103], v[158:161], v[204:207], v[100:103]
	v_mfma_f32_16x16x32_bf16 v[96:99], v[166:169], v[204:207], v[96:99]
	v_mfma_f32_16x16x32_bf16 v[124:127], v[162:165], v[184:187], v[124:127]
	v_mfma_f32_16x16x32_bf16 v[120:123], v[170:173], v[184:187], v[120:123]
	v_mfma_f32_16x16x32_bf16 v[116:119], v[162:165], v[192:195], v[116:119]
	v_mfma_f32_16x16x32_bf16 v[112:115], v[170:173], v[192:195], v[112:115]
	v_mfma_f32_16x16x32_bf16 v[108:111], v[162:165], v[200:203], v[108:111]
	v_mfma_f32_16x16x32_bf16 v[104:107], v[170:173], v[200:203], v[104:107]
	v_mfma_f32_16x16x32_bf16 v[100:103], v[162:165], v[208:211], v[100:103]
	v_mfma_f32_16x16x32_bf16 v[96:99], v[170:173], v[208:211], v[96:99]
	s_setprio 0
	s_barrier
	v_add_u32_e32 v157, 0x10000, v144
	v_lshl_add_u64 v[224:225], v[130:131], 0, s[14:15]
	v_lshl_add_u64 v[226:227], v[224:225], 0, s[64:65]
	s_add_u32 m0, s3, 0x10000
	v_add_u32_e32 v157, 0x12000, v144
	ds_read_b128 v[212:215], v153
	ds_read_b128 v[216:219], v153 offset:1024
	ds_read_b128 v[238:241], v153 offset:2048
	ds_read_b128 v[242:245], v153 offset:3072
	global_load_lds_dwordx4 v[226:227], off
	v_lshl_add_u64 v[226:227], v[132:133], 0, s[14:15]
	v_lshl_add_u64 v[228:229], v[226:227], 0, s[64:65]
	s_add_u32 m0, s3, 0x12000
	s_nop 0
	global_load_lds_dwordx4 v[228:229], off
	s_barrier
	s_waitcnt lgkmcnt(0)
	s_setprio 1
	s_waitcnt lgkmcnt(0)
	v_mfma_f32_16x16x32_bf16 v[92:95], v[212:215], v[180:183], v[92:95]
	v_mfma_f32_16x16x32_bf16 v[88:91], v[238:241], v[180:183], v[88:91]
	v_mfma_f32_16x16x32_bf16 v[84:87], v[212:215], v[188:191], v[84:87]
	v_mfma_f32_16x16x32_bf16 v[80:83], v[238:241], v[188:191], v[80:83]
	v_mfma_f32_16x16x32_bf16 v[76:79], v[212:215], v[196:199], v[76:79]
	v_mfma_f32_16x16x32_bf16 v[72:75], v[238:241], v[196:199], v[72:75]
	v_mfma_f32_16x16x32_bf16 v[68:71], v[212:215], v[204:207], v[68:71]
	v_mfma_f32_16x16x32_bf16 v[64:67], v[238:241], v[204:207], v[64:67]
	v_mfma_f32_16x16x32_bf16 v[92:95], v[216:219], v[184:187], v[92:95]
	v_mfma_f32_16x16x32_bf16 v[88:91], v[242:245], v[184:187], v[88:91]
	v_mfma_f32_16x16x32_bf16 v[84:87], v[216:219], v[192:195], v[84:87]
	v_mfma_f32_16x16x32_bf16 v[80:83], v[242:245], v[192:195], v[80:83]
	v_mfma_f32_16x16x32_bf16 v[76:79], v[216:219], v[200:203], v[76:79]
	v_mfma_f32_16x16x32_bf16 v[72:75], v[242:245], v[200:203], v[72:75]
	v_mfma_f32_16x16x32_bf16 v[68:71], v[216:219], v[208:211], v[68:71]
	v_mfma_f32_16x16x32_bf16 v[64:67], v[242:245], v[208:211], v[64:67]
	s_setprio 0
	v_lshl_add_u64 v[228:229], v[174:175], 0, s[64:65]
	s_mov_b32 m0, s3
	s_barrier
	ds_read_b128 v[180:183], v142 offset:16384
	ds_read_b128 v[184:187], v142 offset:17408
	ds_read_b128 v[188:191], v141 offset:16384
	ds_read_b128 v[192:195], v141 offset:17408
	ds_read_b128 v[196:199], v140 offset:16384
	ds_read_b128 v[200:203], v140 offset:17408
	ds_read_b128 v[204:207], v139 offset:16384
	ds_read_b128 v[208:211], v139 offset:17408
	global_load_lds_dwordx4 v[228:229], off
	v_lshl_add_u64 v[228:229], v[222:223], 0, s[64:65]
	s_add_u32 m0, s3, 0x2000
	s_nop 0
	global_load_lds_dwordx4 v[228:229], off
	s_barrier
	s_waitcnt lgkmcnt(0)
	s_setprio 1
	s_waitcnt lgkmcnt(0)
	v_mfma_f32_16x16x32_bf16 v[60:63], v[158:161], v[180:183], v[60:63]
	v_mfma_f32_16x16x32_bf16 v[56:59], v[166:169], v[180:183], v[56:59]
	v_mfma_f32_16x16x32_bf16 v[52:55], v[158:161], v[188:191], v[52:55]
	v_mfma_f32_16x16x32_bf16 v[48:51], v[166:169], v[188:191], v[48:51]
	v_mfma_f32_16x16x32_bf16 v[44:47], v[158:161], v[196:199], v[44:47]
	v_mfma_f32_16x16x32_bf16 v[40:43], v[166:169], v[196:199], v[40:43]
	v_mfma_f32_16x16x32_bf16 v[36:39], v[158:161], v[204:207], v[36:39]
	v_mfma_f32_16x16x32_bf16 v[32:35], v[166:169], v[204:207], v[32:35]
	v_mfma_f32_16x16x32_bf16 v[60:63], v[162:165], v[184:187], v[60:63]
	v_mfma_f32_16x16x32_bf16 v[56:59], v[170:173], v[184:187], v[56:59]
	v_mfma_f32_16x16x32_bf16 v[52:55], v[162:165], v[192:195], v[52:55]
	v_mfma_f32_16x16x32_bf16 v[48:51], v[170:173], v[192:195], v[48:51]
	v_mfma_f32_16x16x32_bf16 v[44:47], v[162:165], v[200:203], v[44:47]
	v_mfma_f32_16x16x32_bf16 v[40:43], v[170:173], v[200:203], v[40:43]
	v_mfma_f32_16x16x32_bf16 v[36:39], v[162:165], v[208:211], v[36:39]
	v_mfma_f32_16x16x32_bf16 v[32:35], v[170:173], v[208:211], v[32:35]
	s_setprio 0
	s_barrier
; #define STAGE_A(P, half, kt) do { const char* _u = Ab + ((size_t)(half) * 128 * lda + (size_t)(kt) * BK) * 2; \
;     _Pragma("unroll") for (int _i = 0; _i < 2; ++_i) \
;       __builtin_amdgcn_global_load_lds((const unsigned*)(_u + offA[_i]), \
;         (__attribute__((address_space(3))) unsigned*)((__attribute__((address_space(3))) char*)(P) + tidg * 16 + _i * 8192), 16, 0, 0); } while (0)
; #define STAGE_B(P, half, kt) do { const char* _u = Bb + ((size_t)(half) * 128 * ldb + (size_t)(kt) * BK) * 2; \
;     _Pragma("unroll") for (int _i = 0; _i < 2; ++_i) \
;       __builtin_amdgcn_global_load_lds((const unsigned*)(_u + offB[_i]), \
;         (__attribute__((address_space(3))) unsigned*)((__attribute__((address_space(3))) char*)(P) + tidg * 16 + _i * 8192), 16, 0, 0); } while (0)
; #define LDA(dst, b, h) _Pragma("unroll") for (int m = 0; m < 4; ++m) _Pragma("unroll") for (int k = 0; k < 2; ++k) \
;     dst[m][k] = *reinterpret_cast<const bf16x8*>((const char*)SA(b, h) + lds_byte(wr * 64 + m * 16 + fr, k * 32 + fq * 8))
; #define LDB(dst, b, h) _Pragma("unroll") for (int n = 0; n < 2; ++n) _Pragma("unroll") for (int k = 0; k < 2; ++k) \
;     dst[n][k] = *reinterpret_cast<const bf16x8*>((const char*)SB(b, h) + lds_byte(wc * 32 + n * 16 + fr, k * 32 + fq * 8))
; #define MMA(ai, bj, At_, Bt_) do { __builtin_amdgcn_s_setprio(1); \
;     _Pragma("unroll") for (int m = 0; m < 4; ++m) _Pragma("unroll") for (int n = 0; n < 2; ++n) _Pragma("unroll") for (int k = 0; k < 2; ++k) \
;       acc[ai][bj][m][n] = __builtin_amdgcn_mfma_f32_16x16x32_bf16(Bt_[n][k], At_[m][k], acc[ai][bj][m][n], 0, 0, 0); \
;     __builtin_amdgcn_s_setprio(0); } while (0)
; #define BAR __builtin_amdgcn_s_barrier()
; template <bool PF = true, class Epi, class KRF = KRFull>
; __device__ __forceinline__ void gemm_phase(const u16* __restrict__ A, int lda, const u16* __restrict__ Bt, int ldb, int K, int nM, int nN,
;                                            lds_u16* shm, Epi epi, KRF krf = KRFull(), bool flip = false) {
;     ...
;       STAGE_B(SB(0, 1), 1, t + 2);
;       WAIT_V(6); BAR; MMA(1, 1, At, B1); BAR;
;       LDB(B0, 1, 0); SCHED; LDA(At, 1, 0); STAGE_A(SA(0, 1), 1, t + 2);
;       WAIT_L(8); BAR; WAIT_L(0); MMA(0, 0, At, B0); BAR; SCHED;
;       LDB(B1, 1, 1); STAGE_B(SB(1, 0), 0, t + 3);
;       BAR; WAIT_L(0); MMA(0, 1, At, B1); BAR;
;       LDA(At, 1, 1); STAGE_A(SA(1, 0), 0, t + 3);
	v_add_u32_e32 v157, 0x14000, v144
	v_lshl_add_u64 v[158:159], v[224:225], 0, s[66:67]
	v_add_u32_e32 v157, 0x16000, v144
	s_add_u32 m0, s3, 0x14000
	s_nop 0
	global_load_lds_dwordx4 v[158:159], off
	v_lshl_add_u64 v[158:159], v[226:227], 0, s[66:67]
	s_add_u32 m0, s3, 0x16000
	s_nop 0
	global_load_lds_dwordx4 v[158:159], off
	s_waitcnt vmcnt(6)
	s_barrier
	s_setprio 1
	v_mfma_f32_16x16x32_bf16 v[28:31], v[212:215], v[180:183], v[28:31]
	v_mfma_f32_16x16x32_bf16 v[24:27], v[238:241], v[180:183], v[24:27]
	v_mfma_f32_16x16x32_bf16 v[20:23], v[212:215], v[188:191], v[20:23]
	v_mfma_f32_16x16x32_bf16 v[16:19], v[238:241], v[188:191], v[16:19]
	v_mfma_f32_16x16x32_bf16 v[12:15], v[212:215], v[196:199], v[12:15]
	v_mfma_f32_16x16x32_bf16 v[8:11], v[238:241], v[196:199], v[8:11]
	v_mfma_f32_16x16x32_bf16 v[4:7], v[212:215], v[204:207], v[4:7]
	v_mfma_f32_16x16x32_bf16 v[0:3], v[238:241], v[204:207], v[0:3]
	v_mfma_f32_16x16x32_bf16 v[28:31], v[216:219], v[184:187], v[28:31]
	v_mfma_f32_16x16x32_bf16 v[24:27], v[242:245], v[184:187], v[24:27]
	v_mfma_f32_16x16x32_bf16 v[20:23], v[216:219], v[192:195], v[20:23]
	v_mfma_f32_16x16x32_bf16 v[16:19], v[242:245], v[192:195], v[16:19]
	v_mfma_f32_16x16x32_bf16 v[12:15], v[216:219], v[200:203], v[12:15]
	v_mfma_f32_16x16x32_bf16 v[8:11], v[242:245], v[200:203], v[8:11]
	v_mfma_f32_16x16x32_bf16 v[4:7], v[216:219], v[208:211], v[4:7]
	v_mfma_f32_16x16x32_bf16 v[0:3], v[242:245], v[208:211], v[0:3]
	s_setprio 0
	s_barrier
	ds_read_b128 v[158:161], v145
	ds_read_b128 v[162:165], v145 offset:1024
	ds_read_b128 v[166:169], v145 offset:2048
	ds_read_b128 v[170:173], v145 offset:3072
	v_add_u32_e32 v157, 0x4000, v144
	v_lshl_add_u64 v[212:213], v[174:175], 0, s[66:67]
	v_add_u32_e32 v157, 0x6000, v144
	s_add_u32 m0, s3, 0x4000
	ds_read_b128 v[180:183], v142 offset:32768
	ds_read_b128 v[184:187], v142 offset:33792
	ds_read_b128 v[188:191], v141 offset:32768
	ds_read_b128 v[192:195], v141 offset:33792
	ds_read_b128 v[196:199], v140 offset:32768
	ds_read_b128 v[200:203], v140 offset:33792
	ds_read_b128 v[204:207], v139 offset:32768
	ds_read_b128 v[208:211], v139 offset:33792
	global_load_lds_dwordx4 v[212:213], off
	v_lshl_add_u64 v[212:213], v[222:223], 0, s[66:67]
	s_add_u32 m0, s3, 0x6000
	s_nop 0
	global_load_lds_dwordx4 v[212:213], off
	s_waitcnt lgkmcnt(8)
	s_barrier
	s_waitcnt lgkmcnt(0)
	s_setprio 1
	s_waitcnt lgkmcnt(0)
	v_mfma_f32_16x16x32_bf16 v[124:127], v[158:161], v[180:183], v[124:127]
	v_mfma_f32_16x16x32_bf16 v[120:123], v[166:169], v[180:183], v[120:123]
	v_mfma_f32_16x16x32_bf16 v[116:119], v[158:161], v[188:191], v[116:119]
	v_mfma_f32_16x16x32_bf16 v[112:115], v[166:169], v[188:191], v[112:115]
	v_mfma_f32_16x16x32_bf16 v[108:111], v[158:161], v[196:199], v[108:111]
	v_mfma_f32_16x16x32_bf16 v[104:107], v[166:169], v[196:199], v[104:107]
	v_mfma_f32_16x16x32_bf16 v[100:103], v[158:161], v[204:207], v[100:103]
	v_mfma_f32_16x16x32_bf16 v[96:99], v[166:169], v[204:207], v[96:99]
	v_mfma_f32_16x16x32_bf16 v[124:127], v[162:165], v[184:187], v[124:127]
	v_mfma_f32_16x16x32_bf16 v[120:123], v[170:173], v[184:187], v[120:123]
	v_mfma_f32_16x16x32_bf16 v[116:119], v[162:165], v[192:195], v[116:119]
	v_mfma_f32_16x16x32_bf16 v[112:115], v[170:173], v[192:195], v[112:115]
	v_mfma_f32_16x16x32_bf16 v[108:111], v[162:165], v[200:203], v[108:111]
	v_mfma_f32_16x16x32_bf16 v[104:107], v[170:173], v[200:203], v[104:107]
	v_mfma_f32_16x16x32_bf16 v[100:103], v[162:165], v[208:211], v[100:103]
	v_mfma_f32_16x16x32_bf16 v[96:99], v[170:173], v[208:211], v[96:99]
	s_setprio 0
	s_barrier
	v_lshl_add_u64 v[228:229], v[224:225], 0, s[68:69]
	s_add_u32 m0, s3, 0x18000
	ds_read_b128 v[212:215], v143
	ds_read_b128 v[216:219], v143 offset:1024
	ds_read_b128 v[238:241], v143 offset:2048
	ds_read_b128 v[242:245], v143 offset:3072
	global_load_lds_dwordx4 v[228:229], off
	v_lshl_add_u64 v[228:229], v[226:227], 0, s[68:69]
	s_add_u32 m0, s3, 0x1a000
	s_nop 0
	global_load_lds_dwordx4 v[228:229], off
	s_barrier
	s_waitcnt lgkmcnt(0)
	s_setprio 1
	s_waitcnt lgkmcnt(0)
	v_mfma_f32_16x16x32_bf16 v[92:95], v[212:215], v[180:183], v[92:95]
	v_mfma_f32_16x16x32_bf16 v[88:91], v[238:241], v[180:183], v[88:91]
	v_mfma_f32_16x16x32_bf16 v[84:87], v[212:215], v[188:191], v[84:87]
	v_mfma_f32_16x16x32_bf16 v[80:83], v[238:241], v[188:191], v[80:83]
	v_mfma_f32_16x16x32_bf16 v[76:79], v[212:215], v[196:199], v[76:79]
	v_mfma_f32_16x16x32_bf16 v[72:75], v[238:241], v[196:199], v[72:75]
	v_mfma_f32_16x16x32_bf16 v[68:71], v[212:215], v[204:207], v[68:71]
	v_mfma_f32_16x16x32_bf16 v[64:67], v[238:241], v[204:207], v[64:67]
	v_mfma_f32_16x16x32_bf16 v[92:95], v[216:219], v[184:187], v[92:95]
	v_mfma_f32_16x16x32_bf16 v[88:91], v[242:245], v[184:187], v[88:91]
	v_mfma_f32_16x16x32_bf16 v[84:87], v[216:219], v[192:195], v[84:87]
	v_mfma_f32_16x16x32_bf16 v[80:83], v[242:245], v[192:195], v[80:83]
	v_mfma_f32_16x16x32_bf16 v[76:79], v[216:219], v[200:203], v[76:79]
	v_mfma_f32_16x16x32_bf16 v[72:75], v[242:245], v[200:203], v[72:75]
	v_mfma_f32_16x16x32_bf16 v[68:71], v[216:219], v[208:211], v[68:71]
	v_mfma_f32_16x16x32_bf16 v[64:67], v[242:245], v[208:211], v[64:67]
	s_setprio 0
	v_lshl_add_u64 v[174:175], v[174:175], 0, s[68:69]
	s_add_u32 m0, s3, 0x8000
	s_barrier
	ds_read_b128 v[180:183], v142 offset:49152
	ds_read_b128 v[184:187], v142 offset:50176
	ds_read_b128 v[188:191], v141 offset:49152
	ds_read_b128 v[192:195], v141 offset:50176
	ds_read_b128 v[196:199], v140 offset:49152
	ds_read_b128 v[200:203], v140 offset:50176
	ds_read_b128 v[204:207], v139 offset:49152
	ds_read_b128 v[208:211], v139 offset:50176
	global_load_lds_dwordx4 v[174:175], off
	v_lshl_add_u64 v[174:175], v[222:223], 0, s[68:69]
	s_add_u32 m0, s3, 0xa000
	s_nop 0
	global_load_lds_dwordx4 v[174:175], off
	s_barrier
; #define STAGE_A(P, half, kt) do { const char* _u = Ab + ((size_t)(half) * 128 * lda + (size_t)(kt) * BK) * 2; \
;     _Pragma("unroll") for (int _i = 0; _i < 2; ++_i) \
;       __builtin_amdgcn_global_load_lds((const unsigned*)(_u + offA[_i]), \
;         (__attribute__((address_space(3))) unsigned*)((__attribute__((address_space(3))) char*)(P) + tidg * 16 + _i * 8192), 16, 0, 0); } while (0)
; #define STAGE_B(P, half, kt) do { const char* _u = Bb + ((size_t)(half) * 128 * ldb + (size_t)(kt) * BK) * 2; \
;     _Pragma("unroll") for (int _i = 0; _i < 2; ++_i) \
;       __builtin_amdgcn_global_load_lds((const unsigned*)(_u + offB[_i]), \
;         (__attribute__((address_space(3))) unsigned*)((__attribute__((address_space(3))) char*)(P) + tidg * 16 + _i * 8192), 16, 0, 0); } while (0)
; #define LDA(dst, b, h) _Pragma("unroll") for (int m = 0; m < 4; ++m) _Pragma("unroll") for (int k = 0; k < 2; ++k) \
;     dst[m][k] = *reinterpret_cast<const bf16x8*>((const char*)SA(b, h) + lds_byte(wr * 64 + m * 16 + fr, k * 32 + fq * 8))
; #define LDB(dst, b, h) _Pragma("unroll") for (int n = 0; n < 2; ++n) _Pragma("unroll") for (int k = 0; k < 2; ++k) \
;     dst[n][k] = *reinterpret_cast<const bf16x8*>((const char*)SB(b, h) + lds_byte(wc * 32 + n * 16 + fr, k * 32 + fq * 8))
; #define MMA(ai, bj, At_, Bt_) do { __builtin_amdgcn_s_setprio(1); \
;     _Pragma("unroll") for (int m = 0; m < 4; ++m) _Pragma("unroll") for (int n = 0; n < 2; ++n) _Pragma("unroll") for (int k = 0; k < 2; ++k) \
;       acc[ai][bj][m][n] = __builtin_amdgcn_mfma_f32_16x16x32_bf16(Bt_[n][k], At_[m][k], acc[ai][bj][m][n], 0, 0, 0); \
;     __builtin_amdgcn_s_setprio(0); } while (0)
; #define WAIT_V(n) asm volatile("s_waitcnt vmcnt(" #n ")" ::: "memory")
; template <bool PF = true, class Epi, class KRF = KRFull>
; __device__ __forceinline__ void gemm_phase(const u16* __restrict__ A, int lda, const u16* __restrict__ Bt, int ldb, int K, int nM, int nN,
;                                            lds_u16* shm, Epi epi, KRF krf = KRFull(), bool flip = false) {
;     ...
;       BAR; WAIT_L(0); MMA(1, 0, At, B0); BAR; SCHED;
;       STAGE_B(SB(1, 1), 1, t + 3);
;       WAIT_V(6); BAR; MMA(1, 1, At, B1); BAR;
;     }
;     { LDB(B0, 0, 0); LDA(At, 0, 0); STAGE_A(SA(1, 1), 1, nt - 1);
;       BAR; WAIT_L(0); MMA(0, 0, At, B0); BAR;
;       LDB(B1, 0, 1); BAR; WAIT_L(0); MMA(0, 1, At, B1); BAR;
	s_waitcnt lgkmcnt(0)
	s_setprio 1
	s_waitcnt lgkmcnt(0)
	v_mfma_f32_16x16x32_bf16 v[60:63], v[158:161], v[180:183], v[60:63]
	v_mfma_f32_16x16x32_bf16 v[56:59], v[166:169], v[180:183], v[56:59]
	v_mfma_f32_16x16x32_bf16 v[52:55], v[158:161], v[188:191], v[52:55]
	v_mfma_f32_16x16x32_bf16 v[48:51], v[166:169], v[188:191], v[48:51]
	v_mfma_f32_16x16x32_bf16 v[44:47], v[158:161], v[196:199], v[44:47]
	v_mfma_f32_16x16x32_bf16 v[40:43], v[166:169], v[196:199], v[40:43]
	v_mfma_f32_16x16x32_bf16 v[36:39], v[158:161], v[204:207], v[36:39]
	v_mfma_f32_16x16x32_bf16 v[32:35], v[166:169], v[204:207], v[32:35]
	v_mfma_f32_16x16x32_bf16 v[60:63], v[162:165], v[184:187], v[60:63]
	v_mfma_f32_16x16x32_bf16 v[56:59], v[170:173], v[184:187], v[56:59]
	v_mfma_f32_16x16x32_bf16 v[52:55], v[162:165], v[192:195], v[52:55]
	v_mfma_f32_16x16x32_bf16 v[48:51], v[170:173], v[192:195], v[48:51]
	v_mfma_f32_16x16x32_bf16 v[44:47], v[162:165], v[200:203], v[44:47]
	v_mfma_f32_16x16x32_bf16 v[40:43], v[170:173], v[200:203], v[40:43]
	v_mfma_f32_16x16x32_bf16 v[36:39], v[162:165], v[208:211], v[36:39]
	v_mfma_f32_16x16x32_bf16 v[32:35], v[170:173], v[208:211], v[32:35]
	s_setprio 0
	s_barrier
	v_lshl_add_u64 v[158:159], v[224:225], 0, s[70:71]
	s_add_u32 m0, s3, 0x1c000
	s_nop 0
	global_load_lds_dwordx4 v[158:159], off
	v_lshl_add_u64 v[158:159], v[226:227], 0, s[70:71]
	s_add_u32 m0, s3, 0x1e000
	s_nop 0
	global_load_lds_dwordx4 v[158:159], off
	s_waitcnt vmcnt(6)
	s_barrier
	s_setprio 1
	v_mfma_f32_16x16x32_bf16 v[28:31], v[212:215], v[180:183], v[28:31]
	v_mfma_f32_16x16x32_bf16 v[24:27], v[238:241], v[180:183], v[24:27]
	v_mfma_f32_16x16x32_bf16 v[20:23], v[212:215], v[188:191], v[20:23]
	v_mfma_f32_16x16x32_bf16 v[16:19], v[238:241], v[188:191], v[16:19]
	v_mfma_f32_16x16x32_bf16 v[12:15], v[212:215], v[196:199], v[12:15]
	v_mfma_f32_16x16x32_bf16 v[8:11], v[238:241], v[196:199], v[8:11]
	v_mfma_f32_16x16x32_bf16 v[4:7], v[212:215], v[204:207], v[4:7]
	v_mfma_f32_16x16x32_bf16 v[0:3], v[238:241], v[204:207], v[0:3]
	v_mfma_f32_16x16x32_bf16 v[28:31], v[216:219], v[184:187], v[28:31]
	v_mfma_f32_16x16x32_bf16 v[24:27], v[242:245], v[184:187], v[24:27]
	v_mfma_f32_16x16x32_bf16 v[20:23], v[216:219], v[192:195], v[20:23]
	v_mfma_f32_16x16x32_bf16 v[16:19], v[242:245], v[192:195], v[16:19]
	v_mfma_f32_16x16x32_bf16 v[12:15], v[216:219], v[200:203], v[12:15]
	v_mfma_f32_16x16x32_bf16 v[8:11], v[242:245], v[200:203], v[8:11]
	v_mfma_f32_16x16x32_bf16 v[4:7], v[216:219], v[208:211], v[4:7]
	v_mfma_f32_16x16x32_bf16 v[0:3], v[242:245], v[208:211], v[0:3]
	s_setprio 0
	s_add_i32 s2, s2, 2
	s_add_u32 s14, s14, 0x100
	s_addc_u32 s15, s15, 0
	s_cmp_gt_u32 s2, 27
	s_barrier
	s_cbranch_scc0 .LBB0_903
	s_add_u32 s2, s12, 0x80f80
	s_addc_u32 s3, s13, 0
	v_readfirstlane_b32 s4, v155
	v_lshl_add_u64 v[150:151], s[2:3], 0, v[178:179]
	s_mov_b32 m0, s4
	v_lshl_add_u64 v[128:129], s[2:3], 0, v[128:129]
	v_readfirstlane_b32 s2, v156
	ds_read_b128 v[130:133], v154
	ds_read_b128 v[134:137], v154 offset:1024
	ds_read_b128 v[146:149], v154 offset:2048
	ds_read_b128 v[158:161], v154 offset:3072
	ds_read_b128 v[162:165], v142
	ds_read_b128 v[166:169], v142 offset:1024
	ds_read_b128 v[170:173], v141
	ds_read_b128 v[180:183], v141 offset:1024
	ds_read_b128 v[184:187], v140
	ds_read_b128 v[188:191], v140 offset:1024
	ds_read_b128 v[192:195], v139
	ds_read_b128 v[196:199], v139 offset:1024
	global_load_lds_dwordx4 v[150:151], off
	s_mov_b32 m0, s2
	s_nop 0
	global_load_lds_dwordx4 v[128:129], off
	s_barrier
	s_waitcnt lgkmcnt(0)
	s_setprio 1
	s_waitcnt lgkmcnt(0)
	v_mfma_f32_16x16x32_bf16 v[124:127], v[130:133], v[162:165], v[124:127]
	v_mfma_f32_16x16x32_bf16 v[120:123], v[146:149], v[162:165], v[120:123]
	v_mfma_f32_16x16x32_bf16 v[116:119], v[130:133], v[170:173], v[116:119]
	v_mfma_f32_16x16x32_bf16 v[112:115], v[146:149], v[170:173], v[112:115]
	v_mfma_f32_16x16x32_bf16 v[108:111], v[130:133], v[184:187], v[108:111]
	v_mfma_f32_16x16x32_bf16 v[104:107], v[146:149], v[184:187], v[104:107]
	v_mfma_f32_16x16x32_bf16 v[100:103], v[130:133], v[192:195], v[100:103]
	v_mfma_f32_16x16x32_bf16 v[96:99], v[146:149], v[192:195], v[96:99]
	v_mfma_f32_16x16x32_bf16 v[124:127], v[134:137], v[166:169], v[124:127]
	v_mfma_f32_16x16x32_bf16 v[120:123], v[158:161], v[166:169], v[120:123]
	v_mfma_f32_16x16x32_bf16 v[116:119], v[134:137], v[180:183], v[116:119]
	v_mfma_f32_16x16x32_bf16 v[112:115], v[158:161], v[180:183], v[112:115]
	v_mfma_f32_16x16x32_bf16 v[108:111], v[134:137], v[188:191], v[108:111]
	v_mfma_f32_16x16x32_bf16 v[104:107], v[158:161], v[188:191], v[104:107]
	v_mfma_f32_16x16x32_bf16 v[100:103], v[134:137], v[196:199], v[100:103]
	v_mfma_f32_16x16x32_bf16 v[96:99], v[158:161], v[196:199], v[96:99]
	s_setprio 0
	s_barrier
	ds_read_b128 v[154:157], v153
	ds_read_b128 v[200:203], v153 offset:1024
	ds_read_b128 v[204:207], v153 offset:2048
	ds_read_b128 v[150:153], v153 offset:3072
	s_barrier
	s_waitcnt lgkmcnt(0)
	s_setprio 1
	s_waitcnt lgkmcnt(0)
	v_mfma_f32_16x16x32_bf16 v[92:95], v[154:157], v[162:165], v[92:95]
	v_mfma_f32_16x16x32_bf16 v[88:91], v[204:207], v[162:165], v[88:91]
	v_mfma_f32_16x16x32_bf16 v[84:87], v[154:157], v[170:173], v[84:87]
	v_mfma_f32_16x16x32_bf16 v[80:83], v[204:207], v[170:173], v[80:83]
	v_mfma_f32_16x16x32_bf16 v[76:79], v[154:157], v[184:187], v[76:79]
	v_mfma_f32_16x16x32_bf16 v[72:75], v[204:207], v[184:187], v[72:75]
	v_mfma_f32_16x16x32_bf16 v[68:71], v[154:157], v[192:195], v[68:71]
	v_mfma_f32_16x16x32_bf16 v[64:67], v[204:207], v[192:195], v[64:67]
	v_mfma_f32_16x16x32_bf16 v[92:95], v[200:203], v[166:169], v[92:95]
	v_mfma_f32_16x16x32_bf16 v[88:91], v[150:153], v[166:169], v[88:91]
	v_mfma_f32_16x16x32_bf16 v[84:87], v[200:203], v[180:183], v[84:87]
	v_mfma_f32_16x16x32_bf16 v[80:83], v[150:153], v[180:183], v[80:83]
	v_mfma_f32_16x16x32_bf16 v[76:79], v[200:203], v[188:191], v[76:79]
	v_mfma_f32_16x16x32_bf16 v[72:75], v[150:153], v[188:191], v[72:75]
	v_mfma_f32_16x16x32_bf16 v[68:71], v[200:203], v[196:199], v[68:71]
	v_mfma_f32_16x16x32_bf16 v[64:67], v[150:153], v[196:199], v[64:67]
	s_setprio 0
	s_barrier
; #define LDA(dst, b, h) _Pragma("unroll") for (int m = 0; m < 4; ++m) _Pragma("unroll") for (int k = 0; k < 2; ++k) \
;     dst[m][k] = *reinterpret_cast<const bf16x8*>((const char*)SA(b, h) + lds_byte(wr * 64 + m * 16 + fr, k * 32 + fq * 8))
; #define LDB(dst, b, h) _Pragma("unroll") for (int n = 0; n < 2; ++n) _Pragma("unroll") for (int k = 0; k < 2; ++k) \
;     dst[n][k] = *reinterpret_cast<const bf16x8*>((const char*)SB(b, h) + lds_byte(wc * 32 + n * 16 + fr, k * 32 + fq * 8))
; #define MMA(ai, bj, At_, Bt_) do { __builtin_amdgcn_s_setprio(1); \
;     _Pragma("unroll") for (int m = 0; m < 4; ++m) _Pragma("unroll") for (int n = 0; n < 2; ++n) _Pragma("unroll") for (int k = 0; k < 2; ++k) \
;       acc[ai][bj][m][n] = __builtin_amdgcn_mfma_f32_16x16x32_bf16(Bt_[n][k], At_[m][k], acc[ai][bj][m][n], 0, 0, 0); \
;     __builtin_amdgcn_s_setprio(0); } while (0)
; #define WAIT_V(n) asm volatile("s_waitcnt vmcnt(" #n ")" ::: "memory")
; #define WAIT_L(n) asm volatile("s_waitcnt lgkmcnt(" #n ")" ::: "memory")
; #define BAR __builtin_amdgcn_s_barrier()
; template <bool PF = true, class Epi, class KRF = KRFull>
; __device__ __forceinline__ void gemm_phase(const u16* __restrict__ A, int lda, const u16* __restrict__ Bt, int ldb, int K, int nM, int nN,
;                                            lds_u16* shm, Epi epi, KRF krf = KRFull(), bool flip = false) {
;     ...
;       LDA(At, 0, 1); WAIT_V(4); BAR; WAIT_L(0); MMA(1, 0, At, B0); MMA(1, 1, At, B1); BAR; }
;     { LDB(B0, 1, 0); LDA(At, 1, 0); WAIT_V(2); BAR; WAIT_L(0); MMA(0, 0, At, B0); BAR;
	ds_read_b128 v[162:165], v142 offset:16384
	ds_read_b128 v[166:169], v142 offset:17408
	ds_read_b128 v[170:173], v141 offset:16384
	ds_read_b128 v[180:183], v141 offset:17408
	ds_read_b128 v[184:187], v140 offset:16384
	ds_read_b128 v[188:191], v140 offset:17408
	ds_read_b128 v[192:195], v139 offset:16384
	ds_read_b128 v[196:199], v139 offset:17408
	s_waitcnt vmcnt(4)
	s_barrier
	s_waitcnt lgkmcnt(0)
	s_setprio 1
	s_waitcnt lgkmcnt(0)
	v_mfma_f32_16x16x32_bf16 v[60:63], v[130:133], v[162:165], v[60:63]
	v_mfma_f32_16x16x32_bf16 v[56:59], v[146:149], v[162:165], v[56:59]
	v_mfma_f32_16x16x32_bf16 v[52:55], v[130:133], v[170:173], v[52:55]
	v_mfma_f32_16x16x32_bf16 v[48:51], v[146:149], v[170:173], v[48:51]
	v_mfma_f32_16x16x32_bf16 v[44:47], v[130:133], v[184:187], v[44:47]
	v_mfma_f32_16x16x32_bf16 v[40:43], v[146:149], v[184:187], v[40:43]
	v_mfma_f32_16x16x32_bf16 v[36:39], v[130:133], v[192:195], v[36:39]
	v_mfma_f32_16x16x32_bf16 v[32:35], v[146:149], v[192:195], v[32:35]
	v_mfma_f32_16x16x32_bf16 v[60:63], v[134:137], v[166:169], v[60:63]
	v_mfma_f32_16x16x32_bf16 v[56:59], v[158:161], v[166:169], v[56:59]
	v_mfma_f32_16x16x32_bf16 v[52:55], v[134:137], v[180:183], v[52:55]
	v_mfma_f32_16x16x32_bf16 v[48:51], v[158:161], v[180:183], v[48:51]
	v_mfma_f32_16x16x32_bf16 v[44:47], v[134:137], v[188:191], v[44:47]
	v_mfma_f32_16x16x32_bf16 v[40:43], v[158:161], v[188:191], v[40:43]
	v_mfma_f32_16x16x32_bf16 v[36:39], v[134:137], v[196:199], v[36:39]
	v_mfma_f32_16x16x32_bf16 v[32:35], v[158:161], v[196:199], v[32:35]
	s_setprio 0
	s_setprio 1
	v_mfma_f32_16x16x32_bf16 v[28:31], v[154:157], v[162:165], v[28:31]
	v_mfma_f32_16x16x32_bf16 v[24:27], v[204:207], v[162:165], v[24:27]
	v_mfma_f32_16x16x32_bf16 v[20:23], v[154:157], v[170:173], v[20:23]
	v_mfma_f32_16x16x32_bf16 v[16:19], v[204:207], v[170:173], v[16:19]
	v_mfma_f32_16x16x32_bf16 v[12:15], v[154:157], v[184:187], v[12:15]
	v_mfma_f32_16x16x32_bf16 v[8:11], v[204:207], v[184:187], v[8:11]
	v_mfma_f32_16x16x32_bf16 v[4:7], v[154:157], v[192:195], v[4:7]
	v_mfma_f32_16x16x32_bf16 v[0:3], v[204:207], v[192:195], v[0:3]
	v_mfma_f32_16x16x32_bf16 v[28:31], v[200:203], v[166:169], v[28:31]
	v_mfma_f32_16x16x32_bf16 v[24:27], v[150:153], v[166:169], v[24:27]
	v_mfma_f32_16x16x32_bf16 v[20:23], v[200:203], v[180:183], v[20:23]
	v_mfma_f32_16x16x32_bf16 v[16:19], v[150:153], v[180:183], v[16:19]
	v_mfma_f32_16x16x32_bf16 v[12:15], v[200:203], v[188:191], v[12:15]
	v_mfma_f32_16x16x32_bf16 v[8:11], v[150:153], v[188:191], v[8:11]
	v_mfma_f32_16x16x32_bf16 v[4:7], v[200:203], v[196:199], v[4:7]
	v_mfma_f32_16x16x32_bf16 v[0:3], v[150:153], v[196:199], v[0:3]
	s_setprio 0
	s_barrier
	ds_read_b128 v[128:131], v145
	ds_read_b128 v[132:135], v145 offset:1024
	ds_read_b128 v[146:149], v145 offset:2048
	ds_read_b128 v[150:153], v145 offset:3072
	ds_read_b128 v[154:157], v142 offset:32768
	ds_read_b128 v[158:161], v142 offset:33792
	ds_read_b128 v[162:165], v141 offset:32768
	ds_read_b128 v[166:169], v141 offset:33792
	ds_read_b128 v[170:173], v140 offset:32768
	ds_read_b128 v[180:183], v140 offset:33792
	ds_read_b128 v[184:187], v139 offset:32768
	ds_read_b128 v[188:191], v139 offset:33792
	s_waitcnt vmcnt(2)
	s_barrier
	s_waitcnt lgkmcnt(0)
	s_setprio 1
	s_waitcnt lgkmcnt(0)
	v_mfma_f32_16x16x32_bf16 v[124:127], v[128:131], v[154:157], v[124:127]
	v_mfma_f32_16x16x32_bf16 v[120:123], v[146:149], v[154:157], v[120:123]
	v_mfma_f32_16x16x32_bf16 v[116:119], v[128:131], v[162:165], v[116:119]
	v_mfma_f32_16x16x32_bf16 v[112:115], v[146:149], v[162:165], v[112:115]
	v_mfma_f32_16x16x32_bf16 v[108:111], v[128:131], v[170:173], v[108:111]
	v_mfma_f32_16x16x32_bf16 v[104:107], v[146:149], v[170:173], v[104:107]
	v_mfma_f32_16x16x32_bf16 v[100:103], v[128:131], v[184:187], v[100:103]
	v_mfma_f32_16x16x32_bf16 v[96:99], v[146:149], v[184:187], v[96:99]
	v_mfma_f32_16x16x32_bf16 v[124:127], v[132:135], v[158:161], v[124:127]
	v_mfma_f32_16x16x32_bf16 v[120:123], v[150:153], v[158:161], v[120:123]
	v_mfma_f32_16x16x32_bf16 v[116:119], v[132:135], v[166:169], v[116:119]
	v_mfma_f32_16x16x32_bf16 v[112:115], v[150:153], v[166:169], v[112:115]
	v_mfma_f32_16x16x32_bf16 v[108:111], v[132:135], v[180:183], v[108:111]
	v_mfma_f32_16x16x32_bf16 v[104:107], v[150:153], v[180:183], v[104:107]
	v_mfma_f32_16x16x32_bf16 v[100:103], v[132:135], v[188:191], v[100:103]
	v_mfma_f32_16x16x32_bf16 v[96:99], v[150:153], v[188:191], v[96:99]
	s_setprio 0
	s_barrier
; #define LDA(dst, b, h) _Pragma("unroll") for (int m = 0; m < 4; ++m) _Pragma("unroll") for (int k = 0; k < 2; ++k) \
;     dst[m][k] = *reinterpret_cast<const bf16x8*>((const char*)SA(b, h) + lds_byte(wr * 64 + m * 16 + fr, k * 32 + fq * 8))
; #define LDB(dst, b, h) _Pragma("unroll") for (int n = 0; n < 2; ++n) _Pragma("unroll") for (int k = 0; k < 2; ++k) \
;     dst[n][k] = *reinterpret_cast<const bf16x8*>((const char*)SB(b, h) + lds_byte(wc * 32 + n * 16 + fr, k * 32 + fq * 8))
; #define MMA(ai, bj, At_, Bt_) do { __builtin_amdgcn_s_setprio(1); \
;     _Pragma("unroll") for (int m = 0; m < 4; ++m) _Pragma("unroll") for (int n = 0; n < 2; ++n) _Pragma("unroll") for (int k = 0; k < 2; ++k) \
;       acc[ai][bj][m][n] = __builtin_amdgcn_mfma_f32_16x16x32_bf16(Bt_[n][k], At_[m][k], acc[ai][bj][m][n], 0, 0, 0); \
;     __builtin_amdgcn_s_setprio(0); } while (0)
; #define WAIT_V(n) asm volatile("s_waitcnt vmcnt(" #n ")" ::: "memory")
; #define WAIT_L(n) asm volatile("s_waitcnt lgkmcnt(" #n ")" ::: "memory")
; #define BAR __builtin_amdgcn_s_barrier()
; template <bool PF = true, class Epi, class KRF = KRFull>
; __device__ __forceinline__ void gemm_phase(const u16* __restrict__ A, int lda, const u16* __restrict__ Bt, int ldb, int K, int nM, int nN,
;                                            lds_u16* shm, Epi epi, KRF krf = KRFull(), bool flip = false) {
;     ...
;       LDB(B1, 1, 1); WAIT_V(0); BAR; WAIT_L(0); MMA(0, 1, At, B1); BAR;
;       LDA(At, 1, 1); BAR; WAIT_L(0); MMA(1, 0, At, B0); MMA(1, 1, At, B1); BAR; }
;     if (wr == 0) BAR;
	ds_read_b128 v[192:195], v143
	ds_read_b128 v[196:199], v143 offset:1024
	ds_read_b128 v[200:203], v143 offset:2048
	ds_read_b128 v[204:207], v143 offset:3072
	s_waitcnt vmcnt(0)
	s_barrier
	s_waitcnt lgkmcnt(0)
	s_setprio 1
	s_waitcnt lgkmcnt(0)
	v_mfma_f32_16x16x32_bf16 v[92:95], v[192:195], v[154:157], v[92:95]
	v_mfma_f32_16x16x32_bf16 v[88:91], v[200:203], v[154:157], v[88:91]
	v_mfma_f32_16x16x32_bf16 v[84:87], v[192:195], v[162:165], v[84:87]
	v_mfma_f32_16x16x32_bf16 v[80:83], v[200:203], v[162:165], v[80:83]
	v_mfma_f32_16x16x32_bf16 v[76:79], v[192:195], v[170:173], v[76:79]
	v_mfma_f32_16x16x32_bf16 v[72:75], v[200:203], v[170:173], v[72:75]
	v_mfma_f32_16x16x32_bf16 v[68:71], v[192:195], v[184:187], v[68:71]
	v_mfma_f32_16x16x32_bf16 v[64:67], v[200:203], v[184:187], v[64:67]
	v_mfma_f32_16x16x32_bf16 v[92:95], v[196:199], v[158:161], v[92:95]
	v_mfma_f32_16x16x32_bf16 v[88:91], v[204:207], v[158:161], v[88:91]
	v_mfma_f32_16x16x32_bf16 v[84:87], v[196:199], v[166:169], v[84:87]
	v_mfma_f32_16x16x32_bf16 v[80:83], v[204:207], v[166:169], v[80:83]
	v_mfma_f32_16x16x32_bf16 v[76:79], v[196:199], v[180:183], v[76:79]
	v_mfma_f32_16x16x32_bf16 v[72:75], v[204:207], v[180:183], v[72:75]
	v_mfma_f32_16x16x32_bf16 v[68:71], v[196:199], v[188:191], v[68:71]
	v_mfma_f32_16x16x32_bf16 v[64:67], v[204:207], v[188:191], v[64:67]
	s_setprio 0
	s_barrier
	ds_read_b128 v[154:157], v142 offset:49152
	ds_read_b128 v[142:145], v142 offset:50176
	ds_read_b128 v[158:161], v141 offset:49152
	ds_read_b128 v[162:165], v141 offset:50176
	ds_read_b128 v[166:169], v140 offset:49152
	ds_read_b128 v[170:173], v140 offset:50176
	ds_read_b128 v[180:183], v139 offset:49152
	ds_read_b128 v[184:187], v139 offset:50176
	s_barrier
	s_waitcnt lgkmcnt(0)
	s_setprio 1
	s_waitcnt lgkmcnt(0)
	v_mfma_f32_16x16x32_bf16 v[60:63], v[128:131], v[154:157], v[60:63]
	v_mfma_f32_16x16x32_bf16 v[56:59], v[146:149], v[154:157], v[56:59]
	v_mfma_f32_16x16x32_bf16 v[52:55], v[128:131], v[158:161], v[52:55]
	v_mfma_f32_16x16x32_bf16 v[48:51], v[146:149], v[158:161], v[48:51]
	v_mfma_f32_16x16x32_bf16 v[44:47], v[128:131], v[166:169], v[44:47]
	v_mfma_f32_16x16x32_bf16 v[40:43], v[146:149], v[166:169], v[40:43]
	v_mfma_f32_16x16x32_bf16 v[36:39], v[128:131], v[180:183], v[36:39]
	v_mfma_f32_16x16x32_bf16 v[32:35], v[146:149], v[180:183], v[32:35]
	v_mfma_f32_16x16x32_bf16 v[60:63], v[132:135], v[142:145], v[60:63]
	v_mfma_f32_16x16x32_bf16 v[56:59], v[150:153], v[142:145], v[56:59]
	v_mfma_f32_16x16x32_bf16 v[52:55], v[132:135], v[162:165], v[52:55]
	v_mfma_f32_16x16x32_bf16 v[48:51], v[150:153], v[162:165], v[48:51]
	v_mfma_f32_16x16x32_bf16 v[44:47], v[132:135], v[170:173], v[44:47]
	v_mfma_f32_16x16x32_bf16 v[40:43], v[150:153], v[170:173], v[40:43]
	v_mfma_f32_16x16x32_bf16 v[36:39], v[132:135], v[184:187], v[36:39]
	v_mfma_f32_16x16x32_bf16 v[32:35], v[150:153], v[184:187], v[32:35]
	s_setprio 0
	s_setprio 1
	v_mfma_f32_16x16x32_bf16 v[28:31], v[192:195], v[154:157], v[28:31]
	v_mfma_f32_16x16x32_bf16 v[24:27], v[200:203], v[154:157], v[24:27]
	v_mfma_f32_16x16x32_bf16 v[20:23], v[192:195], v[158:161], v[20:23]
	v_mfma_f32_16x16x32_bf16 v[16:19], v[200:203], v[158:161], v[16:19]
	v_mfma_f32_16x16x32_bf16 v[12:15], v[192:195], v[166:169], v[12:15]
	v_mfma_f32_16x16x32_bf16 v[8:11], v[200:203], v[166:169], v[8:11]
	v_mfma_f32_16x16x32_bf16 v[4:7], v[192:195], v[180:183], v[4:7]
	v_mfma_f32_16x16x32_bf16 v[0:3], v[200:203], v[180:183], v[0:3]
	v_mfma_f32_16x16x32_bf16 v[28:31], v[196:199], v[142:145], v[28:31]
	v_mfma_f32_16x16x32_bf16 v[24:27], v[204:207], v[142:145], v[24:27]
	v_mfma_f32_16x16x32_bf16 v[20:23], v[196:199], v[162:165], v[20:23]
	v_mfma_f32_16x16x32_bf16 v[16:19], v[204:207], v[162:165], v[16:19]
	v_mfma_f32_16x16x32_bf16 v[12:15], v[196:199], v[170:173], v[12:15]
	v_mfma_f32_16x16x32_bf16 v[8:11], v[204:207], v[170:173], v[8:11]
	v_mfma_f32_16x16x32_bf16 v[4:7], v[196:199], v[184:187], v[4:7]
	v_mfma_f32_16x16x32_bf16 v[0:3], v[204:207], v[184:187], v[0:3]
	s_setprio 0
	v_cmp_gt_u32_e32 vcc, s95, v138
	s_barrier
	s_and_saveexec_b64 s[14:15], vcc
	s_cbranch_execz .LBB0_906
	s_barrier

; #define STAGE_A(P, half, kt) do { const char* _u = Ab + ((size_t)(half) * 128 * lda + (size_t)(kt) * BK) * 2; \
;     _Pragma("unroll") for (int _i = 0; _i < 2; ++_i) \
;       __builtin_amdgcn_global_load_lds((const unsigned*)(_u + offA[_i]), \
;         (__attribute__((address_space(3))) unsigned*)((__attribute__((address_space(3))) char*)(P) + tidg * 16 + _i * 8192), 16, 0, 0); } while (0)
; #define STAGE_B(P, half, kt) do { const char* _u = Bb + ((size_t)(half) * 128 * ldb + (size_t)(kt) * BK) * 2; \
;     _Pragma("unroll") for (int _i = 0; _i < 2; ++_i) \
;       __builtin_amdgcn_global_load_lds((const unsigned*)(_u + offB[_i]), \
;         (__attribute__((address_space(3))) unsigned*)((__attribute__((address_space(3))) char*)(P) + tidg * 16 + _i * 8192), 16, 0, 0); } while (0)
; #define LDA(dst, b, h) _Pragma("unroll") for (int m = 0; m < 4; ++m) _Pragma("unroll") for (int k = 0; k < 2; ++k) \
;     dst[m][k] = *reinterpret_cast<const bf16x8*>((const char*)SA(b, h) + lds_byte(wr * 64 + m * 16 + fr, k * 32 + fq * 8))
; #define LDB(dst, b, h) _Pragma("unroll") for (int n = 0; n < 2; ++n) _Pragma("unroll") for (int k = 0; k < 2; ++k) \
;     dst[n][k] = *reinterpret_cast<const bf16x8*>((const char*)SB(b, h) + lds_byte(wc * 32 + n * 16 + fr, k * 32 + fq * 8))
; #define MMA(ai, bj, At_, Bt_) do { __builtin_amdgcn_s_setprio(1); \
;     _Pragma("unroll") for (int m = 0; m < 4; ++m) _Pragma("unroll") for (int n = 0; n < 2; ++n) _Pragma("unroll") for (int k = 0; k < 2; ++k) \
;       acc[ai][bj][m][n] = __builtin_amdgcn_mfma_f32_16x16x32_bf16(Bt_[n][k], At_[m][k], acc[ai][bj][m][n], 0, 0, 0); \
;     __builtin_amdgcn_s_setprio(0); } while (0)
; template <bool PF = true, class Epi, class KRF = KRFull>
; __device__ __forceinline__ void gemm_phase(const u16* __restrict__ A, int lda, const u16* __restrict__ Bt, int ldb, int K, int nM, int nN,
;                                            lds_u16* shm, Epi epi, KRF krf = KRFull(), bool flip = false) {
;     ...
;     for (int t = 0; t < nt - 2; t += 2) {
;       LDB(B0, 0, 0); SCHED; LDA(At, 0, 0); STAGE_A(SA(1, 1), 1, t + 1);
;       WAIT_L(8); BAR; WAIT_L(0); MMA(0, 0, At, B0); BAR; SCHED;
;       LDB(B1, 0, 1); STAGE_B(SB(0, 0), 0, t + 2);
;       BAR; WAIT_L(0); MMA(0, 1, At, B1); BAR;
;       LDA(At, 0, 1); STAGE_A(SA(0, 0), 0, t + 2);
;       BAR; WAIT_L(0); MMA(1, 0, At, B0); BAR; SCHED;
.LBB0_922:
	v_readfirstlane_b32 s24, v144
	ds_read_b128 v[158:161], v154
	ds_read_b128 v[162:165], v154 offset:1024
	ds_read_b128 v[166:169], v154 offset:2048
	ds_read_b128 v[170:173], v154 offset:3072
	v_add_u32_e32 v155, 0xc000, v144
	v_lshl_add_u64 v[174:175], v[134:135], 0, s[14:15]
	v_lshl_add_u64 v[156:157], v[174:175], 0, s[72:73]
	s_add_u32 m0, s24, 0xc000
	ds_read_b128 v[180:183], v142
	ds_read_b128 v[184:187], v142 offset:1024
	ds_read_b128 v[188:191], v141
	ds_read_b128 v[192:195], v141 offset:1024
	ds_read_b128 v[196:199], v140
	ds_read_b128 v[200:203], v140 offset:1024
	ds_read_b128 v[204:207], v139
	ds_read_b128 v[208:211], v139 offset:1024
	global_load_lds_dwordx4 v[156:157], off
	v_add_u32_e32 v156, 0xe000, v144
	v_lshl_add_u64 v[222:223], v[136:137], 0, s[14:15]
	v_lshl_add_u64 v[212:213], v[222:223], 0, s[72:73]
	s_add_u32 m0, s24, 0xe000
	s_nop 0
	global_load_lds_dwordx4 v[212:213], off
	s_waitcnt lgkmcnt(8)
	s_barrier
	s_waitcnt lgkmcnt(0)
	s_setprio 1
	s_waitcnt lgkmcnt(0)
	v_mfma_f32_16x16x32_bf16 v[124:127], v[158:161], v[180:183], v[124:127]
	v_mfma_f32_16x16x32_bf16 v[120:123], v[166:169], v[180:183], v[120:123]
	v_mfma_f32_16x16x32_bf16 v[116:119], v[158:161], v[188:191], v[116:119]
	v_mfma_f32_16x16x32_bf16 v[112:115], v[166:169], v[188:191], v[112:115]
	v_mfma_f32_16x16x32_bf16 v[108:111], v[158:161], v[196:199], v[108:111]
	v_mfma_f32_16x16x32_bf16 v[104:107], v[166:169], v[196:199], v[104:107]
	v_mfma_f32_16x16x32_bf16 v[100:103], v[158:161], v[204:207], v[100:103]
	v_mfma_f32_16x16x32_bf16 v[96:99], v[166:169], v[204:207], v[96:99]
	v_mfma_f32_16x16x32_bf16 v[124:127], v[162:165], v[184:187], v[124:127]
	v_mfma_f32_16x16x32_bf16 v[120:123], v[170:173], v[184:187], v[120:123]
	v_mfma_f32_16x16x32_bf16 v[116:119], v[162:165], v[192:195], v[116:119]
	v_mfma_f32_16x16x32_bf16 v[112:115], v[170:173], v[192:195], v[112:115]
	v_mfma_f32_16x16x32_bf16 v[108:111], v[162:165], v[200:203], v[108:111]
	v_mfma_f32_16x16x32_bf16 v[104:107], v[170:173], v[200:203], v[104:107]
	v_mfma_f32_16x16x32_bf16 v[100:103], v[162:165], v[208:211], v[100:103]
	v_mfma_f32_16x16x32_bf16 v[96:99], v[170:173], v[208:211], v[96:99]
	s_setprio 0
	s_barrier
	v_add_u32_e32 v157, 0x10000, v144
	v_lshl_add_u64 v[224:225], v[130:131], 0, s[14:15]
	v_lshl_add_u64 v[226:227], v[224:225], 0, s[64:65]
	s_add_u32 m0, s24, 0x10000
	v_add_u32_e32 v157, 0x12000, v144
	ds_read_b128 v[212:215], v153
	ds_read_b128 v[216:219], v153 offset:1024
	ds_read_b128 v[238:241], v153 offset:2048
	ds_read_b128 v[242:245], v153 offset:3072
	global_load_lds_dwordx4 v[226:227], off
	v_lshl_add_u64 v[226:227], v[132:133], 0, s[14:15]
	v_lshl_add_u64 v[228:229], v[226:227], 0, s[64:65]
	s_add_u32 m0, s24, 0x12000
	s_nop 0
	global_load_lds_dwordx4 v[228:229], off
	s_barrier
	s_waitcnt lgkmcnt(0)
	s_setprio 1
	s_waitcnt lgkmcnt(0)
	v_mfma_f32_16x16x32_bf16 v[92:95], v[212:215], v[180:183], v[92:95]
	v_mfma_f32_16x16x32_bf16 v[88:91], v[238:241], v[180:183], v[88:91]
	v_mfma_f32_16x16x32_bf16 v[84:87], v[212:215], v[188:191], v[84:87]
	v_mfma_f32_16x16x32_bf16 v[80:83], v[238:241], v[188:191], v[80:83]
	v_mfma_f32_16x16x32_bf16 v[76:79], v[212:215], v[196:199], v[76:79]
	v_mfma_f32_16x16x32_bf16 v[72:75], v[238:241], v[196:199], v[72:75]
	v_mfma_f32_16x16x32_bf16 v[68:71], v[212:215], v[204:207], v[68:71]
	v_mfma_f32_16x16x32_bf16 v[64:67], v[238:241], v[204:207], v[64:67]
	v_mfma_f32_16x16x32_bf16 v[92:95], v[216:219], v[184:187], v[92:95]
	v_mfma_f32_16x16x32_bf16 v[88:91], v[242:245], v[184:187], v[88:91]
	v_mfma_f32_16x16x32_bf16 v[84:87], v[216:219], v[192:195], v[84:87]
	v_mfma_f32_16x16x32_bf16 v[80:83], v[242:245], v[192:195], v[80:83]
	v_mfma_f32_16x16x32_bf16 v[76:79], v[216:219], v[200:203], v[76:79]
	v_mfma_f32_16x16x32_bf16 v[72:75], v[242:245], v[200:203], v[72:75]
	v_mfma_f32_16x16x32_bf16 v[68:71], v[216:219], v[208:211], v[68:71]
	v_mfma_f32_16x16x32_bf16 v[64:67], v[242:245], v[208:211], v[64:67]
	s_setprio 0
	v_lshl_add_u64 v[228:229], v[174:175], 0, s[64:65]
	s_mov_b32 m0, s24
	s_barrier
	ds_read_b128 v[180:183], v142 offset:16384
	ds_read_b128 v[184:187], v142 offset:17408
	ds_read_b128 v[188:191], v141 offset:16384
	ds_read_b128 v[192:195], v141 offset:17408
	ds_read_b128 v[196:199], v140 offset:16384
	ds_read_b128 v[200:203], v140 offset:17408
	ds_read_b128 v[204:207], v139 offset:16384
	ds_read_b128 v[208:211], v139 offset:17408
	global_load_lds_dwordx4 v[228:229], off
	v_lshl_add_u64 v[228:229], v[222:223], 0, s[64:65]
	s_add_u32 m0, s24, 0x2000
	s_nop 0
	global_load_lds_dwordx4 v[228:229], off
	s_barrier
	s_waitcnt lgkmcnt(0)
	s_setprio 1
	s_waitcnt lgkmcnt(0)
	v_mfma_f32_16x16x32_bf16 v[60:63], v[158:161], v[180:183], v[60:63]
	v_mfma_f32_16x16x32_bf16 v[56:59], v[166:169], v[180:183], v[56:59]
	v_mfma_f32_16x16x32_bf16 v[52:55], v[158:161], v[188:191], v[52:55]
	v_mfma_f32_16x16x32_bf16 v[48:51], v[166:169], v[188:191], v[48:51]
	v_mfma_f32_16x16x32_bf16 v[44:47], v[158:161], v[196:199], v[44:47]
	v_mfma_f32_16x16x32_bf16 v[40:43], v[166:169], v[196:199], v[40:43]
	v_mfma_f32_16x16x32_bf16 v[36:39], v[158:161], v[204:207], v[36:39]
	v_mfma_f32_16x16x32_bf16 v[32:35], v[166:169], v[204:207], v[32:35]
	v_mfma_f32_16x16x32_bf16 v[60:63], v[162:165], v[184:187], v[60:63]
	v_mfma_f32_16x16x32_bf16 v[56:59], v[170:173], v[184:187], v[56:59]
	v_mfma_f32_16x16x32_bf16 v[52:55], v[162:165], v[192:195], v[52:55]
	v_mfma_f32_16x16x32_bf16 v[48:51], v[170:173], v[192:195], v[48:51]
	v_mfma_f32_16x16x32_bf16 v[44:47], v[162:165], v[200:203], v[44:47]
	v_mfma_f32_16x16x32_bf16 v[40:43], v[170:173], v[200:203], v[40:43]
	v_mfma_f32_16x16x32_bf16 v[36:39], v[162:165], v[208:211], v[36:39]
	v_mfma_f32_16x16x32_bf16 v[32:35], v[170:173], v[208:211], v[32:35]
	s_setprio 0
	s_barrier
; #define STAGE_A(P, half, kt) do { const char* _u = Ab + ((size_t)(half) * 128 * lda + (size_t)(kt) * BK) * 2; \
;     _Pragma("unroll") for (int _i = 0; _i < 2; ++_i) \
;       __builtin_amdgcn_global_load_lds((const unsigned*)(_u + offA[_i]), \
;         (__attribute__((address_space(3))) unsigned*)((__attribute__((address_space(3))) char*)(P) + tidg * 16 + _i * 8192), 16, 0, 0); } while (0)
; #define STAGE_B(P, half, kt) do { const char* _u = Bb + ((size_t)(half) * 128 * ldb + (size_t)(kt) * BK) * 2; \
;     _Pragma("unroll") for (int _i = 0; _i < 2; ++_i) \
;       __builtin_amdgcn_global_load_lds((const unsigned*)(_u + offB[_i]), \
;         (__attribute__((address_space(3))) unsigned*)((__attribute__((address_space(3))) char*)(P) + tidg * 16 + _i * 8192), 16, 0, 0); } while (0)
; #define LDA(dst, b, h) _Pragma("unroll") for (int m = 0; m < 4; ++m) _Pragma("unroll") for (int k = 0; k < 2; ++k) \
;     dst[m][k] = *reinterpret_cast<const bf16x8*>((const char*)SA(b, h) + lds_byte(wr * 64 + m * 16 + fr, k * 32 + fq * 8))
; #define LDB(dst, b, h) _Pragma("unroll") for (int n = 0; n < 2; ++n) _Pragma("unroll") for (int k = 0; k < 2; ++k) \
;     dst[n][k] = *reinterpret_cast<const bf16x8*>((const char*)SB(b, h) + lds_byte(wc * 32 + n * 16 + fr, k * 32 + fq * 8))
; #define MMA(ai, bj, At_, Bt_) do { __builtin_amdgcn_s_setprio(1); \
;     _Pragma("unroll") for (int m = 0; m < 4; ++m) _Pragma("unroll") for (int n = 0; n < 2; ++n) _Pragma("unroll") for (int k = 0; k < 2; ++k) \
;       acc[ai][bj][m][n] = __builtin_amdgcn_mfma_f32_16x16x32_bf16(Bt_[n][k], At_[m][k], acc[ai][bj][m][n], 0, 0, 0); \
;     __builtin_amdgcn_s_setprio(0); } while (0)
; #define BAR __builtin_amdgcn_s_barrier()
; template <bool PF = true, class Epi, class KRF = KRFull>
; __device__ __forceinline__ void gemm_phase(const u16* __restrict__ A, int lda, const u16* __restrict__ Bt, int ldb, int K, int nM, int nN,
;                                            lds_u16* shm, Epi epi, KRF krf = KRFull(), bool flip = false) {
;     ...
;       STAGE_B(SB(0, 1), 1, t + 2);
;       WAIT_V(6); BAR; MMA(1, 1, At, B1); BAR;
;       LDB(B0, 1, 0); SCHED; LDA(At, 1, 0); STAGE_A(SA(0, 1), 1, t + 2);
;       WAIT_L(8); BAR; WAIT_L(0); MMA(0, 0, At, B0); BAR; SCHED;
;       LDB(B1, 1, 1); STAGE_B(SB(1, 0), 0, t + 3);
;       BAR; WAIT_L(0); MMA(0, 1, At, B1); BAR;
;       LDA(At, 1, 1); STAGE_A(SA(1, 0), 0, t + 3);
	v_add_u32_e32 v157, 0x14000, v144
	v_lshl_add_u64 v[158:159], v[224:225], 0, s[74:75]
	v_add_u32_e32 v157, 0x16000, v144
	s_add_u32 m0, s24, 0x14000
	s_nop 0
	global_load_lds_dwordx4 v[158:159], off
	v_lshl_add_u64 v[158:159], v[226:227], 0, s[74:75]
	s_add_u32 m0, s24, 0x16000
	s_nop 0
	global_load_lds_dwordx4 v[158:159], off
	s_waitcnt vmcnt(6)
	s_barrier
	s_setprio 1
	v_mfma_f32_16x16x32_bf16 v[28:31], v[212:215], v[180:183], v[28:31]
	v_mfma_f32_16x16x32_bf16 v[24:27], v[238:241], v[180:183], v[24:27]
	v_mfma_f32_16x16x32_bf16 v[20:23], v[212:215], v[188:191], v[20:23]
	v_mfma_f32_16x16x32_bf16 v[16:19], v[238:241], v[188:191], v[16:19]
	v_mfma_f32_16x16x32_bf16 v[12:15], v[212:215], v[196:199], v[12:15]
	v_mfma_f32_16x16x32_bf16 v[8:11], v[238:241], v[196:199], v[8:11]
	v_mfma_f32_16x16x32_bf16 v[4:7], v[212:215], v[204:207], v[4:7]
	v_mfma_f32_16x16x32_bf16 v[0:3], v[238:241], v[204:207], v[0:3]
	v_mfma_f32_16x16x32_bf16 v[28:31], v[216:219], v[184:187], v[28:31]
	v_mfma_f32_16x16x32_bf16 v[24:27], v[242:245], v[184:187], v[24:27]
	v_mfma_f32_16x16x32_bf16 v[20:23], v[216:219], v[192:195], v[20:23]
	v_mfma_f32_16x16x32_bf16 v[16:19], v[242:245], v[192:195], v[16:19]
	v_mfma_f32_16x16x32_bf16 v[12:15], v[216:219], v[200:203], v[12:15]
	v_mfma_f32_16x16x32_bf16 v[8:11], v[242:245], v[200:203], v[8:11]
	v_mfma_f32_16x16x32_bf16 v[4:7], v[216:219], v[208:211], v[4:7]
	v_mfma_f32_16x16x32_bf16 v[0:3], v[242:245], v[208:211], v[0:3]
	s_setprio 0
	s_barrier
	ds_read_b128 v[158:161], v145
	ds_read_b128 v[162:165], v145 offset:1024
	ds_read_b128 v[166:169], v145 offset:2048
	ds_read_b128 v[170:173], v145 offset:3072
	v_add_u32_e32 v157, 0x4000, v144
	v_lshl_add_u64 v[212:213], v[174:175], 0, s[74:75]
	v_add_u32_e32 v157, 0x6000, v144
	s_add_u32 m0, s24, 0x4000
	ds_read_b128 v[180:183], v142 offset:32768
	ds_read_b128 v[184:187], v142 offset:33792
	ds_read_b128 v[188:191], v141 offset:32768
	ds_read_b128 v[192:195], v141 offset:33792
	ds_read_b128 v[196:199], v140 offset:32768
	ds_read_b128 v[200:203], v140 offset:33792
	ds_read_b128 v[204:207], v139 offset:32768
	ds_read_b128 v[208:211], v139 offset:33792
	global_load_lds_dwordx4 v[212:213], off
	v_lshl_add_u64 v[212:213], v[222:223], 0, s[74:75]
	s_add_u32 m0, s24, 0x6000
	s_nop 0
	global_load_lds_dwordx4 v[212:213], off
	s_waitcnt lgkmcnt(8)
	s_barrier
	s_waitcnt lgkmcnt(0)
	s_setprio 1
	s_waitcnt lgkmcnt(0)
	v_mfma_f32_16x16x32_bf16 v[124:127], v[158:161], v[180:183], v[124:127]
	v_mfma_f32_16x16x32_bf16 v[120:123], v[166:169], v[180:183], v[120:123]
	v_mfma_f32_16x16x32_bf16 v[116:119], v[158:161], v[188:191], v[116:119]
	v_mfma_f32_16x16x32_bf16 v[112:115], v[166:169], v[188:191], v[112:115]
	v_mfma_f32_16x16x32_bf16 v[108:111], v[158:161], v[196:199], v[108:111]
	v_mfma_f32_16x16x32_bf16 v[104:107], v[166:169], v[196:199], v[104:107]
	v_mfma_f32_16x16x32_bf16 v[100:103], v[158:161], v[204:207], v[100:103]
	v_mfma_f32_16x16x32_bf16 v[96:99], v[166:169], v[204:207], v[96:99]
	v_mfma_f32_16x16x32_bf16 v[124:127], v[162:165], v[184:187], v[124:127]
	v_mfma_f32_16x16x32_bf16 v[120:123], v[170:173], v[184:187], v[120:123]
	v_mfma_f32_16x16x32_bf16 v[116:119], v[162:165], v[192:195], v[116:119]
	v_mfma_f32_16x16x32_bf16 v[112:115], v[170:173], v[192:195], v[112:115]
	v_mfma_f32_16x16x32_bf16 v[108:111], v[162:165], v[200:203], v[108:111]
	v_mfma_f32_16x16x32_bf16 v[104:107], v[170:173], v[200:203], v[104:107]
	v_mfma_f32_16x16x32_bf16 v[100:103], v[162:165], v[208:211], v[100:103]
	v_mfma_f32_16x16x32_bf16 v[96:99], v[170:173], v[208:211], v[96:99]
	s_setprio 0
	s_barrier
	v_lshl_add_u64 v[228:229], v[224:225], 0, s[68:69]
	s_add_u32 m0, s24, 0x18000
	ds_read_b128 v[212:215], v143
	ds_read_b128 v[216:219], v143 offset:1024
	ds_read_b128 v[238:241], v143 offset:2048
	ds_read_b128 v[242:245], v143 offset:3072
	global_load_lds_dwordx4 v[228:229], off
	v_lshl_add_u64 v[228:229], v[226:227], 0, s[68:69]
	s_add_u32 m0, s24, 0x1a000
	s_nop 0
	global_load_lds_dwordx4 v[228:229], off
	s_barrier
	s_waitcnt lgkmcnt(0)
	s_setprio 1
	s_waitcnt lgkmcnt(0)
	v_mfma_f32_16x16x32_bf16 v[92:95], v[212:215], v[180:183], v[92:95]
	v_mfma_f32_16x16x32_bf16 v[88:91], v[238:241], v[180:183], v[88:91]
	v_mfma_f32_16x16x32_bf16 v[84:87], v[212:215], v[188:191], v[84:87]
	v_mfma_f32_16x16x32_bf16 v[80:83], v[238:241], v[188:191], v[80:83]
	v_mfma_f32_16x16x32_bf16 v[76:79], v[212:215], v[196:199], v[76:79]
	v_mfma_f32_16x16x32_bf16 v[72:75], v[238:241], v[196:199], v[72:75]
	v_mfma_f32_16x16x32_bf16 v[68:71], v[212:215], v[204:207], v[68:71]
	v_mfma_f32_16x16x32_bf16 v[64:67], v[238:241], v[204:207], v[64:67]
	v_mfma_f32_16x16x32_bf16 v[92:95], v[216:219], v[184:187], v[92:95]
	v_mfma_f32_16x16x32_bf16 v[88:91], v[242:245], v[184:187], v[88:91]
	v_mfma_f32_16x16x32_bf16 v[84:87], v[216:219], v[192:195], v[84:87]
	v_mfma_f32_16x16x32_bf16 v[80:83], v[242:245], v[192:195], v[80:83]
	v_mfma_f32_16x16x32_bf16 v[76:79], v[216:219], v[200:203], v[76:79]
	v_mfma_f32_16x16x32_bf16 v[72:75], v[242:245], v[200:203], v[72:75]
	v_mfma_f32_16x16x32_bf16 v[68:71], v[216:219], v[208:211], v[68:71]
	v_mfma_f32_16x16x32_bf16 v[64:67], v[242:245], v[208:211], v[64:67]
	s_setprio 0
	v_lshl_add_u64 v[174:175], v[174:175], 0, s[68:69]
	s_add_u32 m0, s24, 0x8000
	s_barrier
	ds_read_b128 v[180:183], v142 offset:49152
	ds_read_b128 v[184:187], v142 offset:50176
	ds_read_b128 v[188:191], v141 offset:49152
	ds_read_b128 v[192:195], v141 offset:50176
	ds_read_b128 v[196:199], v140 offset:49152
	ds_read_b128 v[200:203], v140 offset:50176
	ds_read_b128 v[204:207], v139 offset:49152
	ds_read_b128 v[208:211], v139 offset:50176
	global_load_lds_dwordx4 v[174:175], off
	v_lshl_add_u64 v[174:175], v[222:223], 0, s[68:69]
	s_add_u32 m0, s24, 0xa000
	s_nop 0
	global_load_lds_dwordx4 v[174:175], off
	s_barrier
; #define STAGE_A(P, half, kt) do { const char* _u = Ab + ((size_t)(half) * 128 * lda + (size_t)(kt) * BK) * 2; \
;     _Pragma("unroll") for (int _i = 0; _i < 2; ++_i) \
;       __builtin_amdgcn_global_load_lds((const unsigned*)(_u + offA[_i]), \
;         (__attribute__((address_space(3))) unsigned*)((__attribute__((address_space(3))) char*)(P) + tidg * 16 + _i * 8192), 16, 0, 0); } while (0)
; #define STAGE_B(P, half, kt) do { const char* _u = Bb + ((size_t)(half) * 128 * ldb + (size_t)(kt) * BK) * 2; \
;     _Pragma("unroll") for (int _i = 0; _i < 2; ++_i) \
;       __builtin_amdgcn_global_load_lds((const unsigned*)(_u + offB[_i]), \
;         (__attribute__((address_space(3))) unsigned*)((__attribute__((address_space(3))) char*)(P) + tidg * 16 + _i * 8192), 16, 0, 0); } while (0)
; #define LDA(dst, b, h) _Pragma("unroll") for (int m = 0; m < 4; ++m) _Pragma("unroll") for (int k = 0; k < 2; ++k) \
;     dst[m][k] = *reinterpret_cast<const bf16x8*>((const char*)SA(b, h) + lds_byte(wr * 64 + m * 16 + fr, k * 32 + fq * 8))
; #define LDB(dst, b, h) _Pragma("unroll") for (int n = 0; n < 2; ++n) _Pragma("unroll") for (int k = 0; k < 2; ++k) \
;     dst[n][k] = *reinterpret_cast<const bf16x8*>((const char*)SB(b, h) + lds_byte(wc * 32 + n * 16 + fr, k * 32 + fq * 8))
; #define MMA(ai, bj, At_, Bt_) do { __builtin_amdgcn_s_setprio(1); \
;     _Pragma("unroll") for (int m = 0; m < 4; ++m) _Pragma("unroll") for (int n = 0; n < 2; ++n) _Pragma("unroll") for (int k = 0; k < 2; ++k) \
;       acc[ai][bj][m][n] = __builtin_amdgcn_mfma_f32_16x16x32_bf16(Bt_[n][k], At_[m][k], acc[ai][bj][m][n], 0, 0, 0); \
;     __builtin_amdgcn_s_setprio(0); } while (0)
; #define WAIT_V(n) asm volatile("s_waitcnt vmcnt(" #n ")" ::: "memory")
; template <bool PF = true, class Epi, class KRF = KRFull>
; __device__ __forceinline__ void gemm_phase(const u16* __restrict__ A, int lda, const u16* __restrict__ Bt, int ldb, int K, int nM, int nN,
;                                            lds_u16* shm, Epi epi, KRF krf = KRFull(), bool flip = false) {
;     ...
;       BAR; WAIT_L(0); MMA(1, 0, At, B0); BAR; SCHED;
;       STAGE_B(SB(1, 1), 1, t + 3);
;       WAIT_V(6); BAR; MMA(1, 1, At, B1); BAR;
;     }
;     { LDB(B0, 0, 0); LDA(At, 0, 0); STAGE_A(SA(1, 1), 1, nt - 1);
;       BAR; WAIT_L(0); MMA(0, 0, At, B0); BAR;
;       LDB(B1, 0, 1); BAR; WAIT_L(0); MMA(0, 1, At, B1); BAR;
	s_waitcnt lgkmcnt(0)
	s_setprio 1
	s_waitcnt lgkmcnt(0)
	v_mfma_f32_16x16x32_bf16 v[60:63], v[158:161], v[180:183], v[60:63]
	v_mfma_f32_16x16x32_bf16 v[56:59], v[166:169], v[180:183], v[56:59]
	v_mfma_f32_16x16x32_bf16 v[52:55], v[158:161], v[188:191], v[52:55]
	v_mfma_f32_16x16x32_bf16 v[48:51], v[166:169], v[188:191], v[48:51]
	v_mfma_f32_16x16x32_bf16 v[44:47], v[158:161], v[196:199], v[44:47]
	v_mfma_f32_16x16x32_bf16 v[40:43], v[166:169], v[196:199], v[40:43]
	v_mfma_f32_16x16x32_bf16 v[36:39], v[158:161], v[204:207], v[36:39]
	v_mfma_f32_16x16x32_bf16 v[32:35], v[166:169], v[204:207], v[32:35]
	v_mfma_f32_16x16x32_bf16 v[60:63], v[162:165], v[184:187], v[60:63]
	v_mfma_f32_16x16x32_bf16 v[56:59], v[170:173], v[184:187], v[56:59]
	v_mfma_f32_16x16x32_bf16 v[52:55], v[162:165], v[192:195], v[52:55]
	v_mfma_f32_16x16x32_bf16 v[48:51], v[170:173], v[192:195], v[48:51]
	v_mfma_f32_16x16x32_bf16 v[44:47], v[162:165], v[200:203], v[44:47]
	v_mfma_f32_16x16x32_bf16 v[40:43], v[170:173], v[200:203], v[40:43]
	v_mfma_f32_16x16x32_bf16 v[36:39], v[162:165], v[208:211], v[36:39]
	v_mfma_f32_16x16x32_bf16 v[32:35], v[170:173], v[208:211], v[32:35]
	s_setprio 0
	s_barrier
	v_lshl_add_u64 v[158:159], v[224:225], 0, s[76:77]
	s_add_u32 m0, s24, 0x1c000
	s_nop 0
	global_load_lds_dwordx4 v[158:159], off
	v_lshl_add_u64 v[158:159], v[226:227], 0, s[76:77]
	s_add_u32 m0, s24, 0x1e000
	s_nop 0
	global_load_lds_dwordx4 v[158:159], off
	s_waitcnt vmcnt(6)
	s_barrier
	s_setprio 1
	v_mfma_f32_16x16x32_bf16 v[28:31], v[212:215], v[180:183], v[28:31]
	v_mfma_f32_16x16x32_bf16 v[24:27], v[238:241], v[180:183], v[24:27]
	v_mfma_f32_16x16x32_bf16 v[20:23], v[212:215], v[188:191], v[20:23]
	v_mfma_f32_16x16x32_bf16 v[16:19], v[238:241], v[188:191], v[16:19]
	v_mfma_f32_16x16x32_bf16 v[12:15], v[212:215], v[196:199], v[12:15]
	v_mfma_f32_16x16x32_bf16 v[8:11], v[238:241], v[196:199], v[8:11]
	v_mfma_f32_16x16x32_bf16 v[4:7], v[212:215], v[204:207], v[4:7]
	v_mfma_f32_16x16x32_bf16 v[0:3], v[238:241], v[204:207], v[0:3]
	v_mfma_f32_16x16x32_bf16 v[28:31], v[216:219], v[184:187], v[28:31]
	v_mfma_f32_16x16x32_bf16 v[24:27], v[242:245], v[184:187], v[24:27]
	v_mfma_f32_16x16x32_bf16 v[20:23], v[216:219], v[192:195], v[20:23]
	v_mfma_f32_16x16x32_bf16 v[16:19], v[242:245], v[192:195], v[16:19]
	v_mfma_f32_16x16x32_bf16 v[12:15], v[216:219], v[200:203], v[12:15]
	v_mfma_f32_16x16x32_bf16 v[8:11], v[242:245], v[200:203], v[8:11]
	v_mfma_f32_16x16x32_bf16 v[4:7], v[216:219], v[208:211], v[4:7]
	v_mfma_f32_16x16x32_bf16 v[0:3], v[242:245], v[208:211], v[0:3]
	s_setprio 0
	s_add_i32 s23, s23, 2
	s_add_u32 s14, s14, 0x100
	s_addc_u32 s15, s15, 0
	s_cmpk_gt_u32 s23, 0x53
	s_barrier
	s_cbranch_scc0 .LBB0_922
	s_add_u32 s14, s12, 0x162b80
	s_addc_u32 s15, s13, 0
	v_readfirstlane_b32 s23, v155
	v_lshl_add_u64 v[150:151], s[14:15], 0, v[178:179]
	s_mov_b32 m0, s23
	v_lshl_add_u64 v[128:129], s[14:15], 0, v[128:129]
	v_readfirstlane_b32 s14, v156
	ds_read_b128 v[130:133], v154
	ds_read_b128 v[134:137], v154 offset:1024
	ds_read_b128 v[146:149], v154 offset:2048
	ds_read_b128 v[158:161], v154 offset:3072
	ds_read_b128 v[162:165], v142
	ds_read_b128 v[166:169], v142 offset:1024
	ds_read_b128 v[170:173], v141
	ds_read_b128 v[180:183], v141 offset:1024
	ds_read_b128 v[184:187], v140
	ds_read_b128 v[188:191], v140 offset:1024
	ds_read_b128 v[192:195], v139
	ds_read_b128 v[196:199], v139 offset:1024
	global_load_lds_dwordx4 v[150:151], off
	s_mov_b32 m0, s14
	s_nop 0
	global_load_lds_dwordx4 v[128:129], off
	s_barrier
	s_waitcnt lgkmcnt(0)
	s_setprio 1
	s_waitcnt lgkmcnt(0)
	v_mfma_f32_16x16x32_bf16 v[124:127], v[130:133], v[162:165], v[124:127]
	v_mfma_f32_16x16x32_bf16 v[120:123], v[146:149], v[162:165], v[120:123]
	v_mfma_f32_16x16x32_bf16 v[116:119], v[130:133], v[170:173], v[116:119]
	v_mfma_f32_16x16x32_bf16 v[112:115], v[146:149], v[170:173], v[112:115]
	v_mfma_f32_16x16x32_bf16 v[108:111], v[130:133], v[184:187], v[108:111]
	v_mfma_f32_16x16x32_bf16 v[104:107], v[146:149], v[184:187], v[104:107]
	v_mfma_f32_16x16x32_bf16 v[100:103], v[130:133], v[192:195], v[100:103]
	v_mfma_f32_16x16x32_bf16 v[96:99], v[146:149], v[192:195], v[96:99]
	v_mfma_f32_16x16x32_bf16 v[124:127], v[134:137], v[166:169], v[124:127]
	v_mfma_f32_16x16x32_bf16 v[120:123], v[158:161], v[166:169], v[120:123]
	v_mfma_f32_16x16x32_bf16 v[116:119], v[134:137], v[180:183], v[116:119]
	v_mfma_f32_16x16x32_bf16 v[112:115], v[158:161], v[180:183], v[112:115]
	v_mfma_f32_16x16x32_bf16 v[108:111], v[134:137], v[188:191], v[108:111]
	v_mfma_f32_16x16x32_bf16 v[104:107], v[158:161], v[188:191], v[104:107]
	v_mfma_f32_16x16x32_bf16 v[100:103], v[134:137], v[196:199], v[100:103]
	v_mfma_f32_16x16x32_bf16 v[96:99], v[158:161], v[196:199], v[96:99]
	s_setprio 0
	s_barrier
	ds_read_b128 v[154:157], v153
	ds_read_b128 v[200:203], v153 offset:1024
	ds_read_b128 v[204:207], v153 offset:2048
	ds_read_b128 v[150:153], v153 offset:3072
	s_barrier
	s_waitcnt lgkmcnt(0)
	s_setprio 1
	s_waitcnt lgkmcnt(0)
	v_mfma_f32_16x16x32_bf16 v[92:95], v[154:157], v[162:165], v[92:95]
	v_mfma_f32_16x16x32_bf16 v[88:91], v[204:207], v[162:165], v[88:91]
	v_mfma_f32_16x16x32_bf16 v[84:87], v[154:157], v[170:173], v[84:87]
	v_mfma_f32_16x16x32_bf16 v[80:83], v[204:207], v[170:173], v[80:83]
	v_mfma_f32_16x16x32_bf16 v[76:79], v[154:157], v[184:187], v[76:79]
	v_mfma_f32_16x16x32_bf16 v[72:75], v[204:207], v[184:187], v[72:75]
	v_mfma_f32_16x16x32_bf16 v[68:71], v[154:157], v[192:195], v[68:71]
	v_mfma_f32_16x16x32_bf16 v[64:67], v[204:207], v[192:195], v[64:67]
	v_mfma_f32_16x16x32_bf16 v[92:95], v[200:203], v[166:169], v[92:95]
	v_mfma_f32_16x16x32_bf16 v[88:91], v[150:153], v[166:169], v[88:91]
	v_mfma_f32_16x16x32_bf16 v[84:87], v[200:203], v[180:183], v[84:87]
	v_mfma_f32_16x16x32_bf16 v[80:83], v[150:153], v[180:183], v[80:83]
	v_mfma_f32_16x16x32_bf16 v[76:79], v[200:203], v[188:191], v[76:79]
	v_mfma_f32_16x16x32_bf16 v[72:75], v[150:153], v[188:191], v[72:75]
	v_mfma_f32_16x16x32_bf16 v[68:71], v[200:203], v[196:199], v[68:71]
	v_mfma_f32_16x16x32_bf16 v[64:67], v[150:153], v[196:199], v[64:67]
	s_setprio 0
	s_barrier
; #define LDA(dst, b, h) _Pragma("unroll") for (int m = 0; m < 4; ++m) _Pragma("unroll") for (int k = 0; k < 2; ++k) \
;     dst[m][k] = *reinterpret_cast<const bf16x8*>((const char*)SA(b, h) + lds_byte(wr * 64 + m * 16 + fr, k * 32 + fq * 8))
; #define LDB(dst, b, h) _Pragma("unroll") for (int n = 0; n < 2; ++n) _Pragma("unroll") for (int k = 0; k < 2; ++k) \
;     dst[n][k] = *reinterpret_cast<const bf16x8*>((const char*)SB(b, h) + lds_byte(wc * 32 + n * 16 + fr, k * 32 + fq * 8))
; #define MMA(ai, bj, At_, Bt_) do { __builtin_amdgcn_s_setprio(1); \
;     _Pragma("unroll") for (int m = 0; m < 4; ++m) _Pragma("unroll") for (int n = 0; n < 2; ++n) _Pragma("unroll") for (int k = 0; k < 2; ++k) \
;       acc[ai][bj][m][n] = __builtin_amdgcn_mfma_f32_16x16x32_bf16(Bt_[n][k], At_[m][k], acc[ai][bj][m][n], 0, 0, 0); \
;     __builtin_amdgcn_s_setprio(0); } while (0)
; #define WAIT_V(n) asm volatile("s_waitcnt vmcnt(" #n ")" ::: "memory")
; #define WAIT_L(n) asm volatile("s_waitcnt lgkmcnt(" #n ")" ::: "memory")
; #define BAR __builtin_amdgcn_s_barrier()
; template <bool PF = true, class Epi, class KRF = KRFull>
; __device__ __forceinline__ void gemm_phase(const u16* __restrict__ A, int lda, const u16* __restrict__ Bt, int ldb, int K, int nM, int nN,
;                                            lds_u16* shm, Epi epi, KRF krf = KRFull(), bool flip = false) {
;     ...
;       LDA(At, 0, 1); WAIT_V(4); BAR; WAIT_L(0); MMA(1, 0, At, B0); MMA(1, 1, At, B1); BAR; }
;     { LDB(B0, 1, 0); LDA(At, 1, 0); WAIT_V(2); BAR; WAIT_L(0); MMA(0, 0, At, B0); BAR;
	ds_read_b128 v[162:165], v142 offset:16384
	ds_read_b128 v[166:169], v142 offset:17408
	ds_read_b128 v[170:173], v141 offset:16384
	ds_read_b128 v[180:183], v141 offset:17408
	ds_read_b128 v[184:187], v140 offset:16384
	ds_read_b128 v[188:191], v140 offset:17408
	ds_read_b128 v[192:195], v139 offset:16384
	ds_read_b128 v[196:199], v139 offset:17408
	s_waitcnt vmcnt(4)
	s_barrier
	s_waitcnt lgkmcnt(0)
	s_setprio 1
	s_waitcnt lgkmcnt(0)
	v_mfma_f32_16x16x32_bf16 v[60:63], v[130:133], v[162:165], v[60:63]
	v_mfma_f32_16x16x32_bf16 v[56:59], v[146:149], v[162:165], v[56:59]
	v_mfma_f32_16x16x32_bf16 v[52:55], v[130:133], v[170:173], v[52:55]
	v_mfma_f32_16x16x32_bf16 v[48:51], v[146:149], v[170:173], v[48:51]
	v_mfma_f32_16x16x32_bf16 v[44:47], v[130:133], v[184:187], v[44:47]
	v_mfma_f32_16x16x32_bf16 v[40:43], v[146:149], v[184:187], v[40:43]
	v_mfma_f32_16x16x32_bf16 v[36:39], v[130:133], v[192:195], v[36:39]
	v_mfma_f32_16x16x32_bf16 v[32:35], v[146:149], v[192:195], v[32:35]
	v_mfma_f32_16x16x32_bf16 v[60:63], v[134:137], v[166:169], v[60:63]
	v_mfma_f32_16x16x32_bf16 v[56:59], v[158:161], v[166:169], v[56:59]
	v_mfma_f32_16x16x32_bf16 v[52:55], v[134:137], v[180:183], v[52:55]
	v_mfma_f32_16x16x32_bf16 v[48:51], v[158:161], v[180:183], v[48:51]
	v_mfma_f32_16x16x32_bf16 v[44:47], v[134:137], v[188:191], v[44:47]
	v_mfma_f32_16x16x32_bf16 v[40:43], v[158:161], v[188:191], v[40:43]
	v_mfma_f32_16x16x32_bf16 v[36:39], v[134:137], v[196:199], v[36:39]
	v_mfma_f32_16x16x32_bf16 v[32:35], v[158:161], v[196:199], v[32:35]
	s_setprio 0
	s_setprio 1
	v_mfma_f32_16x16x32_bf16 v[28:31], v[154:157], v[162:165], v[28:31]
	v_mfma_f32_16x16x32_bf16 v[24:27], v[204:207], v[162:165], v[24:27]
	v_mfma_f32_16x16x32_bf16 v[20:23], v[154:157], v[170:173], v[20:23]
	v_mfma_f32_16x16x32_bf16 v[16:19], v[204:207], v[170:173], v[16:19]
	v_mfma_f32_16x16x32_bf16 v[12:15], v[154:157], v[184:187], v[12:15]
	v_mfma_f32_16x16x32_bf16 v[8:11], v[204:207], v[184:187], v[8:11]
	v_mfma_f32_16x16x32_bf16 v[4:7], v[154:157], v[192:195], v[4:7]
	v_mfma_f32_16x16x32_bf16 v[0:3], v[204:207], v[192:195], v[0:3]
	v_mfma_f32_16x16x32_bf16 v[28:31], v[200:203], v[166:169], v[28:31]
	v_mfma_f32_16x16x32_bf16 v[24:27], v[150:153], v[166:169], v[24:27]
	v_mfma_f32_16x16x32_bf16 v[20:23], v[200:203], v[180:183], v[20:23]
	v_mfma_f32_16x16x32_bf16 v[16:19], v[150:153], v[180:183], v[16:19]
	v_mfma_f32_16x16x32_bf16 v[12:15], v[200:203], v[188:191], v[12:15]
	v_mfma_f32_16x16x32_bf16 v[8:11], v[150:153], v[188:191], v[8:11]
	v_mfma_f32_16x16x32_bf16 v[4:7], v[200:203], v[196:199], v[4:7]
	v_mfma_f32_16x16x32_bf16 v[0:3], v[150:153], v[196:199], v[0:3]
	s_setprio 0
	s_barrier
	ds_read_b128 v[128:131], v145
	ds_read_b128 v[132:135], v145 offset:1024
	ds_read_b128 v[146:149], v145 offset:2048
	ds_read_b128 v[150:153], v145 offset:3072
	ds_read_b128 v[154:157], v142 offset:32768
	ds_read_b128 v[158:161], v142 offset:33792
	ds_read_b128 v[162:165], v141 offset:32768
	ds_read_b128 v[166:169], v141 offset:33792
	ds_read_b128 v[170:173], v140 offset:32768
	ds_read_b128 v[180:183], v140 offset:33792
	ds_read_b128 v[184:187], v139 offset:32768
	ds_read_b128 v[188:191], v139 offset:33792
	s_waitcnt vmcnt(2)
	s_barrier
	s_waitcnt lgkmcnt(0)
	s_setprio 1
	s_waitcnt lgkmcnt(0)
	v_mfma_f32_16x16x32_bf16 v[124:127], v[128:131], v[154:157], v[124:127]
	v_mfma_f32_16x16x32_bf16 v[120:123], v[146:149], v[154:157], v[120:123]
	v_mfma_f32_16x16x32_bf16 v[116:119], v[128:131], v[162:165], v[116:119]
	v_mfma_f32_16x16x32_bf16 v[112:115], v[146:149], v[162:165], v[112:115]
	v_mfma_f32_16x16x32_bf16 v[108:111], v[128:131], v[170:173], v[108:111]
	v_mfma_f32_16x16x32_bf16 v[104:107], v[146:149], v[170:173], v[104:107]
	v_mfma_f32_16x16x32_bf16 v[100:103], v[128:131], v[184:187], v[100:103]
	v_mfma_f32_16x16x32_bf16 v[96:99], v[146:149], v[184:187], v[96:99]
	v_mfma_f32_16x16x32_bf16 v[124:127], v[132:135], v[158:161], v[124:127]
	v_mfma_f32_16x16x32_bf16 v[120:123], v[150:153], v[158:161], v[120:123]
	v_mfma_f32_16x16x32_bf16 v[116:119], v[132:135], v[166:169], v[116:119]
	v_mfma_f32_16x16x32_bf16 v[112:115], v[150:153], v[166:169], v[112:115]
	v_mfma_f32_16x16x32_bf16 v[108:111], v[132:135], v[180:183], v[108:111]
	v_mfma_f32_16x16x32_bf16 v[104:107], v[150:153], v[180:183], v[104:107]
	v_mfma_f32_16x16x32_bf16 v[100:103], v[132:135], v[188:191], v[100:103]
	v_mfma_f32_16x16x32_bf16 v[96:99], v[150:153], v[188:191], v[96:99]
	s_setprio 0
	s_barrier
; #define LDA(dst, b, h) _Pragma("unroll") for (int m = 0; m < 4; ++m) _Pragma("unroll") for (int k = 0; k < 2; ++k) \
;     dst[m][k] = *reinterpret_cast<const bf16x8*>((const char*)SA(b, h) + lds_byte(wr * 64 + m * 16 + fr, k * 32 + fq * 8))
; #define LDB(dst, b, h) _Pragma("unroll") for (int n = 0; n < 2; ++n) _Pragma("unroll") for (int k = 0; k < 2; ++k) \
;     dst[n][k] = *reinterpret_cast<const bf16x8*>((const char*)SB(b, h) + lds_byte(wc * 32 + n * 16 + fr, k * 32 + fq * 8))
; #define MMA(ai, bj, At_, Bt_) do { __builtin_amdgcn_s_setprio(1); \
;     _Pragma("unroll") for (int m = 0; m < 4; ++m) _Pragma("unroll") for (int n = 0; n < 2; ++n) _Pragma("unroll") for (int k = 0; k < 2; ++k) \
;       acc[ai][bj][m][n] = __builtin_amdgcn_mfma_f32_16x16x32_bf16(Bt_[n][k], At_[m][k], acc[ai][bj][m][n], 0, 0, 0); \
;     __builtin_amdgcn_s_setprio(0); } while (0)
; #define WAIT_V(n) asm volatile("s_waitcnt vmcnt(" #n ")" ::: "memory")
; #define WAIT_L(n) asm volatile("s_waitcnt lgkmcnt(" #n ")" ::: "memory")
; #define BAR __builtin_amdgcn_s_barrier()
; template <bool PF = true, class Epi, class KRF = KRFull>
; __device__ __forceinline__ void gemm_phase(const u16* __restrict__ A, int lda, const u16* __restrict__ Bt, int ldb, int K, int nM, int nN,
;                                            lds_u16* shm, Epi epi, KRF krf = KRFull(), bool flip = false) {
;     ...
;       LDB(B1, 1, 1); WAIT_V(0); BAR; WAIT_L(0); MMA(0, 1, At, B1); BAR;
;       LDA(At, 1, 1); BAR; WAIT_L(0); MMA(1, 0, At, B0); MMA(1, 1, At, B1); BAR; }
;     if (wr == 0) BAR;
	ds_read_b128 v[192:195], v143
	ds_read_b128 v[196:199], v143 offset:1024
	ds_read_b128 v[200:203], v143 offset:2048
	ds_read_b128 v[204:207], v143 offset:3072
	s_waitcnt vmcnt(0)
	s_barrier
	s_waitcnt lgkmcnt(0)
	s_setprio 1
	s_waitcnt lgkmcnt(0)
	v_mfma_f32_16x16x32_bf16 v[92:95], v[192:195], v[154:157], v[92:95]
	v_mfma_f32_16x16x32_bf16 v[88:91], v[200:203], v[154:157], v[88:91]
	v_mfma_f32_16x16x32_bf16 v[84:87], v[192:195], v[162:165], v[84:87]
	v_mfma_f32_16x16x32_bf16 v[80:83], v[200:203], v[162:165], v[80:83]
	v_mfma_f32_16x16x32_bf16 v[76:79], v[192:195], v[170:173], v[76:79]
	v_mfma_f32_16x16x32_bf16 v[72:75], v[200:203], v[170:173], v[72:75]
	v_mfma_f32_16x16x32_bf16 v[68:71], v[192:195], v[184:187], v[68:71]
	v_mfma_f32_16x16x32_bf16 v[64:67], v[200:203], v[184:187], v[64:67]
	v_mfma_f32_16x16x32_bf16 v[92:95], v[196:199], v[158:161], v[92:95]
	v_mfma_f32_16x16x32_bf16 v[88:91], v[204:207], v[158:161], v[88:91]
	v_mfma_f32_16x16x32_bf16 v[84:87], v[196:199], v[166:169], v[84:87]
	v_mfma_f32_16x16x32_bf16 v[80:83], v[204:207], v[166:169], v[80:83]
	v_mfma_f32_16x16x32_bf16 v[76:79], v[196:199], v[180:183], v[76:79]
	v_mfma_f32_16x16x32_bf16 v[72:75], v[204:207], v[180:183], v[72:75]
	v_mfma_f32_16x16x32_bf16 v[68:71], v[196:199], v[188:191], v[68:71]
	v_mfma_f32_16x16x32_bf16 v[64:67], v[204:207], v[188:191], v[64:67]
	s_setprio 0
	s_barrier
	ds_read_b128 v[154:157], v142 offset:49152
	ds_read_b128 v[142:145], v142 offset:50176
	ds_read_b128 v[158:161], v141 offset:49152
	ds_read_b128 v[162:165], v141 offset:50176
	ds_read_b128 v[166:169], v140 offset:49152
	ds_read_b128 v[170:173], v140 offset:50176
	ds_read_b128 v[180:183], v139 offset:49152
	ds_read_b128 v[184:187], v139 offset:50176
	s_barrier
	s_waitcnt lgkmcnt(0)
	s_setprio 1
	s_waitcnt lgkmcnt(0)
	v_mfma_f32_16x16x32_bf16 v[60:63], v[128:131], v[154:157], v[60:63]
	v_mfma_f32_16x16x32_bf16 v[56:59], v[146:149], v[154:157], v[56:59]
	v_mfma_f32_16x16x32_bf16 v[52:55], v[128:131], v[158:161], v[52:55]
	v_mfma_f32_16x16x32_bf16 v[48:51], v[146:149], v[158:161], v[48:51]
	v_mfma_f32_16x16x32_bf16 v[44:47], v[128:131], v[166:169], v[44:47]
	v_mfma_f32_16x16x32_bf16 v[40:43], v[146:149], v[166:169], v[40:43]
	v_mfma_f32_16x16x32_bf16 v[36:39], v[128:131], v[180:183], v[36:39]
	v_mfma_f32_16x16x32_bf16 v[32:35], v[146:149], v[180:183], v[32:35]
	v_mfma_f32_16x16x32_bf16 v[60:63], v[132:135], v[142:145], v[60:63]
	v_mfma_f32_16x16x32_bf16 v[56:59], v[150:153], v[142:145], v[56:59]
	v_mfma_f32_16x16x32_bf16 v[52:55], v[132:135], v[162:165], v[52:55]
	v_mfma_f32_16x16x32_bf16 v[48:51], v[150:153], v[162:165], v[48:51]
	v_mfma_f32_16x16x32_bf16 v[44:47], v[132:135], v[170:173], v[44:47]
	v_mfma_f32_16x16x32_bf16 v[40:43], v[150:153], v[170:173], v[40:43]
	v_mfma_f32_16x16x32_bf16 v[36:39], v[132:135], v[184:187], v[36:39]
	v_mfma_f32_16x16x32_bf16 v[32:35], v[150:153], v[184:187], v[32:35]
	s_setprio 0
	s_setprio 1
	v_mfma_f32_16x16x32_bf16 v[28:31], v[192:195], v[154:157], v[28:31]
	v_mfma_f32_16x16x32_bf16 v[24:27], v[200:203], v[154:157], v[24:27]
	v_mfma_f32_16x16x32_bf16 v[20:23], v[192:195], v[158:161], v[20:23]
	v_mfma_f32_16x16x32_bf16 v[16:19], v[200:203], v[158:161], v[16:19]
	v_mfma_f32_16x16x32_bf16 v[12:15], v[192:195], v[166:169], v[12:15]
	v_mfma_f32_16x16x32_bf16 v[8:11], v[200:203], v[166:169], v[8:11]
	v_mfma_f32_16x16x32_bf16 v[4:7], v[192:195], v[180:183], v[4:7]
	v_mfma_f32_16x16x32_bf16 v[0:3], v[200:203], v[180:183], v[0:3]
	v_mfma_f32_16x16x32_bf16 v[28:31], v[196:199], v[142:145], v[28:31]
	v_mfma_f32_16x16x32_bf16 v[24:27], v[204:207], v[142:145], v[24:27]
	v_mfma_f32_16x16x32_bf16 v[20:23], v[196:199], v[162:165], v[20:23]
	v_mfma_f32_16x16x32_bf16 v[16:19], v[204:207], v[162:165], v[16:19]
	v_mfma_f32_16x16x32_bf16 v[12:15], v[196:199], v[170:173], v[12:15]
	v_mfma_f32_16x16x32_bf16 v[8:11], v[204:207], v[170:173], v[8:11]
	v_mfma_f32_16x16x32_bf16 v[4:7], v[196:199], v[184:187], v[4:7]
	v_mfma_f32_16x16x32_bf16 v[0:3], v[204:207], v[184:187], v[0:3]
	s_setprio 0
	v_cmp_gt_u32_e32 vcc, s95, v138
	s_barrier
	s_and_saveexec_b64 s[14:15], vcc
	s_cbranch_execz .LBB0_925
	s_barrier

; #define STAGE_A(P, half, kt) do { const char* _u = Ab + ((size_t)(half) * 128 * lda + (size_t)(kt) * BK) * 2; \
;     _Pragma("unroll") for (int _i = 0; _i < 2; ++_i) \
;       __builtin_amdgcn_global_load_lds((const unsigned*)(_u + offA[_i]), \
;         (__attribute__((address_space(3))) unsigned*)((__attribute__((address_space(3))) char*)(P) + tidg * 16 + _i * 8192), 16, 0, 0); } while (0)
; #define STAGE_B(P, half, kt) do { const char* _u = Bb + ((size_t)(half) * 128 * ldb + (size_t)(kt) * BK) * 2; \
;     _Pragma("unroll") for (int _i = 0; _i < 2; ++_i) \
;       __builtin_amdgcn_global_load_lds((const unsigned*)(_u + offB[_i]), \
;         (__attribute__((address_space(3))) unsigned*)((__attribute__((address_space(3))) char*)(P) + tidg * 16 + _i * 8192), 16, 0, 0); } while (0)
; #define LDA(dst, b, h) _Pragma("unroll") for (int m = 0; m < 4; ++m) _Pragma("unroll") for (int k = 0; k < 2; ++k) \
;     dst[m][k] = *reinterpret_cast<const bf16x8*>((const char*)SA(b, h) + lds_byte(wr * 64 + m * 16 + fr, k * 32 + fq * 8))
; #define LDB(dst, b, h) _Pragma("unroll") for (int n = 0; n < 2; ++n) _Pragma("unroll") for (int k = 0; k < 2; ++k) \
;     dst[n][k] = *reinterpret_cast<const bf16x8*>((const char*)SB(b, h) + lds_byte(wc * 32 + n * 16 + fr, k * 32 + fq * 8))
; #define MMA(ai, bj, At_, Bt_) do { __builtin_amdgcn_s_setprio(1); \
;     _Pragma("unroll") for (int m = 0; m < 4; ++m) _Pragma("unroll") for (int n = 0; n < 2; ++n) _Pragma("unroll") for (int k = 0; k < 2; ++k) \
;       acc[ai][bj][m][n] = __builtin_amdgcn_mfma_f32_16x16x32_bf16(Bt_[n][k], At_[m][k], acc[ai][bj][m][n], 0, 0, 0); \
;     __builtin_amdgcn_s_setprio(0); } while (0)
; template <bool PF = true, class Epi, class KRF = KRFull>
; __device__ __forceinline__ void gemm_phase(const u16* __restrict__ A, int lda, const u16* __restrict__ Bt, int ldb, int K, int nM, int nN,
;                                            lds_u16* shm, Epi epi, KRF krf = KRFull(), bool flip = false) {
;     ...
;     for (int t = 0; t < nt - 2; t += 2) {
;       LDB(B0, 0, 0); SCHED; LDA(At, 0, 0); STAGE_A(SA(1, 1), 1, t + 1);
;       WAIT_L(8); BAR; WAIT_L(0); MMA(0, 0, At, B0); BAR; SCHED;
;       LDB(B1, 0, 1); STAGE_B(SB(0, 0), 0, t + 2);
;       BAR; WAIT_L(0); MMA(0, 1, At, B1); BAR;
;       LDA(At, 0, 1); STAGE_A(SA(0, 0), 0, t + 2);
;       BAR; WAIT_L(0); MMA(1, 0, At, B0); BAR; SCHED;
.LBB0_948:
	v_readfirstlane_b32 s3, v146
	ds_read_b128 v[160:163], v156
	ds_read_b128 v[164:167], v156 offset:1024
	ds_read_b128 v[168:171], v156 offset:2048
	ds_read_b128 v[172:175], v156 offset:3072
	v_add_u32_e32 v157, 0xc000, v146
	v_lshl_add_u64 v[222:223], v[134:135], 0, s[8:9]
	v_lshl_add_u64 v[158:159], v[222:223], 0, s[62:63]
	s_add_u32 m0, s3, 0xc000
	ds_read_b128 v[180:183], v144
	ds_read_b128 v[184:187], v144 offset:1024
	ds_read_b128 v[188:191], v143
	ds_read_b128 v[192:195], v143 offset:1024
	ds_read_b128 v[196:199], v142
	ds_read_b128 v[200:203], v142 offset:1024
	ds_read_b128 v[204:207], v141
	ds_read_b128 v[208:211], v141 offset:1024
	global_load_lds_dwordx4 v[158:159], off
	v_add_u32_e32 v158, 0xe000, v146
	v_lshl_add_u64 v[224:225], v[136:137], 0, s[8:9]
	v_lshl_add_u64 v[212:213], v[224:225], 0, s[62:63]
	s_add_u32 m0, s3, 0xe000
	s_nop 0
	global_load_lds_dwordx4 v[212:213], off
	s_waitcnt lgkmcnt(8)
	s_barrier
	s_waitcnt lgkmcnt(0)
	s_setprio 1
	s_waitcnt lgkmcnt(0)
	v_mfma_f32_16x16x32_bf16 v[124:127], v[160:163], v[180:183], v[124:127]
	v_mfma_f32_16x16x32_bf16 v[120:123], v[168:171], v[180:183], v[120:123]
	v_mfma_f32_16x16x32_bf16 v[116:119], v[160:163], v[188:191], v[116:119]
	v_mfma_f32_16x16x32_bf16 v[112:115], v[168:171], v[188:191], v[112:115]
	v_mfma_f32_16x16x32_bf16 v[108:111], v[160:163], v[196:199], v[108:111]
	v_mfma_f32_16x16x32_bf16 v[104:107], v[168:171], v[196:199], v[104:107]
	v_mfma_f32_16x16x32_bf16 v[100:103], v[160:163], v[204:207], v[100:103]
	v_mfma_f32_16x16x32_bf16 v[96:99], v[168:171], v[204:207], v[96:99]
	v_mfma_f32_16x16x32_bf16 v[124:127], v[164:167], v[184:187], v[124:127]
	v_mfma_f32_16x16x32_bf16 v[120:123], v[172:175], v[184:187], v[120:123]
	v_mfma_f32_16x16x32_bf16 v[116:119], v[164:167], v[192:195], v[116:119]
	v_mfma_f32_16x16x32_bf16 v[112:115], v[172:175], v[192:195], v[112:115]
	v_mfma_f32_16x16x32_bf16 v[108:111], v[164:167], v[200:203], v[108:111]
	v_mfma_f32_16x16x32_bf16 v[104:107], v[172:175], v[200:203], v[104:107]
	v_mfma_f32_16x16x32_bf16 v[100:103], v[164:167], v[208:211], v[100:103]
	v_mfma_f32_16x16x32_bf16 v[96:99], v[172:175], v[208:211], v[96:99]
	s_setprio 0
	s_barrier
	v_add_u32_e32 v159, 0x10000, v146
	v_lshl_add_u64 v[226:227], v[130:131], 0, s[8:9]
	v_lshl_add_u64 v[228:229], v[226:227], 0, s[64:65]
	s_add_u32 m0, s3, 0x10000
	v_add_u32_e32 v159, 0x12000, v146
	ds_read_b128 v[212:215], v155
	ds_read_b128 v[216:219], v155 offset:1024
	ds_read_b128 v[234:237], v155 offset:2048
	ds_read_b128 v[238:241], v155 offset:3072
	global_load_lds_dwordx4 v[228:229], off
	v_lshl_add_u64 v[228:229], v[132:133], 0, s[8:9]
	v_lshl_add_u64 v[242:243], v[228:229], 0, s[64:65]
	s_add_u32 m0, s3, 0x12000
	s_nop 0
	global_load_lds_dwordx4 v[242:243], off
	s_barrier
	s_waitcnt lgkmcnt(0)
	s_setprio 1
	s_waitcnt lgkmcnt(0)
	v_mfma_f32_16x16x32_bf16 v[92:95], v[212:215], v[180:183], v[92:95]
	v_mfma_f32_16x16x32_bf16 v[88:91], v[234:237], v[180:183], v[88:91]
	v_mfma_f32_16x16x32_bf16 v[84:87], v[212:215], v[188:191], v[84:87]
	v_mfma_f32_16x16x32_bf16 v[80:83], v[234:237], v[188:191], v[80:83]
	v_mfma_f32_16x16x32_bf16 v[76:79], v[212:215], v[196:199], v[76:79]
	v_mfma_f32_16x16x32_bf16 v[72:75], v[234:237], v[196:199], v[72:75]
	v_mfma_f32_16x16x32_bf16 v[68:71], v[212:215], v[204:207], v[68:71]
	v_mfma_f32_16x16x32_bf16 v[64:67], v[234:237], v[204:207], v[64:67]
	v_mfma_f32_16x16x32_bf16 v[92:95], v[216:219], v[184:187], v[92:95]
	v_mfma_f32_16x16x32_bf16 v[88:91], v[238:241], v[184:187], v[88:91]
	v_mfma_f32_16x16x32_bf16 v[84:87], v[216:219], v[192:195], v[84:87]
	v_mfma_f32_16x16x32_bf16 v[80:83], v[238:241], v[192:195], v[80:83]
	v_mfma_f32_16x16x32_bf16 v[76:79], v[216:219], v[200:203], v[76:79]
	v_mfma_f32_16x16x32_bf16 v[72:75], v[238:241], v[200:203], v[72:75]
	v_mfma_f32_16x16x32_bf16 v[68:71], v[216:219], v[208:211], v[68:71]
	v_mfma_f32_16x16x32_bf16 v[64:67], v[238:241], v[208:211], v[64:67]
	s_setprio 0
	v_lshl_add_u64 v[242:243], v[222:223], 0, s[64:65]
	s_mov_b32 m0, s3
	s_barrier
	ds_read_b128 v[180:183], v144 offset:16384
	ds_read_b128 v[184:187], v144 offset:17408
	ds_read_b128 v[188:191], v143 offset:16384
	ds_read_b128 v[192:195], v143 offset:17408
	ds_read_b128 v[196:199], v142 offset:16384
	ds_read_b128 v[200:203], v142 offset:17408
	ds_read_b128 v[204:207], v141 offset:16384
	ds_read_b128 v[208:211], v141 offset:17408
	global_load_lds_dwordx4 v[242:243], off
	v_lshl_add_u64 v[242:243], v[224:225], 0, s[64:65]
	s_add_u32 m0, s3, 0x2000
	s_nop 0
	global_load_lds_dwordx4 v[242:243], off
	s_barrier
	s_waitcnt lgkmcnt(0)
	s_setprio 1
	s_waitcnt lgkmcnt(0)
	v_mfma_f32_16x16x32_bf16 v[60:63], v[160:163], v[180:183], v[60:63]
	v_mfma_f32_16x16x32_bf16 v[56:59], v[168:171], v[180:183], v[56:59]
	v_mfma_f32_16x16x32_bf16 v[52:55], v[160:163], v[188:191], v[52:55]
	v_mfma_f32_16x16x32_bf16 v[48:51], v[168:171], v[188:191], v[48:51]
	v_mfma_f32_16x16x32_bf16 v[44:47], v[160:163], v[196:199], v[44:47]
	v_mfma_f32_16x16x32_bf16 v[40:43], v[168:171], v[196:199], v[40:43]
	v_mfma_f32_16x16x32_bf16 v[36:39], v[160:163], v[204:207], v[36:39]
	v_mfma_f32_16x16x32_bf16 v[32:35], v[168:171], v[204:207], v[32:35]
	v_mfma_f32_16x16x32_bf16 v[60:63], v[164:167], v[184:187], v[60:63]
	v_mfma_f32_16x16x32_bf16 v[56:59], v[172:175], v[184:187], v[56:59]
	v_mfma_f32_16x16x32_bf16 v[52:55], v[164:167], v[192:195], v[52:55]
	v_mfma_f32_16x16x32_bf16 v[48:51], v[172:175], v[192:195], v[48:51]
	v_mfma_f32_16x16x32_bf16 v[44:47], v[164:167], v[200:203], v[44:47]
	v_mfma_f32_16x16x32_bf16 v[40:43], v[172:175], v[200:203], v[40:43]
	v_mfma_f32_16x16x32_bf16 v[36:39], v[164:167], v[208:211], v[36:39]
	v_mfma_f32_16x16x32_bf16 v[32:35], v[172:175], v[208:211], v[32:35]
	s_setprio 0
	s_barrier
; #define STAGE_A(P, half, kt) do { const char* _u = Ab + ((size_t)(half) * 128 * lda + (size_t)(kt) * BK) * 2; \
;     _Pragma("unroll") for (int _i = 0; _i < 2; ++_i) \
;       __builtin_amdgcn_global_load_lds((const unsigned*)(_u + offA[_i]), \
;         (__attribute__((address_space(3))) unsigned*)((__attribute__((address_space(3))) char*)(P) + tidg * 16 + _i * 8192), 16, 0, 0); } while (0)
; #define STAGE_B(P, half, kt) do { const char* _u = Bb + ((size_t)(half) * 128 * ldb + (size_t)(kt) * BK) * 2; \
;     _Pragma("unroll") for (int _i = 0; _i < 2; ++_i) \
;       __builtin_amdgcn_global_load_lds((const unsigned*)(_u + offB[_i]), \
;         (__attribute__((address_space(3))) unsigned*)((__attribute__((address_space(3))) char*)(P) + tidg * 16 + _i * 8192), 16, 0, 0); } while (0)
; #define LDA(dst, b, h) _Pragma("unroll") for (int m = 0; m < 4; ++m) _Pragma("unroll") for (int k = 0; k < 2; ++k) \
;     dst[m][k] = *reinterpret_cast<const bf16x8*>((const char*)SA(b, h) + lds_byte(wr * 64 + m * 16 + fr, k * 32 + fq * 8))
; #define LDB(dst, b, h) _Pragma("unroll") for (int n = 0; n < 2; ++n) _Pragma("unroll") for (int k = 0; k < 2; ++k) \
;     dst[n][k] = *reinterpret_cast<const bf16x8*>((const char*)SB(b, h) + lds_byte(wc * 32 + n * 16 + fr, k * 32 + fq * 8))
; #define MMA(ai, bj, At_, Bt_) do { __builtin_amdgcn_s_setprio(1); \
;     _Pragma("unroll") for (int m = 0; m < 4; ++m) _Pragma("unroll") for (int n = 0; n < 2; ++n) _Pragma("unroll") for (int k = 0; k < 2; ++k) \
;       acc[ai][bj][m][n] = __builtin_amdgcn_mfma_f32_16x16x32_bf16(Bt_[n][k], At_[m][k], acc[ai][bj][m][n], 0, 0, 0); \
;     __builtin_amdgcn_s_setprio(0); } while (0)
; #define BAR __builtin_amdgcn_s_barrier()
; template <bool PF = true, class Epi, class KRF = KRFull>
; __device__ __forceinline__ void gemm_phase(const u16* __restrict__ A, int lda, const u16* __restrict__ Bt, int ldb, int K, int nM, int nN,
;                                            lds_u16* shm, Epi epi, KRF krf = KRFull(), bool flip = false) {
;     ...
;       STAGE_B(SB(0, 1), 1, t + 2);
;       WAIT_V(6); BAR; MMA(1, 1, At, B1); BAR;
;       LDB(B0, 1, 0); SCHED; LDA(At, 1, 0); STAGE_A(SA(0, 1), 1, t + 2);
;       WAIT_L(8); BAR; WAIT_L(0); MMA(0, 0, At, B0); BAR; SCHED;
;       LDB(B1, 1, 1); STAGE_B(SB(1, 0), 0, t + 3);
;       BAR; WAIT_L(0); MMA(0, 1, At, B1); BAR;
;       LDA(At, 1, 1); STAGE_A(SA(1, 0), 0, t + 3);
	v_add_u32_e32 v159, 0x14000, v146
	v_lshl_add_u64 v[160:161], v[226:227], 0, s[66:67]
	v_add_u32_e32 v159, 0x16000, v146
	s_add_u32 m0, s3, 0x14000
	s_nop 0
	global_load_lds_dwordx4 v[160:161], off
	v_lshl_add_u64 v[160:161], v[228:229], 0, s[66:67]
	s_add_u32 m0, s3, 0x16000
	s_nop 0
	global_load_lds_dwordx4 v[160:161], off
	s_waitcnt vmcnt(6)
	s_barrier
	s_setprio 1
	v_mfma_f32_16x16x32_bf16 v[28:31], v[212:215], v[180:183], v[28:31]
	v_mfma_f32_16x16x32_bf16 v[24:27], v[234:237], v[180:183], v[24:27]
	v_mfma_f32_16x16x32_bf16 v[20:23], v[212:215], v[188:191], v[20:23]
	v_mfma_f32_16x16x32_bf16 v[16:19], v[234:237], v[188:191], v[16:19]
	v_mfma_f32_16x16x32_bf16 v[12:15], v[212:215], v[196:199], v[12:15]
	v_mfma_f32_16x16x32_bf16 v[8:11], v[234:237], v[196:199], v[8:11]
	v_mfma_f32_16x16x32_bf16 v[4:7], v[212:215], v[204:207], v[4:7]
	v_mfma_f32_16x16x32_bf16 v[0:3], v[234:237], v[204:207], v[0:3]
	v_mfma_f32_16x16x32_bf16 v[28:31], v[216:219], v[184:187], v[28:31]
	v_mfma_f32_16x16x32_bf16 v[24:27], v[238:241], v[184:187], v[24:27]
	v_mfma_f32_16x16x32_bf16 v[20:23], v[216:219], v[192:195], v[20:23]
	v_mfma_f32_16x16x32_bf16 v[16:19], v[238:241], v[192:195], v[16:19]
	v_mfma_f32_16x16x32_bf16 v[12:15], v[216:219], v[200:203], v[12:15]
	v_mfma_f32_16x16x32_bf16 v[8:11], v[238:241], v[200:203], v[8:11]
	v_mfma_f32_16x16x32_bf16 v[4:7], v[216:219], v[208:211], v[4:7]
	v_mfma_f32_16x16x32_bf16 v[0:3], v[238:241], v[208:211], v[0:3]
	s_setprio 0
	s_barrier
	ds_read_b128 v[160:163], v147
	ds_read_b128 v[164:167], v147 offset:1024
	ds_read_b128 v[168:171], v147 offset:2048
	ds_read_b128 v[172:175], v147 offset:3072
	v_add_u32_e32 v159, 0x4000, v146
	v_lshl_add_u64 v[212:213], v[222:223], 0, s[66:67]
	v_add_u32_e32 v159, 0x6000, v146
	s_add_u32 m0, s3, 0x4000
	ds_read_b128 v[180:183], v144 offset:32768
	ds_read_b128 v[184:187], v144 offset:33792
	ds_read_b128 v[188:191], v143 offset:32768
	ds_read_b128 v[192:195], v143 offset:33792
	ds_read_b128 v[196:199], v142 offset:32768
	ds_read_b128 v[200:203], v142 offset:33792
	ds_read_b128 v[204:207], v141 offset:32768
	ds_read_b128 v[208:211], v141 offset:33792
	global_load_lds_dwordx4 v[212:213], off
	v_lshl_add_u64 v[212:213], v[224:225], 0, s[66:67]
	s_add_u32 m0, s3, 0x6000
	s_nop 0
	global_load_lds_dwordx4 v[212:213], off
	s_waitcnt lgkmcnt(8)
	s_barrier
	s_waitcnt lgkmcnt(0)
	s_setprio 1
	s_waitcnt lgkmcnt(0)
	v_mfma_f32_16x16x32_bf16 v[124:127], v[160:163], v[180:183], v[124:127]
	v_mfma_f32_16x16x32_bf16 v[120:123], v[168:171], v[180:183], v[120:123]
	v_mfma_f32_16x16x32_bf16 v[116:119], v[160:163], v[188:191], v[116:119]
	v_mfma_f32_16x16x32_bf16 v[112:115], v[168:171], v[188:191], v[112:115]
	v_mfma_f32_16x16x32_bf16 v[108:111], v[160:163], v[196:199], v[108:111]
	v_mfma_f32_16x16x32_bf16 v[104:107], v[168:171], v[196:199], v[104:107]
	v_mfma_f32_16x16x32_bf16 v[100:103], v[160:163], v[204:207], v[100:103]
	v_mfma_f32_16x16x32_bf16 v[96:99], v[168:171], v[204:207], v[96:99]
	v_mfma_f32_16x16x32_bf16 v[124:127], v[164:167], v[184:187], v[124:127]
	v_mfma_f32_16x16x32_bf16 v[120:123], v[172:175], v[184:187], v[120:123]
	v_mfma_f32_16x16x32_bf16 v[116:119], v[164:167], v[192:195], v[116:119]
	v_mfma_f32_16x16x32_bf16 v[112:115], v[172:175], v[192:195], v[112:115]
	v_mfma_f32_16x16x32_bf16 v[108:111], v[164:167], v[200:203], v[108:111]
	v_mfma_f32_16x16x32_bf16 v[104:107], v[172:175], v[200:203], v[104:107]
	v_mfma_f32_16x16x32_bf16 v[100:103], v[164:167], v[208:211], v[100:103]
	v_mfma_f32_16x16x32_bf16 v[96:99], v[172:175], v[208:211], v[96:99]
	s_setprio 0
	s_barrier
	v_lshl_add_u64 v[242:243], v[226:227], 0, s[68:69]
	s_add_u32 m0, s3, 0x18000
	ds_read_b128 v[212:215], v145
	ds_read_b128 v[216:219], v145 offset:1024
	ds_read_b128 v[234:237], v145 offset:2048
	ds_read_b128 v[238:241], v145 offset:3072
	global_load_lds_dwordx4 v[242:243], off
	v_lshl_add_u64 v[242:243], v[228:229], 0, s[68:69]
	s_add_u32 m0, s3, 0x1a000
	s_nop 0
	global_load_lds_dwordx4 v[242:243], off
	s_barrier
	s_waitcnt lgkmcnt(0)
	s_setprio 1
	s_waitcnt lgkmcnt(0)
	v_mfma_f32_16x16x32_bf16 v[92:95], v[212:215], v[180:183], v[92:95]
	v_mfma_f32_16x16x32_bf16 v[88:91], v[234:237], v[180:183], v[88:91]
	v_mfma_f32_16x16x32_bf16 v[84:87], v[212:215], v[188:191], v[84:87]
	v_mfma_f32_16x16x32_bf16 v[80:83], v[234:237], v[188:191], v[80:83]
	v_mfma_f32_16x16x32_bf16 v[76:79], v[212:215], v[196:199], v[76:79]
	v_mfma_f32_16x16x32_bf16 v[72:75], v[234:237], v[196:199], v[72:75]
	v_mfma_f32_16x16x32_bf16 v[68:71], v[212:215], v[204:207], v[68:71]
	v_mfma_f32_16x16x32_bf16 v[64:67], v[234:237], v[204:207], v[64:67]
	v_mfma_f32_16x16x32_bf16 v[92:95], v[216:219], v[184:187], v[92:95]
	v_mfma_f32_16x16x32_bf16 v[88:91], v[238:241], v[184:187], v[88:91]
	v_mfma_f32_16x16x32_bf16 v[84:87], v[216:219], v[192:195], v[84:87]
	v_mfma_f32_16x16x32_bf16 v[80:83], v[238:241], v[192:195], v[80:83]
	v_mfma_f32_16x16x32_bf16 v[76:79], v[216:219], v[200:203], v[76:79]
	v_mfma_f32_16x16x32_bf16 v[72:75], v[238:241], v[200:203], v[72:75]
	v_mfma_f32_16x16x32_bf16 v[68:71], v[216:219], v[208:211], v[68:71]
	v_mfma_f32_16x16x32_bf16 v[64:67], v[238:241], v[208:211], v[64:67]
	s_setprio 0
	v_lshl_add_u64 v[222:223], v[222:223], 0, s[68:69]
	s_add_u32 m0, s3, 0x8000
	s_barrier
	ds_read_b128 v[180:183], v144 offset:49152
	ds_read_b128 v[184:187], v144 offset:50176
	ds_read_b128 v[188:191], v143 offset:49152
	ds_read_b128 v[192:195], v143 offset:50176
	ds_read_b128 v[196:199], v142 offset:49152
	ds_read_b128 v[200:203], v142 offset:50176
	ds_read_b128 v[204:207], v141 offset:49152
	ds_read_b128 v[208:211], v141 offset:50176
	global_load_lds_dwordx4 v[222:223], off
	v_lshl_add_u64 v[222:223], v[224:225], 0, s[68:69]
	s_add_u32 m0, s3, 0xa000
	s_nop 0
	global_load_lds_dwordx4 v[222:223], off
	s_barrier
; #define STAGE_A(P, half, kt) do { const char* _u = Ab + ((size_t)(half) * 128 * lda + (size_t)(kt) * BK) * 2; \
;     _Pragma("unroll") for (int _i = 0; _i < 2; ++_i) \
;       __builtin_amdgcn_global_load_lds((const unsigned*)(_u + offA[_i]), \
;         (__attribute__((address_space(3))) unsigned*)((__attribute__((address_space(3))) char*)(P) + tidg * 16 + _i * 8192), 16, 0, 0); } while (0)
; #define STAGE_B(P, half, kt) do { const char* _u = Bb + ((size_t)(half) * 128 * ldb + (size_t)(kt) * BK) * 2; \
;     _Pragma("unroll") for (int _i = 0; _i < 2; ++_i) \
;       __builtin_amdgcn_global_load_lds((const unsigned*)(_u + offB[_i]), \
;         (__attribute__((address_space(3))) unsigned*)((__attribute__((address_space(3))) char*)(P) + tidg * 16 + _i * 8192), 16, 0, 0); } while (0)
; #define LDA(dst, b, h) _Pragma("unroll") for (int m = 0; m < 4; ++m) _Pragma("unroll") for (int k = 0; k < 2; ++k) \
;     dst[m][k] = *reinterpret_cast<const bf16x8*>((const char*)SA(b, h) + lds_byte(wr * 64 + m * 16 + fr, k * 32 + fq * 8))
; #define LDB(dst, b, h) _Pragma("unroll") for (int n = 0; n < 2; ++n) _Pragma("unroll") for (int k = 0; k < 2; ++k) \
;     dst[n][k] = *reinterpret_cast<const bf16x8*>((const char*)SB(b, h) + lds_byte(wc * 32 + n * 16 + fr, k * 32 + fq * 8))
; #define MMA(ai, bj, At_, Bt_) do { __builtin_amdgcn_s_setprio(1); \
;     _Pragma("unroll") for (int m = 0; m < 4; ++m) _Pragma("unroll") for (int n = 0; n < 2; ++n) _Pragma("unroll") for (int k = 0; k < 2; ++k) \
;       acc[ai][bj][m][n] = __builtin_amdgcn_mfma_f32_16x16x32_bf16(Bt_[n][k], At_[m][k], acc[ai][bj][m][n], 0, 0, 0); \
;     __builtin_amdgcn_s_setprio(0); } while (0)
; #define WAIT_V(n) asm volatile("s_waitcnt vmcnt(" #n ")" ::: "memory")
; template <bool PF = true, class Epi, class KRF = KRFull>
; __device__ __forceinline__ void gemm_phase(const u16* __restrict__ A, int lda, const u16* __restrict__ Bt, int ldb, int K, int nM, int nN,
;                                            lds_u16* shm, Epi epi, KRF krf = KRFull(), bool flip = false) {
;     ...
;       BAR; WAIT_L(0); MMA(1, 0, At, B0); BAR; SCHED;
;       STAGE_B(SB(1, 1), 1, t + 3);
;       WAIT_V(6); BAR; MMA(1, 1, At, B1); BAR;
;     }
;     { LDB(B0, 0, 0); LDA(At, 0, 0); STAGE_A(SA(1, 1), 1, nt - 1);
;       BAR; WAIT_L(0); MMA(0, 0, At, B0); BAR;
;       LDB(B1, 0, 1); BAR; WAIT_L(0); MMA(0, 1, At, B1); BAR;
	s_waitcnt lgkmcnt(0)
	s_setprio 1
	s_waitcnt lgkmcnt(0)
	v_mfma_f32_16x16x32_bf16 v[60:63], v[160:163], v[180:183], v[60:63]
	v_mfma_f32_16x16x32_bf16 v[56:59], v[168:171], v[180:183], v[56:59]
	v_mfma_f32_16x16x32_bf16 v[52:55], v[160:163], v[188:191], v[52:55]
	v_mfma_f32_16x16x32_bf16 v[48:51], v[168:171], v[188:191], v[48:51]
	v_mfma_f32_16x16x32_bf16 v[44:47], v[160:163], v[196:199], v[44:47]
	v_mfma_f32_16x16x32_bf16 v[40:43], v[168:171], v[196:199], v[40:43]
	v_mfma_f32_16x16x32_bf16 v[36:39], v[160:163], v[204:207], v[36:39]
	v_mfma_f32_16x16x32_bf16 v[32:35], v[168:171], v[204:207], v[32:35]
	v_mfma_f32_16x16x32_bf16 v[60:63], v[164:167], v[184:187], v[60:63]
	v_mfma_f32_16x16x32_bf16 v[56:59], v[172:175], v[184:187], v[56:59]
	v_mfma_f32_16x16x32_bf16 v[52:55], v[164:167], v[192:195], v[52:55]
	v_mfma_f32_16x16x32_bf16 v[48:51], v[172:175], v[192:195], v[48:51]
	v_mfma_f32_16x16x32_bf16 v[44:47], v[164:167], v[200:203], v[44:47]
	v_mfma_f32_16x16x32_bf16 v[40:43], v[172:175], v[200:203], v[40:43]
	v_mfma_f32_16x16x32_bf16 v[36:39], v[164:167], v[208:211], v[36:39]
	v_mfma_f32_16x16x32_bf16 v[32:35], v[172:175], v[208:211], v[32:35]
	s_setprio 0
	s_barrier
	v_lshl_add_u64 v[160:161], v[226:227], 0, s[70:71]
	s_add_u32 m0, s3, 0x1c000
	s_nop 0
	global_load_lds_dwordx4 v[160:161], off
	v_lshl_add_u64 v[160:161], v[228:229], 0, s[70:71]
	s_add_u32 m0, s3, 0x1e000
	s_nop 0
	global_load_lds_dwordx4 v[160:161], off
	s_waitcnt vmcnt(6)
	s_barrier
	s_setprio 1
	v_mfma_f32_16x16x32_bf16 v[28:31], v[212:215], v[180:183], v[28:31]
	v_mfma_f32_16x16x32_bf16 v[24:27], v[234:237], v[180:183], v[24:27]
	v_mfma_f32_16x16x32_bf16 v[20:23], v[212:215], v[188:191], v[20:23]
	v_mfma_f32_16x16x32_bf16 v[16:19], v[234:237], v[188:191], v[16:19]
	v_mfma_f32_16x16x32_bf16 v[12:15], v[212:215], v[196:199], v[12:15]
	v_mfma_f32_16x16x32_bf16 v[8:11], v[234:237], v[196:199], v[8:11]
	v_mfma_f32_16x16x32_bf16 v[4:7], v[212:215], v[204:207], v[4:7]
	v_mfma_f32_16x16x32_bf16 v[0:3], v[234:237], v[204:207], v[0:3]
	v_mfma_f32_16x16x32_bf16 v[28:31], v[216:219], v[184:187], v[28:31]
	v_mfma_f32_16x16x32_bf16 v[24:27], v[238:241], v[184:187], v[24:27]
	v_mfma_f32_16x16x32_bf16 v[20:23], v[216:219], v[192:195], v[20:23]
	v_mfma_f32_16x16x32_bf16 v[16:19], v[238:241], v[192:195], v[16:19]
	v_mfma_f32_16x16x32_bf16 v[12:15], v[216:219], v[200:203], v[12:15]
	v_mfma_f32_16x16x32_bf16 v[8:11], v[238:241], v[200:203], v[8:11]
	v_mfma_f32_16x16x32_bf16 v[4:7], v[216:219], v[208:211], v[4:7]
	v_mfma_f32_16x16x32_bf16 v[0:3], v[238:241], v[208:211], v[0:3]
	s_setprio 0
	s_add_i32 s2, s2, 2
	s_add_u32 s8, s8, 0x100
	s_addc_u32 s9, s9, 0
	s_cmp_gt_u32 s2, 27
	s_barrier
	s_cbranch_scc0 .LBB0_948
	s_add_u32 s2, s6, 0x80f80
	s_addc_u32 s3, s7, 0
	v_readfirstlane_b32 s6, v157
	v_lshl_add_u64 v[152:153], s[2:3], 0, v[178:179]
	s_mov_b32 m0, s6
	v_lshl_add_u64 v[128:129], s[2:3], 0, v[128:129]
	v_readfirstlane_b32 s2, v158
	ds_read_b128 v[130:133], v156
	ds_read_b128 v[134:137], v156 offset:1024
	ds_read_b128 v[148:151], v156 offset:2048
	ds_read_b128 v[160:163], v156 offset:3072
	ds_read_b128 v[164:167], v144
	ds_read_b128 v[168:171], v144 offset:1024
	ds_read_b128 v[172:175], v143
	ds_read_b128 v[180:183], v143 offset:1024
	ds_read_b128 v[184:187], v142
	ds_read_b128 v[188:191], v142 offset:1024
	ds_read_b128 v[192:195], v141
	ds_read_b128 v[196:199], v141 offset:1024
	global_load_lds_dwordx4 v[152:153], off
	s_mov_b32 m0, s2
	s_nop 0
	global_load_lds_dwordx4 v[128:129], off
	s_barrier
	s_waitcnt lgkmcnt(0)
	s_setprio 1
	s_waitcnt lgkmcnt(0)
	v_mfma_f32_16x16x32_bf16 v[124:127], v[130:133], v[164:167], v[124:127]
	v_mfma_f32_16x16x32_bf16 v[120:123], v[148:151], v[164:167], v[120:123]
	v_mfma_f32_16x16x32_bf16 v[116:119], v[130:133], v[172:175], v[116:119]
	v_mfma_f32_16x16x32_bf16 v[112:115], v[148:151], v[172:175], v[112:115]
	v_mfma_f32_16x16x32_bf16 v[108:111], v[130:133], v[184:187], v[108:111]
	v_mfma_f32_16x16x32_bf16 v[104:107], v[148:151], v[184:187], v[104:107]
	v_mfma_f32_16x16x32_bf16 v[100:103], v[130:133], v[192:195], v[100:103]
	v_mfma_f32_16x16x32_bf16 v[96:99], v[148:151], v[192:195], v[96:99]
	v_mfma_f32_16x16x32_bf16 v[124:127], v[134:137], v[168:171], v[124:127]
	v_mfma_f32_16x16x32_bf16 v[120:123], v[160:163], v[168:171], v[120:123]
	v_mfma_f32_16x16x32_bf16 v[116:119], v[134:137], v[180:183], v[116:119]
	v_mfma_f32_16x16x32_bf16 v[112:115], v[160:163], v[180:183], v[112:115]
	v_mfma_f32_16x16x32_bf16 v[108:111], v[134:137], v[188:191], v[108:111]
	v_mfma_f32_16x16x32_bf16 v[104:107], v[160:163], v[188:191], v[104:107]
	v_mfma_f32_16x16x32_bf16 v[100:103], v[134:137], v[196:199], v[100:103]
	v_mfma_f32_16x16x32_bf16 v[96:99], v[160:163], v[196:199], v[96:99]
	s_setprio 0
	s_barrier
	ds_read_b128 v[156:159], v155
	ds_read_b128 v[200:203], v155 offset:1024
	ds_read_b128 v[204:207], v155 offset:2048
	ds_read_b128 v[152:155], v155 offset:3072
	s_barrier
	s_waitcnt lgkmcnt(0)
	s_setprio 1
	s_waitcnt lgkmcnt(0)
	v_mfma_f32_16x16x32_bf16 v[76:79], v[156:159], v[184:187], v[76:79]
	v_mfma_f32_16x16x32_bf16 v[72:75], v[204:207], v[184:187], v[72:75]
	v_mfma_f32_16x16x32_bf16 v[68:71], v[156:159], v[192:195], v[68:71]
	v_mfma_f32_16x16x32_bf16 v[64:67], v[204:207], v[192:195], v[64:67]
	v_mfma_f32_16x16x32_bf16 v[92:95], v[156:159], v[164:167], v[92:95]
	v_mfma_f32_16x16x32_bf16 v[88:91], v[204:207], v[164:167], v[88:91]
	v_mfma_f32_16x16x32_bf16 v[84:87], v[156:159], v[172:175], v[84:87]
	v_mfma_f32_16x16x32_bf16 v[80:83], v[204:207], v[172:175], v[80:83]
	v_mfma_f32_16x16x32_bf16 v[76:79], v[200:203], v[188:191], v[76:79]
	v_mfma_f32_16x16x32_bf16 v[72:75], v[152:155], v[188:191], v[72:75]
	v_mfma_f32_16x16x32_bf16 v[68:71], v[200:203], v[196:199], v[68:71]
	v_mfma_f32_16x16x32_bf16 v[64:67], v[152:155], v[196:199], v[64:67]
	v_mfma_f32_16x16x32_bf16 v[208:211], v[200:203], v[168:171], v[92:95]
	v_mfma_f32_16x16x32_bf16 v[164:167], v[152:155], v[168:171], v[88:91]
	v_mfma_f32_16x16x32_bf16 v[168:171], v[200:203], v[180:183], v[84:87]
	v_mfma_f32_16x16x32_bf16 v[172:175], v[152:155], v[180:183], v[80:83]
	s_setprio 0
	s_barrier
; #define LDA(dst, b, h) _Pragma("unroll") for (int m = 0; m < 4; ++m) _Pragma("unroll") for (int k = 0; k < 2; ++k) \
;     dst[m][k] = *reinterpret_cast<const bf16x8*>((const char*)SA(b, h) + lds_byte(wr * 64 + m * 16 + fr, k * 32 + fq * 8))
; #define LDB(dst, b, h) _Pragma("unroll") for (int n = 0; n < 2; ++n) _Pragma("unroll") for (int k = 0; k < 2; ++k) \
;     dst[n][k] = *reinterpret_cast<const bf16x8*>((const char*)SB(b, h) + lds_byte(wc * 32 + n * 16 + fr, k * 32 + fq * 8))
; #define MMA(ai, bj, At_, Bt_) do { __builtin_amdgcn_s_setprio(1); \
;     _Pragma("unroll") for (int m = 0; m < 4; ++m) _Pragma("unroll") for (int n = 0; n < 2; ++n) _Pragma("unroll") for (int k = 0; k < 2; ++k) \
;       acc[ai][bj][m][n] = __builtin_amdgcn_mfma_f32_16x16x32_bf16(Bt_[n][k], At_[m][k], acc[ai][bj][m][n], 0, 0, 0); \
;     __builtin_amdgcn_s_setprio(0); } while (0)
; #define WAIT_V(n) asm volatile("s_waitcnt vmcnt(" #n ")" ::: "memory")
; #define WAIT_L(n) asm volatile("s_waitcnt lgkmcnt(" #n ")" ::: "memory")
; #define BAR __builtin_amdgcn_s_barrier()
; template <bool PF = true, class Epi, class KRF = KRFull>
; __device__ __forceinline__ void gemm_phase(const u16* __restrict__ A, int lda, const u16* __restrict__ Bt, int ldb, int K, int nM, int nN,
;                                            lds_u16* shm, Epi epi, KRF krf = KRFull(), bool flip = false) {
;     ...
;       LDA(At, 0, 1); WAIT_V(4); BAR; WAIT_L(0); MMA(1, 0, At, B0); MMA(1, 1, At, B1); BAR; }
;     { LDB(B0, 1, 0); LDA(At, 1, 0); WAIT_V(2); BAR; WAIT_L(0); MMA(0, 0, At, B0); BAR;
	s_nop 0
	ds_read_b128 v[80:83], v144 offset:16384
	ds_read_b128 v[84:87], v144 offset:17408
	ds_read_b128 v[88:91], v143 offset:16384
	ds_read_b128 v[92:95], v143 offset:17408
	ds_read_b128 v[180:183], v142 offset:16384
	ds_read_b128 v[184:187], v142 offset:17408
	ds_read_b128 v[188:191], v141 offset:16384
	ds_read_b128 v[192:195], v141 offset:17408
	s_waitcnt vmcnt(4)
	s_barrier
	s_waitcnt lgkmcnt(0)
	s_setprio 1
	s_waitcnt lgkmcnt(0)
	v_mfma_f32_16x16x32_bf16 v[44:47], v[130:133], v[180:183], v[44:47]
	v_mfma_f32_16x16x32_bf16 v[40:43], v[148:151], v[180:183], v[40:43]
	v_mfma_f32_16x16x32_bf16 v[36:39], v[130:133], v[188:191], v[36:39]
	v_mfma_f32_16x16x32_bf16 v[32:35], v[148:151], v[188:191], v[32:35]
	v_mfma_f32_16x16x32_bf16 v[60:63], v[130:133], v[80:83], v[60:63]
	v_mfma_f32_16x16x32_bf16 v[56:59], v[148:151], v[80:83], v[56:59]
	v_mfma_f32_16x16x32_bf16 v[52:55], v[130:133], v[88:91], v[52:55]
	v_mfma_f32_16x16x32_bf16 v[48:51], v[148:151], v[88:91], v[48:51]
	v_mfma_f32_16x16x32_bf16 v[44:47], v[134:137], v[184:187], v[44:47]
	v_mfma_f32_16x16x32_bf16 v[40:43], v[160:163], v[184:187], v[40:43]
	v_mfma_f32_16x16x32_bf16 v[36:39], v[134:137], v[192:195], v[36:39]
	v_mfma_f32_16x16x32_bf16 v[32:35], v[160:163], v[192:195], v[32:35]
	v_mfma_f32_16x16x32_bf16 v[196:199], v[134:137], v[84:87], v[60:63]
	v_mfma_f32_16x16x32_bf16 v[212:215], v[160:163], v[84:87], v[56:59]
	v_mfma_f32_16x16x32_bf16 v[216:219], v[134:137], v[92:95], v[52:55]
	v_mfma_f32_16x16x32_bf16 v[238:241], v[160:163], v[92:95], v[48:51]
	s_setprio 0
	s_setprio 1
	v_mfma_f32_16x16x32_bf16 v[0:3], v[204:207], v[188:191], v[0:3]
	v_mfma_f32_16x16x32_bf16 v[28:31], v[156:159], v[80:83], v[28:31]
	v_mfma_f32_16x16x32_bf16 v[24:27], v[204:207], v[80:83], v[24:27]
	v_mfma_f32_16x16x32_bf16 v[20:23], v[156:159], v[88:91], v[20:23]
	v_mfma_f32_16x16x32_bf16 v[16:19], v[204:207], v[88:91], v[16:19]
	v_mfma_f32_16x16x32_bf16 v[12:15], v[156:159], v[180:183], v[12:15]
	v_mfma_f32_16x16x32_bf16 v[8:11], v[204:207], v[180:183], v[8:11]
	v_mfma_f32_16x16x32_bf16 v[4:7], v[156:159], v[188:191], v[4:7]
	v_mfma_f32_16x16x32_bf16 v[0:3], v[152:155], v[192:195], v[0:3]
	v_mfma_f32_16x16x32_bf16 v[128:131], v[200:203], v[84:87], v[28:31]
	v_mfma_f32_16x16x32_bf16 v[132:135], v[152:155], v[84:87], v[24:27]
	v_mfma_f32_16x16x32_bf16 v[148:151], v[200:203], v[92:95], v[20:23]
	v_mfma_f32_16x16x32_bf16 v[160:163], v[152:155], v[92:95], v[16:19]
	v_mfma_f32_16x16x32_bf16 v[242:245], v[200:203], v[184:187], v[12:15]
	v_mfma_f32_16x16x32_bf16 v[180:183], v[152:155], v[184:187], v[8:11]
	v_mfma_f32_16x16x32_bf16 v[156:159], v[200:203], v[192:195], v[4:7]
	s_setprio 0
	s_barrier
	s_nop 0
	ds_read_b128 v[4:7], v147
	ds_read_b128 v[8:11], v147 offset:1024
	ds_read_b128 v[12:15], v147 offset:2048
	ds_read_b128 v[152:155], v147 offset:3072
	ds_read_b128 v[16:19], v144 offset:32768
	ds_read_b128 v[20:23], v144 offset:33792
	ds_read_b128 v[24:27], v143 offset:32768
	ds_read_b128 v[48:51], v143 offset:33792
	ds_read_b128 v[184:187], v142 offset:32768
	ds_read_b128 v[188:191], v142 offset:33792
	ds_read_b128 v[192:195], v141 offset:32768
	ds_read_b128 v[200:203], v141 offset:33792
	s_waitcnt vmcnt(2)
	s_barrier
	s_waitcnt lgkmcnt(0)
	s_setprio 1
	s_waitcnt lgkmcnt(0)
	v_mfma_f32_16x16x32_bf16 v[28:31], v[4:7], v[16:19], v[124:127]
	v_mfma_f32_16x16x32_bf16 v[124:127], v[8:11], v[20:23], v[28:31]
	v_mfma_f32_16x16x32_bf16 v[28:31], v[12:15], v[16:19], v[120:123]
	v_mfma_f32_16x16x32_bf16 v[92:95], v[152:155], v[20:23], v[28:31]
	v_mfma_f32_16x16x32_bf16 v[28:31], v[4:7], v[24:27], v[116:119]
	v_mfma_f32_16x16x32_bf16 v[120:123], v[8:11], v[48:51], v[28:31]
	v_mfma_f32_16x16x32_bf16 v[28:31], v[12:15], v[24:27], v[112:115]
	v_mfma_f32_16x16x32_bf16 v[88:91], v[152:155], v[48:51], v[28:31]
	v_mfma_f32_16x16x32_bf16 v[28:31], v[4:7], v[184:187], v[108:111]
	v_mfma_f32_16x16x32_bf16 v[116:119], v[8:11], v[188:191], v[28:31]
	v_mfma_f32_16x16x32_bf16 v[28:31], v[12:15], v[184:187], v[104:107]
	v_mfma_f32_16x16x32_bf16 v[84:87], v[152:155], v[188:191], v[28:31]
	v_mfma_f32_16x16x32_bf16 v[28:31], v[4:7], v[192:195], v[100:103]
	v_mfma_f32_16x16x32_bf16 v[112:115], v[8:11], v[200:203], v[28:31]
	v_mfma_f32_16x16x32_bf16 v[28:31], v[12:15], v[192:195], v[96:99]
	v_mfma_f32_16x16x32_bf16 v[80:83], v[152:155], v[200:203], v[28:31]
	s_setprio 0
	s_barrier
; #define LDA(dst, b, h) _Pragma("unroll") for (int m = 0; m < 4; ++m) _Pragma("unroll") for (int k = 0; k < 2; ++k) \
;     dst[m][k] = *reinterpret_cast<const bf16x8*>((const char*)SA(b, h) + lds_byte(wr * 64 + m * 16 + fr, k * 32 + fq * 8))
; #define LDB(dst, b, h) _Pragma("unroll") for (int n = 0; n < 2; ++n) _Pragma("unroll") for (int k = 0; k < 2; ++k) \
;     dst[n][k] = *reinterpret_cast<const bf16x8*>((const char*)SB(b, h) + lds_byte(wc * 32 + n * 16 + fr, k * 32 + fq * 8))
; #define MMA(ai, bj, At_, Bt_) do { __builtin_amdgcn_s_setprio(1); \
;     _Pragma("unroll") for (int m = 0; m < 4; ++m) _Pragma("unroll") for (int n = 0; n < 2; ++n) _Pragma("unroll") for (int k = 0; k < 2; ++k) \
;       acc[ai][bj][m][n] = __builtin_amdgcn_mfma_f32_16x16x32_bf16(Bt_[n][k], At_[m][k], acc[ai][bj][m][n], 0, 0, 0); \
;     __builtin_amdgcn_s_setprio(0); } while (0)
; #define WAIT_V(n) asm volatile("s_waitcnt vmcnt(" #n ")" ::: "memory")
; #define WAIT_L(n) asm volatile("s_waitcnt lgkmcnt(" #n ")" ::: "memory")
; #define BAR __builtin_amdgcn_s_barrier()
; template <bool PF = true, class Epi, class KRF = KRFull>
; __device__ __forceinline__ void gemm_phase(const u16* __restrict__ A, int lda, const u16* __restrict__ Bt, int ldb, int K, int nM, int nN,
;                                            lds_u16* shm, Epi epi, KRF krf = KRFull(), bool flip = false) {
;     ...
;       LDB(B1, 1, 1); WAIT_V(0); BAR; WAIT_L(0); MMA(0, 1, At, B1); BAR;
;       LDA(At, 1, 1); BAR; WAIT_L(0); MMA(1, 0, At, B0); MMA(1, 1, At, B1); BAR; }
;     if (wr == 0) BAR;
	ds_read_b128 v[204:207], v145
	ds_read_b128 v[246:249], v145 offset:1024
	ds_read_b128 v[250:253], v145 offset:2048
	ds_read_b128 v[234:237], v145 offset:3072
	s_waitcnt vmcnt(0)
	s_barrier
	s_waitcnt lgkmcnt(0)
	s_setprio 1
	s_waitcnt lgkmcnt(0)
	v_mfma_f32_16x16x32_bf16 v[28:31], v[204:207], v[16:19], v[208:211]
	v_mfma_f32_16x16x32_bf16 v[16:19], v[250:253], v[16:19], v[164:167]
	v_mfma_f32_16x16x32_bf16 v[60:63], v[246:249], v[20:23], v[28:31]
	v_mfma_f32_16x16x32_bf16 v[28:31], v[234:237], v[20:23], v[16:19]
	v_mfma_f32_16x16x32_bf16 v[16:19], v[204:207], v[24:27], v[168:171]
	v_mfma_f32_16x16x32_bf16 v[56:59], v[246:249], v[48:51], v[16:19]
	v_mfma_f32_16x16x32_bf16 v[16:19], v[250:253], v[24:27], v[172:175]
	v_mfma_f32_16x16x32_bf16 v[24:27], v[234:237], v[48:51], v[16:19]
	v_mfma_f32_16x16x32_bf16 v[16:19], v[204:207], v[184:187], v[76:79]
	v_mfma_f32_16x16x32_bf16 v[52:55], v[246:249], v[188:191], v[16:19]
	v_mfma_f32_16x16x32_bf16 v[16:19], v[250:253], v[184:187], v[72:75]
	v_mfma_f32_16x16x32_bf16 v[20:23], v[234:237], v[188:191], v[16:19]
	v_mfma_f32_16x16x32_bf16 v[16:19], v[204:207], v[192:195], v[68:71]
	v_mfma_f32_16x16x32_bf16 v[48:51], v[246:249], v[200:203], v[16:19]
	v_mfma_f32_16x16x32_bf16 v[16:19], v[250:253], v[192:195], v[64:67]
	v_mfma_f32_16x16x32_bf16 v[16:19], v[234:237], v[200:203], v[16:19]
	s_setprio 0
	s_barrier
	ds_read_b128 v[164:167], v144 offset:49152
	ds_read_b128 v[144:147], v144 offset:50176
	ds_read_b128 v[168:171], v143 offset:49152
	ds_read_b128 v[172:175], v143 offset:50176
	ds_read_b128 v[184:187], v142 offset:49152
	ds_read_b128 v[188:191], v142 offset:50176
	ds_read_b128 v[192:195], v141 offset:49152
	ds_read_b128 v[200:203], v141 offset:50176
	s_barrier
	s_waitcnt lgkmcnt(0)
	s_setprio 1
	s_waitcnt lgkmcnt(0)
	v_mfma_f32_16x16x32_bf16 v[64:67], v[4:7], v[164:167], v[196:199]
	v_mfma_f32_16x16x32_bf16 v[108:111], v[8:11], v[144:147], v[64:67]
	v_mfma_f32_16x16x32_bf16 v[64:67], v[12:15], v[164:167], v[212:215]
	v_mfma_f32_16x16x32_bf16 v[76:79], v[152:155], v[144:147], v[64:67]
	v_mfma_f32_16x16x32_bf16 v[64:67], v[4:7], v[168:171], v[216:219]
	v_mfma_f32_16x16x32_bf16 v[44:47], v[4:7], v[184:187], v[44:47]
	v_mfma_f32_16x16x32_bf16 v[4:7], v[4:7], v[192:195], v[36:39]
	v_mfma_f32_16x16x32_bf16 v[104:107], v[8:11], v[172:175], v[64:67]
	v_mfma_f32_16x16x32_bf16 v[64:67], v[12:15], v[168:171], v[238:241]
	v_mfma_f32_16x16x32_bf16 v[40:43], v[12:15], v[184:187], v[40:43]
	v_mfma_f32_16x16x32_bf16 v[96:99], v[8:11], v[200:203], v[4:7]
	v_mfma_f32_16x16x32_bf16 v[4:7], v[12:15], v[192:195], v[32:35]
	v_mfma_f32_16x16x32_bf16 v[72:75], v[152:155], v[172:175], v[64:67]
	v_mfma_f32_16x16x32_bf16 v[100:103], v[8:11], v[188:191], v[44:47]
	v_mfma_f32_16x16x32_bf16 v[68:71], v[152:155], v[188:191], v[40:43]
	v_mfma_f32_16x16x32_bf16 v[64:67], v[152:155], v[200:203], v[4:7]
	s_setprio 0
	s_setprio 1
	v_mfma_f32_16x16x32_bf16 v[4:7], v[204:207], v[164:167], v[128:131]
	v_mfma_f32_16x16x32_bf16 v[44:47], v[246:249], v[144:147], v[4:7]
	v_mfma_f32_16x16x32_bf16 v[4:7], v[250:253], v[164:167], v[132:135]
	v_mfma_f32_16x16x32_bf16 v[12:15], v[234:237], v[144:147], v[4:7]
	v_mfma_f32_16x16x32_bf16 v[4:7], v[204:207], v[168:171], v[148:151]
	v_mfma_f32_16x16x32_bf16 v[40:43], v[246:249], v[172:175], v[4:7]
	v_mfma_f32_16x16x32_bf16 v[4:7], v[250:253], v[168:171], v[160:163]
	v_mfma_f32_16x16x32_bf16 v[8:11], v[234:237], v[172:175], v[4:7]
	v_mfma_f32_16x16x32_bf16 v[4:7], v[204:207], v[184:187], v[242:245]
	v_mfma_f32_16x16x32_bf16 v[36:39], v[246:249], v[188:191], v[4:7]
	v_mfma_f32_16x16x32_bf16 v[4:7], v[250:253], v[184:187], v[180:183]
	v_mfma_f32_16x16x32_bf16 v[32:35], v[204:207], v[192:195], v[156:159]
	v_mfma_f32_16x16x32_bf16 v[0:3], v[250:253], v[192:195], v[0:3]
	v_mfma_f32_16x16x32_bf16 v[4:7], v[234:237], v[188:191], v[4:7]
	v_mfma_f32_16x16x32_bf16 v[32:35], v[246:249], v[200:203], v[32:35]
	v_mfma_f32_16x16x32_bf16 v[0:3], v[234:237], v[200:203], v[0:3]
	s_setprio 0
	v_cmp_gt_u32_e32 vcc, s95, v138
	s_barrier
	s_and_saveexec_b64 s[6:7], vcc
	s_cbranch_execz .LBB0_951
	s_barrier

; #define STAGE_A(P, half, kt) do { const char* _u = Ab + ((size_t)(half) * 128 * lda + (size_t)(kt) * BK) * 2; \
;     _Pragma("unroll") for (int _i = 0; _i < 2; ++_i) \
;       __builtin_amdgcn_global_load_lds((const unsigned*)(_u + offA[_i]), \
;         (__attribute__((address_space(3))) unsigned*)((__attribute__((address_space(3))) char*)(P) + tidg * 16 + _i * 8192), 16, 0, 0); } while (0)
; #define STAGE_B(P, half, kt) do { const char* _u = Bb + ((size_t)(half) * 128 * ldb + (size_t)(kt) * BK) * 2; \
;     _Pragma("unroll") for (int _i = 0; _i < 2; ++_i) \
;       __builtin_amdgcn_global_load_lds((const unsigned*)(_u + offB[_i]), \
;         (__attribute__((address_space(3))) unsigned*)((__attribute__((address_space(3))) char*)(P) + tidg * 16 + _i * 8192), 16, 0, 0); } while (0)
; #define LDA(dst, b, h) _Pragma("unroll") for (int m = 0; m < 4; ++m) _Pragma("unroll") for (int k = 0; k < 2; ++k) \
;     dst[m][k] = *reinterpret_cast<const bf16x8*>((const char*)SA(b, h) + lds_byte(wr * 64 + m * 16 + fr, k * 32 + fq * 8))
; #define LDB(dst, b, h) _Pragma("unroll") for (int n = 0; n < 2; ++n) _Pragma("unroll") for (int k = 0; k < 2; ++k) \
;     dst[n][k] = *reinterpret_cast<const bf16x8*>((const char*)SB(b, h) + lds_byte(wc * 32 + n * 16 + fr, k * 32 + fq * 8))
; #define MMA(ai, bj, At_, Bt_) do { __builtin_amdgcn_s_setprio(1); \
;     _Pragma("unroll") for (int m = 0; m < 4; ++m) _Pragma("unroll") for (int n = 0; n < 2; ++n) _Pragma("unroll") for (int k = 0; k < 2; ++k) \
;       acc[ai][bj][m][n] = __builtin_amdgcn_mfma_f32_16x16x32_bf16(Bt_[n][k], At_[m][k], acc[ai][bj][m][n], 0, 0, 0); \
;     __builtin_amdgcn_s_setprio(0); } while (0)
; template <bool PF = true, class Epi, class KRF = KRFull>
; __device__ __forceinline__ void gemm_phase(const u16* __restrict__ A, int lda, const u16* __restrict__ Bt, int ldb, int K, int nM, int nN,
;                                            lds_u16* shm, Epi epi, KRF krf = KRFull(), bool flip = false) {
;     ...
;     for (int t = 0; t < nt - 2; t += 2) {
;       LDB(B0, 0, 0); SCHED; LDA(At, 0, 0); STAGE_A(SA(1, 1), 1, t + 1);
;       WAIT_L(8); BAR; WAIT_L(0); MMA(0, 0, At, B0); BAR; SCHED;
;       LDB(B1, 0, 1); STAGE_B(SB(0, 0), 0, t + 2);
;       BAR; WAIT_L(0); MMA(0, 1, At, B1); BAR;
;       LDA(At, 0, 1); STAGE_A(SA(0, 0), 0, t + 2);
;       BAR; WAIT_L(0); MMA(1, 0, At, B0); BAR; SCHED;
.LBB0_1636:
	v_readfirstlane_b32 s3, v146
	ds_read_b128 v[160:163], v156
	ds_read_b128 v[164:167], v156 offset:1024
	ds_read_b128 v[168:171], v156 offset:2048
	ds_read_b128 v[172:175], v156 offset:3072
	v_add_u32_e32 v157, 0xc000, v146
	v_lshl_add_u64 v[222:223], v[134:135], 0, s[8:9]
	v_lshl_add_u64 v[158:159], v[222:223], 0, s[62:63]
	s_add_u32 m0, s3, 0xc000
	ds_read_b128 v[180:183], v144
	ds_read_b128 v[184:187], v144 offset:1024
	ds_read_b128 v[188:191], v143
	ds_read_b128 v[192:195], v143 offset:1024
	ds_read_b128 v[196:199], v141
	ds_read_b128 v[200:203], v141 offset:1024
	ds_read_b128 v[204:207], v140
	ds_read_b128 v[208:211], v140 offset:1024
	global_load_lds_dwordx4 v[158:159], off
	v_add_u32_e32 v158, 0xe000, v146
	v_lshl_add_u64 v[224:225], v[136:137], 0, s[8:9]
	v_lshl_add_u64 v[212:213], v[224:225], 0, s[62:63]
	s_add_u32 m0, s3, 0xe000
	s_nop 0
	global_load_lds_dwordx4 v[212:213], off
	s_waitcnt lgkmcnt(8)
	s_barrier
	s_waitcnt lgkmcnt(0)
	s_setprio 1
	s_waitcnt lgkmcnt(0)
	v_mfma_f32_16x16x32_bf16 v[124:127], v[160:163], v[180:183], v[124:127]
	v_mfma_f32_16x16x32_bf16 v[120:123], v[168:171], v[180:183], v[120:123]
	v_mfma_f32_16x16x32_bf16 v[116:119], v[160:163], v[188:191], v[116:119]
	v_mfma_f32_16x16x32_bf16 v[112:115], v[168:171], v[188:191], v[112:115]
	v_mfma_f32_16x16x32_bf16 v[108:111], v[160:163], v[196:199], v[108:111]
	v_mfma_f32_16x16x32_bf16 v[104:107], v[168:171], v[196:199], v[104:107]
	v_mfma_f32_16x16x32_bf16 v[100:103], v[160:163], v[204:207], v[100:103]
	v_mfma_f32_16x16x32_bf16 v[96:99], v[168:171], v[204:207], v[96:99]
	v_mfma_f32_16x16x32_bf16 v[124:127], v[164:167], v[184:187], v[124:127]
	v_mfma_f32_16x16x32_bf16 v[120:123], v[172:175], v[184:187], v[120:123]
	v_mfma_f32_16x16x32_bf16 v[116:119], v[164:167], v[192:195], v[116:119]
	v_mfma_f32_16x16x32_bf16 v[112:115], v[172:175], v[192:195], v[112:115]
	v_mfma_f32_16x16x32_bf16 v[108:111], v[164:167], v[200:203], v[108:111]
	v_mfma_f32_16x16x32_bf16 v[104:107], v[172:175], v[200:203], v[104:107]
	v_mfma_f32_16x16x32_bf16 v[100:103], v[164:167], v[208:211], v[100:103]
	v_mfma_f32_16x16x32_bf16 v[96:99], v[172:175], v[208:211], v[96:99]
	s_setprio 0
	s_barrier
	v_add_u32_e32 v159, 0x10000, v146
	v_lshl_add_u64 v[226:227], v[130:131], 0, s[8:9]
	v_lshl_add_u64 v[228:229], v[226:227], 0, s[64:65]
	s_add_u32 m0, s3, 0x10000
	v_add_u32_e32 v159, 0x12000, v146
	ds_read_b128 v[212:215], v155
	ds_read_b128 v[216:219], v155 offset:1024
	ds_read_b128 v[234:237], v155 offset:2048
	ds_read_b128 v[238:241], v155 offset:3072
	global_load_lds_dwordx4 v[228:229], off
	v_lshl_add_u64 v[228:229], v[132:133], 0, s[8:9]
	v_lshl_add_u64 v[242:243], v[228:229], 0, s[64:65]
	s_add_u32 m0, s3, 0x12000
	s_nop 0
	global_load_lds_dwordx4 v[242:243], off
	s_barrier
	s_waitcnt lgkmcnt(0)
	s_setprio 1
	s_waitcnt lgkmcnt(0)
	v_mfma_f32_16x16x32_bf16 v[92:95], v[212:215], v[180:183], v[92:95]
	v_mfma_f32_16x16x32_bf16 v[88:91], v[234:237], v[180:183], v[88:91]
	v_mfma_f32_16x16x32_bf16 v[84:87], v[212:215], v[188:191], v[84:87]
	v_mfma_f32_16x16x32_bf16 v[80:83], v[234:237], v[188:191], v[80:83]
	v_mfma_f32_16x16x32_bf16 v[76:79], v[212:215], v[196:199], v[76:79]
	v_mfma_f32_16x16x32_bf16 v[72:75], v[234:237], v[196:199], v[72:75]
	v_mfma_f32_16x16x32_bf16 v[68:71], v[212:215], v[204:207], v[68:71]
	v_mfma_f32_16x16x32_bf16 v[64:67], v[234:237], v[204:207], v[64:67]
	v_mfma_f32_16x16x32_bf16 v[92:95], v[216:219], v[184:187], v[92:95]
	v_mfma_f32_16x16x32_bf16 v[88:91], v[238:241], v[184:187], v[88:91]
	v_mfma_f32_16x16x32_bf16 v[84:87], v[216:219], v[192:195], v[84:87]
	v_mfma_f32_16x16x32_bf16 v[80:83], v[238:241], v[192:195], v[80:83]
	v_mfma_f32_16x16x32_bf16 v[76:79], v[216:219], v[200:203], v[76:79]
	v_mfma_f32_16x16x32_bf16 v[72:75], v[238:241], v[200:203], v[72:75]
	v_mfma_f32_16x16x32_bf16 v[68:71], v[216:219], v[208:211], v[68:71]
	v_mfma_f32_16x16x32_bf16 v[64:67], v[238:241], v[208:211], v[64:67]
	s_setprio 0
	v_lshl_add_u64 v[242:243], v[222:223], 0, s[64:65]
	s_mov_b32 m0, s3
	s_barrier
	ds_read_b128 v[180:183], v144 offset:16384
	ds_read_b128 v[184:187], v144 offset:17408
	ds_read_b128 v[188:191], v143 offset:16384
	ds_read_b128 v[192:195], v143 offset:17408
	ds_read_b128 v[196:199], v141 offset:16384
	ds_read_b128 v[200:203], v141 offset:17408
	ds_read_b128 v[204:207], v140 offset:16384
	ds_read_b128 v[208:211], v140 offset:17408
	global_load_lds_dwordx4 v[242:243], off
	v_lshl_add_u64 v[242:243], v[224:225], 0, s[64:65]
	s_add_u32 m0, s3, 0x2000
	s_nop 0
	global_load_lds_dwordx4 v[242:243], off
	s_barrier
	s_waitcnt lgkmcnt(0)
	s_setprio 1
	s_waitcnt lgkmcnt(0)
	v_mfma_f32_16x16x32_bf16 v[60:63], v[160:163], v[180:183], v[60:63]
	v_mfma_f32_16x16x32_bf16 v[56:59], v[168:171], v[180:183], v[56:59]
	v_mfma_f32_16x16x32_bf16 v[52:55], v[160:163], v[188:191], v[52:55]
	v_mfma_f32_16x16x32_bf16 v[48:51], v[168:171], v[188:191], v[48:51]
	v_mfma_f32_16x16x32_bf16 v[44:47], v[160:163], v[196:199], v[44:47]
	v_mfma_f32_16x16x32_bf16 v[40:43], v[168:171], v[196:199], v[40:43]
	v_mfma_f32_16x16x32_bf16 v[36:39], v[160:163], v[204:207], v[36:39]
	v_mfma_f32_16x16x32_bf16 v[32:35], v[168:171], v[204:207], v[32:35]
	v_mfma_f32_16x16x32_bf16 v[60:63], v[164:167], v[184:187], v[60:63]
	v_mfma_f32_16x16x32_bf16 v[56:59], v[172:175], v[184:187], v[56:59]
	v_mfma_f32_16x16x32_bf16 v[52:55], v[164:167], v[192:195], v[52:55]
	v_mfma_f32_16x16x32_bf16 v[48:51], v[172:175], v[192:195], v[48:51]
	v_mfma_f32_16x16x32_bf16 v[44:47], v[164:167], v[200:203], v[44:47]
	v_mfma_f32_16x16x32_bf16 v[40:43], v[172:175], v[200:203], v[40:43]
	v_mfma_f32_16x16x32_bf16 v[36:39], v[164:167], v[208:211], v[36:39]
	v_mfma_f32_16x16x32_bf16 v[32:35], v[172:175], v[208:211], v[32:35]
	s_setprio 0
	s_barrier
; #define STAGE_A(P, half, kt) do { const char* _u = Ab + ((size_t)(half) * 128 * lda + (size_t)(kt) * BK) * 2; \
;     _Pragma("unroll") for (int _i = 0; _i < 2; ++_i) \
;       __builtin_amdgcn_global_load_lds((const unsigned*)(_u + offA[_i]), \
;         (__attribute__((address_space(3))) unsigned*)((__attribute__((address_space(3))) char*)(P) + tidg * 16 + _i * 8192), 16, 0, 0); } while (0)
; #define STAGE_B(P, half, kt) do { const char* _u = Bb + ((size_t)(half) * 128 * ldb + (size_t)(kt) * BK) * 2; \
;     _Pragma("unroll") for (int _i = 0; _i < 2; ++_i) \
;       __builtin_amdgcn_global_load_lds((const unsigned*)(_u + offB[_i]), \
;         (__attribute__((address_space(3))) unsigned*)((__attribute__((address_space(3))) char*)(P) + tidg * 16 + _i * 8192), 16, 0, 0); } while (0)
; #define LDA(dst, b, h) _Pragma("unroll") for (int m = 0; m < 4; ++m) _Pragma("unroll") for (int k = 0; k < 2; ++k) \
;     dst[m][k] = *reinterpret_cast<const bf16x8*>((const char*)SA(b, h) + lds_byte(wr * 64 + m * 16 + fr, k * 32 + fq * 8))
; #define LDB(dst, b, h) _Pragma("unroll") for (int n = 0; n < 2; ++n) _Pragma("unroll") for (int k = 0; k < 2; ++k) \
;     dst[n][k] = *reinterpret_cast<const bf16x8*>((const char*)SB(b, h) + lds_byte(wc * 32 + n * 16 + fr, k * 32 + fq * 8))
; #define MMA(ai, bj, At_, Bt_) do { __builtin_amdgcn_s_setprio(1); \
;     _Pragma("unroll") for (int m = 0; m < 4; ++m) _Pragma("unroll") for (int n = 0; n < 2; ++n) _Pragma("unroll") for (int k = 0; k < 2; ++k) \
;       acc[ai][bj][m][n] = __builtin_amdgcn_mfma_f32_16x16x32_bf16(Bt_[n][k], At_[m][k], acc[ai][bj][m][n], 0, 0, 0); \
;     __builtin_amdgcn_s_setprio(0); } while (0)
; #define BAR __builtin_amdgcn_s_barrier()
; template <bool PF = true, class Epi, class KRF = KRFull>
; __device__ __forceinline__ void gemm_phase(const u16* __restrict__ A, int lda, const u16* __restrict__ Bt, int ldb, int K, int nM, int nN,
;                                            lds_u16* shm, Epi epi, KRF krf = KRFull(), bool flip = false) {
;     ...
;       STAGE_B(SB(0, 1), 1, t + 2);
;       WAIT_V(6); BAR; MMA(1, 1, At, B1); BAR;
;       LDB(B0, 1, 0); SCHED; LDA(At, 1, 0); STAGE_A(SA(0, 1), 1, t + 2);
;       WAIT_L(8); BAR; WAIT_L(0); MMA(0, 0, At, B0); BAR; SCHED;
;       LDB(B1, 1, 1); STAGE_B(SB(1, 0), 0, t + 3);
;       BAR; WAIT_L(0); MMA(0, 1, At, B1); BAR;
;       LDA(At, 1, 1); STAGE_A(SA(1, 0), 0, t + 3);
	v_add_u32_e32 v159, 0x14000, v146
	v_lshl_add_u64 v[160:161], v[226:227], 0, s[66:67]
	v_add_u32_e32 v159, 0x16000, v146
	s_add_u32 m0, s3, 0x14000
	s_nop 0
	global_load_lds_dwordx4 v[160:161], off
	v_lshl_add_u64 v[160:161], v[228:229], 0, s[66:67]
	s_add_u32 m0, s3, 0x16000
	s_nop 0
	global_load_lds_dwordx4 v[160:161], off
	s_waitcnt vmcnt(6)
	s_barrier
	s_setprio 1
	v_mfma_f32_16x16x32_bf16 v[28:31], v[212:215], v[180:183], v[28:31]
	v_mfma_f32_16x16x32_bf16 v[24:27], v[234:237], v[180:183], v[24:27]
	v_mfma_f32_16x16x32_bf16 v[20:23], v[212:215], v[188:191], v[20:23]
	v_mfma_f32_16x16x32_bf16 v[16:19], v[234:237], v[188:191], v[16:19]
	v_mfma_f32_16x16x32_bf16 v[12:15], v[212:215], v[196:199], v[12:15]
	v_mfma_f32_16x16x32_bf16 v[8:11], v[234:237], v[196:199], v[8:11]
	v_mfma_f32_16x16x32_bf16 v[4:7], v[212:215], v[204:207], v[4:7]
	v_mfma_f32_16x16x32_bf16 v[0:3], v[234:237], v[204:207], v[0:3]
	v_mfma_f32_16x16x32_bf16 v[28:31], v[216:219], v[184:187], v[28:31]
	v_mfma_f32_16x16x32_bf16 v[24:27], v[238:241], v[184:187], v[24:27]
	v_mfma_f32_16x16x32_bf16 v[20:23], v[216:219], v[192:195], v[20:23]
	v_mfma_f32_16x16x32_bf16 v[16:19], v[238:241], v[192:195], v[16:19]
	v_mfma_f32_16x16x32_bf16 v[12:15], v[216:219], v[200:203], v[12:15]
	v_mfma_f32_16x16x32_bf16 v[8:11], v[238:241], v[200:203], v[8:11]
	v_mfma_f32_16x16x32_bf16 v[4:7], v[216:219], v[208:211], v[4:7]
	v_mfma_f32_16x16x32_bf16 v[0:3], v[238:241], v[208:211], v[0:3]
	s_setprio 0
	s_barrier
	ds_read_b128 v[160:163], v147
	ds_read_b128 v[164:167], v147 offset:1024
	ds_read_b128 v[168:171], v147 offset:2048
	ds_read_b128 v[172:175], v147 offset:3072
	v_add_u32_e32 v159, 0x4000, v146
	v_lshl_add_u64 v[212:213], v[222:223], 0, s[66:67]
	v_add_u32_e32 v159, 0x6000, v146
	s_add_u32 m0, s3, 0x4000
	ds_read_b128 v[180:183], v144 offset:32768
	ds_read_b128 v[184:187], v144 offset:33792
	ds_read_b128 v[188:191], v143 offset:32768
	ds_read_b128 v[192:195], v143 offset:33792
	ds_read_b128 v[196:199], v141 offset:32768
	ds_read_b128 v[200:203], v141 offset:33792
	ds_read_b128 v[204:207], v140 offset:32768
	ds_read_b128 v[208:211], v140 offset:33792
	global_load_lds_dwordx4 v[212:213], off
	v_lshl_add_u64 v[212:213], v[224:225], 0, s[66:67]
	s_add_u32 m0, s3, 0x6000
	s_nop 0
	global_load_lds_dwordx4 v[212:213], off
	s_waitcnt lgkmcnt(8)
	s_barrier
	s_waitcnt lgkmcnt(0)
	s_setprio 1
	s_waitcnt lgkmcnt(0)
	v_mfma_f32_16x16x32_bf16 v[124:127], v[160:163], v[180:183], v[124:127]
	v_mfma_f32_16x16x32_bf16 v[120:123], v[168:171], v[180:183], v[120:123]
	v_mfma_f32_16x16x32_bf16 v[116:119], v[160:163], v[188:191], v[116:119]
	v_mfma_f32_16x16x32_bf16 v[112:115], v[168:171], v[188:191], v[112:115]
	v_mfma_f32_16x16x32_bf16 v[108:111], v[160:163], v[196:199], v[108:111]
	v_mfma_f32_16x16x32_bf16 v[104:107], v[168:171], v[196:199], v[104:107]
	v_mfma_f32_16x16x32_bf16 v[100:103], v[160:163], v[204:207], v[100:103]
	v_mfma_f32_16x16x32_bf16 v[96:99], v[168:171], v[204:207], v[96:99]
	v_mfma_f32_16x16x32_bf16 v[124:127], v[164:167], v[184:187], v[124:127]
	v_mfma_f32_16x16x32_bf16 v[120:123], v[172:175], v[184:187], v[120:123]
	v_mfma_f32_16x16x32_bf16 v[116:119], v[164:167], v[192:195], v[116:119]
	v_mfma_f32_16x16x32_bf16 v[112:115], v[172:175], v[192:195], v[112:115]
	v_mfma_f32_16x16x32_bf16 v[108:111], v[164:167], v[200:203], v[108:111]
	v_mfma_f32_16x16x32_bf16 v[104:107], v[172:175], v[200:203], v[104:107]
	v_mfma_f32_16x16x32_bf16 v[100:103], v[164:167], v[208:211], v[100:103]
	v_mfma_f32_16x16x32_bf16 v[96:99], v[172:175], v[208:211], v[96:99]
	s_setprio 0
	s_barrier
	v_lshl_add_u64 v[242:243], v[226:227], 0, s[68:69]
	s_add_u32 m0, s3, 0x18000
	ds_read_b128 v[212:215], v145
	ds_read_b128 v[216:219], v145 offset:1024
	ds_read_b128 v[234:237], v145 offset:2048
	ds_read_b128 v[238:241], v145 offset:3072
	global_load_lds_dwordx4 v[242:243], off
	v_lshl_add_u64 v[242:243], v[228:229], 0, s[68:69]
	s_add_u32 m0, s3, 0x1a000
	s_nop 0
	global_load_lds_dwordx4 v[242:243], off
	s_barrier
	s_waitcnt lgkmcnt(0)
	s_setprio 1
	s_waitcnt lgkmcnt(0)
	v_mfma_f32_16x16x32_bf16 v[92:95], v[212:215], v[180:183], v[92:95]
	v_mfma_f32_16x16x32_bf16 v[88:91], v[234:237], v[180:183], v[88:91]
	v_mfma_f32_16x16x32_bf16 v[84:87], v[212:215], v[188:191], v[84:87]
	v_mfma_f32_16x16x32_bf16 v[80:83], v[234:237], v[188:191], v[80:83]
	v_mfma_f32_16x16x32_bf16 v[76:79], v[212:215], v[196:199], v[76:79]
	v_mfma_f32_16x16x32_bf16 v[72:75], v[234:237], v[196:199], v[72:75]
	v_mfma_f32_16x16x32_bf16 v[68:71], v[212:215], v[204:207], v[68:71]
	v_mfma_f32_16x16x32_bf16 v[64:67], v[234:237], v[204:207], v[64:67]
	v_mfma_f32_16x16x32_bf16 v[92:95], v[216:219], v[184:187], v[92:95]
	v_mfma_f32_16x16x32_bf16 v[88:91], v[238:241], v[184:187], v[88:91]
	v_mfma_f32_16x16x32_bf16 v[84:87], v[216:219], v[192:195], v[84:87]
	v_mfma_f32_16x16x32_bf16 v[80:83], v[238:241], v[192:195], v[80:83]
	v_mfma_f32_16x16x32_bf16 v[76:79], v[216:219], v[200:203], v[76:79]
	v_mfma_f32_16x16x32_bf16 v[72:75], v[238:241], v[200:203], v[72:75]
	v_mfma_f32_16x16x32_bf16 v[68:71], v[216:219], v[208:211], v[68:71]
	v_mfma_f32_16x16x32_bf16 v[64:67], v[238:241], v[208:211], v[64:67]
	s_setprio 0
	v_lshl_add_u64 v[222:223], v[222:223], 0, s[68:69]
	s_add_u32 m0, s3, 0x8000
	s_barrier
	ds_read_b128 v[180:183], v144 offset:49152
	ds_read_b128 v[184:187], v144 offset:50176
	ds_read_b128 v[188:191], v143 offset:49152
	ds_read_b128 v[192:195], v143 offset:50176
	ds_read_b128 v[196:199], v141 offset:49152
	ds_read_b128 v[200:203], v141 offset:50176
	ds_read_b128 v[204:207], v140 offset:49152
	ds_read_b128 v[208:211], v140 offset:50176
	global_load_lds_dwordx4 v[222:223], off
	v_lshl_add_u64 v[222:223], v[224:225], 0, s[68:69]
	s_add_u32 m0, s3, 0xa000
	s_nop 0
	global_load_lds_dwordx4 v[222:223], off
	s_barrier
; #define STAGE_A(P, half, kt) do { const char* _u = Ab + ((size_t)(half) * 128 * lda + (size_t)(kt) * BK) * 2; \
;     _Pragma("unroll") for (int _i = 0; _i < 2; ++_i) \
;       __builtin_amdgcn_global_load_lds((const unsigned*)(_u + offA[_i]), \
;         (__attribute__((address_space(3))) unsigned*)((__attribute__((address_space(3))) char*)(P) + tidg * 16 + _i * 8192), 16, 0, 0); } while (0)
; #define STAGE_B(P, half, kt) do { const char* _u = Bb + ((size_t)(half) * 128 * ldb + (size_t)(kt) * BK) * 2; \
;     _Pragma("unroll") for (int _i = 0; _i < 2; ++_i) \
;       __builtin_amdgcn_global_load_lds((const unsigned*)(_u + offB[_i]), \
;         (__attribute__((address_space(3))) unsigned*)((__attribute__((address_space(3))) char*)(P) + tidg * 16 + _i * 8192), 16, 0, 0); } while (0)
; #define LDA(dst, b, h) _Pragma("unroll") for (int m = 0; m < 4; ++m) _Pragma("unroll") for (int k = 0; k < 2; ++k) \
;     dst[m][k] = *reinterpret_cast<const bf16x8*>((const char*)SA(b, h) + lds_byte(wr * 64 + m * 16 + fr, k * 32 + fq * 8))
; #define LDB(dst, b, h) _Pragma("unroll") for (int n = 0; n < 2; ++n) _Pragma("unroll") for (int k = 0; k < 2; ++k) \
;     dst[n][k] = *reinterpret_cast<const bf16x8*>((const char*)SB(b, h) + lds_byte(wc * 32 + n * 16 + fr, k * 32 + fq * 8))
; #define MMA(ai, bj, At_, Bt_) do { __builtin_amdgcn_s_setprio(1); \
;     _Pragma("unroll") for (int m = 0; m < 4; ++m) _Pragma("unroll") for (int n = 0; n < 2; ++n) _Pragma("unroll") for (int k = 0; k < 2; ++k) \
;       acc[ai][bj][m][n] = __builtin_amdgcn_mfma_f32_16x16x32_bf16(Bt_[n][k], At_[m][k], acc[ai][bj][m][n], 0, 0, 0); \
;     __builtin_amdgcn_s_setprio(0); } while (0)
; #define WAIT_V(n) asm volatile("s_waitcnt vmcnt(" #n ")" ::: "memory")
; template <bool PF = true, class Epi, class KRF = KRFull>
; __device__ __forceinline__ void gemm_phase(const u16* __restrict__ A, int lda, const u16* __restrict__ Bt, int ldb, int K, int nM, int nN,
;                                            lds_u16* shm, Epi epi, KRF krf = KRFull(), bool flip = false) {
;     ...
;       BAR; WAIT_L(0); MMA(1, 0, At, B0); BAR; SCHED;
;       STAGE_B(SB(1, 1), 1, t + 3);
;       WAIT_V(6); BAR; MMA(1, 1, At, B1); BAR;
;     }
;     { LDB(B0, 0, 0); LDA(At, 0, 0); STAGE_A(SA(1, 1), 1, nt - 1);
;       BAR; WAIT_L(0); MMA(0, 0, At, B0); BAR;
;       LDB(B1, 0, 1); BAR; WAIT_L(0); MMA(0, 1, At, B1); BAR;
	s_waitcnt lgkmcnt(0)
	s_setprio 1
	s_waitcnt lgkmcnt(0)
	v_mfma_f32_16x16x32_bf16 v[60:63], v[160:163], v[180:183], v[60:63]
	v_mfma_f32_16x16x32_bf16 v[56:59], v[168:171], v[180:183], v[56:59]
	v_mfma_f32_16x16x32_bf16 v[52:55], v[160:163], v[188:191], v[52:55]
	v_mfma_f32_16x16x32_bf16 v[48:51], v[168:171], v[188:191], v[48:51]
	v_mfma_f32_16x16x32_bf16 v[44:47], v[160:163], v[196:199], v[44:47]
	v_mfma_f32_16x16x32_bf16 v[40:43], v[168:171], v[196:199], v[40:43]
	v_mfma_f32_16x16x32_bf16 v[36:39], v[160:163], v[204:207], v[36:39]
	v_mfma_f32_16x16x32_bf16 v[32:35], v[168:171], v[204:207], v[32:35]
	v_mfma_f32_16x16x32_bf16 v[60:63], v[164:167], v[184:187], v[60:63]
	v_mfma_f32_16x16x32_bf16 v[56:59], v[172:175], v[184:187], v[56:59]
	v_mfma_f32_16x16x32_bf16 v[52:55], v[164:167], v[192:195], v[52:55]
	v_mfma_f32_16x16x32_bf16 v[48:51], v[172:175], v[192:195], v[48:51]
	v_mfma_f32_16x16x32_bf16 v[44:47], v[164:167], v[200:203], v[44:47]
	v_mfma_f32_16x16x32_bf16 v[40:43], v[172:175], v[200:203], v[40:43]
	v_mfma_f32_16x16x32_bf16 v[36:39], v[164:167], v[208:211], v[36:39]
	v_mfma_f32_16x16x32_bf16 v[32:35], v[172:175], v[208:211], v[32:35]
	s_setprio 0
	s_barrier
	v_lshl_add_u64 v[160:161], v[226:227], 0, s[70:71]
	s_add_u32 m0, s3, 0x1c000
	s_nop 0
	global_load_lds_dwordx4 v[160:161], off
	v_lshl_add_u64 v[160:161], v[228:229], 0, s[70:71]
	s_add_u32 m0, s3, 0x1e000
	s_nop 0
	global_load_lds_dwordx4 v[160:161], off
	s_waitcnt vmcnt(6)
	s_barrier
	s_setprio 1
	v_mfma_f32_16x16x32_bf16 v[28:31], v[212:215], v[180:183], v[28:31]
	v_mfma_f32_16x16x32_bf16 v[24:27], v[234:237], v[180:183], v[24:27]
	v_mfma_f32_16x16x32_bf16 v[20:23], v[212:215], v[188:191], v[20:23]
	v_mfma_f32_16x16x32_bf16 v[16:19], v[234:237], v[188:191], v[16:19]
	v_mfma_f32_16x16x32_bf16 v[12:15], v[212:215], v[196:199], v[12:15]
	v_mfma_f32_16x16x32_bf16 v[8:11], v[234:237], v[196:199], v[8:11]
	v_mfma_f32_16x16x32_bf16 v[4:7], v[212:215], v[204:207], v[4:7]
	v_mfma_f32_16x16x32_bf16 v[0:3], v[234:237], v[204:207], v[0:3]
	v_mfma_f32_16x16x32_bf16 v[28:31], v[216:219], v[184:187], v[28:31]
	v_mfma_f32_16x16x32_bf16 v[24:27], v[238:241], v[184:187], v[24:27]
	v_mfma_f32_16x16x32_bf16 v[20:23], v[216:219], v[192:195], v[20:23]
	v_mfma_f32_16x16x32_bf16 v[16:19], v[238:241], v[192:195], v[16:19]
	v_mfma_f32_16x16x32_bf16 v[12:15], v[216:219], v[200:203], v[12:15]
	v_mfma_f32_16x16x32_bf16 v[8:11], v[238:241], v[200:203], v[8:11]
	v_mfma_f32_16x16x32_bf16 v[4:7], v[216:219], v[208:211], v[4:7]
	v_mfma_f32_16x16x32_bf16 v[0:3], v[238:241], v[208:211], v[0:3]
	s_setprio 0
	s_add_i32 s2, s2, 2
	s_add_u32 s8, s8, 0x100
	s_addc_u32 s9, s9, 0
	s_cmp_gt_u32 s2, 27
	s_barrier
	s_cbranch_scc0 .LBB0_1636
	s_add_u32 s2, s6, 0x80f80
	s_addc_u32 s3, s7, 0
	v_readfirstlane_b32 s6, v157
	v_lshl_add_u64 v[152:153], s[2:3], 0, v[178:179]
	s_mov_b32 m0, s6
	v_lshl_add_u64 v[128:129], s[2:3], 0, v[128:129]
	v_readfirstlane_b32 s2, v158
	ds_read_b128 v[130:133], v156
	ds_read_b128 v[134:137], v156 offset:1024
	ds_read_b128 v[148:151], v156 offset:2048
	ds_read_b128 v[160:163], v156 offset:3072
	ds_read_b128 v[164:167], v144
	ds_read_b128 v[168:171], v144 offset:1024
	ds_read_b128 v[172:175], v143
	ds_read_b128 v[180:183], v143 offset:1024
	ds_read_b128 v[184:187], v141
	ds_read_b128 v[188:191], v141 offset:1024
	ds_read_b128 v[192:195], v140
	ds_read_b128 v[196:199], v140 offset:1024
	global_load_lds_dwordx4 v[152:153], off
	s_mov_b32 m0, s2
	s_nop 0
	global_load_lds_dwordx4 v[128:129], off
	s_barrier
	s_waitcnt lgkmcnt(0)
	s_setprio 1
	s_waitcnt lgkmcnt(0)
	v_mfma_f32_16x16x32_bf16 v[124:127], v[130:133], v[164:167], v[124:127]
	v_mfma_f32_16x16x32_bf16 v[120:123], v[148:151], v[164:167], v[120:123]
	v_mfma_f32_16x16x32_bf16 v[116:119], v[130:133], v[172:175], v[116:119]
	v_mfma_f32_16x16x32_bf16 v[112:115], v[148:151], v[172:175], v[112:115]
	v_mfma_f32_16x16x32_bf16 v[108:111], v[130:133], v[184:187], v[108:111]
	v_mfma_f32_16x16x32_bf16 v[104:107], v[148:151], v[184:187], v[104:107]
	v_mfma_f32_16x16x32_bf16 v[100:103], v[130:133], v[192:195], v[100:103]
	v_mfma_f32_16x16x32_bf16 v[96:99], v[148:151], v[192:195], v[96:99]
	v_mfma_f32_16x16x32_bf16 v[124:127], v[134:137], v[168:171], v[124:127]
	v_mfma_f32_16x16x32_bf16 v[120:123], v[160:163], v[168:171], v[120:123]
	v_mfma_f32_16x16x32_bf16 v[116:119], v[134:137], v[180:183], v[116:119]
	v_mfma_f32_16x16x32_bf16 v[112:115], v[160:163], v[180:183], v[112:115]
	v_mfma_f32_16x16x32_bf16 v[108:111], v[134:137], v[188:191], v[108:111]
	v_mfma_f32_16x16x32_bf16 v[104:107], v[160:163], v[188:191], v[104:107]
	v_mfma_f32_16x16x32_bf16 v[100:103], v[134:137], v[196:199], v[100:103]
	v_mfma_f32_16x16x32_bf16 v[96:99], v[160:163], v[196:199], v[96:99]
	s_setprio 0
	s_barrier
	ds_read_b128 v[156:159], v155
	ds_read_b128 v[200:203], v155 offset:1024
	ds_read_b128 v[204:207], v155 offset:2048
	ds_read_b128 v[152:155], v155 offset:3072
	s_barrier
	s_waitcnt lgkmcnt(0)
	s_setprio 1
	s_waitcnt lgkmcnt(0)
	v_mfma_f32_16x16x32_bf16 v[76:79], v[156:159], v[184:187], v[76:79]
	v_mfma_f32_16x16x32_bf16 v[72:75], v[204:207], v[184:187], v[72:75]
	v_mfma_f32_16x16x32_bf16 v[68:71], v[156:159], v[192:195], v[68:71]
	v_mfma_f32_16x16x32_bf16 v[64:67], v[204:207], v[192:195], v[64:67]
	v_mfma_f32_16x16x32_bf16 v[92:95], v[156:159], v[164:167], v[92:95]
	v_mfma_f32_16x16x32_bf16 v[88:91], v[204:207], v[164:167], v[88:91]
	v_mfma_f32_16x16x32_bf16 v[84:87], v[156:159], v[172:175], v[84:87]
	v_mfma_f32_16x16x32_bf16 v[80:83], v[204:207], v[172:175], v[80:83]
	v_mfma_f32_16x16x32_bf16 v[76:79], v[200:203], v[188:191], v[76:79]
	v_mfma_f32_16x16x32_bf16 v[72:75], v[152:155], v[188:191], v[72:75]
	v_mfma_f32_16x16x32_bf16 v[68:71], v[200:203], v[196:199], v[68:71]
	v_mfma_f32_16x16x32_bf16 v[64:67], v[152:155], v[196:199], v[64:67]
	v_mfma_f32_16x16x32_bf16 v[208:211], v[200:203], v[168:171], v[92:95]
	v_mfma_f32_16x16x32_bf16 v[164:167], v[152:155], v[168:171], v[88:91]
	v_mfma_f32_16x16x32_bf16 v[168:171], v[200:203], v[180:183], v[84:87]
	v_mfma_f32_16x16x32_bf16 v[172:175], v[152:155], v[180:183], v[80:83]
	s_setprio 0
	s_barrier
; #define LDA(dst, b, h) _Pragma("unroll") for (int m = 0; m < 4; ++m) _Pragma("unroll") for (int k = 0; k < 2; ++k) \
;     dst[m][k] = *reinterpret_cast<const bf16x8*>((const char*)SA(b, h) + lds_byte(wr * 64 + m * 16 + fr, k * 32 + fq * 8))
; #define LDB(dst, b, h) _Pragma("unroll") for (int n = 0; n < 2; ++n) _Pragma("unroll") for (int k = 0; k < 2; ++k) \
;     dst[n][k] = *reinterpret_cast<const bf16x8*>((const char*)SB(b, h) + lds_byte(wc * 32 + n * 16 + fr, k * 32 + fq * 8))
; #define MMA(ai, bj, At_, Bt_) do { __builtin_amdgcn_s_setprio(1); \
;     _Pragma("unroll") for (int m = 0; m < 4; ++m) _Pragma("unroll") for (int n = 0; n < 2; ++n) _Pragma("unroll") for (int k = 0; k < 2; ++k) \
;       acc[ai][bj][m][n] = __builtin_amdgcn_mfma_f32_16x16x32_bf16(Bt_[n][k], At_[m][k], acc[ai][bj][m][n], 0, 0, 0); \
;     __builtin_amdgcn_s_setprio(0); } while (0)
; #define WAIT_V(n) asm volatile("s_waitcnt vmcnt(" #n ")" ::: "memory")
; #define WAIT_L(n) asm volatile("s_waitcnt lgkmcnt(" #n ")" ::: "memory")
; #define BAR __builtin_amdgcn_s_barrier()
; template <bool PF = true, class Epi, class KRF = KRFull>
; __device__ __forceinline__ void gemm_phase(const u16* __restrict__ A, int lda, const u16* __restrict__ Bt, int ldb, int K, int nM, int nN,
;                                            lds_u16* shm, Epi epi, KRF krf = KRFull(), bool flip = false) {
;     ...
;       LDA(At, 0, 1); WAIT_V(4); BAR; WAIT_L(0); MMA(1, 0, At, B0); MMA(1, 1, At, B1); BAR; }
;     { LDB(B0, 1, 0); LDA(At, 1, 0); WAIT_V(2); BAR; WAIT_L(0); MMA(0, 0, At, B0); BAR;
	s_nop 0
	ds_read_b128 v[80:83], v144 offset:16384
	ds_read_b128 v[84:87], v144 offset:17408
	ds_read_b128 v[88:91], v143 offset:16384
	ds_read_b128 v[92:95], v143 offset:17408
	ds_read_b128 v[180:183], v141 offset:16384
	ds_read_b128 v[184:187], v141 offset:17408
	ds_read_b128 v[188:191], v140 offset:16384
	ds_read_b128 v[192:195], v140 offset:17408
	s_waitcnt vmcnt(4)
	s_barrier
	s_waitcnt lgkmcnt(0)
	s_setprio 1
	s_waitcnt lgkmcnt(0)
	v_mfma_f32_16x16x32_bf16 v[44:47], v[130:133], v[180:183], v[44:47]
	v_mfma_f32_16x16x32_bf16 v[40:43], v[148:151], v[180:183], v[40:43]
	v_mfma_f32_16x16x32_bf16 v[36:39], v[130:133], v[188:191], v[36:39]
	v_mfma_f32_16x16x32_bf16 v[32:35], v[148:151], v[188:191], v[32:35]
	v_mfma_f32_16x16x32_bf16 v[60:63], v[130:133], v[80:83], v[60:63]
	v_mfma_f32_16x16x32_bf16 v[56:59], v[148:151], v[80:83], v[56:59]
	v_mfma_f32_16x16x32_bf16 v[52:55], v[130:133], v[88:91], v[52:55]
	v_mfma_f32_16x16x32_bf16 v[48:51], v[148:151], v[88:91], v[48:51]
	v_mfma_f32_16x16x32_bf16 v[44:47], v[134:137], v[184:187], v[44:47]
	v_mfma_f32_16x16x32_bf16 v[40:43], v[160:163], v[184:187], v[40:43]
	v_mfma_f32_16x16x32_bf16 v[36:39], v[134:137], v[192:195], v[36:39]
	v_mfma_f32_16x16x32_bf16 v[32:35], v[160:163], v[192:195], v[32:35]
	v_mfma_f32_16x16x32_bf16 v[196:199], v[134:137], v[84:87], v[60:63]
	v_mfma_f32_16x16x32_bf16 v[212:215], v[160:163], v[84:87], v[56:59]
	v_mfma_f32_16x16x32_bf16 v[216:219], v[134:137], v[92:95], v[52:55]
	v_mfma_f32_16x16x32_bf16 v[234:237], v[160:163], v[92:95], v[48:51]
	s_setprio 0
	s_setprio 1
	v_mfma_f32_16x16x32_bf16 v[0:3], v[204:207], v[188:191], v[0:3]
	v_mfma_f32_16x16x32_bf16 v[28:31], v[156:159], v[80:83], v[28:31]
	v_mfma_f32_16x16x32_bf16 v[24:27], v[204:207], v[80:83], v[24:27]
	v_mfma_f32_16x16x32_bf16 v[20:23], v[156:159], v[88:91], v[20:23]
	v_mfma_f32_16x16x32_bf16 v[16:19], v[204:207], v[88:91], v[16:19]
	v_mfma_f32_16x16x32_bf16 v[12:15], v[156:159], v[180:183], v[12:15]
	v_mfma_f32_16x16x32_bf16 v[8:11], v[204:207], v[180:183], v[8:11]
	v_mfma_f32_16x16x32_bf16 v[4:7], v[156:159], v[188:191], v[4:7]
	v_mfma_f32_16x16x32_bf16 v[0:3], v[152:155], v[192:195], v[0:3]
	v_mfma_f32_16x16x32_bf16 v[128:131], v[200:203], v[84:87], v[28:31]
	v_mfma_f32_16x16x32_bf16 v[132:135], v[152:155], v[84:87], v[24:27]
	v_mfma_f32_16x16x32_bf16 v[148:151], v[200:203], v[92:95], v[20:23]
	v_mfma_f32_16x16x32_bf16 v[160:163], v[152:155], v[92:95], v[16:19]
	v_mfma_f32_16x16x32_bf16 v[238:241], v[200:203], v[184:187], v[12:15]
	v_mfma_f32_16x16x32_bf16 v[180:183], v[152:155], v[184:187], v[8:11]
	v_mfma_f32_16x16x32_bf16 v[156:159], v[200:203], v[192:195], v[4:7]
	s_setprio 0
	s_barrier
	s_nop 0
	ds_read_b128 v[4:7], v147
	ds_read_b128 v[8:11], v147 offset:1024
	ds_read_b128 v[12:15], v147 offset:2048
	ds_read_b128 v[152:155], v147 offset:3072
	ds_read_b128 v[16:19], v144 offset:32768
	ds_read_b128 v[20:23], v144 offset:33792
	ds_read_b128 v[24:27], v143 offset:32768
	ds_read_b128 v[48:51], v143 offset:33792
	ds_read_b128 v[184:187], v141 offset:32768
	ds_read_b128 v[188:191], v141 offset:33792
	ds_read_b128 v[192:195], v140 offset:32768
	ds_read_b128 v[200:203], v140 offset:33792
	s_waitcnt vmcnt(2)
	s_barrier
	s_waitcnt lgkmcnt(0)
	s_setprio 1
	s_waitcnt lgkmcnt(0)
	v_mfma_f32_16x16x32_bf16 v[28:31], v[4:7], v[16:19], v[124:127]
	v_mfma_f32_16x16x32_bf16 v[124:127], v[8:11], v[20:23], v[28:31]
	v_mfma_f32_16x16x32_bf16 v[28:31], v[12:15], v[16:19], v[120:123]
	v_mfma_f32_16x16x32_bf16 v[92:95], v[152:155], v[20:23], v[28:31]
	v_mfma_f32_16x16x32_bf16 v[28:31], v[4:7], v[24:27], v[116:119]
	v_mfma_f32_16x16x32_bf16 v[120:123], v[8:11], v[48:51], v[28:31]
	v_mfma_f32_16x16x32_bf16 v[28:31], v[12:15], v[24:27], v[112:115]
	v_mfma_f32_16x16x32_bf16 v[88:91], v[152:155], v[48:51], v[28:31]
	v_mfma_f32_16x16x32_bf16 v[28:31], v[4:7], v[184:187], v[108:111]
	v_mfma_f32_16x16x32_bf16 v[116:119], v[8:11], v[188:191], v[28:31]
	v_mfma_f32_16x16x32_bf16 v[28:31], v[12:15], v[184:187], v[104:107]
	v_mfma_f32_16x16x32_bf16 v[84:87], v[152:155], v[188:191], v[28:31]
	v_mfma_f32_16x16x32_bf16 v[28:31], v[4:7], v[192:195], v[100:103]
	v_mfma_f32_16x16x32_bf16 v[112:115], v[8:11], v[200:203], v[28:31]
	v_mfma_f32_16x16x32_bf16 v[28:31], v[12:15], v[192:195], v[96:99]
	v_mfma_f32_16x16x32_bf16 v[80:83], v[152:155], v[200:203], v[28:31]
	s_setprio 0
	s_barrier
; #define LDA(dst, b, h) _Pragma("unroll") for (int m = 0; m < 4; ++m) _Pragma("unroll") for (int k = 0; k < 2; ++k) \
;     dst[m][k] = *reinterpret_cast<const bf16x8*>((const char*)SA(b, h) + lds_byte(wr * 64 + m * 16 + fr, k * 32 + fq * 8))
; #define LDB(dst, b, h) _Pragma("unroll") for (int n = 0; n < 2; ++n) _Pragma("unroll") for (int k = 0; k < 2; ++k) \
;     dst[n][k] = *reinterpret_cast<const bf16x8*>((const char*)SB(b, h) + lds_byte(wc * 32 + n * 16 + fr, k * 32 + fq * 8))
; #define MMA(ai, bj, At_, Bt_) do { __builtin_amdgcn_s_setprio(1); \
;     _Pragma("unroll") for (int m = 0; m < 4; ++m) _Pragma("unroll") for (int n = 0; n < 2; ++n) _Pragma("unroll") for (int k = 0; k < 2; ++k) \
;       acc[ai][bj][m][n] = __builtin_amdgcn_mfma_f32_16x16x32_bf16(Bt_[n][k], At_[m][k], acc[ai][bj][m][n], 0, 0, 0); \
;     __builtin_amdgcn_s_setprio(0); } while (0)
; #define WAIT_V(n) asm volatile("s_waitcnt vmcnt(" #n ")" ::: "memory")
; #define WAIT_L(n) asm volatile("s_waitcnt lgkmcnt(" #n ")" ::: "memory")
; #define BAR __builtin_amdgcn_s_barrier()
; template <bool PF = true, class Epi, class KRF = KRFull>
; __device__ __forceinline__ void gemm_phase(const u16* __restrict__ A, int lda, const u16* __restrict__ Bt, int ldb, int K, int nM, int nN,
;                                            lds_u16* shm, Epi epi, KRF krf = KRFull(), bool flip = false) {
;     ...
;       LDA(At, 0, 1); WAIT_V(4); BAR; WAIT_L(0); MMA(1, 0, At, B0); MMA(1, 1, At, B1); BAR; }
;     { LDB(B0, 1, 0); LDA(At, 1, 0); WAIT_V(2); BAR; WAIT_L(0); MMA(0, 0, At, B0); BAR;
;       LDB(B1, 1, 1); WAIT_V(0); BAR; WAIT_L(0); MMA(0, 1, At, B1); BAR;
;       LDA(At, 1, 1); BAR; WAIT_L(0); MMA(1, 0, At, B0); MMA(1, 1, At, B1); BAR; }
;     if (wr == 0) BAR;
	ds_read_b128 v[204:207], v145
	ds_read_b128 v[242:245], v145 offset:1024
	ds_read_b128 v[246:249], v145 offset:2048
	ds_read_b128 v[250:253], v145 offset:3072
	s_waitcnt vmcnt(0)
	s_barrier
	s_waitcnt lgkmcnt(0)
	s_setprio 1
	s_waitcnt lgkmcnt(0)
	v_mfma_f32_16x16x32_bf16 v[28:31], v[204:207], v[16:19], v[208:211]
	v_mfma_f32_16x16x32_bf16 v[16:19], v[246:249], v[16:19], v[164:167]
	v_mfma_f32_16x16x32_bf16 v[60:63], v[242:245], v[20:23], v[28:31]
	v_mfma_f32_16x16x32_bf16 v[28:31], v[250:253], v[20:23], v[16:19]
	v_mfma_f32_16x16x32_bf16 v[16:19], v[204:207], v[24:27], v[168:171]
	v_mfma_f32_16x16x32_bf16 v[56:59], v[242:245], v[48:51], v[16:19]
	v_mfma_f32_16x16x32_bf16 v[16:19], v[246:249], v[24:27], v[172:175]
	v_mfma_f32_16x16x32_bf16 v[24:27], v[250:253], v[48:51], v[16:19]
	v_mfma_f32_16x16x32_bf16 v[16:19], v[204:207], v[184:187], v[76:79]
	v_mfma_f32_16x16x32_bf16 v[52:55], v[242:245], v[188:191], v[16:19]
	v_mfma_f32_16x16x32_bf16 v[16:19], v[246:249], v[184:187], v[72:75]
	v_mfma_f32_16x16x32_bf16 v[20:23], v[250:253], v[188:191], v[16:19]
	v_mfma_f32_16x16x32_bf16 v[16:19], v[204:207], v[192:195], v[68:71]
	v_mfma_f32_16x16x32_bf16 v[48:51], v[242:245], v[200:203], v[16:19]
	v_mfma_f32_16x16x32_bf16 v[16:19], v[246:249], v[192:195], v[64:67]
	v_mfma_f32_16x16x32_bf16 v[16:19], v[250:253], v[200:203], v[16:19]
	s_setprio 0
	s_barrier
	ds_read_b128 v[164:167], v144 offset:49152
	ds_read_b128 v[144:147], v144 offset:50176
	ds_read_b128 v[168:171], v143 offset:49152
	ds_read_b128 v[172:175], v143 offset:50176
	ds_read_b128 v[184:187], v141 offset:49152
	ds_read_b128 v[188:191], v141 offset:50176
	ds_read_b128 v[192:195], v140 offset:49152
	ds_read_b128 v[200:203], v140 offset:50176
	s_barrier
	s_waitcnt lgkmcnt(0)
	s_setprio 1
	s_waitcnt lgkmcnt(0)
	v_mfma_f32_16x16x32_bf16 v[64:67], v[4:7], v[164:167], v[196:199]
	v_mfma_f32_16x16x32_bf16 v[108:111], v[8:11], v[144:147], v[64:67]
	v_mfma_f32_16x16x32_bf16 v[64:67], v[12:15], v[164:167], v[212:215]
	v_mfma_f32_16x16x32_bf16 v[76:79], v[152:155], v[144:147], v[64:67]
	v_mfma_f32_16x16x32_bf16 v[64:67], v[4:7], v[168:171], v[216:219]
	v_mfma_f32_16x16x32_bf16 v[44:47], v[4:7], v[184:187], v[44:47]
	v_mfma_f32_16x16x32_bf16 v[4:7], v[4:7], v[192:195], v[36:39]
	v_mfma_f32_16x16x32_bf16 v[104:107], v[8:11], v[172:175], v[64:67]
	v_mfma_f32_16x16x32_bf16 v[64:67], v[12:15], v[168:171], v[234:237]
	v_mfma_f32_16x16x32_bf16 v[40:43], v[12:15], v[184:187], v[40:43]
	v_mfma_f32_16x16x32_bf16 v[96:99], v[8:11], v[200:203], v[4:7]
	v_mfma_f32_16x16x32_bf16 v[4:7], v[12:15], v[192:195], v[32:35]
	v_mfma_f32_16x16x32_bf16 v[72:75], v[152:155], v[172:175], v[64:67]
	v_mfma_f32_16x16x32_bf16 v[100:103], v[8:11], v[188:191], v[44:47]
	v_mfma_f32_16x16x32_bf16 v[68:71], v[152:155], v[188:191], v[40:43]
	v_mfma_f32_16x16x32_bf16 v[64:67], v[152:155], v[200:203], v[4:7]
	s_setprio 0
	s_setprio 1
	v_mfma_f32_16x16x32_bf16 v[4:7], v[204:207], v[164:167], v[128:131]
	v_mfma_f32_16x16x32_bf16 v[44:47], v[242:245], v[144:147], v[4:7]
	v_mfma_f32_16x16x32_bf16 v[4:7], v[246:249], v[164:167], v[132:135]
	v_mfma_f32_16x16x32_bf16 v[12:15], v[250:253], v[144:147], v[4:7]
	v_mfma_f32_16x16x32_bf16 v[4:7], v[204:207], v[168:171], v[148:151]
	v_mfma_f32_16x16x32_bf16 v[40:43], v[242:245], v[172:175], v[4:7]
	v_mfma_f32_16x16x32_bf16 v[4:7], v[246:249], v[168:171], v[160:163]
	v_mfma_f32_16x16x32_bf16 v[8:11], v[250:253], v[172:175], v[4:7]
	v_mfma_f32_16x16x32_bf16 v[4:7], v[204:207], v[184:187], v[238:241]
	v_mfma_f32_16x16x32_bf16 v[36:39], v[242:245], v[188:191], v[4:7]
	v_mfma_f32_16x16x32_bf16 v[4:7], v[246:249], v[184:187], v[180:183]
	v_mfma_f32_16x16x32_bf16 v[32:35], v[204:207], v[192:195], v[156:159]
	v_mfma_f32_16x16x32_bf16 v[0:3], v[246:249], v[192:195], v[0:3]
	v_mfma_f32_16x16x32_bf16 v[4:7], v[250:253], v[188:191], v[4:7]
	v_mfma_f32_16x16x32_bf16 v[32:35], v[242:245], v[200:203], v[32:35]
	v_mfma_f32_16x16x32_bf16 v[0:3], v[250:253], v[200:203], v[0:3]
	s_setprio 0
	v_cmp_gt_u32_e32 vcc, s95, v142
	s_barrier
	s_and_saveexec_b64 s[6:7], vcc
	s_cbranch_execz .LBB0_1639
	s_barrier

; #define STAGE_A(P, half, kt) do { const char* _u = Ab + ((size_t)(half) * 128 * lda + (size_t)(kt) * BK) * 2; \
;     _Pragma("unroll") for (int _i = 0; _i < 2; ++_i) \
;       __builtin_amdgcn_global_load_lds((const unsigned*)(_u + offA[_i]), \
;         (__attribute__((address_space(3))) unsigned*)((__attribute__((address_space(3))) char*)(P) + tidg * 16 + _i * 8192), 16, 0, 0); } while (0)
; #define STAGE_B(P, half, kt) do { const char* _u = Bb + ((size_t)(half) * 128 * ldb + (size_t)(kt) * BK) * 2; \
;     _Pragma("unroll") for (int _i = 0; _i < 2; ++_i) \
;       __builtin_amdgcn_global_load_lds((const unsigned*)(_u + offB[_i]), \
;         (__attribute__((address_space(3))) unsigned*)((__attribute__((address_space(3))) char*)(P) + tidg * 16 + _i * 8192), 16, 0, 0); } while (0)
; #define LDA(dst, b, h) _Pragma("unroll") for (int m = 0; m < 4; ++m) _Pragma("unroll") for (int k = 0; k < 2; ++k) \
;     dst[m][k] = *reinterpret_cast<const bf16x8*>((const char*)SA(b, h) + lds_byte(wr * 64 + m * 16 + fr, k * 32 + fq * 8))
; #define LDB(dst, b, h) _Pragma("unroll") for (int n = 0; n < 2; ++n) _Pragma("unroll") for (int k = 0; k < 2; ++k) \
;     dst[n][k] = *reinterpret_cast<const bf16x8*>((const char*)SB(b, h) + lds_byte(wc * 32 + n * 16 + fr, k * 32 + fq * 8))
; #define MMA(ai, bj, At_, Bt_) do { __builtin_amdgcn_s_setprio(1); \
;     _Pragma("unroll") for (int m = 0; m < 4; ++m) _Pragma("unroll") for (int n = 0; n < 2; ++n) _Pragma("unroll") for (int k = 0; k < 2; ++k) \
;       acc[ai][bj][m][n] = __builtin_amdgcn_mfma_f32_16x16x32_bf16(Bt_[n][k], At_[m][k], acc[ai][bj][m][n], 0, 0, 0); \
;     __builtin_amdgcn_s_setprio(0); } while (0)
; template <bool PF = true, class Epi, class KRF = KRFull>
; __device__ __forceinline__ void gemm_phase(const u16* __restrict__ A, int lda, const u16* __restrict__ Bt, int ldb, int K, int nM, int nN,
;                                            lds_u16* shm, Epi epi, KRF krf = KRFull(), bool flip = false) {
;     ...
;     for (int t = 0; t < nt - 2; t += 2) {
;       LDB(B0, 0, 0); SCHED; LDA(At, 0, 0); STAGE_A(SA(1, 1), 1, t + 1);
;       WAIT_L(8); BAR; WAIT_L(0); MMA(0, 0, At, B0); BAR; SCHED;
;       LDB(B1, 0, 1); STAGE_B(SB(0, 0), 0, t + 2);
;       BAR; WAIT_L(0); MMA(0, 1, At, B1); BAR;
;       LDA(At, 0, 1); STAGE_A(SA(0, 0), 0, t + 2);
;       BAR; WAIT_L(0); MMA(1, 0, At, B0); BAR; SCHED;
.LBB0_2222:
	v_readfirstlane_b32 s16, v145
	ds_read_b128 v[158:161], v155
	ds_read_b128 v[162:165], v155 offset:1024
	ds_read_b128 v[166:169], v155 offset:2048
	ds_read_b128 v[170:173], v155 offset:3072
	v_add_u32_e32 v156, 0xc000, v145
	v_lshl_add_u64 v[174:175], v[134:135], 0, s[12:13]
	v_add_u32_e32 v157, 0xe000, v145
	v_lshl_add_u64 v[212:213], v[174:175], 0, s[82:83]
	s_add_u32 m0, s16, 0xc000
	v_lshl_add_u64 v[234:235], v[136:137], 0, s[12:13]
	ds_read_b128 v[180:183], v143
	ds_read_b128 v[184:187], v143 offset:1024
	ds_read_b128 v[188:191], v142
	ds_read_b128 v[192:195], v142 offset:1024
	ds_read_b128 v[196:199], v141
	ds_read_b128 v[200:203], v141 offset:1024
	ds_read_b128 v[204:207], v139
	ds_read_b128 v[208:211], v139 offset:1024
	global_load_lds_dwordx4 v[212:213], off
	v_lshl_add_u64 v[212:213], v[234:235], 0, s[82:83]
	s_add_u32 m0, s16, 0xe000
	s_nop 0
	global_load_lds_dwordx4 v[212:213], off
	s_waitcnt lgkmcnt(8)
	s_barrier
	s_waitcnt lgkmcnt(0)
	s_setprio 1
	s_waitcnt lgkmcnt(0)
	v_mfma_f32_16x16x32_bf16 v[124:127], v[158:161], v[180:183], v[124:127]
	v_mfma_f32_16x16x32_bf16 v[120:123], v[166:169], v[180:183], v[120:123]
	v_mfma_f32_16x16x32_bf16 v[116:119], v[158:161], v[188:191], v[116:119]
	v_mfma_f32_16x16x32_bf16 v[112:115], v[166:169], v[188:191], v[112:115]
	v_mfma_f32_16x16x32_bf16 v[108:111], v[158:161], v[196:199], v[108:111]
	v_mfma_f32_16x16x32_bf16 v[104:107], v[166:169], v[196:199], v[104:107]
	v_mfma_f32_16x16x32_bf16 v[100:103], v[158:161], v[204:207], v[100:103]
	v_mfma_f32_16x16x32_bf16 v[96:99], v[166:169], v[204:207], v[96:99]
	v_mfma_f32_16x16x32_bf16 v[124:127], v[162:165], v[184:187], v[124:127]
	v_mfma_f32_16x16x32_bf16 v[120:123], v[170:173], v[184:187], v[120:123]
	v_mfma_f32_16x16x32_bf16 v[116:119], v[162:165], v[192:195], v[116:119]
	v_mfma_f32_16x16x32_bf16 v[112:115], v[170:173], v[192:195], v[112:115]
	v_mfma_f32_16x16x32_bf16 v[108:111], v[162:165], v[200:203], v[108:111]
	v_mfma_f32_16x16x32_bf16 v[104:107], v[170:173], v[200:203], v[104:107]
	v_mfma_f32_16x16x32_bf16 v[100:103], v[162:165], v[208:211], v[100:103]
	v_mfma_f32_16x16x32_bf16 v[96:99], v[170:173], v[208:211], v[96:99]
	s_setprio 0
	s_barrier
	v_add_u32_e32 v240, 0x10000, v145
	v_lshl_add_u64 v[236:237], v[130:131], 0, s[12:13]
	v_lshl_add_u64 v[238:239], v[236:237], 0, s[64:65]
	s_add_u32 m0, s16, 0x10000
	v_add_u32_e32 v242, 0x12000, v145
	ds_read_b128 v[212:215], v154
	ds_read_b128 v[216:219], v154 offset:1024
	ds_read_b128 v[222:225], v154 offset:2048
	ds_read_b128 v[226:229], v154 offset:3072
	global_load_lds_dwordx4 v[238:239], off
	v_lshl_add_u64 v[238:239], v[132:133], 0, s[12:13]
	v_lshl_add_u64 v[240:241], v[238:239], 0, s[64:65]
	s_add_u32 m0, s16, 0x12000
	s_add_i32 s7, s7, 2
	global_load_lds_dwordx4 v[240:241], off
	s_barrier
	s_waitcnt lgkmcnt(0)
	s_setprio 1
	s_waitcnt lgkmcnt(0)
	v_mfma_f32_16x16x32_bf16 v[92:95], v[212:215], v[180:183], v[92:95]
	v_mfma_f32_16x16x32_bf16 v[88:91], v[222:225], v[180:183], v[88:91]
	v_mfma_f32_16x16x32_bf16 v[84:87], v[212:215], v[188:191], v[84:87]
	v_mfma_f32_16x16x32_bf16 v[80:83], v[222:225], v[188:191], v[80:83]
	v_mfma_f32_16x16x32_bf16 v[76:79], v[212:215], v[196:199], v[76:79]
	v_mfma_f32_16x16x32_bf16 v[72:75], v[222:225], v[196:199], v[72:75]
	v_mfma_f32_16x16x32_bf16 v[68:71], v[212:215], v[204:207], v[68:71]
	v_mfma_f32_16x16x32_bf16 v[64:67], v[222:225], v[204:207], v[64:67]
	v_mfma_f32_16x16x32_bf16 v[92:95], v[216:219], v[184:187], v[92:95]
	v_mfma_f32_16x16x32_bf16 v[88:91], v[226:229], v[184:187], v[88:91]
	v_mfma_f32_16x16x32_bf16 v[84:87], v[216:219], v[192:195], v[84:87]
	v_mfma_f32_16x16x32_bf16 v[80:83], v[226:229], v[192:195], v[80:83]
	v_mfma_f32_16x16x32_bf16 v[76:79], v[216:219], v[200:203], v[76:79]
	v_mfma_f32_16x16x32_bf16 v[72:75], v[226:229], v[200:203], v[72:75]
	v_mfma_f32_16x16x32_bf16 v[68:71], v[216:219], v[208:211], v[68:71]
	v_mfma_f32_16x16x32_bf16 v[64:67], v[226:229], v[208:211], v[64:67]
	s_setprio 0
	v_lshl_add_u64 v[240:241], v[174:175], 0, s[84:85]
	s_mov_b32 m0, s16
	s_barrier
	ds_read_b128 v[180:183], v143 offset:16384
	ds_read_b128 v[184:187], v143 offset:17408
	ds_read_b128 v[188:191], v142 offset:16384
	ds_read_b128 v[192:195], v142 offset:17408
	ds_read_b128 v[196:199], v141 offset:16384
	ds_read_b128 v[200:203], v141 offset:17408
	ds_read_b128 v[204:207], v139 offset:16384
	ds_read_b128 v[208:211], v139 offset:17408
	global_load_lds_dwordx4 v[240:241], off
	v_lshl_add_u64 v[240:241], v[234:235], 0, s[84:85]
	s_add_u32 m0, s16, 0x2000
	s_nop 0
	global_load_lds_dwordx4 v[240:241], off
	s_barrier
	s_waitcnt lgkmcnt(0)
	s_setprio 1
	s_waitcnt lgkmcnt(0)
	v_mfma_f32_16x16x32_bf16 v[60:63], v[158:161], v[180:183], v[60:63]
	v_mfma_f32_16x16x32_bf16 v[56:59], v[166:169], v[180:183], v[56:59]
	v_mfma_f32_16x16x32_bf16 v[52:55], v[158:161], v[188:191], v[52:55]
	v_mfma_f32_16x16x32_bf16 v[48:51], v[166:169], v[188:191], v[48:51]
	v_mfma_f32_16x16x32_bf16 v[44:47], v[158:161], v[196:199], v[44:47]
	v_mfma_f32_16x16x32_bf16 v[40:43], v[166:169], v[196:199], v[40:43]
	v_mfma_f32_16x16x32_bf16 v[36:39], v[158:161], v[204:207], v[36:39]
	v_mfma_f32_16x16x32_bf16 v[32:35], v[166:169], v[204:207], v[32:35]
	v_mfma_f32_16x16x32_bf16 v[60:63], v[162:165], v[184:187], v[60:63]
	v_mfma_f32_16x16x32_bf16 v[56:59], v[170:173], v[184:187], v[56:59]
	v_mfma_f32_16x16x32_bf16 v[52:55], v[162:165], v[192:195], v[52:55]
	v_mfma_f32_16x16x32_bf16 v[48:51], v[170:173], v[192:195], v[48:51]
	v_mfma_f32_16x16x32_bf16 v[44:47], v[162:165], v[200:203], v[44:47]
	v_mfma_f32_16x16x32_bf16 v[40:43], v[170:173], v[200:203], v[40:43]
	v_mfma_f32_16x16x32_bf16 v[36:39], v[162:165], v[208:211], v[36:39]
	v_mfma_f32_16x16x32_bf16 v[32:35], v[170:173], v[208:211], v[32:35]
	s_setprio 0
	s_barrier
; #define STAGE_A(P, half, kt) do { const char* _u = Ab + ((size_t)(half) * 128 * lda + (size_t)(kt) * BK) * 2; \
;     _Pragma("unroll") for (int _i = 0; _i < 2; ++_i) \
;       __builtin_amdgcn_global_load_lds((const unsigned*)(_u + offA[_i]), \
;         (__attribute__((address_space(3))) unsigned*)((__attribute__((address_space(3))) char*)(P) + tidg * 16 + _i * 8192), 16, 0, 0); } while (0)
; #define STAGE_B(P, half, kt) do { const char* _u = Bb + ((size_t)(half) * 128 * ldb + (size_t)(kt) * BK) * 2; \
;     _Pragma("unroll") for (int _i = 0; _i < 2; ++_i) \
;       __builtin_amdgcn_global_load_lds((const unsigned*)(_u + offB[_i]), \
;         (__attribute__((address_space(3))) unsigned*)((__attribute__((address_space(3))) char*)(P) + tidg * 16 + _i * 8192), 16, 0, 0); } while (0)
; #define LDA(dst, b, h) _Pragma("unroll") for (int m = 0; m < 4; ++m) _Pragma("unroll") for (int k = 0; k < 2; ++k) \
;     dst[m][k] = *reinterpret_cast<const bf16x8*>((const char*)SA(b, h) + lds_byte(wr * 64 + m * 16 + fr, k * 32 + fq * 8))
; #define LDB(dst, b, h) _Pragma("unroll") for (int n = 0; n < 2; ++n) _Pragma("unroll") for (int k = 0; k < 2; ++k) \
;     dst[n][k] = *reinterpret_cast<const bf16x8*>((const char*)SB(b, h) + lds_byte(wc * 32 + n * 16 + fr, k * 32 + fq * 8))
; #define WAIT_V(n) asm volatile("s_waitcnt vmcnt(" #n ")" ::: "memory")
; #define WAIT_L(n) asm volatile("s_waitcnt lgkmcnt(" #n ")" ::: "memory")
; #define BAR __builtin_amdgcn_s_barrier()
; #define SCHED __builtin_amdgcn_sched_barrier(0)
; template <bool PF = true, class Epi, class KRF = KRFull>
; __device__ __forceinline__ void gemm_phase(const u16* __restrict__ A, int lda, const u16* __restrict__ Bt, int ldb, int K, int nM, int nN,
;                                            lds_u16* shm, Epi epi, KRF krf = KRFull(), bool flip = false) {
;     ...
;       STAGE_B(SB(0, 1), 1, t + 2);
;       WAIT_V(6); BAR; MMA(1, 1, At, B1); BAR;
;       LDB(B0, 1, 0); SCHED; LDA(At, 1, 0); STAGE_A(SA(0, 1), 1, t + 2);
;       WAIT_L(8); BAR; WAIT_L(0); MMA(0, 0, At, B0); BAR; SCHED;
;       LDB(B1, 1, 1); STAGE_B(SB(1, 0), 0, t + 3);
;       BAR; WAIT_L(0); MMA(0, 1, At, B1); BAR;
;       LDA(At, 1, 1); STAGE_A(SA(1, 0), 0, t + 3);
;       BAR; WAIT_L(0); MMA(1, 0, At, B0); BAR; SCHED;
	v_add_u32_e32 v160, 0x14000, v145
	v_lshl_add_u64 v[158:159], v[236:237], 0, s[86:87]
	v_add_u32_e32 v160, 0x16000, v145
	s_add_u32 m0, s16, 0x14000
	s_nop 0
	global_load_lds_dwordx4 v[158:159], off
	v_lshl_add_u64 v[158:159], v[238:239], 0, s[86:87]
	s_add_u32 m0, s16, 0x16000
	s_nop 0
	global_load_lds_dwordx4 v[158:159], off
	s_waitcnt vmcnt(6)
	s_barrier
	s_setprio 1
	v_mfma_f32_16x16x32_bf16 v[28:31], v[212:215], v[180:183], v[28:31]
	v_mfma_f32_16x16x32_bf16 v[24:27], v[222:225], v[180:183], v[24:27]
	v_mfma_f32_16x16x32_bf16 v[20:23], v[212:215], v[188:191], v[20:23]
	v_mfma_f32_16x16x32_bf16 v[16:19], v[222:225], v[188:191], v[16:19]
	v_mfma_f32_16x16x32_bf16 v[12:15], v[212:215], v[196:199], v[12:15]
	v_mfma_f32_16x16x32_bf16 v[8:11], v[222:225], v[196:199], v[8:11]
	v_mfma_f32_16x16x32_bf16 v[4:7], v[212:215], v[204:207], v[4:7]
	v_mfma_f32_16x16x32_bf16 v[0:3], v[222:225], v[204:207], v[0:3]
	v_mfma_f32_16x16x32_bf16 v[28:31], v[216:219], v[184:187], v[28:31]
	v_mfma_f32_16x16x32_bf16 v[24:27], v[226:229], v[184:187], v[24:27]
	v_mfma_f32_16x16x32_bf16 v[20:23], v[216:219], v[192:195], v[20:23]
	v_mfma_f32_16x16x32_bf16 v[16:19], v[226:229], v[192:195], v[16:19]
	v_mfma_f32_16x16x32_bf16 v[12:15], v[216:219], v[200:203], v[12:15]
	v_mfma_f32_16x16x32_bf16 v[8:11], v[226:229], v[200:203], v[8:11]
	v_mfma_f32_16x16x32_bf16 v[4:7], v[216:219], v[208:211], v[4:7]
	v_mfma_f32_16x16x32_bf16 v[0:3], v[226:229], v[208:211], v[0:3]
	s_setprio 0
	s_barrier
	ds_read_b128 v[158:161], v146
	ds_read_b128 v[162:165], v146 offset:1024
	ds_read_b128 v[166:169], v146 offset:2048
	ds_read_b128 v[170:173], v146 offset:3072
	v_add_u32_e32 v214, 0x4000, v145
	v_lshl_add_u64 v[212:213], v[174:175], 0, s[88:89]
	v_add_u32_e32 v214, 0x6000, v145
	s_add_u32 m0, s16, 0x4000
	ds_read_b128 v[180:183], v143 offset:32768
	ds_read_b128 v[184:187], v143 offset:33792
	ds_read_b128 v[188:191], v142 offset:32768
	ds_read_b128 v[192:195], v142 offset:33792
	ds_read_b128 v[196:199], v141 offset:32768
	ds_read_b128 v[200:203], v141 offset:33792
	ds_read_b128 v[204:207], v139 offset:32768
	ds_read_b128 v[208:211], v139 offset:33792
	global_load_lds_dwordx4 v[212:213], off
	v_lshl_add_u64 v[212:213], v[234:235], 0, s[88:89]
	s_add_u32 m0, s16, 0x6000
	s_nop 0
	global_load_lds_dwordx4 v[212:213], off
	s_waitcnt lgkmcnt(8)
	s_barrier
	s_waitcnt lgkmcnt(0)
	s_setprio 1
	s_waitcnt lgkmcnt(0)
	v_mfma_f32_16x16x32_bf16 v[124:127], v[158:161], v[180:183], v[124:127]
	v_mfma_f32_16x16x32_bf16 v[120:123], v[166:169], v[180:183], v[120:123]
	v_mfma_f32_16x16x32_bf16 v[116:119], v[158:161], v[188:191], v[116:119]
	v_mfma_f32_16x16x32_bf16 v[112:115], v[166:169], v[188:191], v[112:115]
	v_mfma_f32_16x16x32_bf16 v[108:111], v[158:161], v[196:199], v[108:111]
	v_mfma_f32_16x16x32_bf16 v[104:107], v[166:169], v[196:199], v[104:107]
	v_mfma_f32_16x16x32_bf16 v[100:103], v[158:161], v[204:207], v[100:103]
	v_mfma_f32_16x16x32_bf16 v[96:99], v[166:169], v[204:207], v[96:99]
	v_mfma_f32_16x16x32_bf16 v[124:127], v[162:165], v[184:187], v[124:127]
	v_mfma_f32_16x16x32_bf16 v[120:123], v[170:173], v[184:187], v[120:123]
	v_mfma_f32_16x16x32_bf16 v[116:119], v[162:165], v[192:195], v[116:119]
	v_mfma_f32_16x16x32_bf16 v[112:115], v[170:173], v[192:195], v[112:115]
	v_mfma_f32_16x16x32_bf16 v[108:111], v[162:165], v[200:203], v[108:111]
	v_mfma_f32_16x16x32_bf16 v[104:107], v[170:173], v[200:203], v[104:107]
	v_mfma_f32_16x16x32_bf16 v[100:103], v[162:165], v[208:211], v[100:103]
	v_mfma_f32_16x16x32_bf16 v[96:99], v[170:173], v[208:211], v[96:99]
	s_setprio 0
	s_barrier
	v_lshl_add_u64 v[240:241], v[236:237], 0, s[68:69]
	s_add_u32 m0, s16, 0x18000
	ds_read_b128 v[212:215], v144
	ds_read_b128 v[216:219], v144 offset:1024
	ds_read_b128 v[222:225], v144 offset:2048
	ds_read_b128 v[226:229], v144 offset:3072
	global_load_lds_dwordx4 v[240:241], off
	v_lshl_add_u64 v[240:241], v[238:239], 0, s[68:69]
	s_add_u32 m0, s16, 0x1a000
	s_nop 0
	global_load_lds_dwordx4 v[240:241], off
	s_barrier
	s_waitcnt lgkmcnt(0)
	s_setprio 1
	s_waitcnt lgkmcnt(0)
	v_mfma_f32_16x16x32_bf16 v[92:95], v[212:215], v[180:183], v[92:95]
	v_mfma_f32_16x16x32_bf16 v[88:91], v[222:225], v[180:183], v[88:91]
	v_mfma_f32_16x16x32_bf16 v[84:87], v[212:215], v[188:191], v[84:87]
	v_mfma_f32_16x16x32_bf16 v[80:83], v[222:225], v[188:191], v[80:83]
	v_mfma_f32_16x16x32_bf16 v[76:79], v[212:215], v[196:199], v[76:79]
	v_mfma_f32_16x16x32_bf16 v[72:75], v[222:225], v[196:199], v[72:75]
	v_mfma_f32_16x16x32_bf16 v[68:71], v[212:215], v[204:207], v[68:71]
	v_mfma_f32_16x16x32_bf16 v[64:67], v[222:225], v[204:207], v[64:67]
	v_mfma_f32_16x16x32_bf16 v[92:95], v[216:219], v[184:187], v[92:95]
	v_mfma_f32_16x16x32_bf16 v[88:91], v[226:229], v[184:187], v[88:91]
	v_mfma_f32_16x16x32_bf16 v[84:87], v[216:219], v[192:195], v[84:87]
	v_mfma_f32_16x16x32_bf16 v[80:83], v[226:229], v[192:195], v[80:83]
	v_mfma_f32_16x16x32_bf16 v[76:79], v[216:219], v[200:203], v[76:79]
	v_mfma_f32_16x16x32_bf16 v[72:75], v[226:229], v[200:203], v[72:75]
	v_mfma_f32_16x16x32_bf16 v[68:71], v[216:219], v[208:211], v[68:71]
	v_mfma_f32_16x16x32_bf16 v[64:67], v[226:229], v[208:211], v[64:67]
	s_setprio 0
	v_lshl_add_u64 v[174:175], v[174:175], 0, s[90:91]
	s_add_u32 m0, s16, 0x8000
	s_barrier
	ds_read_b128 v[180:183], v143 offset:49152
	ds_read_b128 v[184:187], v143 offset:50176
	ds_read_b128 v[188:191], v142 offset:49152
	ds_read_b128 v[192:195], v142 offset:50176
	ds_read_b128 v[196:199], v141 offset:49152
	ds_read_b128 v[200:203], v141 offset:50176
	ds_read_b128 v[204:207], v139 offset:49152
	ds_read_b128 v[208:211], v139 offset:50176
	global_load_lds_dwordx4 v[174:175], off
	v_lshl_add_u64 v[174:175], v[234:235], 0, s[90:91]
	s_add_u32 m0, s16, 0xa000
	s_nop 0
	global_load_lds_dwordx4 v[174:175], off
	s_barrier
; #define STAGE_A(P, half, kt) do { const char* _u = Ab + ((size_t)(half) * 128 * lda + (size_t)(kt) * BK) * 2; \
;     _Pragma("unroll") for (int _i = 0; _i < 2; ++_i) \
;       __builtin_amdgcn_global_load_lds((const unsigned*)(_u + offA[_i]), \
;         (__attribute__((address_space(3))) unsigned*)((__attribute__((address_space(3))) char*)(P) + tidg * 16 + _i * 8192), 16, 0, 0); } while (0)
; #define STAGE_B(P, half, kt) do { const char* _u = Bb + ((size_t)(half) * 128 * ldb + (size_t)(kt) * BK) * 2; \
;     _Pragma("unroll") for (int _i = 0; _i < 2; ++_i) \
;       __builtin_amdgcn_global_load_lds((const unsigned*)(_u + offB[_i]), \
;         (__attribute__((address_space(3))) unsigned*)((__attribute__((address_space(3))) char*)(P) + tidg * 16 + _i * 8192), 16, 0, 0); } while (0)
; #define LDA(dst, b, h) _Pragma("unroll") for (int m = 0; m < 4; ++m) _Pragma("unroll") for (int k = 0; k < 2; ++k) \
;     dst[m][k] = *reinterpret_cast<const bf16x8*>((const char*)SA(b, h) + lds_byte(wr * 64 + m * 16 + fr, k * 32 + fq * 8))
; #define LDB(dst, b, h) _Pragma("unroll") for (int n = 0; n < 2; ++n) _Pragma("unroll") for (int k = 0; k < 2; ++k) \
;     dst[n][k] = *reinterpret_cast<const bf16x8*>((const char*)SB(b, h) + lds_byte(wc * 32 + n * 16 + fr, k * 32 + fq * 8))
; #define MMA(ai, bj, At_, Bt_) do { __builtin_amdgcn_s_setprio(1); \
;     _Pragma("unroll") for (int m = 0; m < 4; ++m) _Pragma("unroll") for (int n = 0; n < 2; ++n) _Pragma("unroll") for (int k = 0; k < 2; ++k) \
;       acc[ai][bj][m][n] = __builtin_amdgcn_mfma_f32_16x16x32_bf16(Bt_[n][k], At_[m][k], acc[ai][bj][m][n], 0, 0, 0); \
;     __builtin_amdgcn_s_setprio(0); } while (0)
; #define WAIT_V(n) asm volatile("s_waitcnt vmcnt(" #n ")" ::: "memory")
; #define WAIT_L(n) asm volatile("s_waitcnt lgkmcnt(" #n ")" ::: "memory")
; template <bool PF = true, class Epi, class KRF = KRFull>
; __device__ __forceinline__ void gemm_phase(const u16* __restrict__ A, int lda, const u16* __restrict__ Bt, int ldb, int K, int nM, int nN,
;                                            lds_u16* shm, Epi epi, KRF krf = KRFull(), bool flip = false) {
;     ...
;       STAGE_B(SB(1, 1), 1, t + 3);
;       WAIT_V(6); BAR; MMA(1, 1, At, B1); BAR;
;     }
;     { LDB(B0, 0, 0); LDA(At, 0, 0); STAGE_A(SA(1, 1), 1, nt - 1);
;       BAR; WAIT_L(0); MMA(0, 0, At, B0); BAR;
;       LDB(B1, 0, 1); BAR; WAIT_L(0); MMA(0, 1, At, B1); BAR;
	s_waitcnt lgkmcnt(0)
	s_setprio 1
	s_waitcnt lgkmcnt(0)
	v_mfma_f32_16x16x32_bf16 v[60:63], v[158:161], v[180:183], v[60:63]
	v_mfma_f32_16x16x32_bf16 v[56:59], v[166:169], v[180:183], v[56:59]
	v_mfma_f32_16x16x32_bf16 v[52:55], v[158:161], v[188:191], v[52:55]
	v_mfma_f32_16x16x32_bf16 v[48:51], v[166:169], v[188:191], v[48:51]
	v_mfma_f32_16x16x32_bf16 v[44:47], v[158:161], v[196:199], v[44:47]
	v_mfma_f32_16x16x32_bf16 v[40:43], v[166:169], v[196:199], v[40:43]
	v_mfma_f32_16x16x32_bf16 v[36:39], v[158:161], v[204:207], v[36:39]
	v_mfma_f32_16x16x32_bf16 v[32:35], v[166:169], v[204:207], v[32:35]
	v_mfma_f32_16x16x32_bf16 v[60:63], v[162:165], v[184:187], v[60:63]
	v_mfma_f32_16x16x32_bf16 v[56:59], v[170:173], v[184:187], v[56:59]
	v_mfma_f32_16x16x32_bf16 v[52:55], v[162:165], v[192:195], v[52:55]
	v_mfma_f32_16x16x32_bf16 v[48:51], v[170:173], v[192:195], v[48:51]
	v_mfma_f32_16x16x32_bf16 v[44:47], v[162:165], v[200:203], v[44:47]
	v_mfma_f32_16x16x32_bf16 v[40:43], v[170:173], v[200:203], v[40:43]
	v_mfma_f32_16x16x32_bf16 v[36:39], v[162:165], v[208:211], v[36:39]
	v_mfma_f32_16x16x32_bf16 v[32:35], v[170:173], v[208:211], v[32:35]
	s_setprio 0
	s_barrier
	v_lshl_add_u64 v[158:159], v[236:237], 0, s[92:93]
	s_add_u32 m0, s16, 0x1c000
	s_nop 0
	global_load_lds_dwordx4 v[158:159], off
	v_lshl_add_u64 v[158:159], v[238:239], 0, s[92:93]
	s_add_u32 m0, s16, 0x1e000
	s_nop 0
	global_load_lds_dwordx4 v[158:159], off
	s_waitcnt vmcnt(6)
	s_barrier
	s_setprio 1
	v_mfma_f32_16x16x32_bf16 v[28:31], v[212:215], v[180:183], v[28:31]
	v_mfma_f32_16x16x32_bf16 v[24:27], v[222:225], v[180:183], v[24:27]
	v_mfma_f32_16x16x32_bf16 v[20:23], v[212:215], v[188:191], v[20:23]
	v_mfma_f32_16x16x32_bf16 v[16:19], v[222:225], v[188:191], v[16:19]
	v_mfma_f32_16x16x32_bf16 v[12:15], v[212:215], v[196:199], v[12:15]
	v_mfma_f32_16x16x32_bf16 v[8:11], v[222:225], v[196:199], v[8:11]
	v_mfma_f32_16x16x32_bf16 v[4:7], v[212:215], v[204:207], v[4:7]
	v_mfma_f32_16x16x32_bf16 v[0:3], v[222:225], v[204:207], v[0:3]
	v_mfma_f32_16x16x32_bf16 v[28:31], v[216:219], v[184:187], v[28:31]
	v_mfma_f32_16x16x32_bf16 v[24:27], v[226:229], v[184:187], v[24:27]
	v_mfma_f32_16x16x32_bf16 v[20:23], v[216:219], v[192:195], v[20:23]
	v_mfma_f32_16x16x32_bf16 v[16:19], v[226:229], v[192:195], v[16:19]
	v_mfma_f32_16x16x32_bf16 v[12:15], v[216:219], v[200:203], v[12:15]
	v_mfma_f32_16x16x32_bf16 v[8:11], v[226:229], v[200:203], v[8:11]
	v_mfma_f32_16x16x32_bf16 v[4:7], v[216:219], v[208:211], v[4:7]
	v_mfma_f32_16x16x32_bf16 v[0:3], v[226:229], v[208:211], v[0:3]
	s_setprio 0
	s_add_u32 s12, s12, 0x100
	s_addc_u32 s13, s13, 0
	s_cmp_ge_u32 s7, s3
	s_barrier
	s_cbranch_scc0 .LBB0_2222
	s_lshl_b32 s2, s2, 7
	s_add_u32 s2, s8, s2
	s_addc_u32 s3, s9, 0
	s_add_u32 s2, s2, 0x1ff80
	s_addc_u32 s3, s3, 0
	v_readfirstlane_b32 s7, v156
	v_lshl_add_u64 v[152:153], s[2:3], 0, v[178:179]
	s_mov_b32 m0, s7
	v_lshl_add_u64 v[128:129], s[2:3], 0, v[128:129]
	v_readfirstlane_b32 s2, v157
	ds_read_b128 v[130:133], v155
	ds_read_b128 v[134:137], v155 offset:1024
	ds_read_b128 v[148:151], v155 offset:2048
	ds_read_b128 v[158:161], v155 offset:3072
	ds_read_b128 v[162:165], v143
	ds_read_b128 v[166:169], v143 offset:1024
	ds_read_b128 v[170:173], v142
	ds_read_b128 v[180:183], v142 offset:1024
	ds_read_b128 v[184:187], v141
	ds_read_b128 v[188:191], v141 offset:1024
	ds_read_b128 v[192:195], v139
	ds_read_b128 v[196:199], v139 offset:1024
	global_load_lds_dwordx4 v[152:153], off
	s_mov_b32 m0, s2
	s_nop 0
	global_load_lds_dwordx4 v[128:129], off
	s_barrier
	s_waitcnt lgkmcnt(0)
	s_setprio 1
	s_waitcnt lgkmcnt(0)
	v_mfma_f32_16x16x32_bf16 v[124:127], v[130:133], v[162:165], v[124:127]
	v_mfma_f32_16x16x32_bf16 v[120:123], v[148:151], v[162:165], v[120:123]
	v_mfma_f32_16x16x32_bf16 v[116:119], v[130:133], v[170:173], v[116:119]
	v_mfma_f32_16x16x32_bf16 v[112:115], v[148:151], v[170:173], v[112:115]
	v_mfma_f32_16x16x32_bf16 v[108:111], v[130:133], v[184:187], v[108:111]
	v_mfma_f32_16x16x32_bf16 v[104:107], v[148:151], v[184:187], v[104:107]
	v_mfma_f32_16x16x32_bf16 v[100:103], v[130:133], v[192:195], v[100:103]
	v_mfma_f32_16x16x32_bf16 v[96:99], v[148:151], v[192:195], v[96:99]
	v_mfma_f32_16x16x32_bf16 v[124:127], v[134:137], v[166:169], v[124:127]
	v_mfma_f32_16x16x32_bf16 v[120:123], v[158:161], v[166:169], v[120:123]
	v_mfma_f32_16x16x32_bf16 v[116:119], v[134:137], v[180:183], v[116:119]
	v_mfma_f32_16x16x32_bf16 v[112:115], v[158:161], v[180:183], v[112:115]
	v_mfma_f32_16x16x32_bf16 v[108:111], v[134:137], v[188:191], v[108:111]
	v_mfma_f32_16x16x32_bf16 v[104:107], v[158:161], v[188:191], v[104:107]
	v_mfma_f32_16x16x32_bf16 v[100:103], v[134:137], v[196:199], v[100:103]
	v_mfma_f32_16x16x32_bf16 v[96:99], v[158:161], v[196:199], v[96:99]
	s_setprio 0
	s_barrier
	ds_read_b128 v[200:203], v154
	ds_read_b128 v[204:207], v154 offset:1024
	ds_read_b128 v[208:211], v154 offset:2048
	ds_read_b128 v[152:155], v154 offset:3072
	s_barrier
	s_waitcnt lgkmcnt(0)
	s_setprio 1
	s_waitcnt lgkmcnt(0)
	v_mfma_f32_16x16x32_bf16 v[92:95], v[200:203], v[162:165], v[92:95]
	v_mfma_f32_16x16x32_bf16 v[88:91], v[208:211], v[162:165], v[88:91]
	v_mfma_f32_16x16x32_bf16 v[84:87], v[200:203], v[170:173], v[84:87]
	v_mfma_f32_16x16x32_bf16 v[80:83], v[208:211], v[170:173], v[80:83]
	v_mfma_f32_16x16x32_bf16 v[76:79], v[200:203], v[184:187], v[76:79]
	v_mfma_f32_16x16x32_bf16 v[72:75], v[208:211], v[184:187], v[72:75]
	v_mfma_f32_16x16x32_bf16 v[68:71], v[200:203], v[192:195], v[68:71]
	v_mfma_f32_16x16x32_bf16 v[64:67], v[208:211], v[192:195], v[64:67]
	v_mfma_f32_16x16x32_bf16 v[92:95], v[204:207], v[166:169], v[92:95]
	v_mfma_f32_16x16x32_bf16 v[88:91], v[152:155], v[166:169], v[88:91]
	v_mfma_f32_16x16x32_bf16 v[84:87], v[204:207], v[180:183], v[84:87]
	v_mfma_f32_16x16x32_bf16 v[80:83], v[152:155], v[180:183], v[80:83]
	v_mfma_f32_16x16x32_bf16 v[76:79], v[204:207], v[188:191], v[76:79]
	v_mfma_f32_16x16x32_bf16 v[72:75], v[152:155], v[188:191], v[72:75]
	v_mfma_f32_16x16x32_bf16 v[68:71], v[204:207], v[196:199], v[68:71]
	v_mfma_f32_16x16x32_bf16 v[64:67], v[152:155], v[196:199], v[64:67]
	s_setprio 0
	s_barrier
; #define LDA(dst, b, h) _Pragma("unroll") for (int m = 0; m < 4; ++m) _Pragma("unroll") for (int k = 0; k < 2; ++k) \
;     dst[m][k] = *reinterpret_cast<const bf16x8*>((const char*)SA(b, h) + lds_byte(wr * 64 + m * 16 + fr, k * 32 + fq * 8))
; #define LDB(dst, b, h) _Pragma("unroll") for (int n = 0; n < 2; ++n) _Pragma("unroll") for (int k = 0; k < 2; ++k) \
;     dst[n][k] = *reinterpret_cast<const bf16x8*>((const char*)SB(b, h) + lds_byte(wc * 32 + n * 16 + fr, k * 32 + fq * 8))
; #define MMA(ai, bj, At_, Bt_) do { __builtin_amdgcn_s_setprio(1); \
;     _Pragma("unroll") for (int m = 0; m < 4; ++m) _Pragma("unroll") for (int n = 0; n < 2; ++n) _Pragma("unroll") for (int k = 0; k < 2; ++k) \
;       acc[ai][bj][m][n] = __builtin_amdgcn_mfma_f32_16x16x32_bf16(Bt_[n][k], At_[m][k], acc[ai][bj][m][n], 0, 0, 0); \
;     __builtin_amdgcn_s_setprio(0); } while (0)
; #define WAIT_V(n) asm volatile("s_waitcnt vmcnt(" #n ")" ::: "memory")
; #define WAIT_L(n) asm volatile("s_waitcnt lgkmcnt(" #n ")" ::: "memory")
; #define BAR __builtin_amdgcn_s_barrier()
; template <bool PF = true, class Epi, class KRF = KRFull>
; __device__ __forceinline__ void gemm_phase(const u16* __restrict__ A, int lda, const u16* __restrict__ Bt, int ldb, int K, int nM, int nN,
;                                            lds_u16* shm, Epi epi, KRF krf = KRFull(), bool flip = false) {
;     ...
;       LDB(B1, 0, 1); BAR; WAIT_L(0); MMA(0, 1, At, B1); BAR;
;       LDA(At, 0, 1); WAIT_V(4); BAR; WAIT_L(0); MMA(1, 0, At, B0); MMA(1, 1, At, B1); BAR; }
;     { LDB(B0, 1, 0); LDA(At, 1, 0); WAIT_V(2); BAR; WAIT_L(0); MMA(0, 0, At, B0); BAR;
	ds_read_b128 v[162:165], v143 offset:16384
	ds_read_b128 v[166:169], v143 offset:17408
	ds_read_b128 v[170:173], v142 offset:16384
	ds_read_b128 v[180:183], v142 offset:17408
	ds_read_b128 v[184:187], v141 offset:16384
	ds_read_b128 v[188:191], v141 offset:17408
	ds_read_b128 v[192:195], v139 offset:16384
	ds_read_b128 v[196:199], v139 offset:17408
	s_waitcnt vmcnt(4)
	s_barrier
	s_waitcnt lgkmcnt(0)
	s_setprio 1
	s_waitcnt lgkmcnt(0)
	v_mfma_f32_16x16x32_bf16 v[60:63], v[130:133], v[162:165], v[60:63]
	v_mfma_f32_16x16x32_bf16 v[56:59], v[148:151], v[162:165], v[56:59]
	v_mfma_f32_16x16x32_bf16 v[52:55], v[130:133], v[170:173], v[52:55]
	v_mfma_f32_16x16x32_bf16 v[48:51], v[148:151], v[170:173], v[48:51]
	v_mfma_f32_16x16x32_bf16 v[44:47], v[130:133], v[184:187], v[44:47]
	v_mfma_f32_16x16x32_bf16 v[40:43], v[148:151], v[184:187], v[40:43]
	v_mfma_f32_16x16x32_bf16 v[36:39], v[130:133], v[192:195], v[36:39]
	v_mfma_f32_16x16x32_bf16 v[32:35], v[148:151], v[192:195], v[32:35]
	v_mfma_f32_16x16x32_bf16 v[212:215], v[134:137], v[166:169], v[60:63]
	v_mfma_f32_16x16x32_bf16 v[216:219], v[158:161], v[166:169], v[56:59]
	v_mfma_f32_16x16x32_bf16 v[222:225], v[134:137], v[180:183], v[52:55]
	v_mfma_f32_16x16x32_bf16 v[226:229], v[158:161], v[180:183], v[48:51]
	v_mfma_f32_16x16x32_bf16 v[234:237], v[134:137], v[188:191], v[44:47]
	v_mfma_f32_16x16x32_bf16 v[238:241], v[158:161], v[188:191], v[40:43]
	v_mfma_f32_16x16x32_bf16 v[128:131], v[134:137], v[196:199], v[36:39]
	v_mfma_f32_16x16x32_bf16 v[132:135], v[158:161], v[196:199], v[32:35]
	s_setprio 0
	s_setprio 1
	v_mfma_f32_16x16x32_bf16 v[28:31], v[200:203], v[162:165], v[28:31]
	v_mfma_f32_16x16x32_bf16 v[24:27], v[208:211], v[162:165], v[24:27]
	v_mfma_f32_16x16x32_bf16 v[20:23], v[200:203], v[170:173], v[20:23]
	v_mfma_f32_16x16x32_bf16 v[16:19], v[208:211], v[170:173], v[16:19]
	v_mfma_f32_16x16x32_bf16 v[12:15], v[200:203], v[184:187], v[12:15]
	v_mfma_f32_16x16x32_bf16 v[8:11], v[208:211], v[184:187], v[8:11]
	v_mfma_f32_16x16x32_bf16 v[4:7], v[200:203], v[192:195], v[4:7]
	v_mfma_f32_16x16x32_bf16 v[0:3], v[208:211], v[192:195], v[0:3]
	v_mfma_f32_16x16x32_bf16 v[28:31], v[204:207], v[166:169], v[28:31]
	v_mfma_f32_16x16x32_bf16 v[24:27], v[152:155], v[166:169], v[24:27]
	v_mfma_f32_16x16x32_bf16 v[20:23], v[204:207], v[180:183], v[20:23]
	v_mfma_f32_16x16x32_bf16 v[16:19], v[152:155], v[180:183], v[16:19]
	v_mfma_f32_16x16x32_bf16 v[12:15], v[204:207], v[188:191], v[12:15]
	v_mfma_f32_16x16x32_bf16 v[8:11], v[152:155], v[188:191], v[8:11]
	v_mfma_f32_16x16x32_bf16 v[4:7], v[204:207], v[196:199], v[4:7]
	v_mfma_f32_16x16x32_bf16 v[0:3], v[152:155], v[196:199], v[0:3]
	s_setprio 0
	s_barrier
	ds_read_b128 v[148:151], v146
	ds_read_b128 v[152:155], v146 offset:1024
	ds_read_b128 v[156:159], v146 offset:2048
	ds_read_b128 v[160:163], v146 offset:3072
	ds_read_b128 v[32:35], v143 offset:32768
	ds_read_b128 v[36:39], v143 offset:33792
	ds_read_b128 v[40:43], v142 offset:32768
	ds_read_b128 v[44:47], v142 offset:33792
	ds_read_b128 v[164:167], v141 offset:32768
	ds_read_b128 v[168:171], v141 offset:33792
	ds_read_b128 v[172:175], v139 offset:32768
	ds_read_b128 v[180:183], v139 offset:33792
	s_waitcnt vmcnt(2)
	s_barrier
	s_waitcnt lgkmcnt(0)
	s_setprio 1
	s_waitcnt lgkmcnt(0)
	v_mfma_f32_16x16x32_bf16 v[48:51], v[148:151], v[32:35], v[124:127]
	v_mfma_f32_16x16x32_bf16 v[124:127], v[152:155], v[36:39], v[48:51]
	v_mfma_f32_16x16x32_bf16 v[48:51], v[156:159], v[32:35], v[120:123]
	v_mfma_f32_16x16x32_bf16 v[120:123], v[160:163], v[36:39], v[48:51]
	v_mfma_f32_16x16x32_bf16 v[48:51], v[148:151], v[40:43], v[116:119]
	v_mfma_f32_16x16x32_bf16 v[116:119], v[152:155], v[44:47], v[48:51]
	v_mfma_f32_16x16x32_bf16 v[48:51], v[156:159], v[40:43], v[112:115]
	v_mfma_f32_16x16x32_bf16 v[112:115], v[160:163], v[44:47], v[48:51]
	v_mfma_f32_16x16x32_bf16 v[48:51], v[148:151], v[164:167], v[108:111]
	v_mfma_f32_16x16x32_bf16 v[108:111], v[152:155], v[168:171], v[48:51]
	v_mfma_f32_16x16x32_bf16 v[48:51], v[156:159], v[164:167], v[104:107]
	v_mfma_f32_16x16x32_bf16 v[104:107], v[160:163], v[168:171], v[48:51]
	v_mfma_f32_16x16x32_bf16 v[48:51], v[148:151], v[172:175], v[100:103]
	v_mfma_f32_16x16x32_bf16 v[100:103], v[152:155], v[180:183], v[48:51]
	v_mfma_f32_16x16x32_bf16 v[48:51], v[156:159], v[172:175], v[96:99]
	v_mfma_f32_16x16x32_bf16 v[96:99], v[160:163], v[180:183], v[48:51]
	s_setprio 0
	s_barrier
; #define LDA(dst, b, h) _Pragma("unroll") for (int m = 0; m < 4; ++m) _Pragma("unroll") for (int k = 0; k < 2; ++k) \
;     dst[m][k] = *reinterpret_cast<const bf16x8*>((const char*)SA(b, h) + lds_byte(wr * 64 + m * 16 + fr, k * 32 + fq * 8))
; #define LDB(dst, b, h) _Pragma("unroll") for (int n = 0; n < 2; ++n) _Pragma("unroll") for (int k = 0; k < 2; ++k) \
;     dst[n][k] = *reinterpret_cast<const bf16x8*>((const char*)SB(b, h) + lds_byte(wc * 32 + n * 16 + fr, k * 32 + fq * 8))
; #define MMA(ai, bj, At_, Bt_) do { __builtin_amdgcn_s_setprio(1); \
;     _Pragma("unroll") for (int m = 0; m < 4; ++m) _Pragma("unroll") for (int n = 0; n < 2; ++n) _Pragma("unroll") for (int k = 0; k < 2; ++k) \
;       acc[ai][bj][m][n] = __builtin_amdgcn_mfma_f32_16x16x32_bf16(Bt_[n][k], At_[m][k], acc[ai][bj][m][n], 0, 0, 0); \
;     __builtin_amdgcn_s_setprio(0); } while (0)
; #define WAIT_V(n) asm volatile("s_waitcnt vmcnt(" #n ")" ::: "memory")
; #define WAIT_L(n) asm volatile("s_waitcnt lgkmcnt(" #n ")" ::: "memory")
; #define BAR __builtin_amdgcn_s_barrier()
; template <bool PF = true, class Epi, class KRF = KRFull>
; __device__ __forceinline__ void gemm_phase(const u16* __restrict__ A, int lda, const u16* __restrict__ Bt, int ldb, int K, int nM, int nN,
;                                            lds_u16* shm, Epi epi, KRF krf = KRFull(), bool flip = false) {
;     ...
;       LDB(B1, 1, 1); WAIT_V(0); BAR; WAIT_L(0); MMA(0, 1, At, B1); BAR;
;       LDA(At, 1, 1); BAR; WAIT_L(0); MMA(1, 0, At, B0); MMA(1, 1, At, B1); BAR; }
;     if (wr == 0) BAR;
	ds_read_b128 v[184:187], v144
	ds_read_b128 v[188:191], v144 offset:1024
	ds_read_b128 v[192:195], v144 offset:2048
	ds_read_b128 v[144:147], v144 offset:3072
	s_waitcnt vmcnt(0)
	s_barrier
	s_waitcnt lgkmcnt(0)
	s_setprio 1
	s_waitcnt lgkmcnt(0)
	v_mfma_f32_16x16x32_bf16 v[48:51], v[184:187], v[32:35], v[92:95]
	v_mfma_f32_16x16x32_bf16 v[32:35], v[192:195], v[32:35], v[88:91]
	v_mfma_f32_16x16x32_bf16 v[56:59], v[144:147], v[36:39], v[32:35]
	v_mfma_f32_16x16x32_bf16 v[32:35], v[184:187], v[40:43], v[84:87]
	v_mfma_f32_16x16x32_bf16 v[52:55], v[188:191], v[44:47], v[32:35]
	v_mfma_f32_16x16x32_bf16 v[32:35], v[192:195], v[40:43], v[80:83]
	v_mfma_f32_16x16x32_bf16 v[60:63], v[188:191], v[36:39], v[48:51]
	v_mfma_f32_16x16x32_bf16 v[48:51], v[144:147], v[44:47], v[32:35]
	v_mfma_f32_16x16x32_bf16 v[32:35], v[184:187], v[164:167], v[76:79]
	v_mfma_f32_16x16x32_bf16 v[44:47], v[188:191], v[168:171], v[32:35]
	v_mfma_f32_16x16x32_bf16 v[32:35], v[192:195], v[164:167], v[72:75]
	v_mfma_f32_16x16x32_bf16 v[40:43], v[144:147], v[168:171], v[32:35]
	v_mfma_f32_16x16x32_bf16 v[32:35], v[184:187], v[172:175], v[68:71]
	v_mfma_f32_16x16x32_bf16 v[36:39], v[188:191], v[180:183], v[32:35]
	v_mfma_f32_16x16x32_bf16 v[32:35], v[192:195], v[172:175], v[64:67]
	v_mfma_f32_16x16x32_bf16 v[32:35], v[144:147], v[180:183], v[32:35]
	s_setprio 0
	s_barrier
	ds_read_b128 v[164:167], v143 offset:49152
	ds_read_b128 v[168:171], v143 offset:50176
	ds_read_b128 v[172:175], v142 offset:49152
	ds_read_b128 v[180:183], v142 offset:50176
	ds_read_b128 v[196:199], v141 offset:49152
	ds_read_b128 v[200:203], v141 offset:50176
	ds_read_b128 v[204:207], v139 offset:49152
	ds_read_b128 v[208:211], v139 offset:50176
	s_barrier
	s_waitcnt lgkmcnt(0)
	s_setprio 1
	s_waitcnt lgkmcnt(0)
	v_mfma_f32_16x16x32_bf16 v[64:67], v[148:151], v[164:167], v[212:215]
	v_mfma_f32_16x16x32_bf16 v[92:95], v[152:155], v[168:171], v[64:67]
	v_mfma_f32_16x16x32_bf16 v[64:67], v[156:159], v[164:167], v[216:219]
	v_mfma_f32_16x16x32_bf16 v[88:91], v[160:163], v[168:171], v[64:67]
	v_mfma_f32_16x16x32_bf16 v[64:67], v[148:151], v[172:175], v[222:225]
	v_mfma_f32_16x16x32_bf16 v[84:87], v[152:155], v[180:183], v[64:67]
	v_mfma_f32_16x16x32_bf16 v[64:67], v[156:159], v[172:175], v[226:229]
	v_mfma_f32_16x16x32_bf16 v[80:83], v[160:163], v[180:183], v[64:67]
	v_mfma_f32_16x16x32_bf16 v[64:67], v[148:151], v[196:199], v[234:237]
	v_mfma_f32_16x16x32_bf16 v[76:79], v[152:155], v[200:203], v[64:67]
	v_mfma_f32_16x16x32_bf16 v[64:67], v[156:159], v[196:199], v[238:241]
	v_mfma_f32_16x16x32_bf16 v[72:75], v[160:163], v[200:203], v[64:67]
	v_mfma_f32_16x16x32_bf16 v[64:67], v[148:151], v[204:207], v[128:131]
	v_mfma_f32_16x16x32_bf16 v[68:71], v[152:155], v[208:211], v[64:67]
	v_mfma_f32_16x16x32_bf16 v[64:67], v[156:159], v[204:207], v[132:135]
	v_mfma_f32_16x16x32_bf16 v[64:67], v[160:163], v[208:211], v[64:67]
	s_setprio 0
	s_setprio 1
	v_mfma_f32_16x16x32_bf16 v[28:31], v[184:187], v[164:167], v[28:31]
	v_mfma_f32_16x16x32_bf16 v[24:27], v[192:195], v[164:167], v[24:27]
	v_mfma_f32_16x16x32_bf16 v[20:23], v[184:187], v[172:175], v[20:23]
	v_mfma_f32_16x16x32_bf16 v[16:19], v[192:195], v[172:175], v[16:19]
	v_mfma_f32_16x16x32_bf16 v[12:15], v[184:187], v[196:199], v[12:15]
	v_mfma_f32_16x16x32_bf16 v[8:11], v[192:195], v[196:199], v[8:11]
	v_mfma_f32_16x16x32_bf16 v[4:7], v[184:187], v[204:207], v[4:7]
	v_mfma_f32_16x16x32_bf16 v[0:3], v[192:195], v[204:207], v[0:3]
	v_mfma_f32_16x16x32_bf16 v[28:31], v[188:191], v[168:171], v[28:31]
	v_mfma_f32_16x16x32_bf16 v[24:27], v[144:147], v[168:171], v[24:27]
	v_mfma_f32_16x16x32_bf16 v[20:23], v[188:191], v[180:183], v[20:23]
	v_mfma_f32_16x16x32_bf16 v[16:19], v[144:147], v[180:183], v[16:19]
	v_mfma_f32_16x16x32_bf16 v[12:15], v[188:191], v[200:203], v[12:15]
	v_mfma_f32_16x16x32_bf16 v[8:11], v[144:147], v[200:203], v[8:11]
	v_mfma_f32_16x16x32_bf16 v[4:7], v[188:191], v[208:211], v[4:7]
	v_mfma_f32_16x16x32_bf16 v[0:3], v[144:147], v[208:211], v[0:3]
	s_setprio 0
	v_cmp_gt_u32_e32 vcc, s95, v138
	s_barrier
	s_and_saveexec_b64 s[8:9], vcc
	s_cbranch_execz .LBB0_2225
	s_barrier

; #define STAGE_A(P, half, kt) do { const char* _u = Ab + ((size_t)(half) * 128 * lda + (size_t)(kt) * BK) * 2; \
;     _Pragma("unroll") for (int _i = 0; _i < 2; ++_i) \
;       __builtin_amdgcn_global_load_lds((const unsigned*)(_u + offA[_i]), \
;         (__attribute__((address_space(3))) unsigned*)((__attribute__((address_space(3))) char*)(P) + tidg * 16 + _i * 8192), 16, 0, 0); } while (0)
; #define STAGE_B(P, half, kt) do { const char* _u = Bb + ((size_t)(half) * 128 * ldb + (size_t)(kt) * BK) * 2; \
;     _Pragma("unroll") for (int _i = 0; _i < 2; ++_i) \
;       __builtin_amdgcn_global_load_lds((const unsigned*)(_u + offB[_i]), \
;         (__attribute__((address_space(3))) unsigned*)((__attribute__((address_space(3))) char*)(P) + tidg * 16 + _i * 8192), 16, 0, 0); } while (0)
; #define LDA(dst, b, h) _Pragma("unroll") for (int m = 0; m < 4; ++m) _Pragma("unroll") for (int k = 0; k < 2; ++k) \
;     dst[m][k] = *reinterpret_cast<const bf16x8*>((const char*)SA(b, h) + lds_byte(wr * 64 + m * 16 + fr, k * 32 + fq * 8))
; #define LDB(dst, b, h) _Pragma("unroll") for (int n = 0; n < 2; ++n) _Pragma("unroll") for (int k = 0; k < 2; ++k) \
;     dst[n][k] = *reinterpret_cast<const bf16x8*>((const char*)SB(b, h) + lds_byte(wc * 32 + n * 16 + fr, k * 32 + fq * 8))
; #define MMA(ai, bj, At_, Bt_) do { __builtin_amdgcn_s_setprio(1); \
;     _Pragma("unroll") for (int m = 0; m < 4; ++m) _Pragma("unroll") for (int n = 0; n < 2; ++n) _Pragma("unroll") for (int k = 0; k < 2; ++k) \
;       acc[ai][bj][m][n] = __builtin_amdgcn_mfma_f32_16x16x32_bf16(Bt_[n][k], At_[m][k], acc[ai][bj][m][n], 0, 0, 0); \
;     __builtin_amdgcn_s_setprio(0); } while (0)
; template <bool PF = true, class Epi, class KRF = KRFull>
; __device__ __forceinline__ void gemm_phase(const u16* __restrict__ A, int lda, const u16* __restrict__ Bt, int ldb, int K, int nM, int nN,
;                                            lds_u16* shm, Epi epi, KRF krf = KRFull(), bool flip = false) {
;     ...
;     for (int t = 0; t < nt - 2; t += 2) {
;       LDB(B0, 0, 0); SCHED; LDA(At, 0, 0); STAGE_A(SA(1, 1), 1, t + 1);
;       WAIT_L(8); BAR; WAIT_L(0); MMA(0, 0, At, B0); BAR; SCHED;
;       LDB(B1, 0, 1); STAGE_B(SB(0, 0), 0, t + 2);
;       BAR; WAIT_L(0); MMA(0, 1, At, B1); BAR;
;       LDA(At, 0, 1); STAGE_A(SA(0, 0), 0, t + 2);
;       BAR; WAIT_L(0); MMA(1, 0, At, B0); BAR; SCHED;
.LBB0_2500:
	v_readfirstlane_b32 s15, v144
	ds_read_b128 v[158:161], v154
	ds_read_b128 v[162:165], v154 offset:1024
	ds_read_b128 v[166:169], v154 offset:2048
	ds_read_b128 v[170:173], v154 offset:3072
	v_add_u32_e32 v155, 0xc000, v144
	v_lshl_add_u64 v[174:175], v[134:135], 0, s[18:19]
	v_lshl_add_u64 v[156:157], v[174:175], 0, s[80:81]
	s_add_u32 m0, s15, 0xc000
	ds_read_b128 v[180:183], v142
	ds_read_b128 v[184:187], v142 offset:1024
	ds_read_b128 v[188:191], v141
	ds_read_b128 v[192:195], v141 offset:1024
	ds_read_b128 v[196:199], v140
	ds_read_b128 v[200:203], v140 offset:1024
	ds_read_b128 v[204:207], v139
	ds_read_b128 v[208:211], v139 offset:1024
	global_load_lds_dwordx4 v[156:157], off
	v_add_u32_e32 v156, 0xe000, v144
	v_lshl_add_u64 v[234:235], v[136:137], 0, s[18:19]
	v_lshl_add_u64 v[212:213], v[234:235], 0, s[80:81]
	s_add_u32 m0, s15, 0xe000
	s_nop 0
	global_load_lds_dwordx4 v[212:213], off
	s_waitcnt lgkmcnt(8)
	s_barrier
	s_waitcnt lgkmcnt(0)
	s_setprio 1
	s_waitcnt lgkmcnt(0)
	v_mfma_f32_16x16x32_bf16 v[124:127], v[158:161], v[180:183], v[124:127]
	v_mfma_f32_16x16x32_bf16 v[120:123], v[166:169], v[180:183], v[120:123]
	v_mfma_f32_16x16x32_bf16 v[116:119], v[158:161], v[188:191], v[116:119]
	v_mfma_f32_16x16x32_bf16 v[112:115], v[166:169], v[188:191], v[112:115]
	v_mfma_f32_16x16x32_bf16 v[108:111], v[158:161], v[196:199], v[108:111]
	v_mfma_f32_16x16x32_bf16 v[104:107], v[166:169], v[196:199], v[104:107]
	v_mfma_f32_16x16x32_bf16 v[100:103], v[158:161], v[204:207], v[100:103]
	v_mfma_f32_16x16x32_bf16 v[96:99], v[166:169], v[204:207], v[96:99]
	v_mfma_f32_16x16x32_bf16 v[124:127], v[162:165], v[184:187], v[124:127]
	v_mfma_f32_16x16x32_bf16 v[120:123], v[170:173], v[184:187], v[120:123]
	v_mfma_f32_16x16x32_bf16 v[116:119], v[162:165], v[192:195], v[116:119]
	v_mfma_f32_16x16x32_bf16 v[112:115], v[170:173], v[192:195], v[112:115]
	v_mfma_f32_16x16x32_bf16 v[108:111], v[162:165], v[200:203], v[108:111]
	v_mfma_f32_16x16x32_bf16 v[104:107], v[170:173], v[200:203], v[104:107]
	v_mfma_f32_16x16x32_bf16 v[100:103], v[162:165], v[208:211], v[100:103]
	v_mfma_f32_16x16x32_bf16 v[96:99], v[170:173], v[208:211], v[96:99]
	s_setprio 0
	s_barrier
	v_add_u32_e32 v157, 0x10000, v144
	v_lshl_add_u64 v[236:237], v[130:131], 0, s[18:19]
	v_lshl_add_u64 v[238:239], v[236:237], 0, s[64:65]
	s_add_u32 m0, s15, 0x10000
	v_add_u32_e32 v157, 0x12000, v144
	ds_read_b128 v[212:215], v153
	ds_read_b128 v[216:219], v153 offset:1024
	ds_read_b128 v[222:225], v153 offset:2048
	ds_read_b128 v[226:229], v153 offset:3072
	global_load_lds_dwordx4 v[238:239], off
	v_lshl_add_u64 v[238:239], v[132:133], 0, s[18:19]
	v_lshl_add_u64 v[240:241], v[238:239], 0, s[64:65]
	s_add_u32 m0, s15, 0x12000
	s_nop 0
	global_load_lds_dwordx4 v[240:241], off
	s_barrier
	s_waitcnt lgkmcnt(0)
	s_setprio 1
	s_waitcnt lgkmcnt(0)
	v_mfma_f32_16x16x32_bf16 v[92:95], v[212:215], v[180:183], v[92:95]
	v_mfma_f32_16x16x32_bf16 v[88:91], v[222:225], v[180:183], v[88:91]
	v_mfma_f32_16x16x32_bf16 v[84:87], v[212:215], v[188:191], v[84:87]
	v_mfma_f32_16x16x32_bf16 v[80:83], v[222:225], v[188:191], v[80:83]
	v_mfma_f32_16x16x32_bf16 v[76:79], v[212:215], v[196:199], v[76:79]
	v_mfma_f32_16x16x32_bf16 v[72:75], v[222:225], v[196:199], v[72:75]
	v_mfma_f32_16x16x32_bf16 v[68:71], v[212:215], v[204:207], v[68:71]
	v_mfma_f32_16x16x32_bf16 v[64:67], v[222:225], v[204:207], v[64:67]
	v_mfma_f32_16x16x32_bf16 v[92:95], v[216:219], v[184:187], v[92:95]
	v_mfma_f32_16x16x32_bf16 v[88:91], v[226:229], v[184:187], v[88:91]
	v_mfma_f32_16x16x32_bf16 v[84:87], v[216:219], v[192:195], v[84:87]
	v_mfma_f32_16x16x32_bf16 v[80:83], v[226:229], v[192:195], v[80:83]
	v_mfma_f32_16x16x32_bf16 v[76:79], v[216:219], v[200:203], v[76:79]
	v_mfma_f32_16x16x32_bf16 v[72:75], v[226:229], v[200:203], v[72:75]
	v_mfma_f32_16x16x32_bf16 v[68:71], v[216:219], v[208:211], v[68:71]
	v_mfma_f32_16x16x32_bf16 v[64:67], v[226:229], v[208:211], v[64:67]
	s_setprio 0
	v_lshl_add_u64 v[240:241], v[174:175], 0, s[64:65]
	s_mov_b32 m0, s15
	s_barrier
	ds_read_b128 v[180:183], v142 offset:16384
	ds_read_b128 v[184:187], v142 offset:17408
	ds_read_b128 v[188:191], v141 offset:16384
	ds_read_b128 v[192:195], v141 offset:17408
	ds_read_b128 v[196:199], v140 offset:16384
	ds_read_b128 v[200:203], v140 offset:17408
	ds_read_b128 v[204:207], v139 offset:16384
	ds_read_b128 v[208:211], v139 offset:17408
	global_load_lds_dwordx4 v[240:241], off
	v_lshl_add_u64 v[240:241], v[234:235], 0, s[64:65]
	s_add_u32 m0, s15, 0x2000
	s_nop 0
	global_load_lds_dwordx4 v[240:241], off
	s_barrier
	s_waitcnt lgkmcnt(0)
	s_setprio 1
	s_waitcnt lgkmcnt(0)
	v_mfma_f32_16x16x32_bf16 v[60:63], v[158:161], v[180:183], v[60:63]
	v_mfma_f32_16x16x32_bf16 v[56:59], v[166:169], v[180:183], v[56:59]
	v_mfma_f32_16x16x32_bf16 v[52:55], v[158:161], v[188:191], v[52:55]
	v_mfma_f32_16x16x32_bf16 v[48:51], v[166:169], v[188:191], v[48:51]
	v_mfma_f32_16x16x32_bf16 v[44:47], v[158:161], v[196:199], v[44:47]
	v_mfma_f32_16x16x32_bf16 v[40:43], v[166:169], v[196:199], v[40:43]
	v_mfma_f32_16x16x32_bf16 v[36:39], v[158:161], v[204:207], v[36:39]
	v_mfma_f32_16x16x32_bf16 v[32:35], v[166:169], v[204:207], v[32:35]
	v_mfma_f32_16x16x32_bf16 v[60:63], v[162:165], v[184:187], v[60:63]
	v_mfma_f32_16x16x32_bf16 v[56:59], v[170:173], v[184:187], v[56:59]
	v_mfma_f32_16x16x32_bf16 v[52:55], v[162:165], v[192:195], v[52:55]
	v_mfma_f32_16x16x32_bf16 v[48:51], v[170:173], v[192:195], v[48:51]
	v_mfma_f32_16x16x32_bf16 v[44:47], v[162:165], v[200:203], v[44:47]
	v_mfma_f32_16x16x32_bf16 v[40:43], v[170:173], v[200:203], v[40:43]
	v_mfma_f32_16x16x32_bf16 v[36:39], v[162:165], v[208:211], v[36:39]
	v_mfma_f32_16x16x32_bf16 v[32:35], v[170:173], v[208:211], v[32:35]
	s_setprio 0
	s_barrier
; #define STAGE_A(P, half, kt) do { const char* _u = Ab + ((size_t)(half) * 128 * lda + (size_t)(kt) * BK) * 2; \
;     _Pragma("unroll") for (int _i = 0; _i < 2; ++_i) \
;       __builtin_amdgcn_global_load_lds((const unsigned*)(_u + offA[_i]), \
;         (__attribute__((address_space(3))) unsigned*)((__attribute__((address_space(3))) char*)(P) + tidg * 16 + _i * 8192), 16, 0, 0); } while (0)
; #define STAGE_B(P, half, kt) do { const char* _u = Bb + ((size_t)(half) * 128 * ldb + (size_t)(kt) * BK) * 2; \
;     _Pragma("unroll") for (int _i = 0; _i < 2; ++_i) \
;       __builtin_amdgcn_global_load_lds((const unsigned*)(_u + offB[_i]), \
;         (__attribute__((address_space(3))) unsigned*)((__attribute__((address_space(3))) char*)(P) + tidg * 16 + _i * 8192), 16, 0, 0); } while (0)
; #define LDA(dst, b, h) _Pragma("unroll") for (int m = 0; m < 4; ++m) _Pragma("unroll") for (int k = 0; k < 2; ++k) \
;     dst[m][k] = *reinterpret_cast<const bf16x8*>((const char*)SA(b, h) + lds_byte(wr * 64 + m * 16 + fr, k * 32 + fq * 8))
; #define LDB(dst, b, h) _Pragma("unroll") for (int n = 0; n < 2; ++n) _Pragma("unroll") for (int k = 0; k < 2; ++k) \
;     dst[n][k] = *reinterpret_cast<const bf16x8*>((const char*)SB(b, h) + lds_byte(wc * 32 + n * 16 + fr, k * 32 + fq * 8))
; #define WAIT_V(n) asm volatile("s_waitcnt vmcnt(" #n ")" ::: "memory")
; #define WAIT_L(n) asm volatile("s_waitcnt lgkmcnt(" #n ")" ::: "memory")
; #define BAR __builtin_amdgcn_s_barrier()
; #define SCHED __builtin_amdgcn_sched_barrier(0)
; template <bool PF = true, class Epi, class KRF = KRFull>
; __device__ __forceinline__ void gemm_phase(const u16* __restrict__ A, int lda, const u16* __restrict__ Bt, int ldb, int K, int nM, int nN,
;                                            lds_u16* shm, Epi epi, KRF krf = KRFull(), bool flip = false) {
;     ...
;       STAGE_B(SB(0, 1), 1, t + 2);
;       WAIT_V(6); BAR; MMA(1, 1, At, B1); BAR;
;       LDB(B0, 1, 0); SCHED; LDA(At, 1, 0); STAGE_A(SA(0, 1), 1, t + 2);
;       WAIT_L(8); BAR; WAIT_L(0); MMA(0, 0, At, B0); BAR; SCHED;
;       LDB(B1, 1, 1); STAGE_B(SB(1, 0), 0, t + 3);
;       BAR; WAIT_L(0); MMA(0, 1, At, B1); BAR;
;       LDA(At, 1, 1); STAGE_A(SA(1, 0), 0, t + 3);
;       BAR; WAIT_L(0); MMA(1, 0, At, B0); BAR; SCHED;
	v_add_u32_e32 v157, 0x14000, v144
	v_lshl_add_u64 v[158:159], v[236:237], 0, s[86:87]
	v_add_u32_e32 v157, 0x16000, v144
	s_add_u32 m0, s15, 0x14000
	s_nop 0
	global_load_lds_dwordx4 v[158:159], off
	v_lshl_add_u64 v[158:159], v[238:239], 0, s[86:87]
	s_add_u32 m0, s15, 0x16000
	s_nop 0
	global_load_lds_dwordx4 v[158:159], off
	s_waitcnt vmcnt(6)
	s_barrier
	s_setprio 1
	v_mfma_f32_16x16x32_bf16 v[28:31], v[212:215], v[180:183], v[28:31]
	v_mfma_f32_16x16x32_bf16 v[24:27], v[222:225], v[180:183], v[24:27]
	v_mfma_f32_16x16x32_bf16 v[20:23], v[212:215], v[188:191], v[20:23]
	v_mfma_f32_16x16x32_bf16 v[16:19], v[222:225], v[188:191], v[16:19]
	v_mfma_f32_16x16x32_bf16 v[12:15], v[212:215], v[196:199], v[12:15]
	v_mfma_f32_16x16x32_bf16 v[8:11], v[222:225], v[196:199], v[8:11]
	v_mfma_f32_16x16x32_bf16 v[4:7], v[212:215], v[204:207], v[4:7]
	v_mfma_f32_16x16x32_bf16 v[0:3], v[222:225], v[204:207], v[0:3]
	v_mfma_f32_16x16x32_bf16 v[28:31], v[216:219], v[184:187], v[28:31]
	v_mfma_f32_16x16x32_bf16 v[24:27], v[226:229], v[184:187], v[24:27]
	v_mfma_f32_16x16x32_bf16 v[20:23], v[216:219], v[192:195], v[20:23]
	v_mfma_f32_16x16x32_bf16 v[16:19], v[226:229], v[192:195], v[16:19]
	v_mfma_f32_16x16x32_bf16 v[12:15], v[216:219], v[200:203], v[12:15]
	v_mfma_f32_16x16x32_bf16 v[8:11], v[226:229], v[200:203], v[8:11]
	v_mfma_f32_16x16x32_bf16 v[4:7], v[216:219], v[208:211], v[4:7]
	v_mfma_f32_16x16x32_bf16 v[0:3], v[226:229], v[208:211], v[0:3]
	s_setprio 0
	s_barrier
	ds_read_b128 v[158:161], v145
	ds_read_b128 v[162:165], v145 offset:1024
	ds_read_b128 v[166:169], v145 offset:2048
	ds_read_b128 v[170:173], v145 offset:3072
	v_add_u32_e32 v157, 0x4000, v144
	v_lshl_add_u64 v[212:213], v[174:175], 0, s[86:87]
	v_add_u32_e32 v157, 0x6000, v144
	s_add_u32 m0, s15, 0x4000
	ds_read_b128 v[180:183], v142 offset:32768
	ds_read_b128 v[184:187], v142 offset:33792
	ds_read_b128 v[188:191], v141 offset:32768
	ds_read_b128 v[192:195], v141 offset:33792
	ds_read_b128 v[196:199], v140 offset:32768
	ds_read_b128 v[200:203], v140 offset:33792
	ds_read_b128 v[204:207], v139 offset:32768
	ds_read_b128 v[208:211], v139 offset:33792
	global_load_lds_dwordx4 v[212:213], off
	v_lshl_add_u64 v[212:213], v[234:235], 0, s[86:87]
	s_add_u32 m0, s15, 0x6000
	s_nop 0
	global_load_lds_dwordx4 v[212:213], off
	s_waitcnt lgkmcnt(8)
	s_barrier
	s_waitcnt lgkmcnt(0)
	s_setprio 1
	s_waitcnt lgkmcnt(0)
	v_mfma_f32_16x16x32_bf16 v[124:127], v[158:161], v[180:183], v[124:127]
	v_mfma_f32_16x16x32_bf16 v[120:123], v[166:169], v[180:183], v[120:123]
	v_mfma_f32_16x16x32_bf16 v[116:119], v[158:161], v[188:191], v[116:119]
	v_mfma_f32_16x16x32_bf16 v[112:115], v[166:169], v[188:191], v[112:115]
	v_mfma_f32_16x16x32_bf16 v[108:111], v[158:161], v[196:199], v[108:111]
	v_mfma_f32_16x16x32_bf16 v[104:107], v[166:169], v[196:199], v[104:107]
	v_mfma_f32_16x16x32_bf16 v[100:103], v[158:161], v[204:207], v[100:103]
	v_mfma_f32_16x16x32_bf16 v[96:99], v[166:169], v[204:207], v[96:99]
	v_mfma_f32_16x16x32_bf16 v[124:127], v[162:165], v[184:187], v[124:127]
	v_mfma_f32_16x16x32_bf16 v[120:123], v[170:173], v[184:187], v[120:123]
	v_mfma_f32_16x16x32_bf16 v[116:119], v[162:165], v[192:195], v[116:119]
	v_mfma_f32_16x16x32_bf16 v[112:115], v[170:173], v[192:195], v[112:115]
	v_mfma_f32_16x16x32_bf16 v[108:111], v[162:165], v[200:203], v[108:111]
	v_mfma_f32_16x16x32_bf16 v[104:107], v[170:173], v[200:203], v[104:107]
	v_mfma_f32_16x16x32_bf16 v[100:103], v[162:165], v[208:211], v[100:103]
	v_mfma_f32_16x16x32_bf16 v[96:99], v[170:173], v[208:211], v[96:99]
	s_setprio 0
	s_barrier
	v_lshl_add_u64 v[240:241], v[236:237], 0, s[68:69]
	s_add_u32 m0, s15, 0x18000
	ds_read_b128 v[212:215], v143
	ds_read_b128 v[216:219], v143 offset:1024
	ds_read_b128 v[222:225], v143 offset:2048
	ds_read_b128 v[226:229], v143 offset:3072
	global_load_lds_dwordx4 v[240:241], off
	v_lshl_add_u64 v[240:241], v[238:239], 0, s[68:69]
	s_add_u32 m0, s15, 0x1a000
	s_nop 0
	global_load_lds_dwordx4 v[240:241], off
	s_barrier
	s_waitcnt lgkmcnt(0)
	s_setprio 1
	s_waitcnt lgkmcnt(0)
	v_mfma_f32_16x16x32_bf16 v[92:95], v[212:215], v[180:183], v[92:95]
	v_mfma_f32_16x16x32_bf16 v[88:91], v[222:225], v[180:183], v[88:91]
	v_mfma_f32_16x16x32_bf16 v[84:87], v[212:215], v[188:191], v[84:87]
	v_mfma_f32_16x16x32_bf16 v[80:83], v[222:225], v[188:191], v[80:83]
	v_mfma_f32_16x16x32_bf16 v[76:79], v[212:215], v[196:199], v[76:79]
	v_mfma_f32_16x16x32_bf16 v[72:75], v[222:225], v[196:199], v[72:75]
	v_mfma_f32_16x16x32_bf16 v[68:71], v[212:215], v[204:207], v[68:71]
	v_mfma_f32_16x16x32_bf16 v[64:67], v[222:225], v[204:207], v[64:67]
	v_mfma_f32_16x16x32_bf16 v[92:95], v[216:219], v[184:187], v[92:95]
	v_mfma_f32_16x16x32_bf16 v[88:91], v[226:229], v[184:187], v[88:91]
	v_mfma_f32_16x16x32_bf16 v[84:87], v[216:219], v[192:195], v[84:87]
	v_mfma_f32_16x16x32_bf16 v[80:83], v[226:229], v[192:195], v[80:83]
	v_mfma_f32_16x16x32_bf16 v[76:79], v[216:219], v[200:203], v[76:79]
	v_mfma_f32_16x16x32_bf16 v[72:75], v[226:229], v[200:203], v[72:75]
	v_mfma_f32_16x16x32_bf16 v[68:71], v[216:219], v[208:211], v[68:71]
	v_mfma_f32_16x16x32_bf16 v[64:67], v[226:229], v[208:211], v[64:67]
	s_setprio 0
	v_lshl_add_u64 v[174:175], v[174:175], 0, s[68:69]
	s_add_u32 m0, s15, 0x8000
	s_barrier
	ds_read_b128 v[180:183], v142 offset:49152
	ds_read_b128 v[184:187], v142 offset:50176
	ds_read_b128 v[188:191], v141 offset:49152
	ds_read_b128 v[192:195], v141 offset:50176
	ds_read_b128 v[196:199], v140 offset:49152
	ds_read_b128 v[200:203], v140 offset:50176
	ds_read_b128 v[204:207], v139 offset:49152
	ds_read_b128 v[208:211], v139 offset:50176
	global_load_lds_dwordx4 v[174:175], off
	v_lshl_add_u64 v[174:175], v[234:235], 0, s[68:69]
	s_add_u32 m0, s15, 0xa000
	s_nop 0
	global_load_lds_dwordx4 v[174:175], off
	s_barrier
; #define STAGE_A(P, half, kt) do { const char* _u = Ab + ((size_t)(half) * 128 * lda + (size_t)(kt) * BK) * 2; \
;     _Pragma("unroll") for (int _i = 0; _i < 2; ++_i) \
;       __builtin_amdgcn_global_load_lds((const unsigned*)(_u + offA[_i]), \
;         (__attribute__((address_space(3))) unsigned*)((__attribute__((address_space(3))) char*)(P) + tidg * 16 + _i * 8192), 16, 0, 0); } while (0)
; #define STAGE_B(P, half, kt) do { const char* _u = Bb + ((size_t)(half) * 128 * ldb + (size_t)(kt) * BK) * 2; \
;     _Pragma("unroll") for (int _i = 0; _i < 2; ++_i) \
;       __builtin_amdgcn_global_load_lds((const unsigned*)(_u + offB[_i]), \
;         (__attribute__((address_space(3))) unsigned*)((__attribute__((address_space(3))) char*)(P) + tidg * 16 + _i * 8192), 16, 0, 0); } while (0)
; #define LDA(dst, b, h) _Pragma("unroll") for (int m = 0; m < 4; ++m) _Pragma("unroll") for (int k = 0; k < 2; ++k) \
;     dst[m][k] = *reinterpret_cast<const bf16x8*>((const char*)SA(b, h) + lds_byte(wr * 64 + m * 16 + fr, k * 32 + fq * 8))
; #define LDB(dst, b, h) _Pragma("unroll") for (int n = 0; n < 2; ++n) _Pragma("unroll") for (int k = 0; k < 2; ++k) \
;     dst[n][k] = *reinterpret_cast<const bf16x8*>((const char*)SB(b, h) + lds_byte(wc * 32 + n * 16 + fr, k * 32 + fq * 8))
; #define MMA(ai, bj, At_, Bt_) do { __builtin_amdgcn_s_setprio(1); \
;     _Pragma("unroll") for (int m = 0; m < 4; ++m) _Pragma("unroll") for (int n = 0; n < 2; ++n) _Pragma("unroll") for (int k = 0; k < 2; ++k) \
;       acc[ai][bj][m][n] = __builtin_amdgcn_mfma_f32_16x16x32_bf16(Bt_[n][k], At_[m][k], acc[ai][bj][m][n], 0, 0, 0); \
;     __builtin_amdgcn_s_setprio(0); } while (0)
; #define WAIT_V(n) asm volatile("s_waitcnt vmcnt(" #n ")" ::: "memory")
; #define WAIT_L(n) asm volatile("s_waitcnt lgkmcnt(" #n ")" ::: "memory")
; template <bool PF = true, class Epi, class KRF = KRFull>
; __device__ __forceinline__ void gemm_phase(const u16* __restrict__ A, int lda, const u16* __restrict__ Bt, int ldb, int K, int nM, int nN,
;                                            lds_u16* shm, Epi epi, KRF krf = KRFull(), bool flip = false) {
;     ...
;       STAGE_B(SB(1, 1), 1, t + 3);
;       WAIT_V(6); BAR; MMA(1, 1, At, B1); BAR;
;     }
;     { LDB(B0, 0, 0); LDA(At, 0, 0); STAGE_A(SA(1, 1), 1, nt - 1);
;       BAR; WAIT_L(0); MMA(0, 0, At, B0); BAR;
;       LDB(B1, 0, 1); BAR; WAIT_L(0); MMA(0, 1, At, B1); BAR;
	s_waitcnt lgkmcnt(0)
	s_setprio 1
	s_waitcnt lgkmcnt(0)
	v_mfma_f32_16x16x32_bf16 v[60:63], v[158:161], v[180:183], v[60:63]
	v_mfma_f32_16x16x32_bf16 v[56:59], v[166:169], v[180:183], v[56:59]
	v_mfma_f32_16x16x32_bf16 v[52:55], v[158:161], v[188:191], v[52:55]
	v_mfma_f32_16x16x32_bf16 v[48:51], v[166:169], v[188:191], v[48:51]
	v_mfma_f32_16x16x32_bf16 v[44:47], v[158:161], v[196:199], v[44:47]
	v_mfma_f32_16x16x32_bf16 v[40:43], v[166:169], v[196:199], v[40:43]
	v_mfma_f32_16x16x32_bf16 v[36:39], v[158:161], v[204:207], v[36:39]
	v_mfma_f32_16x16x32_bf16 v[32:35], v[166:169], v[204:207], v[32:35]
	v_mfma_f32_16x16x32_bf16 v[60:63], v[162:165], v[184:187], v[60:63]
	v_mfma_f32_16x16x32_bf16 v[56:59], v[170:173], v[184:187], v[56:59]
	v_mfma_f32_16x16x32_bf16 v[52:55], v[162:165], v[192:195], v[52:55]
	v_mfma_f32_16x16x32_bf16 v[48:51], v[170:173], v[192:195], v[48:51]
	v_mfma_f32_16x16x32_bf16 v[44:47], v[162:165], v[200:203], v[44:47]
	v_mfma_f32_16x16x32_bf16 v[40:43], v[170:173], v[200:203], v[40:43]
	v_mfma_f32_16x16x32_bf16 v[36:39], v[162:165], v[208:211], v[36:39]
	v_mfma_f32_16x16x32_bf16 v[32:35], v[170:173], v[208:211], v[32:35]
	s_setprio 0
	s_barrier
	v_lshl_add_u64 v[158:159], v[236:237], 0, s[92:93]
	s_add_u32 m0, s15, 0x1c000
	s_nop 0
	global_load_lds_dwordx4 v[158:159], off
	v_lshl_add_u64 v[158:159], v[238:239], 0, s[92:93]
	s_add_u32 m0, s15, 0x1e000
	s_nop 0
	global_load_lds_dwordx4 v[158:159], off
	s_waitcnt vmcnt(6)
	s_barrier
	s_setprio 1
	v_mfma_f32_16x16x32_bf16 v[28:31], v[212:215], v[180:183], v[28:31]
	v_mfma_f32_16x16x32_bf16 v[24:27], v[222:225], v[180:183], v[24:27]
	v_mfma_f32_16x16x32_bf16 v[20:23], v[212:215], v[188:191], v[20:23]
	v_mfma_f32_16x16x32_bf16 v[16:19], v[222:225], v[188:191], v[16:19]
	v_mfma_f32_16x16x32_bf16 v[12:15], v[212:215], v[196:199], v[12:15]
	v_mfma_f32_16x16x32_bf16 v[8:11], v[222:225], v[196:199], v[8:11]
	v_mfma_f32_16x16x32_bf16 v[4:7], v[212:215], v[204:207], v[4:7]
	v_mfma_f32_16x16x32_bf16 v[0:3], v[222:225], v[204:207], v[0:3]
	v_mfma_f32_16x16x32_bf16 v[28:31], v[216:219], v[184:187], v[28:31]
	v_mfma_f32_16x16x32_bf16 v[24:27], v[226:229], v[184:187], v[24:27]
	v_mfma_f32_16x16x32_bf16 v[20:23], v[216:219], v[192:195], v[20:23]
	v_mfma_f32_16x16x32_bf16 v[16:19], v[226:229], v[192:195], v[16:19]
	v_mfma_f32_16x16x32_bf16 v[12:15], v[216:219], v[200:203], v[12:15]
	v_mfma_f32_16x16x32_bf16 v[8:11], v[226:229], v[200:203], v[8:11]
	v_mfma_f32_16x16x32_bf16 v[4:7], v[216:219], v[208:211], v[4:7]
	v_mfma_f32_16x16x32_bf16 v[0:3], v[226:229], v[208:211], v[0:3]
	s_setprio 0
	s_add_i32 s13, s13, 2
	s_add_u32 s18, s18, 0x100
	s_addc_u32 s19, s19, 0
	s_cmp_gt_u32 s13, 3
	s_barrier
	s_cbranch_scc0 .LBB0_2500
	s_add_u32 s16, s10, 0x20380
	s_addc_u32 s17, s11, 0
	v_readfirstlane_b32 s13, v155
	v_lshl_add_u64 v[150:151], s[16:17], 0, v[178:179]
	s_mov_b32 m0, s13
	v_readfirstlane_b32 s13, v156
	ds_read_b128 v[130:133], v154
	ds_read_b128 v[134:137], v154 offset:1024
	ds_read_b128 v[146:149], v154 offset:2048
	ds_read_b128 v[158:161], v154 offset:3072
	ds_read_b128 v[162:165], v142
	ds_read_b128 v[166:169], v142 offset:1024
	ds_read_b128 v[170:173], v141
	ds_read_b128 v[180:183], v141 offset:1024
	ds_read_b128 v[184:187], v140
	ds_read_b128 v[188:191], v140 offset:1024
	ds_read_b128 v[192:195], v139
	ds_read_b128 v[196:199], v139 offset:1024
	global_load_lds_dwordx4 v[150:151], off
	v_lshl_add_u64 v[128:129], s[16:17], 0, v[128:129]
	s_mov_b32 m0, s13
	s_nop 0
	global_load_lds_dwordx4 v[128:129], off
	s_barrier
	s_waitcnt lgkmcnt(0)
	s_setprio 1
	s_waitcnt lgkmcnt(0)
	v_mfma_f32_16x16x32_bf16 v[124:127], v[130:133], v[162:165], v[124:127]
	v_mfma_f32_16x16x32_bf16 v[120:123], v[146:149], v[162:165], v[120:123]
	v_mfma_f32_16x16x32_bf16 v[116:119], v[130:133], v[170:173], v[116:119]
	v_mfma_f32_16x16x32_bf16 v[112:115], v[146:149], v[170:173], v[112:115]
	v_mfma_f32_16x16x32_bf16 v[108:111], v[130:133], v[184:187], v[108:111]
	v_mfma_f32_16x16x32_bf16 v[104:107], v[146:149], v[184:187], v[104:107]
	v_mfma_f32_16x16x32_bf16 v[100:103], v[130:133], v[192:195], v[100:103]
	v_mfma_f32_16x16x32_bf16 v[96:99], v[146:149], v[192:195], v[96:99]
	v_mfma_f32_16x16x32_bf16 v[124:127], v[134:137], v[166:169], v[124:127]
	v_mfma_f32_16x16x32_bf16 v[120:123], v[158:161], v[166:169], v[120:123]
	v_mfma_f32_16x16x32_bf16 v[116:119], v[134:137], v[180:183], v[116:119]
	v_mfma_f32_16x16x32_bf16 v[112:115], v[158:161], v[180:183], v[112:115]
	v_mfma_f32_16x16x32_bf16 v[108:111], v[134:137], v[188:191], v[108:111]
	v_mfma_f32_16x16x32_bf16 v[104:107], v[158:161], v[188:191], v[104:107]
	v_mfma_f32_16x16x32_bf16 v[100:103], v[134:137], v[196:199], v[100:103]
	v_mfma_f32_16x16x32_bf16 v[96:99], v[158:161], v[196:199], v[96:99]
	s_setprio 0
	s_barrier
	ds_read_b128 v[154:157], v153
	ds_read_b128 v[200:203], v153 offset:1024
	ds_read_b128 v[204:207], v153 offset:2048
	ds_read_b128 v[150:153], v153 offset:3072
	s_barrier
	s_waitcnt lgkmcnt(0)
	s_setprio 1
	s_waitcnt lgkmcnt(0)
	v_mfma_f32_16x16x32_bf16 v[88:91], v[204:207], v[162:165], v[88:91]
	v_mfma_f32_16x16x32_bf16 v[80:83], v[204:207], v[170:173], v[80:83]
	v_mfma_f32_16x16x32_bf16 v[76:79], v[154:157], v[184:187], v[76:79]
	v_mfma_f32_16x16x32_bf16 v[72:75], v[204:207], v[184:187], v[72:75]
	v_mfma_f32_16x16x32_bf16 v[68:71], v[154:157], v[192:195], v[68:71]
	v_mfma_f32_16x16x32_bf16 v[92:95], v[154:157], v[162:165], v[92:95]
	v_mfma_f32_16x16x32_bf16 v[88:91], v[150:153], v[166:169], v[88:91]
	v_mfma_f32_16x16x32_bf16 v[84:87], v[154:157], v[170:173], v[84:87]
	v_mfma_f32_16x16x32_bf16 v[80:83], v[150:153], v[180:183], v[80:83]
	v_mfma_f32_16x16x32_bf16 v[76:79], v[200:203], v[188:191], v[76:79]
	v_mfma_f32_16x16x32_bf16 v[72:75], v[150:153], v[188:191], v[72:75]
	v_mfma_f32_16x16x32_bf16 v[68:71], v[200:203], v[196:199], v[68:71]
	v_mfma_f32_16x16x32_bf16 v[64:67], v[204:207], v[192:195], v[64:67]
	v_mfma_f32_16x16x32_bf16 v[208:211], v[200:203], v[166:169], v[92:95]
	v_mfma_f32_16x16x32_bf16 v[162:165], v[200:203], v[180:183], v[84:87]
	v_mfma_f32_16x16x32_bf16 v[166:169], v[150:153], v[196:199], v[64:67]
	s_setprio 0
	s_barrier
; #define LDA(dst, b, h) _Pragma("unroll") for (int m = 0; m < 4; ++m) _Pragma("unroll") for (int k = 0; k < 2; ++k) \
;     dst[m][k] = *reinterpret_cast<const bf16x8*>((const char*)SA(b, h) + lds_byte(wr * 64 + m * 16 + fr, k * 32 + fq * 8))
; #define LDB(dst, b, h) _Pragma("unroll") for (int n = 0; n < 2; ++n) _Pragma("unroll") for (int k = 0; k < 2; ++k) \
;     dst[n][k] = *reinterpret_cast<const bf16x8*>((const char*)SB(b, h) + lds_byte(wc * 32 + n * 16 + fr, k * 32 + fq * 8))
; #define MMA(ai, bj, At_, Bt_) do { __builtin_amdgcn_s_setprio(1); \
;     _Pragma("unroll") for (int m = 0; m < 4; ++m) _Pragma("unroll") for (int n = 0; n < 2; ++n) _Pragma("unroll") for (int k = 0; k < 2; ++k) \
;       acc[ai][bj][m][n] = __builtin_amdgcn_mfma_f32_16x16x32_bf16(Bt_[n][k], At_[m][k], acc[ai][bj][m][n], 0, 0, 0); \
;     __builtin_amdgcn_s_setprio(0); } while (0)
; #define WAIT_V(n) asm volatile("s_waitcnt vmcnt(" #n ")" ::: "memory")
; #define WAIT_L(n) asm volatile("s_waitcnt lgkmcnt(" #n ")" ::: "memory")
; #define BAR __builtin_amdgcn_s_barrier()
; template <bool PF = true, class Epi, class KRF = KRFull>
; __device__ __forceinline__ void gemm_phase(const u16* __restrict__ A, int lda, const u16* __restrict__ Bt, int ldb, int K, int nM, int nN,
;                                            lds_u16* shm, Epi epi, KRF krf = KRFull(), bool flip = false) {
;     ...
;       LDB(B1, 0, 1); BAR; WAIT_L(0); MMA(0, 1, At, B1); BAR;
;       LDA(At, 0, 1); WAIT_V(4); BAR; WAIT_L(0); MMA(1, 0, At, B0); MMA(1, 1, At, B1); BAR; }
;     { LDB(B0, 1, 0); LDA(At, 1, 0); WAIT_V(2); BAR; WAIT_L(0); MMA(0, 0, At, B0); BAR;
	s_nop 2
	ds_read_b128 v[64:67], v142 offset:16384
	ds_read_b128 v[84:87], v142 offset:17408
	ds_read_b128 v[92:95], v141 offset:16384
	ds_read_b128 v[170:173], v141 offset:17408
	ds_read_b128 v[180:183], v140 offset:16384
	ds_read_b128 v[184:187], v140 offset:17408
	ds_read_b128 v[188:191], v139 offset:16384
	ds_read_b128 v[192:195], v139 offset:17408
	s_waitcnt vmcnt(4)
	s_barrier
	s_waitcnt lgkmcnt(0)
	s_setprio 1
	s_waitcnt lgkmcnt(0)
	v_mfma_f32_16x16x32_bf16 v[60:63], v[130:133], v[64:67], v[60:63]
	v_mfma_f32_16x16x32_bf16 v[52:55], v[130:133], v[92:95], v[52:55]
	v_mfma_f32_16x16x32_bf16 v[48:51], v[146:149], v[92:95], v[48:51]
	v_mfma_f32_16x16x32_bf16 v[44:47], v[130:133], v[180:183], v[44:47]
	v_mfma_f32_16x16x32_bf16 v[40:43], v[146:149], v[180:183], v[40:43]
	v_mfma_f32_16x16x32_bf16 v[36:39], v[130:133], v[188:191], v[36:39]
	v_mfma_f32_16x16x32_bf16 v[32:35], v[146:149], v[188:191], v[32:35]
	v_mfma_f32_16x16x32_bf16 v[60:63], v[134:137], v[84:87], v[60:63]
	v_mfma_f32_16x16x32_bf16 v[56:59], v[146:149], v[64:67], v[56:59]
	v_mfma_f32_16x16x32_bf16 v[52:55], v[134:137], v[170:173], v[52:55]
	v_mfma_f32_16x16x32_bf16 v[48:51], v[158:161], v[170:173], v[48:51]
	v_mfma_f32_16x16x32_bf16 v[44:47], v[134:137], v[184:187], v[44:47]
	v_mfma_f32_16x16x32_bf16 v[40:43], v[158:161], v[184:187], v[40:43]
	v_mfma_f32_16x16x32_bf16 v[36:39], v[134:137], v[192:195], v[36:39]
	v_mfma_f32_16x16x32_bf16 v[32:35], v[158:161], v[192:195], v[32:35]
	v_mfma_f32_16x16x32_bf16 v[196:199], v[158:161], v[84:87], v[56:59]
	s_setprio 0
	s_setprio 1
	v_mfma_f32_16x16x32_bf16 v[28:31], v[154:157], v[64:67], v[28:31]
	v_mfma_f32_16x16x32_bf16 v[24:27], v[204:207], v[64:67], v[24:27]
	v_mfma_f32_16x16x32_bf16 v[20:23], v[154:157], v[92:95], v[20:23]
	v_mfma_f32_16x16x32_bf16 v[16:19], v[204:207], v[92:95], v[16:19]
	v_mfma_f32_16x16x32_bf16 v[12:15], v[154:157], v[180:183], v[12:15]
	v_mfma_f32_16x16x32_bf16 v[8:11], v[204:207], v[180:183], v[8:11]
	v_mfma_f32_16x16x32_bf16 v[4:7], v[154:157], v[188:191], v[4:7]
	v_mfma_f32_16x16x32_bf16 v[0:3], v[204:207], v[188:191], v[0:3]
	v_mfma_f32_16x16x32_bf16 v[28:31], v[200:203], v[84:87], v[28:31]
	v_mfma_f32_16x16x32_bf16 v[24:27], v[150:153], v[84:87], v[24:27]
	v_mfma_f32_16x16x32_bf16 v[20:23], v[200:203], v[170:173], v[20:23]
	v_mfma_f32_16x16x32_bf16 v[16:19], v[150:153], v[170:173], v[16:19]
	v_mfma_f32_16x16x32_bf16 v[12:15], v[200:203], v[184:187], v[12:15]
	v_mfma_f32_16x16x32_bf16 v[8:11], v[150:153], v[184:187], v[8:11]
	v_mfma_f32_16x16x32_bf16 v[4:7], v[200:203], v[192:195], v[4:7]
	v_mfma_f32_16x16x32_bf16 v[0:3], v[150:153], v[192:195], v[0:3]
	s_setprio 0
	s_barrier
	ds_read_b128 v[128:131], v145
	ds_read_b128 v[132:135], v145 offset:1024
	ds_read_b128 v[146:149], v145 offset:2048
	ds_read_b128 v[150:153], v145 offset:3072
	ds_read_b128 v[56:59], v142 offset:32768
	ds_read_b128 v[64:67], v142 offset:33792
	ds_read_b128 v[154:157], v141 offset:32768
	ds_read_b128 v[158:161], v141 offset:33792
	ds_read_b128 v[170:173], v140 offset:32768
	ds_read_b128 v[180:183], v140 offset:33792
	ds_read_b128 v[184:187], v139 offset:32768
	ds_read_b128 v[188:191], v139 offset:33792
	s_waitcnt vmcnt(2)
	s_barrier
	s_waitcnt lgkmcnt(0)
	s_setprio 1
	s_waitcnt lgkmcnt(0)
	v_mfma_f32_16x16x32_bf16 v[84:87], v[128:131], v[56:59], v[124:127]
	v_mfma_f32_16x16x32_bf16 v[124:127], v[132:135], v[64:67], v[84:87]
	v_mfma_f32_16x16x32_bf16 v[84:87], v[146:149], v[56:59], v[120:123]
	v_mfma_f32_16x16x32_bf16 v[120:123], v[150:153], v[64:67], v[84:87]
	v_mfma_f32_16x16x32_bf16 v[84:87], v[128:131], v[154:157], v[116:119]
	v_mfma_f32_16x16x32_bf16 v[116:119], v[132:135], v[158:161], v[84:87]
	v_mfma_f32_16x16x32_bf16 v[84:87], v[146:149], v[154:157], v[112:115]
	v_mfma_f32_16x16x32_bf16 v[112:115], v[150:153], v[158:161], v[84:87]
	v_mfma_f32_16x16x32_bf16 v[84:87], v[128:131], v[170:173], v[108:111]
	v_mfma_f32_16x16x32_bf16 v[108:111], v[132:135], v[180:183], v[84:87]
	v_mfma_f32_16x16x32_bf16 v[84:87], v[146:149], v[170:173], v[104:107]
	v_mfma_f32_16x16x32_bf16 v[104:107], v[150:153], v[180:183], v[84:87]
	v_mfma_f32_16x16x32_bf16 v[84:87], v[128:131], v[184:187], v[100:103]
	v_mfma_f32_16x16x32_bf16 v[92:95], v[132:135], v[188:191], v[84:87]
	v_mfma_f32_16x16x32_bf16 v[84:87], v[146:149], v[184:187], v[96:99]
	v_mfma_f32_16x16x32_bf16 v[84:87], v[150:153], v[188:191], v[84:87]
	s_setprio 0
	s_barrier
; #define LDA(dst, b, h) _Pragma("unroll") for (int m = 0; m < 4; ++m) _Pragma("unroll") for (int k = 0; k < 2; ++k) \
;     dst[m][k] = *reinterpret_cast<const bf16x8*>((const char*)SA(b, h) + lds_byte(wr * 64 + m * 16 + fr, k * 32 + fq * 8))
; #define LDB(dst, b, h) _Pragma("unroll") for (int n = 0; n < 2; ++n) _Pragma("unroll") for (int k = 0; k < 2; ++k) \
;     dst[n][k] = *reinterpret_cast<const bf16x8*>((const char*)SB(b, h) + lds_byte(wc * 32 + n * 16 + fr, k * 32 + fq * 8))
; #define MMA(ai, bj, At_, Bt_) do { __builtin_amdgcn_s_setprio(1); \
;     _Pragma("unroll") for (int m = 0; m < 4; ++m) _Pragma("unroll") for (int n = 0; n < 2; ++n) _Pragma("unroll") for (int k = 0; k < 2; ++k) \
;       acc[ai][bj][m][n] = __builtin_amdgcn_mfma_f32_16x16x32_bf16(Bt_[n][k], At_[m][k], acc[ai][bj][m][n], 0, 0, 0); \
;     __builtin_amdgcn_s_setprio(0); } while (0)
; #define WAIT_V(n) asm volatile("s_waitcnt vmcnt(" #n ")" ::: "memory")
; #define WAIT_L(n) asm volatile("s_waitcnt lgkmcnt(" #n ")" ::: "memory")
; #define BAR __builtin_amdgcn_s_barrier()
; template <bool PF = true, class Epi, class KRF = KRFull>
; __device__ __forceinline__ void gemm_phase(const u16* __restrict__ A, int lda, const u16* __restrict__ Bt, int ldb, int K, int nM, int nN,
;                                            lds_u16* shm, Epi epi, KRF krf = KRFull(), bool flip = false) {
;     ...
;       LDB(B1, 1, 1); WAIT_V(0); BAR; WAIT_L(0); MMA(0, 1, At, B1); BAR;
;       LDA(At, 1, 1); BAR; WAIT_L(0); MMA(1, 0, At, B0); MMA(1, 1, At, B1); BAR; }
;     if (wr == 0) BAR;
	ds_read_b128 v[192:195], v143
	ds_read_b128 v[200:203], v143 offset:1024
	ds_read_b128 v[204:207], v143 offset:2048
	ds_read_b128 v[212:215], v143 offset:3072
	s_waitcnt vmcnt(0)
	s_barrier
	s_waitcnt lgkmcnt(0)
	s_setprio 1
	s_waitcnt lgkmcnt(0)
	v_mfma_f32_16x16x32_bf16 v[96:99], v[192:195], v[56:59], v[208:211]
	v_mfma_f32_16x16x32_bf16 v[56:59], v[204:207], v[56:59], v[88:91]
	v_mfma_f32_16x16x32_bf16 v[100:103], v[200:203], v[64:67], v[96:99]
	v_mfma_f32_16x16x32_bf16 v[96:99], v[212:215], v[64:67], v[56:59]
	v_mfma_f32_16x16x32_bf16 v[56:59], v[192:195], v[154:157], v[162:165]
	v_mfma_f32_16x16x32_bf16 v[88:91], v[200:203], v[158:161], v[56:59]
	v_mfma_f32_16x16x32_bf16 v[56:59], v[204:207], v[154:157], v[80:83]
	v_mfma_f32_16x16x32_bf16 v[80:83], v[212:215], v[158:161], v[56:59]
	v_mfma_f32_16x16x32_bf16 v[56:59], v[192:195], v[170:173], v[76:79]
	v_mfma_f32_16x16x32_bf16 v[76:79], v[200:203], v[180:183], v[56:59]
	v_mfma_f32_16x16x32_bf16 v[56:59], v[204:207], v[170:173], v[72:75]
	v_mfma_f32_16x16x32_bf16 v[72:75], v[212:215], v[180:183], v[56:59]
	v_mfma_f32_16x16x32_bf16 v[56:59], v[192:195], v[184:187], v[68:71]
	v_mfma_f32_16x16x32_bf16 v[64:67], v[200:203], v[188:191], v[56:59]
	v_mfma_f32_16x16x32_bf16 v[56:59], v[204:207], v[184:187], v[166:169]
	v_mfma_f32_16x16x32_bf16 v[56:59], v[212:215], v[188:191], v[56:59]
	s_setprio 0
	s_barrier
	ds_read_b128 v[154:157], v142 offset:49152
	ds_read_b128 v[142:145], v142 offset:50176
	ds_read_b128 v[158:161], v141 offset:49152
	ds_read_b128 v[162:165], v141 offset:50176
	ds_read_b128 v[166:169], v140 offset:49152
	ds_read_b128 v[170:173], v140 offset:50176
	ds_read_b128 v[180:183], v139 offset:49152
	ds_read_b128 v[184:187], v139 offset:50176
	s_barrier
	s_waitcnt lgkmcnt(0)
	s_setprio 1
	s_waitcnt lgkmcnt(0)
	v_mfma_f32_16x16x32_bf16 v[60:63], v[128:131], v[154:157], v[60:63]
	v_mfma_f32_16x16x32_bf16 v[68:71], v[132:135], v[142:145], v[60:63]
	v_mfma_f32_16x16x32_bf16 v[60:63], v[146:149], v[154:157], v[196:199]
	v_mfma_f32_16x16x32_bf16 v[52:55], v[128:131], v[158:161], v[52:55]
	v_mfma_f32_16x16x32_bf16 v[48:51], v[146:149], v[158:161], v[48:51]
	v_mfma_f32_16x16x32_bf16 v[44:47], v[128:131], v[166:169], v[44:47]
	v_mfma_f32_16x16x32_bf16 v[40:43], v[146:149], v[166:169], v[40:43]
	v_mfma_f32_16x16x32_bf16 v[36:39], v[128:131], v[180:183], v[36:39]
	v_mfma_f32_16x16x32_bf16 v[32:35], v[146:149], v[180:183], v[32:35]
	v_mfma_f32_16x16x32_bf16 v[60:63], v[150:153], v[142:145], v[60:63]
	v_mfma_f32_16x16x32_bf16 v[52:55], v[132:135], v[162:165], v[52:55]
	v_mfma_f32_16x16x32_bf16 v[48:51], v[150:153], v[162:165], v[48:51]
	v_mfma_f32_16x16x32_bf16 v[44:47], v[132:135], v[170:173], v[44:47]
	v_mfma_f32_16x16x32_bf16 v[40:43], v[150:153], v[170:173], v[40:43]
	v_mfma_f32_16x16x32_bf16 v[36:39], v[132:135], v[184:187], v[36:39]
	v_mfma_f32_16x16x32_bf16 v[32:35], v[150:153], v[184:187], v[32:35]
	s_setprio 0
	s_setprio 1
	v_mfma_f32_16x16x32_bf16 v[28:31], v[192:195], v[154:157], v[28:31]
	v_mfma_f32_16x16x32_bf16 v[24:27], v[204:207], v[154:157], v[24:27]
	v_mfma_f32_16x16x32_bf16 v[20:23], v[192:195], v[158:161], v[20:23]
	v_mfma_f32_16x16x32_bf16 v[16:19], v[204:207], v[158:161], v[16:19]
	v_mfma_f32_16x16x32_bf16 v[12:15], v[192:195], v[166:169], v[12:15]
	v_mfma_f32_16x16x32_bf16 v[8:11], v[204:207], v[166:169], v[8:11]
	v_mfma_f32_16x16x32_bf16 v[4:7], v[192:195], v[180:183], v[4:7]
	v_mfma_f32_16x16x32_bf16 v[0:3], v[204:207], v[180:183], v[0:3]
	v_mfma_f32_16x16x32_bf16 v[28:31], v[200:203], v[142:145], v[28:31]
	v_mfma_f32_16x16x32_bf16 v[24:27], v[212:215], v[142:145], v[24:27]
	v_mfma_f32_16x16x32_bf16 v[20:23], v[200:203], v[162:165], v[20:23]
	v_mfma_f32_16x16x32_bf16 v[16:19], v[212:215], v[162:165], v[16:19]
	v_mfma_f32_16x16x32_bf16 v[12:15], v[200:203], v[170:173], v[12:15]
	v_mfma_f32_16x16x32_bf16 v[8:11], v[212:215], v[170:173], v[8:11]
	v_mfma_f32_16x16x32_bf16 v[4:7], v[200:203], v[184:187], v[4:7]
	v_mfma_f32_16x16x32_bf16 v[0:3], v[212:215], v[184:187], v[0:3]
	s_setprio 0
	v_cmp_gt_u32_e32 vcc, s95, v138
	s_barrier
	s_and_saveexec_b64 s[16:17], vcc
	s_cbranch_execz .LBB0_2503
	s_barrier

; #define STAGE_A(P, half, kt) do { const char* _u = Ab + ((size_t)(half) * 128 * lda + (size_t)(kt) * BK) * 2; \
;     _Pragma("unroll") for (int _i = 0; _i < 2; ++_i) \
;       __builtin_amdgcn_global_load_lds((const unsigned*)(_u + offA[_i]), \
;         (__attribute__((address_space(3))) unsigned*)((__attribute__((address_space(3))) char*)(P) + tidg * 16 + _i * 8192), 16, 0, 0); } while (0)
; #define STAGE_B(P, half, kt) do { const char* _u = Bb + ((size_t)(half) * 128 * ldb + (size_t)(kt) * BK) * 2; \
;     _Pragma("unroll") for (int _i = 0; _i < 2; ++_i) \
;       __builtin_amdgcn_global_load_lds((const unsigned*)(_u + offB[_i]), \
;         (__attribute__((address_space(3))) unsigned*)((__attribute__((address_space(3))) char*)(P) + tidg * 16 + _i * 8192), 16, 0, 0); } while (0)
; #define LDA(dst, b, h) _Pragma("unroll") for (int m = 0; m < 4; ++m) _Pragma("unroll") for (int k = 0; k < 2; ++k) \
;     dst[m][k] = *reinterpret_cast<const bf16x8*>((const char*)SA(b, h) + lds_byte(wr * 64 + m * 16 + fr, k * 32 + fq * 8))
; #define LDB(dst, b, h) _Pragma("unroll") for (int n = 0; n < 2; ++n) _Pragma("unroll") for (int k = 0; k < 2; ++k) \
;     dst[n][k] = *reinterpret_cast<const bf16x8*>((const char*)SB(b, h) + lds_byte(wc * 32 + n * 16 + fr, k * 32 + fq * 8))
; #define MMA(ai, bj, At_, Bt_) do { __builtin_amdgcn_s_setprio(1); \
;     _Pragma("unroll") for (int m = 0; m < 4; ++m) _Pragma("unroll") for (int n = 0; n < 2; ++n) _Pragma("unroll") for (int k = 0; k < 2; ++k) \
;       acc[ai][bj][m][n] = __builtin_amdgcn_mfma_f32_16x16x32_bf16(Bt_[n][k], At_[m][k], acc[ai][bj][m][n], 0, 0, 0); \
;     __builtin_amdgcn_s_setprio(0); } while (0)
; template <bool PF = true, class Epi, class KRF = KRFull>
; __device__ __forceinline__ void gemm_phase(const u16* __restrict__ A, int lda, const u16* __restrict__ Bt, int ldb, int K, int nM, int nN,
;                                            lds_u16* shm, Epi epi, KRF krf = KRFull(), bool flip = false) {
;     ...
;     for (int t = 0; t < nt - 2; t += 2) {
;       LDB(B0, 0, 0); SCHED; LDA(At, 0, 0); STAGE_A(SA(1, 1), 1, t + 1);
;       WAIT_L(8); BAR; WAIT_L(0); MMA(0, 0, At, B0); BAR; SCHED;
;       LDB(B1, 0, 1); STAGE_B(SB(0, 0), 0, t + 2);
;       BAR; WAIT_L(0); MMA(0, 1, At, B1); BAR;
;       LDA(At, 0, 1); STAGE_A(SA(0, 0), 0, t + 2);
;       BAR; WAIT_L(0); MMA(1, 0, At, B0); BAR; SCHED;
.LBB0_2517:
	v_readfirstlane_b32 s3, v143
	ds_read_b128 v[156:159], v153
	ds_read_b128 v[164:167], v153 offset:1024
	ds_read_b128 v[168:171], v153 offset:2048
	ds_read_b128 v[172:175], v153 offset:3072
	v_add_u32_e32 v154, 0xc000, v143
	v_lshl_add_u64 v[160:161], v[134:135], 0, s[20:21]
	v_add_u32_e32 v155, 0xe000, v143
	v_lshl_add_u64 v[212:213], v[160:161], 0, s[62:63]
	s_add_u32 m0, s3, 0xc000
	v_lshl_add_u64 v[234:235], v[136:137], 0, s[20:21]
	ds_read_b128 v[180:183], v141
	ds_read_b128 v[184:187], v141 offset:1024
	ds_read_b128 v[188:191], v140
	ds_read_b128 v[192:195], v140 offset:1024
	ds_read_b128 v[196:199], v139
	ds_read_b128 v[200:203], v139 offset:1024
	ds_read_b128 v[204:207], v138
	ds_read_b128 v[208:211], v138 offset:1024
	global_load_lds_dwordx4 v[212:213], off
	v_lshl_add_u64 v[212:213], v[234:235], 0, s[62:63]
	s_add_u32 m0, s3, 0xe000
	s_nop 0
	global_load_lds_dwordx4 v[212:213], off
	s_waitcnt lgkmcnt(8)
	s_barrier
	s_waitcnt lgkmcnt(0)
	s_setprio 1
	s_waitcnt lgkmcnt(0)
	v_mfma_f32_16x16x32_bf16 v[124:127], v[156:159], v[180:183], v[124:127]
	v_mfma_f32_16x16x32_bf16 v[120:123], v[168:171], v[180:183], v[120:123]
	v_mfma_f32_16x16x32_bf16 v[116:119], v[156:159], v[188:191], v[116:119]
	v_mfma_f32_16x16x32_bf16 v[112:115], v[168:171], v[188:191], v[112:115]
	v_mfma_f32_16x16x32_bf16 v[108:111], v[156:159], v[196:199], v[108:111]
	v_mfma_f32_16x16x32_bf16 v[104:107], v[168:171], v[196:199], v[104:107]
	v_mfma_f32_16x16x32_bf16 v[100:103], v[156:159], v[204:207], v[100:103]
	v_mfma_f32_16x16x32_bf16 v[96:99], v[168:171], v[204:207], v[96:99]
	v_mfma_f32_16x16x32_bf16 v[124:127], v[164:167], v[184:187], v[124:127]
	v_mfma_f32_16x16x32_bf16 v[120:123], v[172:175], v[184:187], v[120:123]
	v_mfma_f32_16x16x32_bf16 v[116:119], v[164:167], v[192:195], v[116:119]
	v_mfma_f32_16x16x32_bf16 v[112:115], v[172:175], v[192:195], v[112:115]
	v_mfma_f32_16x16x32_bf16 v[108:111], v[164:167], v[200:203], v[108:111]
	v_mfma_f32_16x16x32_bf16 v[104:107], v[172:175], v[200:203], v[104:107]
	v_mfma_f32_16x16x32_bf16 v[100:103], v[164:167], v[208:211], v[100:103]
	v_mfma_f32_16x16x32_bf16 v[96:99], v[172:175], v[208:211], v[96:99]
	s_setprio 0
	s_barrier
	v_add_u32_e32 v163, 0x10000, v143
	v_lshl_add_u64 v[236:237], v[130:131], 0, s[20:21]
	v_lshl_add_u64 v[238:239], v[236:237], 0, s[64:65]
	s_add_u32 m0, s3, 0x10000
	v_add_u32_e32 v163, 0x12000, v143
	ds_read_b128 v[212:215], v152
	ds_read_b128 v[216:219], v152 offset:1024
	ds_read_b128 v[222:225], v152 offset:2048
	ds_read_b128 v[226:229], v152 offset:3072
	global_load_lds_dwordx4 v[238:239], off
	v_lshl_add_u64 v[238:239], v[132:133], 0, s[20:21]
	v_lshl_add_u64 v[240:241], v[238:239], 0, s[64:65]
	s_add_u32 m0, s3, 0x12000
	s_nop 0
	global_load_lds_dwordx4 v[240:241], off
	s_barrier
	s_waitcnt lgkmcnt(0)
	s_setprio 1
	s_waitcnt lgkmcnt(0)
	v_mfma_f32_16x16x32_bf16 v[92:95], v[212:215], v[180:183], v[92:95]
	v_mfma_f32_16x16x32_bf16 v[88:91], v[222:225], v[180:183], v[88:91]
	v_mfma_f32_16x16x32_bf16 v[84:87], v[212:215], v[188:191], v[84:87]
	v_mfma_f32_16x16x32_bf16 v[80:83], v[222:225], v[188:191], v[80:83]
	v_mfma_f32_16x16x32_bf16 v[76:79], v[212:215], v[196:199], v[76:79]
	v_mfma_f32_16x16x32_bf16 v[72:75], v[222:225], v[196:199], v[72:75]
	v_mfma_f32_16x16x32_bf16 v[68:71], v[212:215], v[204:207], v[68:71]
	v_mfma_f32_16x16x32_bf16 v[64:67], v[222:225], v[204:207], v[64:67]
	v_mfma_f32_16x16x32_bf16 v[92:95], v[216:219], v[184:187], v[92:95]
	v_mfma_f32_16x16x32_bf16 v[88:91], v[226:229], v[184:187], v[88:91]
	v_mfma_f32_16x16x32_bf16 v[84:87], v[216:219], v[192:195], v[84:87]
	v_mfma_f32_16x16x32_bf16 v[80:83], v[226:229], v[192:195], v[80:83]
	v_mfma_f32_16x16x32_bf16 v[76:79], v[216:219], v[200:203], v[76:79]
	v_mfma_f32_16x16x32_bf16 v[72:75], v[226:229], v[200:203], v[72:75]
	v_mfma_f32_16x16x32_bf16 v[68:71], v[216:219], v[208:211], v[68:71]
	v_mfma_f32_16x16x32_bf16 v[64:67], v[226:229], v[208:211], v[64:67]
	s_setprio 0
	v_lshl_add_u64 v[240:241], v[160:161], 0, s[64:65]
	s_mov_b32 m0, s3
	s_barrier
	ds_read_b128 v[180:183], v141 offset:16384
	ds_read_b128 v[184:187], v141 offset:17408
	ds_read_b128 v[188:191], v140 offset:16384
	ds_read_b128 v[192:195], v140 offset:17408
	ds_read_b128 v[196:199], v139 offset:16384
	ds_read_b128 v[200:203], v139 offset:17408
	ds_read_b128 v[204:207], v138 offset:16384
	ds_read_b128 v[208:211], v138 offset:17408
	global_load_lds_dwordx4 v[240:241], off
	v_lshl_add_u64 v[240:241], v[234:235], 0, s[64:65]
	s_add_u32 m0, s3, 0x2000
	s_nop 0
	global_load_lds_dwordx4 v[240:241], off
	s_barrier
	s_waitcnt lgkmcnt(0)
	s_setprio 1
	s_waitcnt lgkmcnt(0)
	v_mfma_f32_16x16x32_bf16 v[60:63], v[156:159], v[180:183], v[60:63]
	v_mfma_f32_16x16x32_bf16 v[56:59], v[168:171], v[180:183], v[56:59]
	v_mfma_f32_16x16x32_bf16 v[52:55], v[156:159], v[188:191], v[52:55]
	v_mfma_f32_16x16x32_bf16 v[48:51], v[168:171], v[188:191], v[48:51]
	v_mfma_f32_16x16x32_bf16 v[44:47], v[156:159], v[196:199], v[44:47]
	v_mfma_f32_16x16x32_bf16 v[40:43], v[168:171], v[196:199], v[40:43]
	v_mfma_f32_16x16x32_bf16 v[36:39], v[156:159], v[204:207], v[36:39]
	v_mfma_f32_16x16x32_bf16 v[32:35], v[168:171], v[204:207], v[32:35]
	v_mfma_f32_16x16x32_bf16 v[60:63], v[164:167], v[184:187], v[60:63]
	v_mfma_f32_16x16x32_bf16 v[56:59], v[172:175], v[184:187], v[56:59]
	v_mfma_f32_16x16x32_bf16 v[52:55], v[164:167], v[192:195], v[52:55]
	v_mfma_f32_16x16x32_bf16 v[48:51], v[172:175], v[192:195], v[48:51]
	v_mfma_f32_16x16x32_bf16 v[44:47], v[164:167], v[200:203], v[44:47]
	v_mfma_f32_16x16x32_bf16 v[40:43], v[172:175], v[200:203], v[40:43]
	v_mfma_f32_16x16x32_bf16 v[36:39], v[164:167], v[208:211], v[36:39]
	v_mfma_f32_16x16x32_bf16 v[32:35], v[172:175], v[208:211], v[32:35]
	s_setprio 0
	s_barrier
; #define STAGE_A(P, half, kt) do { const char* _u = Ab + ((size_t)(half) * 128 * lda + (size_t)(kt) * BK) * 2; \
;     _Pragma("unroll") for (int _i = 0; _i < 2; ++_i) \
;       __builtin_amdgcn_global_load_lds((const unsigned*)(_u + offA[_i]), \
;         (__attribute__((address_space(3))) unsigned*)((__attribute__((address_space(3))) char*)(P) + tidg * 16 + _i * 8192), 16, 0, 0); } while (0)
; #define STAGE_B(P, half, kt) do { const char* _u = Bb + ((size_t)(half) * 128 * ldb + (size_t)(kt) * BK) * 2; \
;     _Pragma("unroll") for (int _i = 0; _i < 2; ++_i) \
;       __builtin_amdgcn_global_load_lds((const unsigned*)(_u + offB[_i]), \
;         (__attribute__((address_space(3))) unsigned*)((__attribute__((address_space(3))) char*)(P) + tidg * 16 + _i * 8192), 16, 0, 0); } while (0)
; #define LDA(dst, b, h) _Pragma("unroll") for (int m = 0; m < 4; ++m) _Pragma("unroll") for (int k = 0; k < 2; ++k) \
;     dst[m][k] = *reinterpret_cast<const bf16x8*>((const char*)SA(b, h) + lds_byte(wr * 64 + m * 16 + fr, k * 32 + fq * 8))
; #define LDB(dst, b, h) _Pragma("unroll") for (int n = 0; n < 2; ++n) _Pragma("unroll") for (int k = 0; k < 2; ++k) \
;     dst[n][k] = *reinterpret_cast<const bf16x8*>((const char*)SB(b, h) + lds_byte(wc * 32 + n * 16 + fr, k * 32 + fq * 8))
; #define WAIT_V(n) asm volatile("s_waitcnt vmcnt(" #n ")" ::: "memory")
; #define WAIT_L(n) asm volatile("s_waitcnt lgkmcnt(" #n ")" ::: "memory")
; #define BAR __builtin_amdgcn_s_barrier()
; #define SCHED __builtin_amdgcn_sched_barrier(0)
; template <bool PF = true, class Epi, class KRF = KRFull>
; __device__ __forceinline__ void gemm_phase(const u16* __restrict__ A, int lda, const u16* __restrict__ Bt, int ldb, int K, int nM, int nN,
;                                            lds_u16* shm, Epi epi, KRF krf = KRFull(), bool flip = false) {
;     ...
;       STAGE_B(SB(0, 1), 1, t + 2);
;       WAIT_V(6); BAR; MMA(1, 1, At, B1); BAR;
;       LDB(B0, 1, 0); SCHED; LDA(At, 1, 0); STAGE_A(SA(0, 1), 1, t + 2);
;       WAIT_L(8); BAR; WAIT_L(0); MMA(0, 0, At, B0); BAR; SCHED;
;       LDB(B1, 1, 1); STAGE_B(SB(1, 0), 0, t + 3);
;       BAR; WAIT_L(0); MMA(0, 1, At, B1); BAR;
;       LDA(At, 1, 1); STAGE_A(SA(1, 0), 0, t + 3);
;       BAR; WAIT_L(0); MMA(1, 0, At, B0); BAR; SCHED;
	v_add_u32_e32 v158, 0x14000, v143
	v_lshl_add_u64 v[156:157], v[236:237], 0, s[66:67]
	v_add_u32_e32 v158, 0x16000, v143
	s_add_u32 m0, s3, 0x14000
	s_nop 0
	global_load_lds_dwordx4 v[156:157], off
	v_lshl_add_u64 v[156:157], v[238:239], 0, s[66:67]
	s_add_u32 m0, s3, 0x16000
	s_nop 0
	global_load_lds_dwordx4 v[156:157], off
	s_waitcnt vmcnt(6)
	s_barrier
	s_setprio 1
	v_mfma_f32_16x16x32_bf16 v[28:31], v[212:215], v[180:183], v[28:31]
	v_mfma_f32_16x16x32_bf16 v[24:27], v[222:225], v[180:183], v[24:27]
	v_mfma_f32_16x16x32_bf16 v[20:23], v[212:215], v[188:191], v[20:23]
	v_mfma_f32_16x16x32_bf16 v[16:19], v[222:225], v[188:191], v[16:19]
	v_mfma_f32_16x16x32_bf16 v[12:15], v[212:215], v[196:199], v[12:15]
	v_mfma_f32_16x16x32_bf16 v[8:11], v[222:225], v[196:199], v[8:11]
	v_mfma_f32_16x16x32_bf16 v[4:7], v[212:215], v[204:207], v[4:7]
	v_mfma_f32_16x16x32_bf16 v[0:3], v[222:225], v[204:207], v[0:3]
	v_mfma_f32_16x16x32_bf16 v[28:31], v[216:219], v[184:187], v[28:31]
	v_mfma_f32_16x16x32_bf16 v[24:27], v[226:229], v[184:187], v[24:27]
	v_mfma_f32_16x16x32_bf16 v[20:23], v[216:219], v[192:195], v[20:23]
	v_mfma_f32_16x16x32_bf16 v[16:19], v[226:229], v[192:195], v[16:19]
	v_mfma_f32_16x16x32_bf16 v[12:15], v[216:219], v[200:203], v[12:15]
	v_mfma_f32_16x16x32_bf16 v[8:11], v[226:229], v[200:203], v[8:11]
	v_mfma_f32_16x16x32_bf16 v[4:7], v[216:219], v[208:211], v[4:7]
	v_mfma_f32_16x16x32_bf16 v[0:3], v[226:229], v[208:211], v[0:3]
	s_setprio 0
	s_barrier
	ds_read_b128 v[156:159], v144
	ds_read_b128 v[164:167], v144 offset:1024
	ds_read_b128 v[168:171], v144 offset:2048
	ds_read_b128 v[172:175], v144 offset:3072
	v_add_u32_e32 v163, 0x4000, v143
	v_lshl_add_u64 v[212:213], v[160:161], 0, s[66:67]
	v_add_u32_e32 v163, 0x6000, v143
	s_add_u32 m0, s3, 0x4000
	ds_read_b128 v[180:183], v141 offset:32768
	ds_read_b128 v[184:187], v141 offset:33792
	ds_read_b128 v[188:191], v140 offset:32768
	ds_read_b128 v[192:195], v140 offset:33792
	ds_read_b128 v[196:199], v139 offset:32768
	ds_read_b128 v[200:203], v139 offset:33792
	ds_read_b128 v[204:207], v138 offset:32768
	ds_read_b128 v[208:211], v138 offset:33792
	global_load_lds_dwordx4 v[212:213], off
	v_lshl_add_u64 v[212:213], v[234:235], 0, s[66:67]
	s_add_u32 m0, s3, 0x6000
	s_nop 0
	global_load_lds_dwordx4 v[212:213], off
	s_waitcnt lgkmcnt(8)
	s_barrier
	s_waitcnt lgkmcnt(0)
	s_setprio 1
	s_waitcnt lgkmcnt(0)
	v_mfma_f32_16x16x32_bf16 v[124:127], v[156:159], v[180:183], v[124:127]
	v_mfma_f32_16x16x32_bf16 v[120:123], v[168:171], v[180:183], v[120:123]
	v_mfma_f32_16x16x32_bf16 v[116:119], v[156:159], v[188:191], v[116:119]
	v_mfma_f32_16x16x32_bf16 v[112:115], v[168:171], v[188:191], v[112:115]
	v_mfma_f32_16x16x32_bf16 v[108:111], v[156:159], v[196:199], v[108:111]
	v_mfma_f32_16x16x32_bf16 v[104:107], v[168:171], v[196:199], v[104:107]
	v_mfma_f32_16x16x32_bf16 v[100:103], v[156:159], v[204:207], v[100:103]
	v_mfma_f32_16x16x32_bf16 v[96:99], v[168:171], v[204:207], v[96:99]
	v_mfma_f32_16x16x32_bf16 v[124:127], v[164:167], v[184:187], v[124:127]
	v_mfma_f32_16x16x32_bf16 v[120:123], v[172:175], v[184:187], v[120:123]
	v_mfma_f32_16x16x32_bf16 v[116:119], v[164:167], v[192:195], v[116:119]
	v_mfma_f32_16x16x32_bf16 v[112:115], v[172:175], v[192:195], v[112:115]
	v_mfma_f32_16x16x32_bf16 v[108:111], v[164:167], v[200:203], v[108:111]
	v_mfma_f32_16x16x32_bf16 v[104:107], v[172:175], v[200:203], v[104:107]
	v_mfma_f32_16x16x32_bf16 v[100:103], v[164:167], v[208:211], v[100:103]
	v_mfma_f32_16x16x32_bf16 v[96:99], v[172:175], v[208:211], v[96:99]
	s_setprio 0
	s_barrier
	v_lshl_add_u64 v[240:241], v[236:237], 0, s[68:69]
	s_add_u32 m0, s3, 0x18000
	ds_read_b128 v[212:215], v142
	ds_read_b128 v[216:219], v142 offset:1024
	ds_read_b128 v[222:225], v142 offset:2048
	ds_read_b128 v[226:229], v142 offset:3072
	global_load_lds_dwordx4 v[240:241], off
	v_lshl_add_u64 v[240:241], v[238:239], 0, s[68:69]
	s_add_u32 m0, s3, 0x1a000
	s_nop 0
	global_load_lds_dwordx4 v[240:241], off
	s_barrier
	s_waitcnt lgkmcnt(0)
	s_setprio 1
	s_waitcnt lgkmcnt(0)
	v_mfma_f32_16x16x32_bf16 v[92:95], v[212:215], v[180:183], v[92:95]
	v_mfma_f32_16x16x32_bf16 v[88:91], v[222:225], v[180:183], v[88:91]
	v_mfma_f32_16x16x32_bf16 v[84:87], v[212:215], v[188:191], v[84:87]
	v_mfma_f32_16x16x32_bf16 v[80:83], v[222:225], v[188:191], v[80:83]
	v_mfma_f32_16x16x32_bf16 v[76:79], v[212:215], v[196:199], v[76:79]
	v_mfma_f32_16x16x32_bf16 v[72:75], v[222:225], v[196:199], v[72:75]
	v_mfma_f32_16x16x32_bf16 v[68:71], v[212:215], v[204:207], v[68:71]
	v_mfma_f32_16x16x32_bf16 v[64:67], v[222:225], v[204:207], v[64:67]
	v_mfma_f32_16x16x32_bf16 v[92:95], v[216:219], v[184:187], v[92:95]
	v_mfma_f32_16x16x32_bf16 v[88:91], v[226:229], v[184:187], v[88:91]
	v_mfma_f32_16x16x32_bf16 v[84:87], v[216:219], v[192:195], v[84:87]
	v_mfma_f32_16x16x32_bf16 v[80:83], v[226:229], v[192:195], v[80:83]
	v_mfma_f32_16x16x32_bf16 v[76:79], v[216:219], v[200:203], v[76:79]
	v_mfma_f32_16x16x32_bf16 v[72:75], v[226:229], v[200:203], v[72:75]
	v_mfma_f32_16x16x32_bf16 v[68:71], v[216:219], v[208:211], v[68:71]
	v_mfma_f32_16x16x32_bf16 v[64:67], v[226:229], v[208:211], v[64:67]
	s_setprio 0
	v_lshl_add_u64 v[160:161], v[160:161], 0, s[68:69]
	s_add_u32 m0, s3, 0x8000
	s_barrier
	ds_read_b128 v[180:183], v141 offset:49152
	ds_read_b128 v[184:187], v141 offset:50176
	ds_read_b128 v[188:191], v140 offset:49152
	ds_read_b128 v[192:195], v140 offset:50176
	ds_read_b128 v[196:199], v139 offset:49152
	ds_read_b128 v[200:203], v139 offset:50176
	ds_read_b128 v[204:207], v138 offset:49152
	ds_read_b128 v[208:211], v138 offset:50176
	global_load_lds_dwordx4 v[160:161], off
	v_lshl_add_u64 v[160:161], v[234:235], 0, s[68:69]
	s_add_u32 m0, s3, 0xa000
	s_nop 0
	global_load_lds_dwordx4 v[160:161], off
	s_barrier
; #define STAGE_A(P, half, kt) do { const char* _u = Ab + ((size_t)(half) * 128 * lda + (size_t)(kt) * BK) * 2; \
;     _Pragma("unroll") for (int _i = 0; _i < 2; ++_i) \
;       __builtin_amdgcn_global_load_lds((const unsigned*)(_u + offA[_i]), \
;         (__attribute__((address_space(3))) unsigned*)((__attribute__((address_space(3))) char*)(P) + tidg * 16 + _i * 8192), 16, 0, 0); } while (0)
; #define STAGE_B(P, half, kt) do { const char* _u = Bb + ((size_t)(half) * 128 * ldb + (size_t)(kt) * BK) * 2; \
;     _Pragma("unroll") for (int _i = 0; _i < 2; ++_i) \
;       __builtin_amdgcn_global_load_lds((const unsigned*)(_u + offB[_i]), \
;         (__attribute__((address_space(3))) unsigned*)((__attribute__((address_space(3))) char*)(P) + tidg * 16 + _i * 8192), 16, 0, 0); } while (0)
; #define LDA(dst, b, h) _Pragma("unroll") for (int m = 0; m < 4; ++m) _Pragma("unroll") for (int k = 0; k < 2; ++k) \
;     dst[m][k] = *reinterpret_cast<const bf16x8*>((const char*)SA(b, h) + lds_byte(wr * 64 + m * 16 + fr, k * 32 + fq * 8))
; #define LDB(dst, b, h) _Pragma("unroll") for (int n = 0; n < 2; ++n) _Pragma("unroll") for (int k = 0; k < 2; ++k) \
;     dst[n][k] = *reinterpret_cast<const bf16x8*>((const char*)SB(b, h) + lds_byte(wc * 32 + n * 16 + fr, k * 32 + fq * 8))
; #define MMA(ai, bj, At_, Bt_) do { __builtin_amdgcn_s_setprio(1); \
;     _Pragma("unroll") for (int m = 0; m < 4; ++m) _Pragma("unroll") for (int n = 0; n < 2; ++n) _Pragma("unroll") for (int k = 0; k < 2; ++k) \
;       acc[ai][bj][m][n] = __builtin_amdgcn_mfma_f32_16x16x32_bf16(Bt_[n][k], At_[m][k], acc[ai][bj][m][n], 0, 0, 0); \
;     __builtin_amdgcn_s_setprio(0); } while (0)
; #define WAIT_V(n) asm volatile("s_waitcnt vmcnt(" #n ")" ::: "memory")
; #define WAIT_L(n) asm volatile("s_waitcnt lgkmcnt(" #n ")" ::: "memory")
; template <bool PF = true, class Epi, class KRF = KRFull>
; __device__ __forceinline__ void gemm_phase(const u16* __restrict__ A, int lda, const u16* __restrict__ Bt, int ldb, int K, int nM, int nN,
;                                            lds_u16* shm, Epi epi, KRF krf = KRFull(), bool flip = false) {
;     ...
;       STAGE_B(SB(1, 1), 1, t + 3);
;       WAIT_V(6); BAR; MMA(1, 1, At, B1); BAR;
;     }
;     { LDB(B0, 0, 0); LDA(At, 0, 0); STAGE_A(SA(1, 1), 1, nt - 1);
;       BAR; WAIT_L(0); MMA(0, 0, At, B0); BAR;
;       LDB(B1, 0, 1); BAR; WAIT_L(0); MMA(0, 1, At, B1); BAR;
	s_waitcnt lgkmcnt(0)
	s_setprio 1
	s_waitcnt lgkmcnt(0)
	v_mfma_f32_16x16x32_bf16 v[60:63], v[156:159], v[180:183], v[60:63]
	v_mfma_f32_16x16x32_bf16 v[56:59], v[168:171], v[180:183], v[56:59]
	v_mfma_f32_16x16x32_bf16 v[52:55], v[156:159], v[188:191], v[52:55]
	v_mfma_f32_16x16x32_bf16 v[48:51], v[168:171], v[188:191], v[48:51]
	v_mfma_f32_16x16x32_bf16 v[44:47], v[156:159], v[196:199], v[44:47]
	v_mfma_f32_16x16x32_bf16 v[40:43], v[168:171], v[196:199], v[40:43]
	v_mfma_f32_16x16x32_bf16 v[36:39], v[156:159], v[204:207], v[36:39]
	v_mfma_f32_16x16x32_bf16 v[32:35], v[168:171], v[204:207], v[32:35]
	v_mfma_f32_16x16x32_bf16 v[60:63], v[164:167], v[184:187], v[60:63]
	v_mfma_f32_16x16x32_bf16 v[56:59], v[172:175], v[184:187], v[56:59]
	v_mfma_f32_16x16x32_bf16 v[52:55], v[164:167], v[192:195], v[52:55]
	v_mfma_f32_16x16x32_bf16 v[48:51], v[172:175], v[192:195], v[48:51]
	v_mfma_f32_16x16x32_bf16 v[44:47], v[164:167], v[200:203], v[44:47]
	v_mfma_f32_16x16x32_bf16 v[40:43], v[172:175], v[200:203], v[40:43]
	v_mfma_f32_16x16x32_bf16 v[36:39], v[164:167], v[208:211], v[36:39]
	v_mfma_f32_16x16x32_bf16 v[32:35], v[172:175], v[208:211], v[32:35]
	s_setprio 0
	s_barrier
	v_lshl_add_u64 v[156:157], v[236:237], 0, s[70:71]
	s_add_u32 m0, s3, 0x1c000
	s_nop 0
	global_load_lds_dwordx4 v[156:157], off
	v_lshl_add_u64 v[156:157], v[238:239], 0, s[70:71]
	s_add_u32 m0, s3, 0x1e000
	s_nop 0
	global_load_lds_dwordx4 v[156:157], off
	s_waitcnt vmcnt(6)
	s_barrier
	s_setprio 1
	v_mfma_f32_16x16x32_bf16 v[28:31], v[212:215], v[180:183], v[28:31]
	v_mfma_f32_16x16x32_bf16 v[24:27], v[222:225], v[180:183], v[24:27]
	v_mfma_f32_16x16x32_bf16 v[20:23], v[212:215], v[188:191], v[20:23]
	v_mfma_f32_16x16x32_bf16 v[16:19], v[222:225], v[188:191], v[16:19]
	v_mfma_f32_16x16x32_bf16 v[12:15], v[212:215], v[196:199], v[12:15]
	v_mfma_f32_16x16x32_bf16 v[8:11], v[222:225], v[196:199], v[8:11]
	v_mfma_f32_16x16x32_bf16 v[4:7], v[212:215], v[204:207], v[4:7]
	v_mfma_f32_16x16x32_bf16 v[0:3], v[222:225], v[204:207], v[0:3]
	v_mfma_f32_16x16x32_bf16 v[28:31], v[216:219], v[184:187], v[28:31]
	v_mfma_f32_16x16x32_bf16 v[24:27], v[226:229], v[184:187], v[24:27]
	v_mfma_f32_16x16x32_bf16 v[20:23], v[216:219], v[192:195], v[20:23]
	v_mfma_f32_16x16x32_bf16 v[16:19], v[226:229], v[192:195], v[16:19]
	v_mfma_f32_16x16x32_bf16 v[12:15], v[216:219], v[200:203], v[12:15]
	v_mfma_f32_16x16x32_bf16 v[8:11], v[226:229], v[200:203], v[8:11]
	v_mfma_f32_16x16x32_bf16 v[4:7], v[216:219], v[208:211], v[4:7]
	v_mfma_f32_16x16x32_bf16 v[0:3], v[226:229], v[208:211], v[0:3]
	s_setprio 0
	s_add_i32 s2, s2, 2
	s_add_u32 s20, s20, 0x100
	s_addc_u32 s21, s21, 0
	s_cmp_gt_u32 s2, 27
	s_barrier
	s_cbranch_scc0 .LBB0_2517
	s_add_u32 s2, s12, 0x80f80
	s_addc_u32 s3, s13, 0
	v_readfirstlane_b32 s15, v154
	v_lshl_add_u64 v[150:151], s[2:3], 0, v[178:179]
	s_mov_b32 m0, s15
	v_lshl_add_u64 v[128:129], s[2:3], 0, v[128:129]
	v_readfirstlane_b32 s2, v155
	ds_read_b128 v[130:133], v153
	ds_read_b128 v[134:137], v153 offset:1024
	ds_read_b128 v[146:149], v153 offset:2048
	ds_read_b128 v[156:159], v153 offset:3072
	ds_read_b128 v[164:167], v141
	ds_read_b128 v[168:171], v141 offset:1024
	ds_read_b128 v[172:175], v140
	ds_read_b128 v[180:183], v140 offset:1024
	ds_read_b128 v[184:187], v139
	ds_read_b128 v[188:191], v139 offset:1024
	ds_read_b128 v[192:195], v138
	ds_read_b128 v[196:199], v138 offset:1024
	global_load_lds_dwordx4 v[150:151], off
	s_mov_b32 m0, s2
	s_nop 0
	global_load_lds_dwordx4 v[128:129], off
	s_barrier
	s_waitcnt lgkmcnt(0)
	s_setprio 1
	s_waitcnt lgkmcnt(0)
	v_mfma_f32_16x16x32_bf16 v[124:127], v[130:133], v[164:167], v[124:127]
	v_mfma_f32_16x16x32_bf16 v[120:123], v[146:149], v[164:167], v[120:123]
	v_mfma_f32_16x16x32_bf16 v[116:119], v[130:133], v[172:175], v[116:119]
	v_mfma_f32_16x16x32_bf16 v[112:115], v[146:149], v[172:175], v[112:115]
	v_mfma_f32_16x16x32_bf16 v[100:103], v[130:133], v[192:195], v[100:103]
	v_mfma_f32_16x16x32_bf16 v[96:99], v[146:149], v[192:195], v[96:99]
	v_mfma_f32_16x16x32_bf16 v[124:127], v[134:137], v[168:171], v[124:127]
	v_mfma_f32_16x16x32_bf16 v[120:123], v[156:159], v[168:171], v[120:123]
	v_mfma_f32_16x16x32_bf16 v[116:119], v[134:137], v[180:183], v[116:119]
	v_mfma_f32_16x16x32_bf16 v[112:115], v[156:159], v[180:183], v[112:115]
	v_mfma_f32_16x16x32_bf16 v[108:111], v[130:133], v[184:187], v[108:111]
	v_mfma_f32_16x16x32_bf16 v[104:107], v[146:149], v[184:187], v[104:107]
	v_mfma_f32_16x16x32_bf16 v[100:103], v[134:137], v[196:199], v[100:103]
	v_mfma_f32_16x16x32_bf16 v[96:99], v[156:159], v[196:199], v[96:99]
	v_mfma_f32_16x16x32_bf16 v[200:203], v[134:137], v[188:191], v[108:111]
	v_mfma_f32_16x16x32_bf16 v[204:207], v[156:159], v[188:191], v[104:107]
	s_setprio 0
	s_barrier
	s_nop 1
	ds_read_b128 v[104:107], v152
	ds_read_b128 v[108:111], v152 offset:1024
	ds_read_b128 v[208:211], v152 offset:2048
	ds_read_b128 v[150:153], v152 offset:3072
	s_barrier
	s_waitcnt lgkmcnt(0)
	s_setprio 1
	s_waitcnt lgkmcnt(0)
	v_mfma_f32_16x16x32_bf16 v[84:87], v[104:107], v[172:175], v[84:87]
	v_mfma_f32_16x16x32_bf16 v[80:83], v[208:211], v[172:175], v[80:83]
	v_mfma_f32_16x16x32_bf16 v[68:71], v[104:107], v[192:195], v[68:71]
	v_mfma_f32_16x16x32_bf16 v[64:67], v[208:211], v[192:195], v[64:67]
	v_mfma_f32_16x16x32_bf16 v[92:95], v[104:107], v[164:167], v[92:95]
	v_mfma_f32_16x16x32_bf16 v[88:91], v[208:211], v[164:167], v[88:91]
	v_mfma_f32_16x16x32_bf16 v[84:87], v[108:111], v[180:183], v[84:87]
	v_mfma_f32_16x16x32_bf16 v[80:83], v[150:153], v[180:183], v[80:83]
	v_mfma_f32_16x16x32_bf16 v[76:79], v[104:107], v[184:187], v[76:79]
	v_mfma_f32_16x16x32_bf16 v[72:75], v[208:211], v[184:187], v[72:75]
	v_mfma_f32_16x16x32_bf16 v[68:71], v[108:111], v[196:199], v[68:71]
	v_mfma_f32_16x16x32_bf16 v[64:67], v[150:153], v[196:199], v[64:67]
	v_mfma_f32_16x16x32_bf16 v[212:215], v[108:111], v[168:171], v[92:95]
	v_mfma_f32_16x16x32_bf16 v[164:167], v[150:153], v[168:171], v[88:91]
	v_mfma_f32_16x16x32_bf16 v[168:171], v[108:111], v[188:191], v[76:79]
	v_mfma_f32_16x16x32_bf16 v[172:175], v[150:153], v[188:191], v[72:75]
	s_setprio 0
	s_barrier
; #define LDA(dst, b, h) _Pragma("unroll") for (int m = 0; m < 4; ++m) _Pragma("unroll") for (int k = 0; k < 2; ++k) \
;     dst[m][k] = *reinterpret_cast<const bf16x8*>((const char*)SA(b, h) + lds_byte(wr * 64 + m * 16 + fr, k * 32 + fq * 8))
; #define LDB(dst, b, h) _Pragma("unroll") for (int n = 0; n < 2; ++n) _Pragma("unroll") for (int k = 0; k < 2; ++k) \
;     dst[n][k] = *reinterpret_cast<const bf16x8*>((const char*)SB(b, h) + lds_byte(wc * 32 + n * 16 + fr, k * 32 + fq * 8))
; #define MMA(ai, bj, At_, Bt_) do { __builtin_amdgcn_s_setprio(1); \
;     _Pragma("unroll") for (int m = 0; m < 4; ++m) _Pragma("unroll") for (int n = 0; n < 2; ++n) _Pragma("unroll") for (int k = 0; k < 2; ++k) \
;       acc[ai][bj][m][n] = __builtin_amdgcn_mfma_f32_16x16x32_bf16(Bt_[n][k], At_[m][k], acc[ai][bj][m][n], 0, 0, 0); \
;     __builtin_amdgcn_s_setprio(0); } while (0)
; #define WAIT_V(n) asm volatile("s_waitcnt vmcnt(" #n ")" ::: "memory")
; #define WAIT_L(n) asm volatile("s_waitcnt lgkmcnt(" #n ")" ::: "memory")
; #define BAR __builtin_amdgcn_s_barrier()
; template <bool PF = true, class Epi, class KRF = KRFull>
; __device__ __forceinline__ void gemm_phase(const u16* __restrict__ A, int lda, const u16* __restrict__ Bt, int ldb, int K, int nM, int nN,
;                                            lds_u16* shm, Epi epi, KRF krf = KRFull(), bool flip = false) {
;     ...
;       LDB(B1, 0, 1); BAR; WAIT_L(0); MMA(0, 1, At, B1); BAR;
;       LDA(At, 0, 1); WAIT_V(4); BAR; WAIT_L(0); MMA(1, 0, At, B0); MMA(1, 1, At, B1); BAR; }
;     { LDB(B0, 1, 0); LDA(At, 1, 0); WAIT_V(2); BAR; WAIT_L(0); MMA(0, 0, At, B0); BAR;
	s_nop 0
	ds_read_b128 v[72:75], v141 offset:16384
	ds_read_b128 v[76:79], v141 offset:17408
	ds_read_b128 v[88:91], v140 offset:16384
	ds_read_b128 v[92:95], v140 offset:17408
	ds_read_b128 v[180:183], v139 offset:16384
	ds_read_b128 v[184:187], v139 offset:17408
	ds_read_b128 v[188:191], v138 offset:16384
	ds_read_b128 v[192:195], v138 offset:17408
	s_waitcnt vmcnt(4)
	s_barrier
	s_waitcnt lgkmcnt(0)
	s_setprio 1
	s_waitcnt lgkmcnt(0)
	v_mfma_f32_16x16x32_bf16 v[60:63], v[130:133], v[72:75], v[60:63]
	v_mfma_f32_16x16x32_bf16 v[56:59], v[146:149], v[72:75], v[56:59]
	v_mfma_f32_16x16x32_bf16 v[52:55], v[130:133], v[88:91], v[52:55]
	v_mfma_f32_16x16x32_bf16 v[48:51], v[146:149], v[88:91], v[48:51]
	v_mfma_f32_16x16x32_bf16 v[36:39], v[130:133], v[188:191], v[36:39]
	v_mfma_f32_16x16x32_bf16 v[32:35], v[146:149], v[188:191], v[32:35]
	v_mfma_f32_16x16x32_bf16 v[60:63], v[134:137], v[76:79], v[60:63]
	v_mfma_f32_16x16x32_bf16 v[56:59], v[156:159], v[76:79], v[56:59]
	v_mfma_f32_16x16x32_bf16 v[52:55], v[134:137], v[92:95], v[52:55]
	v_mfma_f32_16x16x32_bf16 v[48:51], v[156:159], v[92:95], v[48:51]
	v_mfma_f32_16x16x32_bf16 v[44:47], v[130:133], v[180:183], v[44:47]
	v_mfma_f32_16x16x32_bf16 v[40:43], v[146:149], v[180:183], v[40:43]
	v_mfma_f32_16x16x32_bf16 v[36:39], v[134:137], v[192:195], v[36:39]
	v_mfma_f32_16x16x32_bf16 v[32:35], v[156:159], v[192:195], v[32:35]
	v_mfma_f32_16x16x32_bf16 v[196:199], v[134:137], v[184:187], v[44:47]
	v_mfma_f32_16x16x32_bf16 v[216:219], v[156:159], v[184:187], v[40:43]
	s_setprio 0
	s_setprio 1
	v_mfma_f32_16x16x32_bf16 v[20:23], v[104:107], v[88:91], v[20:23]
	v_mfma_f32_16x16x32_bf16 v[16:19], v[208:211], v[88:91], v[16:19]
	v_mfma_f32_16x16x32_bf16 v[4:7], v[104:107], v[188:191], v[4:7]
	v_mfma_f32_16x16x32_bf16 v[0:3], v[208:211], v[188:191], v[0:3]
	v_mfma_f32_16x16x32_bf16 v[28:31], v[104:107], v[72:75], v[28:31]
	v_mfma_f32_16x16x32_bf16 v[24:27], v[208:211], v[72:75], v[24:27]
	v_mfma_f32_16x16x32_bf16 v[20:23], v[108:111], v[92:95], v[20:23]
	v_mfma_f32_16x16x32_bf16 v[16:19], v[150:153], v[92:95], v[16:19]
	v_mfma_f32_16x16x32_bf16 v[12:15], v[104:107], v[180:183], v[12:15]
	v_mfma_f32_16x16x32_bf16 v[8:11], v[208:211], v[180:183], v[8:11]
	v_mfma_f32_16x16x32_bf16 v[4:7], v[108:111], v[192:195], v[4:7]
	v_mfma_f32_16x16x32_bf16 v[0:3], v[150:153], v[192:195], v[0:3]
	v_mfma_f32_16x16x32_bf16 v[128:131], v[108:111], v[76:79], v[28:31]
	v_mfma_f32_16x16x32_bf16 v[132:135], v[150:153], v[76:79], v[24:27]
	v_mfma_f32_16x16x32_bf16 v[146:149], v[108:111], v[184:187], v[12:15]
	v_mfma_f32_16x16x32_bf16 v[154:157], v[150:153], v[184:187], v[8:11]
	s_setprio 0
	s_barrier
	s_nop 0
	ds_read_b128 v[8:11], v144
	ds_read_b128 v[12:15], v144 offset:1024
	ds_read_b128 v[150:153], v144 offset:2048
	ds_read_b128 v[158:161], v144 offset:3072
	ds_read_b128 v[24:27], v141 offset:32768
	ds_read_b128 v[28:31], v141 offset:33792
	ds_read_b128 v[40:43], v140 offset:32768
	ds_read_b128 v[44:47], v140 offset:33792
	ds_read_b128 v[180:183], v139 offset:32768
	ds_read_b128 v[184:187], v139 offset:33792
	ds_read_b128 v[188:191], v138 offset:32768
	ds_read_b128 v[192:195], v138 offset:33792
	s_waitcnt vmcnt(2)
	s_barrier
	s_waitcnt lgkmcnt(0)
	s_setprio 1
	s_waitcnt lgkmcnt(0)
	v_mfma_f32_16x16x32_bf16 v[72:75], v[8:11], v[24:27], v[124:127]
	v_mfma_f32_16x16x32_bf16 v[124:127], v[12:15], v[28:31], v[72:75]
	v_mfma_f32_16x16x32_bf16 v[72:75], v[150:153], v[24:27], v[120:123]
	v_mfma_f32_16x16x32_bf16 v[120:123], v[158:161], v[28:31], v[72:75]
	v_mfma_f32_16x16x32_bf16 v[72:75], v[8:11], v[40:43], v[116:119]
	v_mfma_f32_16x16x32_bf16 v[108:111], v[12:15], v[44:47], v[72:75]
	v_mfma_f32_16x16x32_bf16 v[72:75], v[150:153], v[40:43], v[112:115]
	v_mfma_f32_16x16x32_bf16 v[104:107], v[158:161], v[44:47], v[72:75]
	v_mfma_f32_16x16x32_bf16 v[72:75], v[8:11], v[180:183], v[200:203]
	v_mfma_f32_16x16x32_bf16 v[92:95], v[12:15], v[184:187], v[72:75]
	v_mfma_f32_16x16x32_bf16 v[72:75], v[150:153], v[180:183], v[204:207]
	v_mfma_f32_16x16x32_bf16 v[88:91], v[158:161], v[184:187], v[72:75]
	v_mfma_f32_16x16x32_bf16 v[72:75], v[8:11], v[188:191], v[100:103]
	v_mfma_f32_16x16x32_bf16 v[76:79], v[12:15], v[192:195], v[72:75]
	v_mfma_f32_16x16x32_bf16 v[72:75], v[150:153], v[188:191], v[96:99]
	v_mfma_f32_16x16x32_bf16 v[72:75], v[158:161], v[192:195], v[72:75]
	s_setprio 0
	s_barrier
; #define LDA(dst, b, h) _Pragma("unroll") for (int m = 0; m < 4; ++m) _Pragma("unroll") for (int k = 0; k < 2; ++k) \
;     dst[m][k] = *reinterpret_cast<const bf16x8*>((const char*)SA(b, h) + lds_byte(wr * 64 + m * 16 + fr, k * 32 + fq * 8))
; #define LDB(dst, b, h) _Pragma("unroll") for (int n = 0; n < 2; ++n) _Pragma("unroll") for (int k = 0; k < 2; ++k) \
;     dst[n][k] = *reinterpret_cast<const bf16x8*>((const char*)SB(b, h) + lds_byte(wc * 32 + n * 16 + fr, k * 32 + fq * 8))
; #define MMA(ai, bj, At_, Bt_) do { __builtin_amdgcn_s_setprio(1); \
;     _Pragma("unroll") for (int m = 0; m < 4; ++m) _Pragma("unroll") for (int n = 0; n < 2; ++n) _Pragma("unroll") for (int k = 0; k < 2; ++k) \
;       acc[ai][bj][m][n] = __builtin_amdgcn_mfma_f32_16x16x32_bf16(Bt_[n][k], At_[m][k], acc[ai][bj][m][n], 0, 0, 0); \
;     __builtin_amdgcn_s_setprio(0); } while (0)
; #define WAIT_V(n) asm volatile("s_waitcnt vmcnt(" #n ")" ::: "memory")
; #define WAIT_L(n) asm volatile("s_waitcnt lgkmcnt(" #n ")" ::: "memory")
; #define BAR __builtin_amdgcn_s_barrier()
; template <bool PF = true, class Epi, class KRF = KRFull>
; __device__ __forceinline__ void gemm_phase(const u16* __restrict__ A, int lda, const u16* __restrict__ Bt, int ldb, int K, int nM, int nN,
;                                            lds_u16* shm, Epi epi, KRF krf = KRFull(), bool flip = false) {
;     ...
;       LDB(B1, 1, 1); WAIT_V(0); BAR; WAIT_L(0); MMA(0, 1, At, B1); BAR;
;       LDA(At, 1, 1); BAR; WAIT_L(0); MMA(1, 0, At, B0); MMA(1, 1, At, B1); BAR; }
;     if (wr == 0) BAR;
	ds_read_b128 v[200:203], v142
	ds_read_b128 v[204:207], v142 offset:1024
	ds_read_b128 v[208:211], v142 offset:2048
	ds_read_b128 v[142:145], v142 offset:3072
	s_waitcnt vmcnt(0)
	s_barrier
	s_waitcnt lgkmcnt(0)
	s_setprio 1
	s_waitcnt lgkmcnt(0)
	v_mfma_f32_16x16x32_bf16 v[96:99], v[200:203], v[24:27], v[212:215]
	v_mfma_f32_16x16x32_bf16 v[24:27], v[208:211], v[24:27], v[164:167]
	v_mfma_f32_16x16x32_bf16 v[112:115], v[142:145], v[28:31], v[24:27]
	v_mfma_f32_16x16x32_bf16 v[24:27], v[200:203], v[40:43], v[84:87]
	v_mfma_f32_16x16x32_bf16 v[100:103], v[204:207], v[44:47], v[24:27]
	v_mfma_f32_16x16x32_bf16 v[24:27], v[208:211], v[40:43], v[80:83]
	v_mfma_f32_16x16x32_bf16 v[116:119], v[204:207], v[28:31], v[96:99]
	v_mfma_f32_16x16x32_bf16 v[96:99], v[142:145], v[44:47], v[24:27]
	v_mfma_f32_16x16x32_bf16 v[24:27], v[200:203], v[180:183], v[168:171]
	v_mfma_f32_16x16x32_bf16 v[84:87], v[204:207], v[184:187], v[24:27]
	v_mfma_f32_16x16x32_bf16 v[24:27], v[208:211], v[180:183], v[172:175]
	v_mfma_f32_16x16x32_bf16 v[80:83], v[142:145], v[184:187], v[24:27]
	v_mfma_f32_16x16x32_bf16 v[24:27], v[200:203], v[188:191], v[68:71]
	v_mfma_f32_16x16x32_bf16 v[68:71], v[204:207], v[192:195], v[24:27]
	v_mfma_f32_16x16x32_bf16 v[24:27], v[208:211], v[188:191], v[64:67]
	v_mfma_f32_16x16x32_bf16 v[64:67], v[142:145], v[192:195], v[24:27]
	s_setprio 0
	s_barrier
	ds_read_b128 v[164:167], v141 offset:49152
	ds_read_b128 v[168:171], v141 offset:50176
	ds_read_b128 v[172:175], v140 offset:49152
	ds_read_b128 v[180:183], v140 offset:50176
	ds_read_b128 v[184:187], v139 offset:49152
	ds_read_b128 v[188:191], v139 offset:50176
	ds_read_b128 v[192:195], v138 offset:49152
	ds_read_b128 v[136:139], v138 offset:50176
	s_barrier
	s_waitcnt lgkmcnt(0)
	s_setprio 1
	s_waitcnt lgkmcnt(0)
	v_mfma_f32_16x16x32_bf16 v[24:27], v[8:11], v[164:167], v[60:63]
	v_mfma_f32_16x16x32_bf16 v[60:63], v[12:15], v[168:171], v[24:27]
	v_mfma_f32_16x16x32_bf16 v[24:27], v[150:153], v[164:167], v[56:59]
	v_mfma_f32_16x16x32_bf16 v[56:59], v[158:161], v[168:171], v[24:27]
	v_mfma_f32_16x16x32_bf16 v[24:27], v[8:11], v[172:175], v[52:55]
	v_mfma_f32_16x16x32_bf16 v[44:47], v[12:15], v[180:183], v[24:27]
	v_mfma_f32_16x16x32_bf16 v[24:27], v[150:153], v[172:175], v[48:51]
	v_mfma_f32_16x16x32_bf16 v[40:43], v[158:161], v[180:183], v[24:27]
	v_mfma_f32_16x16x32_bf16 v[24:27], v[8:11], v[184:187], v[196:199]
	v_mfma_f32_16x16x32_bf16 v[8:11], v[8:11], v[192:195], v[36:39]
	v_mfma_f32_16x16x32_bf16 v[28:31], v[12:15], v[188:191], v[24:27]
	v_mfma_f32_16x16x32_bf16 v[24:27], v[150:153], v[184:187], v[216:219]
	v_mfma_f32_16x16x32_bf16 v[12:15], v[12:15], v[136:139], v[8:11]
	v_mfma_f32_16x16x32_bf16 v[8:11], v[150:153], v[192:195], v[32:35]
	v_mfma_f32_16x16x32_bf16 v[24:27], v[158:161], v[188:191], v[24:27]
	v_mfma_f32_16x16x32_bf16 v[8:11], v[158:161], v[136:139], v[8:11]
	s_setprio 0
	s_setprio 1
	v_mfma_f32_16x16x32_bf16 v[32:35], v[200:203], v[164:167], v[128:131]
	v_mfma_f32_16x16x32_bf16 v[52:55], v[204:207], v[168:171], v[32:35]
	v_mfma_f32_16x16x32_bf16 v[32:35], v[208:211], v[164:167], v[132:135]
	v_mfma_f32_16x16x32_bf16 v[16:19], v[208:211], v[172:175], v[16:19]
	v_mfma_f32_16x16x32_bf16 v[48:51], v[142:145], v[168:171], v[32:35]
	v_mfma_f32_16x16x32_bf16 v[20:23], v[200:203], v[172:175], v[20:23]
	v_mfma_f32_16x16x32_bf16 v[32:35], v[142:145], v[180:183], v[16:19]
	v_mfma_f32_16x16x32_bf16 v[16:19], v[200:203], v[184:187], v[146:149]
	v_mfma_f32_16x16x32_bf16 v[36:39], v[204:207], v[180:183], v[20:23]
	v_mfma_f32_16x16x32_bf16 v[20:23], v[204:207], v[188:191], v[16:19]
	v_mfma_f32_16x16x32_bf16 v[16:19], v[208:211], v[184:187], v[154:157]
	v_mfma_f32_16x16x32_bf16 v[4:7], v[200:203], v[192:195], v[4:7]
	v_mfma_f32_16x16x32_bf16 v[0:3], v[208:211], v[192:195], v[0:3]
	v_mfma_f32_16x16x32_bf16 v[16:19], v[142:145], v[188:191], v[16:19]
	v_mfma_f32_16x16x32_bf16 v[4:7], v[204:207], v[136:139], v[4:7]
	v_mfma_f32_16x16x32_bf16 v[0:3], v[142:145], v[136:139], v[0:3]
	s_setprio 0
	v_cmp_gt_u32_e32 vcc, s95, v162
	s_barrier
	s_and_saveexec_b64 s[16:17], vcc
	s_cbranch_execz .LBB0_2520
	s_barrier

; #define STAGE_A(P, half, kt) do { const char* _u = Ab + ((size_t)(half) * 128 * lda + (size_t)(kt) * BK) * 2; \
;     _Pragma("unroll") for (int _i = 0; _i < 2; ++_i) \
;       __builtin_amdgcn_global_load_lds((const unsigned*)(_u + offA[_i]), \
;         (__attribute__((address_space(3))) unsigned*)((__attribute__((address_space(3))) char*)(P) + tidg * 16 + _i * 8192), 16, 0, 0); } while (0)
; #define STAGE_B(P, half, kt) do { const char* _u = Bb + ((size_t)(half) * 128 * ldb + (size_t)(kt) * BK) * 2; \
;     _Pragma("unroll") for (int _i = 0; _i < 2; ++_i) \
;       __builtin_amdgcn_global_load_lds((const unsigned*)(_u + offB[_i]), \
;         (__attribute__((address_space(3))) unsigned*)((__attribute__((address_space(3))) char*)(P) + tidg * 16 + _i * 8192), 16, 0, 0); } while (0)
; #define LDA(dst, b, h) _Pragma("unroll") for (int m = 0; m < 4; ++m) _Pragma("unroll") for (int k = 0; k < 2; ++k) \
;     dst[m][k] = *reinterpret_cast<const bf16x8*>((const char*)SA(b, h) + lds_byte(wr * 64 + m * 16 + fr, k * 32 + fq * 8))
; #define LDB(dst, b, h) _Pragma("unroll") for (int n = 0; n < 2; ++n) _Pragma("unroll") for (int k = 0; k < 2; ++k) \
;     dst[n][k] = *reinterpret_cast<const bf16x8*>((const char*)SB(b, h) + lds_byte(wc * 32 + n * 16 + fr, k * 32 + fq * 8))
; #define MMA(ai, bj, At_, Bt_) do { __builtin_amdgcn_s_setprio(1); \
;     _Pragma("unroll") for (int m = 0; m < 4; ++m) _Pragma("unroll") for (int n = 0; n < 2; ++n) _Pragma("unroll") for (int k = 0; k < 2; ++k) \
;       acc[ai][bj][m][n] = __builtin_amdgcn_mfma_f32_16x16x32_bf16(Bt_[n][k], At_[m][k], acc[ai][bj][m][n], 0, 0, 0); \
;     __builtin_amdgcn_s_setprio(0); } while (0)
; template <bool PF = true, class Epi, class KRF = KRFull>
; __device__ __forceinline__ void gemm_phase(const u16* __restrict__ A, int lda, const u16* __restrict__ Bt, int ldb, int K, int nM, int nN,
;                                            lds_u16* shm, Epi epi, KRF krf = KRFull(), bool flip = false) {
;     ...
;     for (int t = 0; t < nt - 2; t += 2) {
;       LDB(B0, 0, 0); SCHED; LDA(At, 0, 0); STAGE_A(SA(1, 1), 1, t + 1);
;       WAIT_L(8); BAR; WAIT_L(0); MMA(0, 0, At, B0); BAR; SCHED;
;       LDB(B1, 0, 1); STAGE_B(SB(0, 0), 0, t + 2);
;       BAR; WAIT_L(0); MMA(0, 1, At, B1); BAR;
;       LDA(At, 0, 1); STAGE_A(SA(0, 0), 0, t + 2);
;       BAR; WAIT_L(0); MMA(1, 0, At, B0); BAR; SCHED;
.LBB0_2535:
	v_readfirstlane_b32 s15, v144
	ds_read_b128 v[158:161], v154
	ds_read_b128 v[162:165], v154 offset:1024
	ds_read_b128 v[166:169], v154 offset:2048
	ds_read_b128 v[170:173], v154 offset:3072
	v_add_u32_e32 v155, 0xc000, v144
	v_lshl_add_u64 v[174:175], v[134:135], 0, s[18:19]
	v_lshl_add_u64 v[156:157], v[174:175], 0, s[62:63]
	s_add_u32 m0, s15, 0xc000
	ds_read_b128 v[180:183], v142
	ds_read_b128 v[184:187], v142 offset:1024
	ds_read_b128 v[188:191], v141
	ds_read_b128 v[192:195], v141 offset:1024
	ds_read_b128 v[196:199], v140
	ds_read_b128 v[200:203], v140 offset:1024
	ds_read_b128 v[204:207], v139
	ds_read_b128 v[208:211], v139 offset:1024
	global_load_lds_dwordx4 v[156:157], off
	v_add_u32_e32 v156, 0xe000, v144
	v_lshl_add_u64 v[234:235], v[136:137], 0, s[18:19]
	v_lshl_add_u64 v[212:213], v[234:235], 0, s[62:63]
	s_add_u32 m0, s15, 0xe000
	s_nop 0
	global_load_lds_dwordx4 v[212:213], off
	s_waitcnt lgkmcnt(8)
	s_barrier
	s_waitcnt lgkmcnt(0)
	s_setprio 1
	s_waitcnt lgkmcnt(0)
	v_mfma_f32_16x16x32_bf16 v[124:127], v[158:161], v[180:183], v[124:127]
	v_mfma_f32_16x16x32_bf16 v[120:123], v[166:169], v[180:183], v[120:123]
	v_mfma_f32_16x16x32_bf16 v[116:119], v[158:161], v[188:191], v[116:119]
	v_mfma_f32_16x16x32_bf16 v[112:115], v[166:169], v[188:191], v[112:115]
	v_mfma_f32_16x16x32_bf16 v[108:111], v[158:161], v[196:199], v[108:111]
	v_mfma_f32_16x16x32_bf16 v[104:107], v[166:169], v[196:199], v[104:107]
	v_mfma_f32_16x16x32_bf16 v[100:103], v[158:161], v[204:207], v[100:103]
	v_mfma_f32_16x16x32_bf16 v[96:99], v[166:169], v[204:207], v[96:99]
	v_mfma_f32_16x16x32_bf16 v[124:127], v[162:165], v[184:187], v[124:127]
	v_mfma_f32_16x16x32_bf16 v[120:123], v[170:173], v[184:187], v[120:123]
	v_mfma_f32_16x16x32_bf16 v[116:119], v[162:165], v[192:195], v[116:119]
	v_mfma_f32_16x16x32_bf16 v[112:115], v[170:173], v[192:195], v[112:115]
	v_mfma_f32_16x16x32_bf16 v[108:111], v[162:165], v[200:203], v[108:111]
	v_mfma_f32_16x16x32_bf16 v[104:107], v[170:173], v[200:203], v[104:107]
	v_mfma_f32_16x16x32_bf16 v[100:103], v[162:165], v[208:211], v[100:103]
	v_mfma_f32_16x16x32_bf16 v[96:99], v[170:173], v[208:211], v[96:99]
	s_setprio 0
	s_barrier
	v_add_u32_e32 v157, 0x10000, v144
	v_lshl_add_u64 v[236:237], v[130:131], 0, s[18:19]
	v_lshl_add_u64 v[238:239], v[236:237], 0, s[64:65]
	s_add_u32 m0, s15, 0x10000
	v_add_u32_e32 v157, 0x12000, v144
	ds_read_b128 v[212:215], v153
	ds_read_b128 v[216:219], v153 offset:1024
	ds_read_b128 v[222:225], v153 offset:2048
	ds_read_b128 v[226:229], v153 offset:3072
	global_load_lds_dwordx4 v[238:239], off
	v_lshl_add_u64 v[238:239], v[132:133], 0, s[18:19]
	v_lshl_add_u64 v[240:241], v[238:239], 0, s[64:65]
	s_add_u32 m0, s15, 0x12000
	s_nop 0
	global_load_lds_dwordx4 v[240:241], off
	s_barrier
	s_waitcnt lgkmcnt(0)
	s_setprio 1
	s_waitcnt lgkmcnt(0)
	v_mfma_f32_16x16x32_bf16 v[92:95], v[212:215], v[180:183], v[92:95]
	v_mfma_f32_16x16x32_bf16 v[88:91], v[222:225], v[180:183], v[88:91]
	v_mfma_f32_16x16x32_bf16 v[84:87], v[212:215], v[188:191], v[84:87]
	v_mfma_f32_16x16x32_bf16 v[80:83], v[222:225], v[188:191], v[80:83]
	v_mfma_f32_16x16x32_bf16 v[76:79], v[212:215], v[196:199], v[76:79]
	v_mfma_f32_16x16x32_bf16 v[72:75], v[222:225], v[196:199], v[72:75]
	v_mfma_f32_16x16x32_bf16 v[68:71], v[212:215], v[204:207], v[68:71]
	v_mfma_f32_16x16x32_bf16 v[64:67], v[222:225], v[204:207], v[64:67]
	v_mfma_f32_16x16x32_bf16 v[92:95], v[216:219], v[184:187], v[92:95]
	v_mfma_f32_16x16x32_bf16 v[88:91], v[226:229], v[184:187], v[88:91]
	v_mfma_f32_16x16x32_bf16 v[84:87], v[216:219], v[192:195], v[84:87]
	v_mfma_f32_16x16x32_bf16 v[80:83], v[226:229], v[192:195], v[80:83]
	v_mfma_f32_16x16x32_bf16 v[76:79], v[216:219], v[200:203], v[76:79]
	v_mfma_f32_16x16x32_bf16 v[72:75], v[226:229], v[200:203], v[72:75]
	v_mfma_f32_16x16x32_bf16 v[68:71], v[216:219], v[208:211], v[68:71]
	v_mfma_f32_16x16x32_bf16 v[64:67], v[226:229], v[208:211], v[64:67]
	s_setprio 0
	v_lshl_add_u64 v[240:241], v[174:175], 0, s[64:65]
	s_mov_b32 m0, s15
	s_barrier
	ds_read_b128 v[180:183], v142 offset:16384
	ds_read_b128 v[184:187], v142 offset:17408
	ds_read_b128 v[188:191], v141 offset:16384
	ds_read_b128 v[192:195], v141 offset:17408
	ds_read_b128 v[196:199], v140 offset:16384
	ds_read_b128 v[200:203], v140 offset:17408
	ds_read_b128 v[204:207], v139 offset:16384
	ds_read_b128 v[208:211], v139 offset:17408
	global_load_lds_dwordx4 v[240:241], off
	v_lshl_add_u64 v[240:241], v[234:235], 0, s[64:65]
	s_add_u32 m0, s15, 0x2000
	s_nop 0
	global_load_lds_dwordx4 v[240:241], off
	s_barrier
	s_waitcnt lgkmcnt(0)
	s_setprio 1
	s_waitcnt lgkmcnt(0)
	v_mfma_f32_16x16x32_bf16 v[60:63], v[158:161], v[180:183], v[60:63]
	v_mfma_f32_16x16x32_bf16 v[56:59], v[166:169], v[180:183], v[56:59]
	v_mfma_f32_16x16x32_bf16 v[52:55], v[158:161], v[188:191], v[52:55]
	v_mfma_f32_16x16x32_bf16 v[48:51], v[166:169], v[188:191], v[48:51]
	v_mfma_f32_16x16x32_bf16 v[44:47], v[158:161], v[196:199], v[44:47]
	v_mfma_f32_16x16x32_bf16 v[40:43], v[166:169], v[196:199], v[40:43]
	v_mfma_f32_16x16x32_bf16 v[36:39], v[158:161], v[204:207], v[36:39]
	v_mfma_f32_16x16x32_bf16 v[32:35], v[166:169], v[204:207], v[32:35]
	v_mfma_f32_16x16x32_bf16 v[60:63], v[162:165], v[184:187], v[60:63]
	v_mfma_f32_16x16x32_bf16 v[56:59], v[170:173], v[184:187], v[56:59]
	v_mfma_f32_16x16x32_bf16 v[52:55], v[162:165], v[192:195], v[52:55]
	v_mfma_f32_16x16x32_bf16 v[48:51], v[170:173], v[192:195], v[48:51]
	v_mfma_f32_16x16x32_bf16 v[44:47], v[162:165], v[200:203], v[44:47]
	v_mfma_f32_16x16x32_bf16 v[40:43], v[170:173], v[200:203], v[40:43]
	v_mfma_f32_16x16x32_bf16 v[36:39], v[162:165], v[208:211], v[36:39]
	v_mfma_f32_16x16x32_bf16 v[32:35], v[170:173], v[208:211], v[32:35]
	s_setprio 0
	s_barrier
; #define STAGE_A(P, half, kt) do { const char* _u = Ab + ((size_t)(half) * 128 * lda + (size_t)(kt) * BK) * 2; \
;     _Pragma("unroll") for (int _i = 0; _i < 2; ++_i) \
;       __builtin_amdgcn_global_load_lds((const unsigned*)(_u + offA[_i]), \
;         (__attribute__((address_space(3))) unsigned*)((__attribute__((address_space(3))) char*)(P) + tidg * 16 + _i * 8192), 16, 0, 0); } while (0)
; #define STAGE_B(P, half, kt) do { const char* _u = Bb + ((size_t)(half) * 128 * ldb + (size_t)(kt) * BK) * 2; \
;     _Pragma("unroll") for (int _i = 0; _i < 2; ++_i) \
;       __builtin_amdgcn_global_load_lds((const unsigned*)(_u + offB[_i]), \
;         (__attribute__((address_space(3))) unsigned*)((__attribute__((address_space(3))) char*)(P) + tidg * 16 + _i * 8192), 16, 0, 0); } while (0)
; #define LDA(dst, b, h) _Pragma("unroll") for (int m = 0; m < 4; ++m) _Pragma("unroll") for (int k = 0; k < 2; ++k) \
;     dst[m][k] = *reinterpret_cast<const bf16x8*>((const char*)SA(b, h) + lds_byte(wr * 64 + m * 16 + fr, k * 32 + fq * 8))
; #define LDB(dst, b, h) _Pragma("unroll") for (int n = 0; n < 2; ++n) _Pragma("unroll") for (int k = 0; k < 2; ++k) \
;     dst[n][k] = *reinterpret_cast<const bf16x8*>((const char*)SB(b, h) + lds_byte(wc * 32 + n * 16 + fr, k * 32 + fq * 8))
; #define WAIT_V(n) asm volatile("s_waitcnt vmcnt(" #n ")" ::: "memory")
; #define WAIT_L(n) asm volatile("s_waitcnt lgkmcnt(" #n ")" ::: "memory")
; #define BAR __builtin_amdgcn_s_barrier()
; #define SCHED __builtin_amdgcn_sched_barrier(0)
; template <bool PF = true, class Epi, class KRF = KRFull>
; __device__ __forceinline__ void gemm_phase(const u16* __restrict__ A, int lda, const u16* __restrict__ Bt, int ldb, int K, int nM, int nN,
;                                            lds_u16* shm, Epi epi, KRF krf = KRFull(), bool flip = false) {
;     ...
;       STAGE_B(SB(0, 1), 1, t + 2);
;       WAIT_V(6); BAR; MMA(1, 1, At, B1); BAR;
;       LDB(B0, 1, 0); SCHED; LDA(At, 1, 0); STAGE_A(SA(0, 1), 1, t + 2);
;       WAIT_L(8); BAR; WAIT_L(0); MMA(0, 0, At, B0); BAR; SCHED;
;       LDB(B1, 1, 1); STAGE_B(SB(1, 0), 0, t + 3);
;       BAR; WAIT_L(0); MMA(0, 1, At, B1); BAR;
;       LDA(At, 1, 1); STAGE_A(SA(1, 0), 0, t + 3);
;       BAR; WAIT_L(0); MMA(1, 0, At, B0); BAR; SCHED;
	v_add_u32_e32 v157, 0x14000, v144
	v_lshl_add_u64 v[158:159], v[236:237], 0, s[66:67]
	v_add_u32_e32 v157, 0x16000, v144
	s_add_u32 m0, s15, 0x14000
	s_nop 0
	global_load_lds_dwordx4 v[158:159], off
	v_lshl_add_u64 v[158:159], v[238:239], 0, s[66:67]
	s_add_u32 m0, s15, 0x16000
	s_nop 0
	global_load_lds_dwordx4 v[158:159], off
	s_waitcnt vmcnt(6)
	s_barrier
	s_setprio 1
	v_mfma_f32_16x16x32_bf16 v[28:31], v[212:215], v[180:183], v[28:31]
	v_mfma_f32_16x16x32_bf16 v[24:27], v[222:225], v[180:183], v[24:27]
	v_mfma_f32_16x16x32_bf16 v[20:23], v[212:215], v[188:191], v[20:23]
	v_mfma_f32_16x16x32_bf16 v[16:19], v[222:225], v[188:191], v[16:19]
	v_mfma_f32_16x16x32_bf16 v[12:15], v[212:215], v[196:199], v[12:15]
	v_mfma_f32_16x16x32_bf16 v[8:11], v[222:225], v[196:199], v[8:11]
	v_mfma_f32_16x16x32_bf16 v[4:7], v[212:215], v[204:207], v[4:7]
	v_mfma_f32_16x16x32_bf16 v[0:3], v[222:225], v[204:207], v[0:3]
	v_mfma_f32_16x16x32_bf16 v[28:31], v[216:219], v[184:187], v[28:31]
	v_mfma_f32_16x16x32_bf16 v[24:27], v[226:229], v[184:187], v[24:27]
	v_mfma_f32_16x16x32_bf16 v[20:23], v[216:219], v[192:195], v[20:23]
	v_mfma_f32_16x16x32_bf16 v[16:19], v[226:229], v[192:195], v[16:19]
	v_mfma_f32_16x16x32_bf16 v[12:15], v[216:219], v[200:203], v[12:15]
	v_mfma_f32_16x16x32_bf16 v[8:11], v[226:229], v[200:203], v[8:11]
	v_mfma_f32_16x16x32_bf16 v[4:7], v[216:219], v[208:211], v[4:7]
	v_mfma_f32_16x16x32_bf16 v[0:3], v[226:229], v[208:211], v[0:3]
	s_setprio 0
	s_barrier
	ds_read_b128 v[158:161], v145
	ds_read_b128 v[162:165], v145 offset:1024
	ds_read_b128 v[166:169], v145 offset:2048
	ds_read_b128 v[170:173], v145 offset:3072
	v_add_u32_e32 v157, 0x4000, v144
	v_lshl_add_u64 v[212:213], v[174:175], 0, s[66:67]
	v_add_u32_e32 v157, 0x6000, v144
	s_add_u32 m0, s15, 0x4000
	ds_read_b128 v[180:183], v142 offset:32768
	ds_read_b128 v[184:187], v142 offset:33792
	ds_read_b128 v[188:191], v141 offset:32768
	ds_read_b128 v[192:195], v141 offset:33792
	ds_read_b128 v[196:199], v140 offset:32768
	ds_read_b128 v[200:203], v140 offset:33792
	ds_read_b128 v[204:207], v139 offset:32768
	ds_read_b128 v[208:211], v139 offset:33792
	global_load_lds_dwordx4 v[212:213], off
	v_lshl_add_u64 v[212:213], v[234:235], 0, s[66:67]
	s_add_u32 m0, s15, 0x6000
	s_nop 0
	global_load_lds_dwordx4 v[212:213], off
	s_waitcnt lgkmcnt(8)
	s_barrier
	s_waitcnt lgkmcnt(0)
	s_setprio 1
	s_waitcnt lgkmcnt(0)
	v_mfma_f32_16x16x32_bf16 v[124:127], v[158:161], v[180:183], v[124:127]
	v_mfma_f32_16x16x32_bf16 v[120:123], v[166:169], v[180:183], v[120:123]
	v_mfma_f32_16x16x32_bf16 v[116:119], v[158:161], v[188:191], v[116:119]
	v_mfma_f32_16x16x32_bf16 v[112:115], v[166:169], v[188:191], v[112:115]
	v_mfma_f32_16x16x32_bf16 v[108:111], v[158:161], v[196:199], v[108:111]
	v_mfma_f32_16x16x32_bf16 v[104:107], v[166:169], v[196:199], v[104:107]
	v_mfma_f32_16x16x32_bf16 v[100:103], v[158:161], v[204:207], v[100:103]
	v_mfma_f32_16x16x32_bf16 v[96:99], v[166:169], v[204:207], v[96:99]
	v_mfma_f32_16x16x32_bf16 v[124:127], v[162:165], v[184:187], v[124:127]
	v_mfma_f32_16x16x32_bf16 v[120:123], v[170:173], v[184:187], v[120:123]
	v_mfma_f32_16x16x32_bf16 v[116:119], v[162:165], v[192:195], v[116:119]
	v_mfma_f32_16x16x32_bf16 v[112:115], v[170:173], v[192:195], v[112:115]
	v_mfma_f32_16x16x32_bf16 v[108:111], v[162:165], v[200:203], v[108:111]
	v_mfma_f32_16x16x32_bf16 v[104:107], v[170:173], v[200:203], v[104:107]
	v_mfma_f32_16x16x32_bf16 v[100:103], v[162:165], v[208:211], v[100:103]
	v_mfma_f32_16x16x32_bf16 v[96:99], v[170:173], v[208:211], v[96:99]
	s_setprio 0
	s_barrier
	v_lshl_add_u64 v[240:241], v[236:237], 0, s[68:69]
	s_add_u32 m0, s15, 0x18000
	ds_read_b128 v[212:215], v143
	ds_read_b128 v[216:219], v143 offset:1024
	ds_read_b128 v[222:225], v143 offset:2048
	ds_read_b128 v[226:229], v143 offset:3072
	global_load_lds_dwordx4 v[240:241], off
	v_lshl_add_u64 v[240:241], v[238:239], 0, s[68:69]
	s_add_u32 m0, s15, 0x1a000
	s_nop 0
	global_load_lds_dwordx4 v[240:241], off
	s_barrier
	s_waitcnt lgkmcnt(0)
	s_setprio 1
	s_waitcnt lgkmcnt(0)
	v_mfma_f32_16x16x32_bf16 v[92:95], v[212:215], v[180:183], v[92:95]
	v_mfma_f32_16x16x32_bf16 v[88:91], v[222:225], v[180:183], v[88:91]
	v_mfma_f32_16x16x32_bf16 v[84:87], v[212:215], v[188:191], v[84:87]
	v_mfma_f32_16x16x32_bf16 v[80:83], v[222:225], v[188:191], v[80:83]
	v_mfma_f32_16x16x32_bf16 v[76:79], v[212:215], v[196:199], v[76:79]
	v_mfma_f32_16x16x32_bf16 v[72:75], v[222:225], v[196:199], v[72:75]
	v_mfma_f32_16x16x32_bf16 v[68:71], v[212:215], v[204:207], v[68:71]
	v_mfma_f32_16x16x32_bf16 v[64:67], v[222:225], v[204:207], v[64:67]
	v_mfma_f32_16x16x32_bf16 v[92:95], v[216:219], v[184:187], v[92:95]
	v_mfma_f32_16x16x32_bf16 v[88:91], v[226:229], v[184:187], v[88:91]
	v_mfma_f32_16x16x32_bf16 v[84:87], v[216:219], v[192:195], v[84:87]
	v_mfma_f32_16x16x32_bf16 v[80:83], v[226:229], v[192:195], v[80:83]
	v_mfma_f32_16x16x32_bf16 v[76:79], v[216:219], v[200:203], v[76:79]
	v_mfma_f32_16x16x32_bf16 v[72:75], v[226:229], v[200:203], v[72:75]
	v_mfma_f32_16x16x32_bf16 v[68:71], v[216:219], v[208:211], v[68:71]
	v_mfma_f32_16x16x32_bf16 v[64:67], v[226:229], v[208:211], v[64:67]
	s_setprio 0
	v_lshl_add_u64 v[174:175], v[174:175], 0, s[68:69]
	s_add_u32 m0, s15, 0x8000
	s_barrier
	ds_read_b128 v[180:183], v142 offset:49152
	ds_read_b128 v[184:187], v142 offset:50176
	ds_read_b128 v[188:191], v141 offset:49152
	ds_read_b128 v[192:195], v141 offset:50176
	ds_read_b128 v[196:199], v140 offset:49152
	ds_read_b128 v[200:203], v140 offset:50176
	ds_read_b128 v[204:207], v139 offset:49152
	ds_read_b128 v[208:211], v139 offset:50176
	global_load_lds_dwordx4 v[174:175], off
	v_lshl_add_u64 v[174:175], v[234:235], 0, s[68:69]
	s_add_u32 m0, s15, 0xa000
	s_nop 0
	global_load_lds_dwordx4 v[174:175], off
	s_barrier
; #define STAGE_A(P, half, kt) do { const char* _u = Ab + ((size_t)(half) * 128 * lda + (size_t)(kt) * BK) * 2; \
;     _Pragma("unroll") for (int _i = 0; _i < 2; ++_i) \
;       __builtin_amdgcn_global_load_lds((const unsigned*)(_u + offA[_i]), \
;         (__attribute__((address_space(3))) unsigned*)((__attribute__((address_space(3))) char*)(P) + tidg * 16 + _i * 8192), 16, 0, 0); } while (0)
; #define STAGE_B(P, half, kt) do { const char* _u = Bb + ((size_t)(half) * 128 * ldb + (size_t)(kt) * BK) * 2; \
;     _Pragma("unroll") for (int _i = 0; _i < 2; ++_i) \
;       __builtin_amdgcn_global_load_lds((const unsigned*)(_u + offB[_i]), \
;         (__attribute__((address_space(3))) unsigned*)((__attribute__((address_space(3))) char*)(P) + tidg * 16 + _i * 8192), 16, 0, 0); } while (0)
; #define LDA(dst, b, h) _Pragma("unroll") for (int m = 0; m < 4; ++m) _Pragma("unroll") for (int k = 0; k < 2; ++k) \
;     dst[m][k] = *reinterpret_cast<const bf16x8*>((const char*)SA(b, h) + lds_byte(wr * 64 + m * 16 + fr, k * 32 + fq * 8))
; #define LDB(dst, b, h) _Pragma("unroll") for (int n = 0; n < 2; ++n) _Pragma("unroll") for (int k = 0; k < 2; ++k) \
;     dst[n][k] = *reinterpret_cast<const bf16x8*>((const char*)SB(b, h) + lds_byte(wc * 32 + n * 16 + fr, k * 32 + fq * 8))
; #define MMA(ai, bj, At_, Bt_) do { __builtin_amdgcn_s_setprio(1); \
;     _Pragma("unroll") for (int m = 0; m < 4; ++m) _Pragma("unroll") for (int n = 0; n < 2; ++n) _Pragma("unroll") for (int k = 0; k < 2; ++k) \
;       acc[ai][bj][m][n] = __builtin_amdgcn_mfma_f32_16x16x32_bf16(Bt_[n][k], At_[m][k], acc[ai][bj][m][n], 0, 0, 0); \
;     __builtin_amdgcn_s_setprio(0); } while (0)
; #define WAIT_V(n) asm volatile("s_waitcnt vmcnt(" #n ")" ::: "memory")
; #define WAIT_L(n) asm volatile("s_waitcnt lgkmcnt(" #n ")" ::: "memory")
; template <bool PF = true, class Epi, class KRF = KRFull>
; __device__ __forceinline__ void gemm_phase(const u16* __restrict__ A, int lda, const u16* __restrict__ Bt, int ldb, int K, int nM, int nN,
;                                            lds_u16* shm, Epi epi, KRF krf = KRFull(), bool flip = false) {
;     ...
;       STAGE_B(SB(1, 1), 1, t + 3);
;       WAIT_V(6); BAR; MMA(1, 1, At, B1); BAR;
;     }
;     { LDB(B0, 0, 0); LDA(At, 0, 0); STAGE_A(SA(1, 1), 1, nt - 1);
;       BAR; WAIT_L(0); MMA(0, 0, At, B0); BAR;
;       LDB(B1, 0, 1); BAR; WAIT_L(0); MMA(0, 1, At, B1); BAR;
	s_waitcnt lgkmcnt(0)
	s_setprio 1
	s_waitcnt lgkmcnt(0)
	v_mfma_f32_16x16x32_bf16 v[60:63], v[158:161], v[180:183], v[60:63]
	v_mfma_f32_16x16x32_bf16 v[56:59], v[166:169], v[180:183], v[56:59]
	v_mfma_f32_16x16x32_bf16 v[52:55], v[158:161], v[188:191], v[52:55]
	v_mfma_f32_16x16x32_bf16 v[48:51], v[166:169], v[188:191], v[48:51]
	v_mfma_f32_16x16x32_bf16 v[44:47], v[158:161], v[196:199], v[44:47]
	v_mfma_f32_16x16x32_bf16 v[40:43], v[166:169], v[196:199], v[40:43]
	v_mfma_f32_16x16x32_bf16 v[36:39], v[158:161], v[204:207], v[36:39]
	v_mfma_f32_16x16x32_bf16 v[32:35], v[166:169], v[204:207], v[32:35]
	v_mfma_f32_16x16x32_bf16 v[60:63], v[162:165], v[184:187], v[60:63]
	v_mfma_f32_16x16x32_bf16 v[56:59], v[170:173], v[184:187], v[56:59]
	v_mfma_f32_16x16x32_bf16 v[52:55], v[162:165], v[192:195], v[52:55]
	v_mfma_f32_16x16x32_bf16 v[48:51], v[170:173], v[192:195], v[48:51]
	v_mfma_f32_16x16x32_bf16 v[44:47], v[162:165], v[200:203], v[44:47]
	v_mfma_f32_16x16x32_bf16 v[40:43], v[170:173], v[200:203], v[40:43]
	v_mfma_f32_16x16x32_bf16 v[36:39], v[162:165], v[208:211], v[36:39]
	v_mfma_f32_16x16x32_bf16 v[32:35], v[170:173], v[208:211], v[32:35]
	s_setprio 0
	s_barrier
	v_lshl_add_u64 v[158:159], v[236:237], 0, s[70:71]
	s_add_u32 m0, s15, 0x1c000
	s_nop 0
	global_load_lds_dwordx4 v[158:159], off
	v_lshl_add_u64 v[158:159], v[238:239], 0, s[70:71]
	s_add_u32 m0, s15, 0x1e000
	s_nop 0
	global_load_lds_dwordx4 v[158:159], off
	s_waitcnt vmcnt(6)
	s_barrier
	s_setprio 1
	v_mfma_f32_16x16x32_bf16 v[28:31], v[212:215], v[180:183], v[28:31]
	v_mfma_f32_16x16x32_bf16 v[24:27], v[222:225], v[180:183], v[24:27]
	v_mfma_f32_16x16x32_bf16 v[20:23], v[212:215], v[188:191], v[20:23]
	v_mfma_f32_16x16x32_bf16 v[16:19], v[222:225], v[188:191], v[16:19]
	v_mfma_f32_16x16x32_bf16 v[12:15], v[212:215], v[196:199], v[12:15]
	v_mfma_f32_16x16x32_bf16 v[8:11], v[222:225], v[196:199], v[8:11]
	v_mfma_f32_16x16x32_bf16 v[4:7], v[212:215], v[204:207], v[4:7]
	v_mfma_f32_16x16x32_bf16 v[0:3], v[222:225], v[204:207], v[0:3]
	v_mfma_f32_16x16x32_bf16 v[28:31], v[216:219], v[184:187], v[28:31]
	v_mfma_f32_16x16x32_bf16 v[24:27], v[226:229], v[184:187], v[24:27]
	v_mfma_f32_16x16x32_bf16 v[20:23], v[216:219], v[192:195], v[20:23]
	v_mfma_f32_16x16x32_bf16 v[16:19], v[226:229], v[192:195], v[16:19]
	v_mfma_f32_16x16x32_bf16 v[12:15], v[216:219], v[200:203], v[12:15]
	v_mfma_f32_16x16x32_bf16 v[8:11], v[226:229], v[200:203], v[8:11]
	v_mfma_f32_16x16x32_bf16 v[4:7], v[216:219], v[208:211], v[4:7]
	v_mfma_f32_16x16x32_bf16 v[0:3], v[226:229], v[208:211], v[0:3]
	s_setprio 0
	s_add_i32 s13, s13, 2
	s_add_u32 s18, s18, 0x100
	s_addc_u32 s19, s19, 0
	s_cmp_gt_u32 s13, 27
	s_barrier
	s_cbranch_scc0 .LBB0_2535
	s_add_u32 s16, s6, 0x80f80
	s_addc_u32 s17, s7, 0
	v_readfirstlane_b32 s13, v155
	v_lshl_add_u64 v[150:151], s[16:17], 0, v[178:179]
	s_mov_b32 m0, s13
	v_readfirstlane_b32 s13, v156
	ds_read_b128 v[130:133], v154
	ds_read_b128 v[134:137], v154 offset:1024
	ds_read_b128 v[146:149], v154 offset:2048
	ds_read_b128 v[158:161], v154 offset:3072
	ds_read_b128 v[162:165], v142
	ds_read_b128 v[166:169], v142 offset:1024
	ds_read_b128 v[170:173], v141
	ds_read_b128 v[180:183], v141 offset:1024
	ds_read_b128 v[184:187], v140
	ds_read_b128 v[188:191], v140 offset:1024
	ds_read_b128 v[192:195], v139
	ds_read_b128 v[196:199], v139 offset:1024
	global_load_lds_dwordx4 v[150:151], off
	v_lshl_add_u64 v[128:129], s[16:17], 0, v[128:129]
	s_mov_b32 m0, s13
	s_nop 0
	global_load_lds_dwordx4 v[128:129], off
	s_barrier
	s_waitcnt lgkmcnt(0)
	s_setprio 1
	s_waitcnt lgkmcnt(0)
	v_mfma_f32_16x16x32_bf16 v[124:127], v[130:133], v[162:165], v[124:127]
	v_mfma_f32_16x16x32_bf16 v[120:123], v[146:149], v[162:165], v[120:123]
	v_mfma_f32_16x16x32_bf16 v[116:119], v[130:133], v[170:173], v[116:119]
	v_mfma_f32_16x16x32_bf16 v[112:115], v[146:149], v[170:173], v[112:115]
	v_mfma_f32_16x16x32_bf16 v[108:111], v[130:133], v[184:187], v[108:111]
	v_mfma_f32_16x16x32_bf16 v[104:107], v[146:149], v[184:187], v[104:107]
	v_mfma_f32_16x16x32_bf16 v[100:103], v[130:133], v[192:195], v[100:103]
	v_mfma_f32_16x16x32_bf16 v[96:99], v[146:149], v[192:195], v[96:99]
	v_mfma_f32_16x16x32_bf16 v[124:127], v[134:137], v[166:169], v[124:127]
	v_mfma_f32_16x16x32_bf16 v[120:123], v[158:161], v[166:169], v[120:123]
	v_mfma_f32_16x16x32_bf16 v[116:119], v[134:137], v[180:183], v[116:119]
	v_mfma_f32_16x16x32_bf16 v[112:115], v[158:161], v[180:183], v[112:115]
	v_mfma_f32_16x16x32_bf16 v[108:111], v[134:137], v[188:191], v[108:111]
	v_mfma_f32_16x16x32_bf16 v[104:107], v[158:161], v[188:191], v[104:107]
	v_mfma_f32_16x16x32_bf16 v[100:103], v[134:137], v[196:199], v[100:103]
	v_mfma_f32_16x16x32_bf16 v[96:99], v[158:161], v[196:199], v[96:99]
	s_setprio 0
	s_barrier
	ds_read_b128 v[154:157], v153
	ds_read_b128 v[200:203], v153 offset:1024
	ds_read_b128 v[204:207], v153 offset:2048
	ds_read_b128 v[150:153], v153 offset:3072
	s_barrier
	s_waitcnt lgkmcnt(0)
	s_setprio 1
	s_waitcnt lgkmcnt(0)
	v_mfma_f32_16x16x32_bf16 v[92:95], v[154:157], v[162:165], v[92:95]
	v_mfma_f32_16x16x32_bf16 v[88:91], v[204:207], v[162:165], v[88:91]
	v_mfma_f32_16x16x32_bf16 v[84:87], v[154:157], v[170:173], v[84:87]
	v_mfma_f32_16x16x32_bf16 v[80:83], v[204:207], v[170:173], v[80:83]
	v_mfma_f32_16x16x32_bf16 v[76:79], v[154:157], v[184:187], v[76:79]
	v_mfma_f32_16x16x32_bf16 v[72:75], v[204:207], v[184:187], v[72:75]
	v_mfma_f32_16x16x32_bf16 v[68:71], v[154:157], v[192:195], v[68:71]
	v_mfma_f32_16x16x32_bf16 v[64:67], v[204:207], v[192:195], v[64:67]
	v_mfma_f32_16x16x32_bf16 v[92:95], v[200:203], v[166:169], v[92:95]
	v_mfma_f32_16x16x32_bf16 v[88:91], v[150:153], v[166:169], v[88:91]
	v_mfma_f32_16x16x32_bf16 v[84:87], v[200:203], v[180:183], v[84:87]
	v_mfma_f32_16x16x32_bf16 v[80:83], v[150:153], v[180:183], v[80:83]
	v_mfma_f32_16x16x32_bf16 v[76:79], v[200:203], v[188:191], v[76:79]
	v_mfma_f32_16x16x32_bf16 v[72:75], v[150:153], v[188:191], v[72:75]
	v_mfma_f32_16x16x32_bf16 v[68:71], v[200:203], v[196:199], v[68:71]
	v_mfma_f32_16x16x32_bf16 v[64:67], v[150:153], v[196:199], v[64:67]
	s_setprio 0
	s_barrier
; #define LDA(dst, b, h) _Pragma("unroll") for (int m = 0; m < 4; ++m) _Pragma("unroll") for (int k = 0; k < 2; ++k) \
;     dst[m][k] = *reinterpret_cast<const bf16x8*>((const char*)SA(b, h) + lds_byte(wr * 64 + m * 16 + fr, k * 32 + fq * 8))
; #define LDB(dst, b, h) _Pragma("unroll") for (int n = 0; n < 2; ++n) _Pragma("unroll") for (int k = 0; k < 2; ++k) \
;     dst[n][k] = *reinterpret_cast<const bf16x8*>((const char*)SB(b, h) + lds_byte(wc * 32 + n * 16 + fr, k * 32 + fq * 8))
; #define MMA(ai, bj, At_, Bt_) do { __builtin_amdgcn_s_setprio(1); \
;     _Pragma("unroll") for (int m = 0; m < 4; ++m) _Pragma("unroll") for (int n = 0; n < 2; ++n) _Pragma("unroll") for (int k = 0; k < 2; ++k) \
;       acc[ai][bj][m][n] = __builtin_amdgcn_mfma_f32_16x16x32_bf16(Bt_[n][k], At_[m][k], acc[ai][bj][m][n], 0, 0, 0); \
;     __builtin_amdgcn_s_setprio(0); } while (0)
; #define WAIT_V(n) asm volatile("s_waitcnt vmcnt(" #n ")" ::: "memory")
; #define WAIT_L(n) asm volatile("s_waitcnt lgkmcnt(" #n ")" ::: "memory")
; #define BAR __builtin_amdgcn_s_barrier()
; template <bool PF = true, class Epi, class KRF = KRFull>
; __device__ __forceinline__ void gemm_phase(const u16* __restrict__ A, int lda, const u16* __restrict__ Bt, int ldb, int K, int nM, int nN,
;                                            lds_u16* shm, Epi epi, KRF krf = KRFull(), bool flip = false) {
;     ...
;       LDB(B1, 0, 1); BAR; WAIT_L(0); MMA(0, 1, At, B1); BAR;
;       LDA(At, 0, 1); WAIT_V(4); BAR; WAIT_L(0); MMA(1, 0, At, B0); MMA(1, 1, At, B1); BAR; }
;     { LDB(B0, 1, 0); LDA(At, 1, 0); WAIT_V(2); BAR; WAIT_L(0); MMA(0, 0, At, B0); BAR;
	ds_read_b128 v[162:165], v142 offset:16384
	ds_read_b128 v[166:169], v142 offset:17408
	ds_read_b128 v[170:173], v141 offset:16384
	ds_read_b128 v[180:183], v141 offset:17408
	ds_read_b128 v[184:187], v140 offset:16384
	ds_read_b128 v[188:191], v140 offset:17408
	ds_read_b128 v[192:195], v139 offset:16384
	ds_read_b128 v[196:199], v139 offset:17408
	s_waitcnt vmcnt(4)
	s_barrier
	s_waitcnt lgkmcnt(0)
	s_setprio 1
	s_waitcnt lgkmcnt(0)
	v_mfma_f32_16x16x32_bf16 v[60:63], v[130:133], v[162:165], v[60:63]
	v_mfma_f32_16x16x32_bf16 v[56:59], v[146:149], v[162:165], v[56:59]
	v_mfma_f32_16x16x32_bf16 v[52:55], v[130:133], v[170:173], v[52:55]
	v_mfma_f32_16x16x32_bf16 v[48:51], v[146:149], v[170:173], v[48:51]
	v_mfma_f32_16x16x32_bf16 v[44:47], v[130:133], v[184:187], v[44:47]
	v_mfma_f32_16x16x32_bf16 v[40:43], v[146:149], v[184:187], v[40:43]
	v_mfma_f32_16x16x32_bf16 v[36:39], v[130:133], v[192:195], v[36:39]
	v_mfma_f32_16x16x32_bf16 v[32:35], v[146:149], v[192:195], v[32:35]
	v_mfma_f32_16x16x32_bf16 v[60:63], v[134:137], v[166:169], v[60:63]
	v_mfma_f32_16x16x32_bf16 v[56:59], v[158:161], v[166:169], v[56:59]
	v_mfma_f32_16x16x32_bf16 v[52:55], v[134:137], v[180:183], v[52:55]
	v_mfma_f32_16x16x32_bf16 v[48:51], v[158:161], v[180:183], v[48:51]
	v_mfma_f32_16x16x32_bf16 v[44:47], v[134:137], v[188:191], v[44:47]
	v_mfma_f32_16x16x32_bf16 v[40:43], v[158:161], v[188:191], v[40:43]
	v_mfma_f32_16x16x32_bf16 v[36:39], v[134:137], v[196:199], v[36:39]
	v_mfma_f32_16x16x32_bf16 v[32:35], v[158:161], v[196:199], v[32:35]
	s_setprio 0
	s_setprio 1
	v_mfma_f32_16x16x32_bf16 v[28:31], v[154:157], v[162:165], v[28:31]
	v_mfma_f32_16x16x32_bf16 v[24:27], v[204:207], v[162:165], v[24:27]
	v_mfma_f32_16x16x32_bf16 v[20:23], v[154:157], v[170:173], v[20:23]
	v_mfma_f32_16x16x32_bf16 v[16:19], v[204:207], v[170:173], v[16:19]
	v_mfma_f32_16x16x32_bf16 v[12:15], v[154:157], v[184:187], v[12:15]
	v_mfma_f32_16x16x32_bf16 v[8:11], v[204:207], v[184:187], v[8:11]
	v_mfma_f32_16x16x32_bf16 v[4:7], v[154:157], v[192:195], v[4:7]
	v_mfma_f32_16x16x32_bf16 v[0:3], v[204:207], v[192:195], v[0:3]
	v_mfma_f32_16x16x32_bf16 v[28:31], v[200:203], v[166:169], v[28:31]
	v_mfma_f32_16x16x32_bf16 v[24:27], v[150:153], v[166:169], v[24:27]
	v_mfma_f32_16x16x32_bf16 v[20:23], v[200:203], v[180:183], v[20:23]
	v_mfma_f32_16x16x32_bf16 v[16:19], v[150:153], v[180:183], v[16:19]
	v_mfma_f32_16x16x32_bf16 v[12:15], v[200:203], v[188:191], v[12:15]
	v_mfma_f32_16x16x32_bf16 v[8:11], v[150:153], v[188:191], v[8:11]
	v_mfma_f32_16x16x32_bf16 v[4:7], v[200:203], v[196:199], v[4:7]
	v_mfma_f32_16x16x32_bf16 v[0:3], v[150:153], v[196:199], v[0:3]
	s_setprio 0
	s_barrier
	ds_read_b128 v[128:131], v145
	ds_read_b128 v[132:135], v145 offset:1024
	ds_read_b128 v[146:149], v145 offset:2048
	ds_read_b128 v[150:153], v145 offset:3072
	ds_read_b128 v[154:157], v142 offset:32768
	ds_read_b128 v[158:161], v142 offset:33792
	ds_read_b128 v[162:165], v141 offset:32768
	ds_read_b128 v[166:169], v141 offset:33792
	ds_read_b128 v[170:173], v140 offset:32768
	ds_read_b128 v[180:183], v140 offset:33792
	ds_read_b128 v[184:187], v139 offset:32768
	ds_read_b128 v[188:191], v139 offset:33792
	s_waitcnt vmcnt(2)
	s_barrier
	s_waitcnt lgkmcnt(0)
	s_setprio 1
	s_waitcnt lgkmcnt(0)
	v_mfma_f32_16x16x32_bf16 v[124:127], v[128:131], v[154:157], v[124:127]
	v_mfma_f32_16x16x32_bf16 v[120:123], v[146:149], v[154:157], v[120:123]
	v_mfma_f32_16x16x32_bf16 v[116:119], v[128:131], v[162:165], v[116:119]
	v_mfma_f32_16x16x32_bf16 v[112:115], v[146:149], v[162:165], v[112:115]
	v_mfma_f32_16x16x32_bf16 v[108:111], v[128:131], v[170:173], v[108:111]
	v_mfma_f32_16x16x32_bf16 v[104:107], v[146:149], v[170:173], v[104:107]
	v_mfma_f32_16x16x32_bf16 v[100:103], v[128:131], v[184:187], v[100:103]
	v_mfma_f32_16x16x32_bf16 v[96:99], v[146:149], v[184:187], v[96:99]
	v_mfma_f32_16x16x32_bf16 v[124:127], v[132:135], v[158:161], v[124:127]
	v_mfma_f32_16x16x32_bf16 v[120:123], v[150:153], v[158:161], v[120:123]
	v_mfma_f32_16x16x32_bf16 v[116:119], v[132:135], v[166:169], v[116:119]
	v_mfma_f32_16x16x32_bf16 v[112:115], v[150:153], v[166:169], v[112:115]
	v_mfma_f32_16x16x32_bf16 v[108:111], v[132:135], v[180:183], v[108:111]
	v_mfma_f32_16x16x32_bf16 v[104:107], v[150:153], v[180:183], v[104:107]
	v_mfma_f32_16x16x32_bf16 v[100:103], v[132:135], v[188:191], v[100:103]
	v_mfma_f32_16x16x32_bf16 v[96:99], v[150:153], v[188:191], v[96:99]
	s_setprio 0
	s_barrier
; #define LDA(dst, b, h) _Pragma("unroll") for (int m = 0; m < 4; ++m) _Pragma("unroll") for (int k = 0; k < 2; ++k) \
;     dst[m][k] = *reinterpret_cast<const bf16x8*>((const char*)SA(b, h) + lds_byte(wr * 64 + m * 16 + fr, k * 32 + fq * 8))
; #define LDB(dst, b, h) _Pragma("unroll") for (int n = 0; n < 2; ++n) _Pragma("unroll") for (int k = 0; k < 2; ++k) \
;     dst[n][k] = *reinterpret_cast<const bf16x8*>((const char*)SB(b, h) + lds_byte(wc * 32 + n * 16 + fr, k * 32 + fq * 8))
; #define MMA(ai, bj, At_, Bt_) do { __builtin_amdgcn_s_setprio(1); \
;     _Pragma("unroll") for (int m = 0; m < 4; ++m) _Pragma("unroll") for (int n = 0; n < 2; ++n) _Pragma("unroll") for (int k = 0; k < 2; ++k) \
;       acc[ai][bj][m][n] = __builtin_amdgcn_mfma_f32_16x16x32_bf16(Bt_[n][k], At_[m][k], acc[ai][bj][m][n], 0, 0, 0); \
;     __builtin_amdgcn_s_setprio(0); } while (0)
; #define WAIT_V(n) asm volatile("s_waitcnt vmcnt(" #n ")" ::: "memory")
; #define WAIT_L(n) asm volatile("s_waitcnt lgkmcnt(" #n ")" ::: "memory")
; #define BAR __builtin_amdgcn_s_barrier()
; template <bool PF = true, class Epi, class KRF = KRFull>
; __device__ __forceinline__ void gemm_phase(const u16* __restrict__ A, int lda, const u16* __restrict__ Bt, int ldb, int K, int nM, int nN,
;                                            lds_u16* shm, Epi epi, KRF krf = KRFull(), bool flip = false) {
;     ...
;       LDB(B1, 1, 1); WAIT_V(0); BAR; WAIT_L(0); MMA(0, 1, At, B1); BAR;
;       LDA(At, 1, 1); BAR; WAIT_L(0); MMA(1, 0, At, B0); MMA(1, 1, At, B1); BAR; }
;     if (wr == 0) BAR;
	ds_read_b128 v[192:195], v143
	ds_read_b128 v[196:199], v143 offset:1024
	ds_read_b128 v[200:203], v143 offset:2048
	ds_read_b128 v[204:207], v143 offset:3072
	s_waitcnt vmcnt(0)
	s_barrier
	s_waitcnt lgkmcnt(0)
	s_setprio 1
	s_waitcnt lgkmcnt(0)
	v_mfma_f32_16x16x32_bf16 v[92:95], v[192:195], v[154:157], v[92:95]
	v_mfma_f32_16x16x32_bf16 v[88:91], v[200:203], v[154:157], v[88:91]
	v_mfma_f32_16x16x32_bf16 v[84:87], v[192:195], v[162:165], v[84:87]
	v_mfma_f32_16x16x32_bf16 v[80:83], v[200:203], v[162:165], v[80:83]
	v_mfma_f32_16x16x32_bf16 v[76:79], v[192:195], v[170:173], v[76:79]
	v_mfma_f32_16x16x32_bf16 v[72:75], v[200:203], v[170:173], v[72:75]
	v_mfma_f32_16x16x32_bf16 v[68:71], v[192:195], v[184:187], v[68:71]
	v_mfma_f32_16x16x32_bf16 v[64:67], v[200:203], v[184:187], v[64:67]
	v_mfma_f32_16x16x32_bf16 v[92:95], v[196:199], v[158:161], v[92:95]
	v_mfma_f32_16x16x32_bf16 v[88:91], v[204:207], v[158:161], v[88:91]
	v_mfma_f32_16x16x32_bf16 v[84:87], v[196:199], v[166:169], v[84:87]
	v_mfma_f32_16x16x32_bf16 v[80:83], v[204:207], v[166:169], v[80:83]
	v_mfma_f32_16x16x32_bf16 v[76:79], v[196:199], v[180:183], v[76:79]
	v_mfma_f32_16x16x32_bf16 v[72:75], v[204:207], v[180:183], v[72:75]
	v_mfma_f32_16x16x32_bf16 v[68:71], v[196:199], v[188:191], v[68:71]
	v_mfma_f32_16x16x32_bf16 v[64:67], v[204:207], v[188:191], v[64:67]
	s_setprio 0
	s_barrier
	ds_read_b128 v[154:157], v142 offset:49152
	ds_read_b128 v[142:145], v142 offset:50176
	ds_read_b128 v[158:161], v141 offset:49152
	ds_read_b128 v[162:165], v141 offset:50176
	ds_read_b128 v[166:169], v140 offset:49152
	ds_read_b128 v[170:173], v140 offset:50176
	ds_read_b128 v[180:183], v139 offset:49152
	ds_read_b128 v[184:187], v139 offset:50176
	s_barrier
	s_waitcnt lgkmcnt(0)
	s_setprio 1
	s_waitcnt lgkmcnt(0)
	v_mfma_f32_16x16x32_bf16 v[60:63], v[128:131], v[154:157], v[60:63]
	v_mfma_f32_16x16x32_bf16 v[56:59], v[146:149], v[154:157], v[56:59]
	v_mfma_f32_16x16x32_bf16 v[52:55], v[128:131], v[158:161], v[52:55]
	v_mfma_f32_16x16x32_bf16 v[48:51], v[146:149], v[158:161], v[48:51]
	v_mfma_f32_16x16x32_bf16 v[44:47], v[128:131], v[166:169], v[44:47]
	v_mfma_f32_16x16x32_bf16 v[40:43], v[146:149], v[166:169], v[40:43]
	v_mfma_f32_16x16x32_bf16 v[36:39], v[128:131], v[180:183], v[36:39]
	v_mfma_f32_16x16x32_bf16 v[32:35], v[146:149], v[180:183], v[32:35]
	v_mfma_f32_16x16x32_bf16 v[60:63], v[132:135], v[142:145], v[60:63]
	v_mfma_f32_16x16x32_bf16 v[56:59], v[150:153], v[142:145], v[56:59]
	v_mfma_f32_16x16x32_bf16 v[52:55], v[132:135], v[162:165], v[52:55]
	v_mfma_f32_16x16x32_bf16 v[48:51], v[150:153], v[162:165], v[48:51]
	v_mfma_f32_16x16x32_bf16 v[44:47], v[132:135], v[170:173], v[44:47]
	v_mfma_f32_16x16x32_bf16 v[40:43], v[150:153], v[170:173], v[40:43]
	v_mfma_f32_16x16x32_bf16 v[36:39], v[132:135], v[184:187], v[36:39]
	v_mfma_f32_16x16x32_bf16 v[32:35], v[150:153], v[184:187], v[32:35]
	s_setprio 0
	s_setprio 1
	v_mfma_f32_16x16x32_bf16 v[28:31], v[192:195], v[154:157], v[28:31]
	v_mfma_f32_16x16x32_bf16 v[24:27], v[200:203], v[154:157], v[24:27]
	v_mfma_f32_16x16x32_bf16 v[20:23], v[192:195], v[158:161], v[20:23]
	v_mfma_f32_16x16x32_bf16 v[16:19], v[200:203], v[158:161], v[16:19]
	v_mfma_f32_16x16x32_bf16 v[12:15], v[192:195], v[166:169], v[12:15]
	v_mfma_f32_16x16x32_bf16 v[8:11], v[200:203], v[166:169], v[8:11]
	v_mfma_f32_16x16x32_bf16 v[4:7], v[192:195], v[180:183], v[4:7]
	v_mfma_f32_16x16x32_bf16 v[0:3], v[200:203], v[180:183], v[0:3]
	v_mfma_f32_16x16x32_bf16 v[28:31], v[196:199], v[142:145], v[28:31]
	v_mfma_f32_16x16x32_bf16 v[24:27], v[204:207], v[142:145], v[24:27]
	v_mfma_f32_16x16x32_bf16 v[20:23], v[196:199], v[162:165], v[20:23]
	v_mfma_f32_16x16x32_bf16 v[16:19], v[204:207], v[162:165], v[16:19]
	v_mfma_f32_16x16x32_bf16 v[12:15], v[196:199], v[170:173], v[12:15]
	v_mfma_f32_16x16x32_bf16 v[8:11], v[204:207], v[170:173], v[8:11]
	v_mfma_f32_16x16x32_bf16 v[4:7], v[196:199], v[184:187], v[4:7]
	v_mfma_f32_16x16x32_bf16 v[0:3], v[204:207], v[184:187], v[0:3]
	s_setprio 0
	v_cmp_gt_u32_e32 vcc, s95, v138
	s_barrier
	s_and_saveexec_b64 s[16:17], vcc
	s_cbranch_execz .LBB0_2538
	s_barrier

; #define STAGE_A(P, half, kt) do { const char* _u = Ab + ((size_t)(half) * 128 * lda + (size_t)(kt) * BK) * 2; \
;     _Pragma("unroll") for (int _i = 0; _i < 2; ++_i) \
;       __builtin_amdgcn_global_load_lds((const unsigned*)(_u + offA[_i]), \
;         (__attribute__((address_space(3))) unsigned*)((__attribute__((address_space(3))) char*)(P) + tidg * 16 + _i * 8192), 16, 0, 0); } while (0)
; #define STAGE_B(P, half, kt) do { const char* _u = Bb + ((size_t)(half) * 128 * ldb + (size_t)(kt) * BK) * 2; \
;     _Pragma("unroll") for (int _i = 0; _i < 2; ++_i) \
;       __builtin_amdgcn_global_load_lds((const unsigned*)(_u + offB[_i]), \
;         (__attribute__((address_space(3))) unsigned*)((__attribute__((address_space(3))) char*)(P) + tidg * 16 + _i * 8192), 16, 0, 0); } while (0)
; #define LDA(dst, b, h) _Pragma("unroll") for (int m = 0; m < 4; ++m) _Pragma("unroll") for (int k = 0; k < 2; ++k) \
;     dst[m][k] = *reinterpret_cast<const bf16x8*>((const char*)SA(b, h) + lds_byte(wr * 64 + m * 16 + fr, k * 32 + fq * 8))
; #define LDB(dst, b, h) _Pragma("unroll") for (int n = 0; n < 2; ++n) _Pragma("unroll") for (int k = 0; k < 2; ++k) \
;     dst[n][k] = *reinterpret_cast<const bf16x8*>((const char*)SB(b, h) + lds_byte(wc * 32 + n * 16 + fr, k * 32 + fq * 8))
; #define MMA(ai, bj, At_, Bt_) do { __builtin_amdgcn_s_setprio(1); \
;     _Pragma("unroll") for (int m = 0; m < 4; ++m) _Pragma("unroll") for (int n = 0; n < 2; ++n) _Pragma("unroll") for (int k = 0; k < 2; ++k) \
;       acc[ai][bj][m][n] = __builtin_amdgcn_mfma_f32_16x16x32_bf16(Bt_[n][k], At_[m][k], acc[ai][bj][m][n], 0, 0, 0); \
;     __builtin_amdgcn_s_setprio(0); } while (0)
; template <bool PF = true, class Epi, class KRF = KRFull>
; __device__ __forceinline__ void gemm_phase(const u16* __restrict__ A, int lda, const u16* __restrict__ Bt, int ldb, int K, int nM, int nN,
;                                            lds_u16* shm, Epi epi, KRF krf = KRFull(), bool flip = false) {
;     ...
;     for (int t = 0; t < nt - 2; t += 2) {
;       LDB(B0, 0, 0); SCHED; LDA(At, 0, 0); STAGE_A(SA(1, 1), 1, t + 1);
;       WAIT_L(8); BAR; WAIT_L(0); MMA(0, 0, At, B0); BAR; SCHED;
;       LDB(B1, 0, 1); STAGE_B(SB(0, 0), 0, t + 2);
;       BAR; WAIT_L(0); MMA(0, 1, At, B1); BAR;
;       LDA(At, 0, 1); STAGE_A(SA(0, 0), 0, t + 2);
;       BAR; WAIT_L(0); MMA(1, 0, At, B0); BAR; SCHED;
.LBB0_2562:
	v_readfirstlane_b32 s3, v144
	ds_read_b128 v[158:161], v154
	ds_read_b128 v[162:165], v154 offset:1024
	ds_read_b128 v[166:169], v154 offset:2048
	ds_read_b128 v[170:173], v154 offset:3072
	v_add_u32_e32 v155, 0xc000, v144
	v_lshl_add_u64 v[174:175], v[134:135], 0, s[12:13]
	v_lshl_add_u64 v[156:157], v[174:175], 0, s[62:63]
	s_add_u32 m0, s3, 0xc000
	ds_read_b128 v[180:183], v142
	ds_read_b128 v[184:187], v142 offset:1024
	ds_read_b128 v[188:191], v141
	ds_read_b128 v[192:195], v141 offset:1024
	ds_read_b128 v[196:199], v140
	ds_read_b128 v[200:203], v140 offset:1024
	ds_read_b128 v[204:207], v139
	ds_read_b128 v[208:211], v139 offset:1024
	global_load_lds_dwordx4 v[156:157], off
	v_add_u32_e32 v156, 0xe000, v144
	v_lshl_add_u64 v[234:235], v[136:137], 0, s[12:13]
	v_lshl_add_u64 v[212:213], v[234:235], 0, s[62:63]
	s_add_u32 m0, s3, 0xe000
	s_nop 0
	global_load_lds_dwordx4 v[212:213], off
	s_waitcnt lgkmcnt(8)
	s_barrier
	s_waitcnt lgkmcnt(0)
	s_setprio 1
	s_waitcnt lgkmcnt(0)
	v_mfma_f32_16x16x32_bf16 v[124:127], v[158:161], v[180:183], v[124:127]
	v_mfma_f32_16x16x32_bf16 v[120:123], v[166:169], v[180:183], v[120:123]
	v_mfma_f32_16x16x32_bf16 v[116:119], v[158:161], v[188:191], v[116:119]
	v_mfma_f32_16x16x32_bf16 v[112:115], v[166:169], v[188:191], v[112:115]
	v_mfma_f32_16x16x32_bf16 v[108:111], v[158:161], v[196:199], v[108:111]
	v_mfma_f32_16x16x32_bf16 v[104:107], v[166:169], v[196:199], v[104:107]
	v_mfma_f32_16x16x32_bf16 v[100:103], v[158:161], v[204:207], v[100:103]
	v_mfma_f32_16x16x32_bf16 v[96:99], v[166:169], v[204:207], v[96:99]
	v_mfma_f32_16x16x32_bf16 v[124:127], v[162:165], v[184:187], v[124:127]
	v_mfma_f32_16x16x32_bf16 v[120:123], v[170:173], v[184:187], v[120:123]
	v_mfma_f32_16x16x32_bf16 v[116:119], v[162:165], v[192:195], v[116:119]
	v_mfma_f32_16x16x32_bf16 v[112:115], v[170:173], v[192:195], v[112:115]
	v_mfma_f32_16x16x32_bf16 v[108:111], v[162:165], v[200:203], v[108:111]
	v_mfma_f32_16x16x32_bf16 v[104:107], v[170:173], v[200:203], v[104:107]
	v_mfma_f32_16x16x32_bf16 v[100:103], v[162:165], v[208:211], v[100:103]
	v_mfma_f32_16x16x32_bf16 v[96:99], v[170:173], v[208:211], v[96:99]
	s_setprio 0
	s_barrier
	v_add_u32_e32 v157, 0x10000, v144
	v_lshl_add_u64 v[236:237], v[130:131], 0, s[12:13]
	v_lshl_add_u64 v[238:239], v[236:237], 0, s[64:65]
	s_add_u32 m0, s3, 0x10000
	v_add_u32_e32 v157, 0x12000, v144
	ds_read_b128 v[212:215], v153
	ds_read_b128 v[216:219], v153 offset:1024
	ds_read_b128 v[222:225], v153 offset:2048
	ds_read_b128 v[226:229], v153 offset:3072
	global_load_lds_dwordx4 v[238:239], off
	v_lshl_add_u64 v[238:239], v[132:133], 0, s[12:13]
	v_lshl_add_u64 v[240:241], v[238:239], 0, s[64:65]
	s_add_u32 m0, s3, 0x12000
	s_nop 0
	global_load_lds_dwordx4 v[240:241], off
	s_barrier
	s_waitcnt lgkmcnt(0)
	s_setprio 1
	s_waitcnt lgkmcnt(0)
	v_mfma_f32_16x16x32_bf16 v[92:95], v[212:215], v[180:183], v[92:95]
	v_mfma_f32_16x16x32_bf16 v[88:91], v[222:225], v[180:183], v[88:91]
	v_mfma_f32_16x16x32_bf16 v[84:87], v[212:215], v[188:191], v[84:87]
	v_mfma_f32_16x16x32_bf16 v[80:83], v[222:225], v[188:191], v[80:83]
	v_mfma_f32_16x16x32_bf16 v[76:79], v[212:215], v[196:199], v[76:79]
	v_mfma_f32_16x16x32_bf16 v[72:75], v[222:225], v[196:199], v[72:75]
	v_mfma_f32_16x16x32_bf16 v[68:71], v[212:215], v[204:207], v[68:71]
	v_mfma_f32_16x16x32_bf16 v[64:67], v[222:225], v[204:207], v[64:67]
	v_mfma_f32_16x16x32_bf16 v[92:95], v[216:219], v[184:187], v[92:95]
	v_mfma_f32_16x16x32_bf16 v[88:91], v[226:229], v[184:187], v[88:91]
	v_mfma_f32_16x16x32_bf16 v[84:87], v[216:219], v[192:195], v[84:87]
	v_mfma_f32_16x16x32_bf16 v[80:83], v[226:229], v[192:195], v[80:83]
	v_mfma_f32_16x16x32_bf16 v[76:79], v[216:219], v[200:203], v[76:79]
	v_mfma_f32_16x16x32_bf16 v[72:75], v[226:229], v[200:203], v[72:75]
	v_mfma_f32_16x16x32_bf16 v[68:71], v[216:219], v[208:211], v[68:71]
	v_mfma_f32_16x16x32_bf16 v[64:67], v[226:229], v[208:211], v[64:67]
	s_setprio 0
	v_lshl_add_u64 v[240:241], v[174:175], 0, s[64:65]
	s_mov_b32 m0, s3
	s_barrier
	ds_read_b128 v[180:183], v142 offset:16384
	ds_read_b128 v[184:187], v142 offset:17408
	ds_read_b128 v[188:191], v141 offset:16384
	ds_read_b128 v[192:195], v141 offset:17408
	ds_read_b128 v[196:199], v140 offset:16384
	ds_read_b128 v[200:203], v140 offset:17408
	ds_read_b128 v[204:207], v139 offset:16384
	ds_read_b128 v[208:211], v139 offset:17408
	global_load_lds_dwordx4 v[240:241], off
	v_lshl_add_u64 v[240:241], v[234:235], 0, s[64:65]
	s_add_u32 m0, s3, 0x2000
	s_nop 0
	global_load_lds_dwordx4 v[240:241], off
	s_barrier
	s_waitcnt lgkmcnt(0)
	s_setprio 1
	s_waitcnt lgkmcnt(0)
	v_mfma_f32_16x16x32_bf16 v[60:63], v[158:161], v[180:183], v[60:63]
	v_mfma_f32_16x16x32_bf16 v[56:59], v[166:169], v[180:183], v[56:59]
	v_mfma_f32_16x16x32_bf16 v[52:55], v[158:161], v[188:191], v[52:55]
	v_mfma_f32_16x16x32_bf16 v[48:51], v[166:169], v[188:191], v[48:51]
	v_mfma_f32_16x16x32_bf16 v[44:47], v[158:161], v[196:199], v[44:47]
	v_mfma_f32_16x16x32_bf16 v[40:43], v[166:169], v[196:199], v[40:43]
	v_mfma_f32_16x16x32_bf16 v[36:39], v[158:161], v[204:207], v[36:39]
	v_mfma_f32_16x16x32_bf16 v[32:35], v[166:169], v[204:207], v[32:35]
	v_mfma_f32_16x16x32_bf16 v[60:63], v[162:165], v[184:187], v[60:63]
	v_mfma_f32_16x16x32_bf16 v[56:59], v[170:173], v[184:187], v[56:59]
	v_mfma_f32_16x16x32_bf16 v[52:55], v[162:165], v[192:195], v[52:55]
	v_mfma_f32_16x16x32_bf16 v[48:51], v[170:173], v[192:195], v[48:51]
	v_mfma_f32_16x16x32_bf16 v[44:47], v[162:165], v[200:203], v[44:47]
	v_mfma_f32_16x16x32_bf16 v[40:43], v[170:173], v[200:203], v[40:43]
	v_mfma_f32_16x16x32_bf16 v[36:39], v[162:165], v[208:211], v[36:39]
	v_mfma_f32_16x16x32_bf16 v[32:35], v[170:173], v[208:211], v[32:35]
	s_setprio 0
	s_barrier
; #define STAGE_A(P, half, kt) do { const char* _u = Ab + ((size_t)(half) * 128 * lda + (size_t)(kt) * BK) * 2; \
;     _Pragma("unroll") for (int _i = 0; _i < 2; ++_i) \
;       __builtin_amdgcn_global_load_lds((const unsigned*)(_u + offA[_i]), \
;         (__attribute__((address_space(3))) unsigned*)((__attribute__((address_space(3))) char*)(P) + tidg * 16 + _i * 8192), 16, 0, 0); } while (0)
; #define STAGE_B(P, half, kt) do { const char* _u = Bb + ((size_t)(half) * 128 * ldb + (size_t)(kt) * BK) * 2; \
;     _Pragma("unroll") for (int _i = 0; _i < 2; ++_i) \
;       __builtin_amdgcn_global_load_lds((const unsigned*)(_u + offB[_i]), \
;         (__attribute__((address_space(3))) unsigned*)((__attribute__((address_space(3))) char*)(P) + tidg * 16 + _i * 8192), 16, 0, 0); } while (0)
; #define LDA(dst, b, h) _Pragma("unroll") for (int m = 0; m < 4; ++m) _Pragma("unroll") for (int k = 0; k < 2; ++k) \
;     dst[m][k] = *reinterpret_cast<const bf16x8*>((const char*)SA(b, h) + lds_byte(wr * 64 + m * 16 + fr, k * 32 + fq * 8))
; #define LDB(dst, b, h) _Pragma("unroll") for (int n = 0; n < 2; ++n) _Pragma("unroll") for (int k = 0; k < 2; ++k) \
;     dst[n][k] = *reinterpret_cast<const bf16x8*>((const char*)SB(b, h) + lds_byte(wc * 32 + n * 16 + fr, k * 32 + fq * 8))
; #define MMA(ai, bj, At_, Bt_) do { __builtin_amdgcn_s_setprio(1); \
;     _Pragma("unroll") for (int m = 0; m < 4; ++m) _Pragma("unroll") for (int n = 0; n < 2; ++n) _Pragma("unroll") for (int k = 0; k < 2; ++k) \
;       acc[ai][bj][m][n] = __builtin_amdgcn_mfma_f32_16x16x32_bf16(Bt_[n][k], At_[m][k], acc[ai][bj][m][n], 0, 0, 0); \
;     __builtin_amdgcn_s_setprio(0); } while (0)
; #define BAR __builtin_amdgcn_s_barrier()
; template <bool PF = true, class Epi, class KRF = KRFull>
; __device__ __forceinline__ void gemm_phase(const u16* __restrict__ A, int lda, const u16* __restrict__ Bt, int ldb, int K, int nM, int nN,
;                                            lds_u16* shm, Epi epi, KRF krf = KRFull(), bool flip = false) {
;     ...
;       STAGE_B(SB(0, 1), 1, t + 2);
;       WAIT_V(6); BAR; MMA(1, 1, At, B1); BAR;
;       LDB(B0, 1, 0); SCHED; LDA(At, 1, 0); STAGE_A(SA(0, 1), 1, t + 2);
;       WAIT_L(8); BAR; WAIT_L(0); MMA(0, 0, At, B0); BAR; SCHED;
;       LDB(B1, 1, 1); STAGE_B(SB(1, 0), 0, t + 3);
;       BAR; WAIT_L(0); MMA(0, 1, At, B1); BAR;
;       LDA(At, 1, 1); STAGE_A(SA(1, 0), 0, t + 3);
	v_add_u32_e32 v157, 0x14000, v144
	v_lshl_add_u64 v[158:159], v[236:237], 0, s[66:67]
	v_add_u32_e32 v157, 0x16000, v144
	s_add_u32 m0, s3, 0x14000
	s_nop 0
	global_load_lds_dwordx4 v[158:159], off
	v_lshl_add_u64 v[158:159], v[238:239], 0, s[66:67]
	s_add_u32 m0, s3, 0x16000
	s_nop 0
	global_load_lds_dwordx4 v[158:159], off
	s_waitcnt vmcnt(6)
	s_barrier
	s_setprio 1
	v_mfma_f32_16x16x32_bf16 v[28:31], v[212:215], v[180:183], v[28:31]
	v_mfma_f32_16x16x32_bf16 v[24:27], v[222:225], v[180:183], v[24:27]
	v_mfma_f32_16x16x32_bf16 v[20:23], v[212:215], v[188:191], v[20:23]
	v_mfma_f32_16x16x32_bf16 v[16:19], v[222:225], v[188:191], v[16:19]
	v_mfma_f32_16x16x32_bf16 v[12:15], v[212:215], v[196:199], v[12:15]
	v_mfma_f32_16x16x32_bf16 v[8:11], v[222:225], v[196:199], v[8:11]
	v_mfma_f32_16x16x32_bf16 v[4:7], v[212:215], v[204:207], v[4:7]
	v_mfma_f32_16x16x32_bf16 v[0:3], v[222:225], v[204:207], v[0:3]
	v_mfma_f32_16x16x32_bf16 v[28:31], v[216:219], v[184:187], v[28:31]
	v_mfma_f32_16x16x32_bf16 v[24:27], v[226:229], v[184:187], v[24:27]
	v_mfma_f32_16x16x32_bf16 v[20:23], v[216:219], v[192:195], v[20:23]
	v_mfma_f32_16x16x32_bf16 v[16:19], v[226:229], v[192:195], v[16:19]
	v_mfma_f32_16x16x32_bf16 v[12:15], v[216:219], v[200:203], v[12:15]
	v_mfma_f32_16x16x32_bf16 v[8:11], v[226:229], v[200:203], v[8:11]
	v_mfma_f32_16x16x32_bf16 v[4:7], v[216:219], v[208:211], v[4:7]
	v_mfma_f32_16x16x32_bf16 v[0:3], v[226:229], v[208:211], v[0:3]
	s_setprio 0
	s_barrier
	ds_read_b128 v[158:161], v145
	ds_read_b128 v[162:165], v145 offset:1024
	ds_read_b128 v[166:169], v145 offset:2048
	ds_read_b128 v[170:173], v145 offset:3072
	v_add_u32_e32 v157, 0x4000, v144
	v_lshl_add_u64 v[212:213], v[174:175], 0, s[66:67]
	v_add_u32_e32 v157, 0x6000, v144
	s_add_u32 m0, s3, 0x4000
	ds_read_b128 v[180:183], v142 offset:32768
	ds_read_b128 v[184:187], v142 offset:33792
	ds_read_b128 v[188:191], v141 offset:32768
	ds_read_b128 v[192:195], v141 offset:33792
	ds_read_b128 v[196:199], v140 offset:32768
	ds_read_b128 v[200:203], v140 offset:33792
	ds_read_b128 v[204:207], v139 offset:32768
	ds_read_b128 v[208:211], v139 offset:33792
	global_load_lds_dwordx4 v[212:213], off
	v_lshl_add_u64 v[212:213], v[234:235], 0, s[66:67]
	s_add_u32 m0, s3, 0x6000
	s_nop 0
	global_load_lds_dwordx4 v[212:213], off
	s_waitcnt lgkmcnt(8)
	s_barrier
	s_waitcnt lgkmcnt(0)
	s_setprio 1
	s_waitcnt lgkmcnt(0)
	v_mfma_f32_16x16x32_bf16 v[124:127], v[158:161], v[180:183], v[124:127]
	v_mfma_f32_16x16x32_bf16 v[120:123], v[166:169], v[180:183], v[120:123]
	v_mfma_f32_16x16x32_bf16 v[116:119], v[158:161], v[188:191], v[116:119]
	v_mfma_f32_16x16x32_bf16 v[112:115], v[166:169], v[188:191], v[112:115]
	v_mfma_f32_16x16x32_bf16 v[108:111], v[158:161], v[196:199], v[108:111]
	v_mfma_f32_16x16x32_bf16 v[104:107], v[166:169], v[196:199], v[104:107]
	v_mfma_f32_16x16x32_bf16 v[100:103], v[158:161], v[204:207], v[100:103]
	v_mfma_f32_16x16x32_bf16 v[96:99], v[166:169], v[204:207], v[96:99]
	v_mfma_f32_16x16x32_bf16 v[124:127], v[162:165], v[184:187], v[124:127]
	v_mfma_f32_16x16x32_bf16 v[120:123], v[170:173], v[184:187], v[120:123]
	v_mfma_f32_16x16x32_bf16 v[116:119], v[162:165], v[192:195], v[116:119]
	v_mfma_f32_16x16x32_bf16 v[112:115], v[170:173], v[192:195], v[112:115]
	v_mfma_f32_16x16x32_bf16 v[108:111], v[162:165], v[200:203], v[108:111]
	v_mfma_f32_16x16x32_bf16 v[104:107], v[170:173], v[200:203], v[104:107]
	v_mfma_f32_16x16x32_bf16 v[100:103], v[162:165], v[208:211], v[100:103]
	v_mfma_f32_16x16x32_bf16 v[96:99], v[170:173], v[208:211], v[96:99]
	s_setprio 0
	s_barrier
	v_lshl_add_u64 v[240:241], v[236:237], 0, s[68:69]
	s_add_u32 m0, s3, 0x18000
	ds_read_b128 v[212:215], v143
	ds_read_b128 v[216:219], v143 offset:1024
	ds_read_b128 v[222:225], v143 offset:2048
	ds_read_b128 v[226:229], v143 offset:3072
	global_load_lds_dwordx4 v[240:241], off
	v_lshl_add_u64 v[240:241], v[238:239], 0, s[68:69]
	s_add_u32 m0, s3, 0x1a000
	s_nop 0
	global_load_lds_dwordx4 v[240:241], off
	s_barrier
	s_waitcnt lgkmcnt(0)
	s_setprio 1
	s_waitcnt lgkmcnt(0)
	v_mfma_f32_16x16x32_bf16 v[92:95], v[212:215], v[180:183], v[92:95]
	v_mfma_f32_16x16x32_bf16 v[88:91], v[222:225], v[180:183], v[88:91]
	v_mfma_f32_16x16x32_bf16 v[84:87], v[212:215], v[188:191], v[84:87]
	v_mfma_f32_16x16x32_bf16 v[80:83], v[222:225], v[188:191], v[80:83]
	v_mfma_f32_16x16x32_bf16 v[76:79], v[212:215], v[196:199], v[76:79]
	v_mfma_f32_16x16x32_bf16 v[72:75], v[222:225], v[196:199], v[72:75]
	v_mfma_f32_16x16x32_bf16 v[68:71], v[212:215], v[204:207], v[68:71]
	v_mfma_f32_16x16x32_bf16 v[64:67], v[222:225], v[204:207], v[64:67]
	v_mfma_f32_16x16x32_bf16 v[92:95], v[216:219], v[184:187], v[92:95]
	v_mfma_f32_16x16x32_bf16 v[88:91], v[226:229], v[184:187], v[88:91]
	v_mfma_f32_16x16x32_bf16 v[84:87], v[216:219], v[192:195], v[84:87]
	v_mfma_f32_16x16x32_bf16 v[80:83], v[226:229], v[192:195], v[80:83]
	v_mfma_f32_16x16x32_bf16 v[76:79], v[216:219], v[200:203], v[76:79]
	v_mfma_f32_16x16x32_bf16 v[72:75], v[226:229], v[200:203], v[72:75]
	v_mfma_f32_16x16x32_bf16 v[68:71], v[216:219], v[208:211], v[68:71]
	v_mfma_f32_16x16x32_bf16 v[64:67], v[226:229], v[208:211], v[64:67]
	s_setprio 0
	v_lshl_add_u64 v[174:175], v[174:175], 0, s[68:69]
	s_add_u32 m0, s3, 0x8000
	s_barrier
	ds_read_b128 v[180:183], v142 offset:49152
	ds_read_b128 v[184:187], v142 offset:50176
	ds_read_b128 v[188:191], v141 offset:49152
	ds_read_b128 v[192:195], v141 offset:50176
	ds_read_b128 v[196:199], v140 offset:49152
	ds_read_b128 v[200:203], v140 offset:50176
	ds_read_b128 v[204:207], v139 offset:49152
	ds_read_b128 v[208:211], v139 offset:50176
	global_load_lds_dwordx4 v[174:175], off
	v_lshl_add_u64 v[174:175], v[234:235], 0, s[68:69]
	s_add_u32 m0, s3, 0xa000
	s_nop 0
	global_load_lds_dwordx4 v[174:175], off
	s_barrier
; #define STAGE_A(P, half, kt) do { const char* _u = Ab + ((size_t)(half) * 128 * lda + (size_t)(kt) * BK) * 2; \
;     _Pragma("unroll") for (int _i = 0; _i < 2; ++_i) \
;       __builtin_amdgcn_global_load_lds((const unsigned*)(_u + offA[_i]), \
;         (__attribute__((address_space(3))) unsigned*)((__attribute__((address_space(3))) char*)(P) + tidg * 16 + _i * 8192), 16, 0, 0); } while (0)
; #define STAGE_B(P, half, kt) do { const char* _u = Bb + ((size_t)(half) * 128 * ldb + (size_t)(kt) * BK) * 2; \
;     _Pragma("unroll") for (int _i = 0; _i < 2; ++_i) \
;       __builtin_amdgcn_global_load_lds((const unsigned*)(_u + offB[_i]), \
;         (__attribute__((address_space(3))) unsigned*)((__attribute__((address_space(3))) char*)(P) + tidg * 16 + _i * 8192), 16, 0, 0); } while (0)
; #define LDA(dst, b, h) _Pragma("unroll") for (int m = 0; m < 4; ++m) _Pragma("unroll") for (int k = 0; k < 2; ++k) \
;     dst[m][k] = *reinterpret_cast<const bf16x8*>((const char*)SA(b, h) + lds_byte(wr * 64 + m * 16 + fr, k * 32 + fq * 8))
; #define LDB(dst, b, h) _Pragma("unroll") for (int n = 0; n < 2; ++n) _Pragma("unroll") for (int k = 0; k < 2; ++k) \
;     dst[n][k] = *reinterpret_cast<const bf16x8*>((const char*)SB(b, h) + lds_byte(wc * 32 + n * 16 + fr, k * 32 + fq * 8))
; #define MMA(ai, bj, At_, Bt_) do { __builtin_amdgcn_s_setprio(1); \
;     _Pragma("unroll") for (int m = 0; m < 4; ++m) _Pragma("unroll") for (int n = 0; n < 2; ++n) _Pragma("unroll") for (int k = 0; k < 2; ++k) \
;       acc[ai][bj][m][n] = __builtin_amdgcn_mfma_f32_16x16x32_bf16(Bt_[n][k], At_[m][k], acc[ai][bj][m][n], 0, 0, 0); \
;     __builtin_amdgcn_s_setprio(0); } while (0)
; #define WAIT_V(n) asm volatile("s_waitcnt vmcnt(" #n ")" ::: "memory")
; template <bool PF = true, class Epi, class KRF = KRFull>
; __device__ __forceinline__ void gemm_phase(const u16* __restrict__ A, int lda, const u16* __restrict__ Bt, int ldb, int K, int nM, int nN,
;                                            lds_u16* shm, Epi epi, KRF krf = KRFull(), bool flip = false) {
;     ...
;       BAR; WAIT_L(0); MMA(1, 0, At, B0); BAR; SCHED;
;       STAGE_B(SB(1, 1), 1, t + 3);
;       WAIT_V(6); BAR; MMA(1, 1, At, B1); BAR;
;     }
;     { LDB(B0, 0, 0); LDA(At, 0, 0); STAGE_A(SA(1, 1), 1, nt - 1);
;       BAR; WAIT_L(0); MMA(0, 0, At, B0); BAR;
;       LDB(B1, 0, 1); BAR; WAIT_L(0); MMA(0, 1, At, B1); BAR;
	s_waitcnt lgkmcnt(0)
	s_setprio 1
	s_waitcnt lgkmcnt(0)
	v_mfma_f32_16x16x32_bf16 v[60:63], v[158:161], v[180:183], v[60:63]
	v_mfma_f32_16x16x32_bf16 v[56:59], v[166:169], v[180:183], v[56:59]
	v_mfma_f32_16x16x32_bf16 v[52:55], v[158:161], v[188:191], v[52:55]
	v_mfma_f32_16x16x32_bf16 v[48:51], v[166:169], v[188:191], v[48:51]
	v_mfma_f32_16x16x32_bf16 v[44:47], v[158:161], v[196:199], v[44:47]
	v_mfma_f32_16x16x32_bf16 v[40:43], v[166:169], v[196:199], v[40:43]
	v_mfma_f32_16x16x32_bf16 v[36:39], v[158:161], v[204:207], v[36:39]
	v_mfma_f32_16x16x32_bf16 v[32:35], v[166:169], v[204:207], v[32:35]
	v_mfma_f32_16x16x32_bf16 v[60:63], v[162:165], v[184:187], v[60:63]
	v_mfma_f32_16x16x32_bf16 v[56:59], v[170:173], v[184:187], v[56:59]
	v_mfma_f32_16x16x32_bf16 v[52:55], v[162:165], v[192:195], v[52:55]
	v_mfma_f32_16x16x32_bf16 v[48:51], v[170:173], v[192:195], v[48:51]
	v_mfma_f32_16x16x32_bf16 v[44:47], v[162:165], v[200:203], v[44:47]
	v_mfma_f32_16x16x32_bf16 v[40:43], v[170:173], v[200:203], v[40:43]
	v_mfma_f32_16x16x32_bf16 v[36:39], v[162:165], v[208:211], v[36:39]
	v_mfma_f32_16x16x32_bf16 v[32:35], v[170:173], v[208:211], v[32:35]
	s_setprio 0
	s_barrier
	v_lshl_add_u64 v[158:159], v[236:237], 0, s[70:71]
	s_add_u32 m0, s3, 0x1c000
	s_nop 0
	global_load_lds_dwordx4 v[158:159], off
	v_lshl_add_u64 v[158:159], v[238:239], 0, s[70:71]
	s_add_u32 m0, s3, 0x1e000
	s_nop 0
	global_load_lds_dwordx4 v[158:159], off
	s_waitcnt vmcnt(6)
	s_barrier
	s_setprio 1
	v_mfma_f32_16x16x32_bf16 v[28:31], v[212:215], v[180:183], v[28:31]
	v_mfma_f32_16x16x32_bf16 v[24:27], v[222:225], v[180:183], v[24:27]
	v_mfma_f32_16x16x32_bf16 v[20:23], v[212:215], v[188:191], v[20:23]
	v_mfma_f32_16x16x32_bf16 v[16:19], v[222:225], v[188:191], v[16:19]
	v_mfma_f32_16x16x32_bf16 v[12:15], v[212:215], v[196:199], v[12:15]
	v_mfma_f32_16x16x32_bf16 v[8:11], v[222:225], v[196:199], v[8:11]
	v_mfma_f32_16x16x32_bf16 v[4:7], v[212:215], v[204:207], v[4:7]
	v_mfma_f32_16x16x32_bf16 v[0:3], v[222:225], v[204:207], v[0:3]
	v_mfma_f32_16x16x32_bf16 v[28:31], v[216:219], v[184:187], v[28:31]
	v_mfma_f32_16x16x32_bf16 v[24:27], v[226:229], v[184:187], v[24:27]
	v_mfma_f32_16x16x32_bf16 v[20:23], v[216:219], v[192:195], v[20:23]
	v_mfma_f32_16x16x32_bf16 v[16:19], v[226:229], v[192:195], v[16:19]
	v_mfma_f32_16x16x32_bf16 v[12:15], v[216:219], v[200:203], v[12:15]
	v_mfma_f32_16x16x32_bf16 v[8:11], v[226:229], v[200:203], v[8:11]
	v_mfma_f32_16x16x32_bf16 v[4:7], v[216:219], v[208:211], v[4:7]
	v_mfma_f32_16x16x32_bf16 v[0:3], v[226:229], v[208:211], v[0:3]
	s_setprio 0
	s_add_i32 s2, s2, 2
	s_add_u32 s12, s12, 0x100
	s_addc_u32 s13, s13, 0
	s_cmp_gt_u32 s2, 27
	s_barrier
	s_cbranch_scc0 .LBB0_2562
	s_add_u32 s2, s10, 0x80f80
	s_addc_u32 s3, s11, 0
	v_readfirstlane_b32 s12, v155
	v_lshl_add_u64 v[150:151], s[2:3], 0, v[178:179]
	s_mov_b32 m0, s12
	v_lshl_add_u64 v[128:129], s[2:3], 0, v[128:129]
	v_readfirstlane_b32 s2, v156
	ds_read_b128 v[130:133], v154
	ds_read_b128 v[134:137], v154 offset:1024
	ds_read_b128 v[146:149], v154 offset:2048
	ds_read_b128 v[158:161], v154 offset:3072
	ds_read_b128 v[162:165], v142
	ds_read_b128 v[166:169], v142 offset:1024
	ds_read_b128 v[170:173], v141
	ds_read_b128 v[180:183], v141 offset:1024
	ds_read_b128 v[184:187], v140
	ds_read_b128 v[188:191], v140 offset:1024
	ds_read_b128 v[192:195], v139
	ds_read_b128 v[196:199], v139 offset:1024
	global_load_lds_dwordx4 v[150:151], off
	s_mov_b32 m0, s2
	s_nop 0
	global_load_lds_dwordx4 v[128:129], off
	s_barrier
	s_waitcnt lgkmcnt(0)
	s_setprio 1
	s_waitcnt lgkmcnt(0)
	v_mfma_f32_16x16x32_bf16 v[124:127], v[130:133], v[162:165], v[124:127]
	v_mfma_f32_16x16x32_bf16 v[120:123], v[146:149], v[162:165], v[120:123]
	v_mfma_f32_16x16x32_bf16 v[116:119], v[130:133], v[170:173], v[116:119]
	v_mfma_f32_16x16x32_bf16 v[112:115], v[146:149], v[170:173], v[112:115]
	v_mfma_f32_16x16x32_bf16 v[108:111], v[130:133], v[184:187], v[108:111]
	v_mfma_f32_16x16x32_bf16 v[104:107], v[146:149], v[184:187], v[104:107]
	v_mfma_f32_16x16x32_bf16 v[100:103], v[130:133], v[192:195], v[100:103]
	v_mfma_f32_16x16x32_bf16 v[96:99], v[146:149], v[192:195], v[96:99]
	v_mfma_f32_16x16x32_bf16 v[124:127], v[134:137], v[166:169], v[124:127]
	v_mfma_f32_16x16x32_bf16 v[120:123], v[158:161], v[166:169], v[120:123]
	v_mfma_f32_16x16x32_bf16 v[116:119], v[134:137], v[180:183], v[116:119]
	v_mfma_f32_16x16x32_bf16 v[112:115], v[158:161], v[180:183], v[112:115]
	v_mfma_f32_16x16x32_bf16 v[108:111], v[134:137], v[188:191], v[108:111]
	v_mfma_f32_16x16x32_bf16 v[104:107], v[158:161], v[188:191], v[104:107]
	v_mfma_f32_16x16x32_bf16 v[100:103], v[134:137], v[196:199], v[100:103]
	v_mfma_f32_16x16x32_bf16 v[96:99], v[158:161], v[196:199], v[96:99]
	s_setprio 0
	s_barrier
	ds_read_b128 v[154:157], v153
	ds_read_b128 v[200:203], v153 offset:1024
	ds_read_b128 v[204:207], v153 offset:2048
	ds_read_b128 v[150:153], v153 offset:3072
	s_barrier
	s_waitcnt lgkmcnt(0)
	s_setprio 1
	s_waitcnt lgkmcnt(0)
	v_mfma_f32_16x16x32_bf16 v[92:95], v[154:157], v[162:165], v[92:95]
	v_mfma_f32_16x16x32_bf16 v[88:91], v[204:207], v[162:165], v[88:91]
	v_mfma_f32_16x16x32_bf16 v[84:87], v[154:157], v[170:173], v[84:87]
	v_mfma_f32_16x16x32_bf16 v[80:83], v[204:207], v[170:173], v[80:83]
	v_mfma_f32_16x16x32_bf16 v[76:79], v[154:157], v[184:187], v[76:79]
	v_mfma_f32_16x16x32_bf16 v[72:75], v[204:207], v[184:187], v[72:75]
	v_mfma_f32_16x16x32_bf16 v[68:71], v[154:157], v[192:195], v[68:71]
	v_mfma_f32_16x16x32_bf16 v[64:67], v[204:207], v[192:195], v[64:67]
	v_mfma_f32_16x16x32_bf16 v[92:95], v[200:203], v[166:169], v[92:95]
	v_mfma_f32_16x16x32_bf16 v[88:91], v[150:153], v[166:169], v[88:91]
	v_mfma_f32_16x16x32_bf16 v[84:87], v[200:203], v[180:183], v[84:87]
	v_mfma_f32_16x16x32_bf16 v[80:83], v[150:153], v[180:183], v[80:83]
	v_mfma_f32_16x16x32_bf16 v[76:79], v[200:203], v[188:191], v[76:79]
	v_mfma_f32_16x16x32_bf16 v[72:75], v[150:153], v[188:191], v[72:75]
	v_mfma_f32_16x16x32_bf16 v[68:71], v[200:203], v[196:199], v[68:71]
	v_mfma_f32_16x16x32_bf16 v[64:67], v[150:153], v[196:199], v[64:67]
	s_setprio 0
	s_barrier
; #define LDA(dst, b, h) _Pragma("unroll") for (int m = 0; m < 4; ++m) _Pragma("unroll") for (int k = 0; k < 2; ++k) \
;     dst[m][k] = *reinterpret_cast<const bf16x8*>((const char*)SA(b, h) + lds_byte(wr * 64 + m * 16 + fr, k * 32 + fq * 8))
; #define LDB(dst, b, h) _Pragma("unroll") for (int n = 0; n < 2; ++n) _Pragma("unroll") for (int k = 0; k < 2; ++k) \
;     dst[n][k] = *reinterpret_cast<const bf16x8*>((const char*)SB(b, h) + lds_byte(wc * 32 + n * 16 + fr, k * 32 + fq * 8))
; #define MMA(ai, bj, At_, Bt_) do { __builtin_amdgcn_s_setprio(1); \
;     _Pragma("unroll") for (int m = 0; m < 4; ++m) _Pragma("unroll") for (int n = 0; n < 2; ++n) _Pragma("unroll") for (int k = 0; k < 2; ++k) \
;       acc[ai][bj][m][n] = __builtin_amdgcn_mfma_f32_16x16x32_bf16(Bt_[n][k], At_[m][k], acc[ai][bj][m][n], 0, 0, 0); \
;     __builtin_amdgcn_s_setprio(0); } while (0)
; #define WAIT_V(n) asm volatile("s_waitcnt vmcnt(" #n ")" ::: "memory")
; #define WAIT_L(n) asm volatile("s_waitcnt lgkmcnt(" #n ")" ::: "memory")
; #define BAR __builtin_amdgcn_s_barrier()
; template <bool PF = true, class Epi, class KRF = KRFull>
; __device__ __forceinline__ void gemm_phase(const u16* __restrict__ A, int lda, const u16* __restrict__ Bt, int ldb, int K, int nM, int nN,
;                                            lds_u16* shm, Epi epi, KRF krf = KRFull(), bool flip = false) {
;     ...
;       LDA(At, 0, 1); WAIT_V(4); BAR; WAIT_L(0); MMA(1, 0, At, B0); MMA(1, 1, At, B1); BAR; }
;     { LDB(B0, 1, 0); LDA(At, 1, 0); WAIT_V(2); BAR; WAIT_L(0); MMA(0, 0, At, B0); BAR;
	ds_read_b128 v[162:165], v142 offset:16384
	ds_read_b128 v[166:169], v142 offset:17408
	ds_read_b128 v[170:173], v141 offset:16384
	ds_read_b128 v[180:183], v141 offset:17408
	ds_read_b128 v[184:187], v140 offset:16384
	ds_read_b128 v[188:191], v140 offset:17408
	ds_read_b128 v[192:195], v139 offset:16384
	ds_read_b128 v[196:199], v139 offset:17408
	s_waitcnt vmcnt(4)
	s_barrier
	s_waitcnt lgkmcnt(0)
	s_setprio 1
	s_waitcnt lgkmcnt(0)
	v_mfma_f32_16x16x32_bf16 v[60:63], v[130:133], v[162:165], v[60:63]
	v_mfma_f32_16x16x32_bf16 v[56:59], v[146:149], v[162:165], v[56:59]
	v_mfma_f32_16x16x32_bf16 v[52:55], v[130:133], v[170:173], v[52:55]
	v_mfma_f32_16x16x32_bf16 v[48:51], v[146:149], v[170:173], v[48:51]
	v_mfma_f32_16x16x32_bf16 v[44:47], v[130:133], v[184:187], v[44:47]
	v_mfma_f32_16x16x32_bf16 v[40:43], v[146:149], v[184:187], v[40:43]
	v_mfma_f32_16x16x32_bf16 v[36:39], v[130:133], v[192:195], v[36:39]
	v_mfma_f32_16x16x32_bf16 v[32:35], v[146:149], v[192:195], v[32:35]
	v_mfma_f32_16x16x32_bf16 v[60:63], v[134:137], v[166:169], v[60:63]
	v_mfma_f32_16x16x32_bf16 v[56:59], v[158:161], v[166:169], v[56:59]
	v_mfma_f32_16x16x32_bf16 v[52:55], v[134:137], v[180:183], v[52:55]
	v_mfma_f32_16x16x32_bf16 v[48:51], v[158:161], v[180:183], v[48:51]
	v_mfma_f32_16x16x32_bf16 v[44:47], v[134:137], v[188:191], v[44:47]
	v_mfma_f32_16x16x32_bf16 v[40:43], v[158:161], v[188:191], v[40:43]
	v_mfma_f32_16x16x32_bf16 v[36:39], v[134:137], v[196:199], v[36:39]
	v_mfma_f32_16x16x32_bf16 v[32:35], v[158:161], v[196:199], v[32:35]
	s_setprio 0
	s_setprio 1
	v_mfma_f32_16x16x32_bf16 v[28:31], v[154:157], v[162:165], v[28:31]
	v_mfma_f32_16x16x32_bf16 v[24:27], v[204:207], v[162:165], v[24:27]
	v_mfma_f32_16x16x32_bf16 v[20:23], v[154:157], v[170:173], v[20:23]
	v_mfma_f32_16x16x32_bf16 v[16:19], v[204:207], v[170:173], v[16:19]
	v_mfma_f32_16x16x32_bf16 v[12:15], v[154:157], v[184:187], v[12:15]
	v_mfma_f32_16x16x32_bf16 v[8:11], v[204:207], v[184:187], v[8:11]
	v_mfma_f32_16x16x32_bf16 v[4:7], v[154:157], v[192:195], v[4:7]
	v_mfma_f32_16x16x32_bf16 v[0:3], v[204:207], v[192:195], v[0:3]
	v_mfma_f32_16x16x32_bf16 v[28:31], v[200:203], v[166:169], v[28:31]
	v_mfma_f32_16x16x32_bf16 v[24:27], v[150:153], v[166:169], v[24:27]
	v_mfma_f32_16x16x32_bf16 v[20:23], v[200:203], v[180:183], v[20:23]
	v_mfma_f32_16x16x32_bf16 v[16:19], v[150:153], v[180:183], v[16:19]
	v_mfma_f32_16x16x32_bf16 v[12:15], v[200:203], v[188:191], v[12:15]
	v_mfma_f32_16x16x32_bf16 v[8:11], v[150:153], v[188:191], v[8:11]
	v_mfma_f32_16x16x32_bf16 v[4:7], v[200:203], v[196:199], v[4:7]
	v_mfma_f32_16x16x32_bf16 v[0:3], v[150:153], v[196:199], v[0:3]
	s_setprio 0
	s_barrier
	ds_read_b128 v[128:131], v145
	ds_read_b128 v[132:135], v145 offset:1024
	ds_read_b128 v[146:149], v145 offset:2048
	ds_read_b128 v[150:153], v145 offset:3072
	ds_read_b128 v[154:157], v142 offset:32768
	ds_read_b128 v[158:161], v142 offset:33792
	ds_read_b128 v[162:165], v141 offset:32768
	ds_read_b128 v[166:169], v141 offset:33792
	ds_read_b128 v[170:173], v140 offset:32768
	ds_read_b128 v[180:183], v140 offset:33792
	ds_read_b128 v[184:187], v139 offset:32768
	ds_read_b128 v[188:191], v139 offset:33792
	s_waitcnt vmcnt(2)
	s_barrier
	s_waitcnt lgkmcnt(0)
	s_setprio 1
	s_waitcnt lgkmcnt(0)
	v_mfma_f32_16x16x32_bf16 v[124:127], v[128:131], v[154:157], v[124:127]
	v_mfma_f32_16x16x32_bf16 v[120:123], v[146:149], v[154:157], v[120:123]
	v_mfma_f32_16x16x32_bf16 v[116:119], v[128:131], v[162:165], v[116:119]
	v_mfma_f32_16x16x32_bf16 v[112:115], v[146:149], v[162:165], v[112:115]
	v_mfma_f32_16x16x32_bf16 v[108:111], v[128:131], v[170:173], v[108:111]
	v_mfma_f32_16x16x32_bf16 v[104:107], v[146:149], v[170:173], v[104:107]
	v_mfma_f32_16x16x32_bf16 v[100:103], v[128:131], v[184:187], v[100:103]
	v_mfma_f32_16x16x32_bf16 v[96:99], v[146:149], v[184:187], v[96:99]
	v_mfma_f32_16x16x32_bf16 v[124:127], v[132:135], v[158:161], v[124:127]
	v_mfma_f32_16x16x32_bf16 v[120:123], v[150:153], v[158:161], v[120:123]
	v_mfma_f32_16x16x32_bf16 v[116:119], v[132:135], v[166:169], v[116:119]
	v_mfma_f32_16x16x32_bf16 v[112:115], v[150:153], v[166:169], v[112:115]
	v_mfma_f32_16x16x32_bf16 v[108:111], v[132:135], v[180:183], v[108:111]
	v_mfma_f32_16x16x32_bf16 v[104:107], v[150:153], v[180:183], v[104:107]
	v_mfma_f32_16x16x32_bf16 v[100:103], v[132:135], v[188:191], v[100:103]
	v_mfma_f32_16x16x32_bf16 v[96:99], v[150:153], v[188:191], v[96:99]
	s_setprio 0
	s_barrier
; #define LDA(dst, b, h) _Pragma("unroll") for (int m = 0; m < 4; ++m) _Pragma("unroll") for (int k = 0; k < 2; ++k) \
;     dst[m][k] = *reinterpret_cast<const bf16x8*>((const char*)SA(b, h) + lds_byte(wr * 64 + m * 16 + fr, k * 32 + fq * 8))
; #define LDB(dst, b, h) _Pragma("unroll") for (int n = 0; n < 2; ++n) _Pragma("unroll") for (int k = 0; k < 2; ++k) \
;     dst[n][k] = *reinterpret_cast<const bf16x8*>((const char*)SB(b, h) + lds_byte(wc * 32 + n * 16 + fr, k * 32 + fq * 8))
; #define MMA(ai, bj, At_, Bt_) do { __builtin_amdgcn_s_setprio(1); \
;     _Pragma("unroll") for (int m = 0; m < 4; ++m) _Pragma("unroll") for (int n = 0; n < 2; ++n) _Pragma("unroll") for (int k = 0; k < 2; ++k) \
;       acc[ai][bj][m][n] = __builtin_amdgcn_mfma_f32_16x16x32_bf16(Bt_[n][k], At_[m][k], acc[ai][bj][m][n], 0, 0, 0); \
;     __builtin_amdgcn_s_setprio(0); } while (0)
; #define WAIT_V(n) asm volatile("s_waitcnt vmcnt(" #n ")" ::: "memory")
; #define WAIT_L(n) asm volatile("s_waitcnt lgkmcnt(" #n ")" ::: "memory")
; #define BAR __builtin_amdgcn_s_barrier()
; template <bool PF = true, class Epi, class KRF = KRFull>
; __device__ __forceinline__ void gemm_phase(const u16* __restrict__ A, int lda, const u16* __restrict__ Bt, int ldb, int K, int nM, int nN,
;                                            lds_u16* shm, Epi epi, KRF krf = KRFull(), bool flip = false) {
;     ...
;       LDB(B1, 1, 1); WAIT_V(0); BAR; WAIT_L(0); MMA(0, 1, At, B1); BAR;
;       LDA(At, 1, 1); BAR; WAIT_L(0); MMA(1, 0, At, B0); MMA(1, 1, At, B1); BAR; }
;     if (wr == 0) BAR;
	ds_read_b128 v[192:195], v143
	ds_read_b128 v[196:199], v143 offset:1024
	ds_read_b128 v[200:203], v143 offset:2048
	ds_read_b128 v[204:207], v143 offset:3072
	s_waitcnt vmcnt(0)
	s_barrier
	s_waitcnt lgkmcnt(0)
	s_setprio 1
	s_waitcnt lgkmcnt(0)
	v_mfma_f32_16x16x32_bf16 v[92:95], v[192:195], v[154:157], v[92:95]
	v_mfma_f32_16x16x32_bf16 v[88:91], v[200:203], v[154:157], v[88:91]
	v_mfma_f32_16x16x32_bf16 v[84:87], v[192:195], v[162:165], v[84:87]
	v_mfma_f32_16x16x32_bf16 v[80:83], v[200:203], v[162:165], v[80:83]
	v_mfma_f32_16x16x32_bf16 v[76:79], v[192:195], v[170:173], v[76:79]
	v_mfma_f32_16x16x32_bf16 v[72:75], v[200:203], v[170:173], v[72:75]
	v_mfma_f32_16x16x32_bf16 v[68:71], v[192:195], v[184:187], v[68:71]
	v_mfma_f32_16x16x32_bf16 v[64:67], v[200:203], v[184:187], v[64:67]
	v_mfma_f32_16x16x32_bf16 v[92:95], v[196:199], v[158:161], v[92:95]
	v_mfma_f32_16x16x32_bf16 v[88:91], v[204:207], v[158:161], v[88:91]
	v_mfma_f32_16x16x32_bf16 v[84:87], v[196:199], v[166:169], v[84:87]
	v_mfma_f32_16x16x32_bf16 v[80:83], v[204:207], v[166:169], v[80:83]
	v_mfma_f32_16x16x32_bf16 v[76:79], v[196:199], v[180:183], v[76:79]
	v_mfma_f32_16x16x32_bf16 v[72:75], v[204:207], v[180:183], v[72:75]
	v_mfma_f32_16x16x32_bf16 v[68:71], v[196:199], v[188:191], v[68:71]
	v_mfma_f32_16x16x32_bf16 v[64:67], v[204:207], v[188:191], v[64:67]
	s_setprio 0
	s_barrier
	ds_read_b128 v[154:157], v142 offset:49152
	ds_read_b128 v[142:145], v142 offset:50176
	ds_read_b128 v[158:161], v141 offset:49152
	ds_read_b128 v[162:165], v141 offset:50176
	ds_read_b128 v[166:169], v140 offset:49152
	ds_read_b128 v[170:173], v140 offset:50176
	ds_read_b128 v[180:183], v139 offset:49152
	ds_read_b128 v[184:187], v139 offset:50176
	s_barrier
	s_waitcnt lgkmcnt(0)
	s_setprio 1
	s_waitcnt lgkmcnt(0)
	v_mfma_f32_16x16x32_bf16 v[60:63], v[128:131], v[154:157], v[60:63]
	v_mfma_f32_16x16x32_bf16 v[56:59], v[146:149], v[154:157], v[56:59]
	v_mfma_f32_16x16x32_bf16 v[52:55], v[128:131], v[158:161], v[52:55]
	v_mfma_f32_16x16x32_bf16 v[48:51], v[146:149], v[158:161], v[48:51]
	v_mfma_f32_16x16x32_bf16 v[44:47], v[128:131], v[166:169], v[44:47]
	v_mfma_f32_16x16x32_bf16 v[40:43], v[146:149], v[166:169], v[40:43]
	v_mfma_f32_16x16x32_bf16 v[36:39], v[128:131], v[180:183], v[36:39]
	v_mfma_f32_16x16x32_bf16 v[32:35], v[146:149], v[180:183], v[32:35]
	v_mfma_f32_16x16x32_bf16 v[60:63], v[132:135], v[142:145], v[60:63]
	v_mfma_f32_16x16x32_bf16 v[56:59], v[150:153], v[142:145], v[56:59]
	v_mfma_f32_16x16x32_bf16 v[52:55], v[132:135], v[162:165], v[52:55]
	v_mfma_f32_16x16x32_bf16 v[48:51], v[150:153], v[162:165], v[48:51]
	v_mfma_f32_16x16x32_bf16 v[44:47], v[132:135], v[170:173], v[44:47]
	v_mfma_f32_16x16x32_bf16 v[40:43], v[150:153], v[170:173], v[40:43]
	v_mfma_f32_16x16x32_bf16 v[36:39], v[132:135], v[184:187], v[36:39]
	v_mfma_f32_16x16x32_bf16 v[32:35], v[150:153], v[184:187], v[32:35]
	s_setprio 0
	s_setprio 1
	v_mfma_f32_16x16x32_bf16 v[28:31], v[192:195], v[154:157], v[28:31]
	v_mfma_f32_16x16x32_bf16 v[24:27], v[200:203], v[154:157], v[24:27]
	v_mfma_f32_16x16x32_bf16 v[20:23], v[192:195], v[158:161], v[20:23]
	v_mfma_f32_16x16x32_bf16 v[16:19], v[200:203], v[158:161], v[16:19]
	v_mfma_f32_16x16x32_bf16 v[12:15], v[192:195], v[166:169], v[12:15]
	v_mfma_f32_16x16x32_bf16 v[8:11], v[200:203], v[166:169], v[8:11]
	v_mfma_f32_16x16x32_bf16 v[4:7], v[192:195], v[180:183], v[4:7]
	v_mfma_f32_16x16x32_bf16 v[0:3], v[200:203], v[180:183], v[0:3]
	v_mfma_f32_16x16x32_bf16 v[28:31], v[196:199], v[142:145], v[28:31]
	v_mfma_f32_16x16x32_bf16 v[24:27], v[204:207], v[142:145], v[24:27]
	v_mfma_f32_16x16x32_bf16 v[20:23], v[196:199], v[162:165], v[20:23]
	v_mfma_f32_16x16x32_bf16 v[16:19], v[204:207], v[162:165], v[16:19]
	v_mfma_f32_16x16x32_bf16 v[12:15], v[196:199], v[170:173], v[12:15]
	v_mfma_f32_16x16x32_bf16 v[8:11], v[204:207], v[170:173], v[8:11]
	v_mfma_f32_16x16x32_bf16 v[4:7], v[196:199], v[184:187], v[4:7]
	v_mfma_f32_16x16x32_bf16 v[0:3], v[204:207], v[184:187], v[0:3]
	s_setprio 0
	v_cmp_gt_u32_e32 vcc, s95, v138
	s_barrier
	s_and_saveexec_b64 s[12:13], vcc
	s_cbranch_execz .LBB0_2565
	s_barrier

; #define STAGE_A(P, half, kt) do { const char* _u = Ab + ((size_t)(half) * 128 * lda + (size_t)(kt) * BK) * 2; \
;     _Pragma("unroll") for (int _i = 0; _i < 2; ++_i) \
;       __builtin_amdgcn_global_load_lds((const unsigned*)(_u + offA[_i]), \
;         (__attribute__((address_space(3))) unsigned*)((__attribute__((address_space(3))) char*)(P) + tidg * 16 + _i * 8192), 16, 0, 0); } while (0)
; #define STAGE_B(P, half, kt) do { const char* _u = Bb + ((size_t)(half) * 128 * ldb + (size_t)(kt) * BK) * 2; \
;     _Pragma("unroll") for (int _i = 0; _i < 2; ++_i) \
;       __builtin_amdgcn_global_load_lds((const unsigned*)(_u + offB[_i]), \
;         (__attribute__((address_space(3))) unsigned*)((__attribute__((address_space(3))) char*)(P) + tidg * 16 + _i * 8192), 16, 0, 0); } while (0)
; #define LDA(dst, b, h) _Pragma("unroll") for (int m = 0; m < 4; ++m) _Pragma("unroll") for (int k = 0; k < 2; ++k) \
;     dst[m][k] = *reinterpret_cast<const bf16x8*>((const char*)SA(b, h) + lds_byte(wr * 64 + m * 16 + fr, k * 32 + fq * 8))
; #define LDB(dst, b, h) _Pragma("unroll") for (int n = 0; n < 2; ++n) _Pragma("unroll") for (int k = 0; k < 2; ++k) \
;     dst[n][k] = *reinterpret_cast<const bf16x8*>((const char*)SB(b, h) + lds_byte(wc * 32 + n * 16 + fr, k * 32 + fq * 8))
; #define MMA(ai, bj, At_, Bt_) do { __builtin_amdgcn_s_setprio(1); \
;     _Pragma("unroll") for (int m = 0; m < 4; ++m) _Pragma("unroll") for (int n = 0; n < 2; ++n) _Pragma("unroll") for (int k = 0; k < 2; ++k) \
;       acc[ai][bj][m][n] = __builtin_amdgcn_mfma_f32_16x16x32_bf16(Bt_[n][k], At_[m][k], acc[ai][bj][m][n], 0, 0, 0); \
;     __builtin_amdgcn_s_setprio(0); } while (0)
; #define BAR __builtin_amdgcn_s_barrier()
; template <bool PF = true, class Epi, class KRF = KRFull>
; __device__ __forceinline__ void gemm_phase(const u16* __restrict__ A, int lda, const u16* __restrict__ Bt, int ldb, int K, int nM, int nN,
;                                            lds_u16* shm, Epi epi, KRF krf = KRFull(), bool flip = false) {
;     ...
;       LDB(B0, 0, 0); SCHED; LDA(At, 0, 0); STAGE_A(SA(1, 1), 1, t + 1);
;       WAIT_L(8); BAR; WAIT_L(0); MMA(0, 0, At, B0); BAR; SCHED;
;       LDB(B1, 0, 1); STAGE_B(SB(0, 0), 0, t + 2);
;       BAR; WAIT_L(0); MMA(0, 1, At, B1); BAR;
;       LDA(At, 0, 1); STAGE_A(SA(0, 0), 0, t + 2);
;       BAR; WAIT_L(0); MMA(1, 0, At, B0); BAR; SCHED;
.LBB0_2580:
	v_readfirstlane_b32 s22, v144
	ds_read_b128 v[158:161], v154
	ds_read_b128 v[162:165], v154 offset:1024
	ds_read_b128 v[166:169], v154 offset:2048
	ds_read_b128 v[170:173], v154 offset:3072
	v_add_u32_e32 v155, 0xc000, v144
	v_lshl_add_u64 v[174:175], v[134:135], 0, s[12:13]
	v_lshl_add_u64 v[156:157], v[174:175], 0, s[72:73]
	s_add_u32 m0, s22, 0xc000
	ds_read_b128 v[180:183], v142
	ds_read_b128 v[184:187], v142 offset:1024
	ds_read_b128 v[188:191], v141
	ds_read_b128 v[192:195], v141 offset:1024
	ds_read_b128 v[196:199], v140
	ds_read_b128 v[200:203], v140 offset:1024
	ds_read_b128 v[204:207], v139
	ds_read_b128 v[208:211], v139 offset:1024
	global_load_lds_dwordx4 v[156:157], off
	v_add_u32_e32 v156, 0xe000, v144
	v_lshl_add_u64 v[234:235], v[136:137], 0, s[12:13]
	v_lshl_add_u64 v[212:213], v[234:235], 0, s[72:73]
	s_add_u32 m0, s22, 0xe000
	s_nop 0
	global_load_lds_dwordx4 v[212:213], off
	s_waitcnt lgkmcnt(8)
	s_barrier
	s_waitcnt lgkmcnt(0)
	s_setprio 1
	s_waitcnt lgkmcnt(0)
	v_mfma_f32_16x16x32_bf16 v[124:127], v[158:161], v[180:183], v[124:127]
	v_mfma_f32_16x16x32_bf16 v[120:123], v[166:169], v[180:183], v[120:123]
	v_mfma_f32_16x16x32_bf16 v[116:119], v[158:161], v[188:191], v[116:119]
	v_mfma_f32_16x16x32_bf16 v[112:115], v[166:169], v[188:191], v[112:115]
	v_mfma_f32_16x16x32_bf16 v[108:111], v[158:161], v[196:199], v[108:111]
	v_mfma_f32_16x16x32_bf16 v[104:107], v[166:169], v[196:199], v[104:107]
	v_mfma_f32_16x16x32_bf16 v[100:103], v[158:161], v[204:207], v[100:103]
	v_mfma_f32_16x16x32_bf16 v[96:99], v[166:169], v[204:207], v[96:99]
	v_mfma_f32_16x16x32_bf16 v[124:127], v[162:165], v[184:187], v[124:127]
	v_mfma_f32_16x16x32_bf16 v[120:123], v[170:173], v[184:187], v[120:123]
	v_mfma_f32_16x16x32_bf16 v[116:119], v[162:165], v[192:195], v[116:119]
	v_mfma_f32_16x16x32_bf16 v[112:115], v[170:173], v[192:195], v[112:115]
	v_mfma_f32_16x16x32_bf16 v[108:111], v[162:165], v[200:203], v[108:111]
	v_mfma_f32_16x16x32_bf16 v[104:107], v[170:173], v[200:203], v[104:107]
	v_mfma_f32_16x16x32_bf16 v[100:103], v[162:165], v[208:211], v[100:103]
	v_mfma_f32_16x16x32_bf16 v[96:99], v[170:173], v[208:211], v[96:99]
	s_setprio 0
	s_barrier
	v_add_u32_e32 v157, 0x10000, v144
	v_lshl_add_u64 v[236:237], v[130:131], 0, s[12:13]
	v_lshl_add_u64 v[238:239], v[236:237], 0, s[64:65]
	s_add_u32 m0, s22, 0x10000
	v_add_u32_e32 v157, 0x12000, v144
	ds_read_b128 v[212:215], v153
	ds_read_b128 v[216:219], v153 offset:1024
	ds_read_b128 v[222:225], v153 offset:2048
	ds_read_b128 v[226:229], v153 offset:3072
	global_load_lds_dwordx4 v[238:239], off
	v_lshl_add_u64 v[238:239], v[132:133], 0, s[12:13]
	v_lshl_add_u64 v[240:241], v[238:239], 0, s[64:65]
	s_add_u32 m0, s22, 0x12000
	s_nop 0
	global_load_lds_dwordx4 v[240:241], off
	s_barrier
	s_waitcnt lgkmcnt(0)
	s_setprio 1
	s_waitcnt lgkmcnt(0)
	v_mfma_f32_16x16x32_bf16 v[92:95], v[212:215], v[180:183], v[92:95]
	v_mfma_f32_16x16x32_bf16 v[88:91], v[222:225], v[180:183], v[88:91]
	v_mfma_f32_16x16x32_bf16 v[84:87], v[212:215], v[188:191], v[84:87]
	v_mfma_f32_16x16x32_bf16 v[80:83], v[222:225], v[188:191], v[80:83]
	v_mfma_f32_16x16x32_bf16 v[76:79], v[212:215], v[196:199], v[76:79]
	v_mfma_f32_16x16x32_bf16 v[72:75], v[222:225], v[196:199], v[72:75]
	v_mfma_f32_16x16x32_bf16 v[68:71], v[212:215], v[204:207], v[68:71]
	v_mfma_f32_16x16x32_bf16 v[64:67], v[222:225], v[204:207], v[64:67]
	v_mfma_f32_16x16x32_bf16 v[92:95], v[216:219], v[184:187], v[92:95]
	v_mfma_f32_16x16x32_bf16 v[88:91], v[226:229], v[184:187], v[88:91]
	v_mfma_f32_16x16x32_bf16 v[84:87], v[216:219], v[192:195], v[84:87]
	v_mfma_f32_16x16x32_bf16 v[80:83], v[226:229], v[192:195], v[80:83]
	v_mfma_f32_16x16x32_bf16 v[76:79], v[216:219], v[200:203], v[76:79]
	v_mfma_f32_16x16x32_bf16 v[72:75], v[226:229], v[200:203], v[72:75]
	v_mfma_f32_16x16x32_bf16 v[68:71], v[216:219], v[208:211], v[68:71]
	v_mfma_f32_16x16x32_bf16 v[64:67], v[226:229], v[208:211], v[64:67]
	s_setprio 0
	v_lshl_add_u64 v[240:241], v[174:175], 0, s[64:65]
	s_mov_b32 m0, s22
	s_barrier
	ds_read_b128 v[180:183], v142 offset:16384
	ds_read_b128 v[184:187], v142 offset:17408
	ds_read_b128 v[188:191], v141 offset:16384
	ds_read_b128 v[192:195], v141 offset:17408
	ds_read_b128 v[196:199], v140 offset:16384
	ds_read_b128 v[200:203], v140 offset:17408
	ds_read_b128 v[204:207], v139 offset:16384
	ds_read_b128 v[208:211], v139 offset:17408
	global_load_lds_dwordx4 v[240:241], off
	v_lshl_add_u64 v[240:241], v[234:235], 0, s[64:65]
	s_add_u32 m0, s22, 0x2000
	s_nop 0
	global_load_lds_dwordx4 v[240:241], off
	s_barrier
	s_waitcnt lgkmcnt(0)
	s_setprio 1
	s_waitcnt lgkmcnt(0)
	v_mfma_f32_16x16x32_bf16 v[60:63], v[158:161], v[180:183], v[60:63]
	v_mfma_f32_16x16x32_bf16 v[56:59], v[166:169], v[180:183], v[56:59]
	v_mfma_f32_16x16x32_bf16 v[52:55], v[158:161], v[188:191], v[52:55]
	v_mfma_f32_16x16x32_bf16 v[48:51], v[166:169], v[188:191], v[48:51]
	v_mfma_f32_16x16x32_bf16 v[44:47], v[158:161], v[196:199], v[44:47]
	v_mfma_f32_16x16x32_bf16 v[40:43], v[166:169], v[196:199], v[40:43]
	v_mfma_f32_16x16x32_bf16 v[36:39], v[158:161], v[204:207], v[36:39]
	v_mfma_f32_16x16x32_bf16 v[32:35], v[166:169], v[204:207], v[32:35]
	v_mfma_f32_16x16x32_bf16 v[60:63], v[162:165], v[184:187], v[60:63]
	v_mfma_f32_16x16x32_bf16 v[56:59], v[170:173], v[184:187], v[56:59]
	v_mfma_f32_16x16x32_bf16 v[52:55], v[162:165], v[192:195], v[52:55]
	v_mfma_f32_16x16x32_bf16 v[48:51], v[170:173], v[192:195], v[48:51]
	v_mfma_f32_16x16x32_bf16 v[44:47], v[162:165], v[200:203], v[44:47]
	v_mfma_f32_16x16x32_bf16 v[40:43], v[170:173], v[200:203], v[40:43]
	v_mfma_f32_16x16x32_bf16 v[36:39], v[162:165], v[208:211], v[36:39]
	v_mfma_f32_16x16x32_bf16 v[32:35], v[170:173], v[208:211], v[32:35]
	s_setprio 0
	s_barrier
; #define STAGE_A(P, half, kt) do { const char* _u = Ab + ((size_t)(half) * 128 * lda + (size_t)(kt) * BK) * 2; \
;     _Pragma("unroll") for (int _i = 0; _i < 2; ++_i) \
;       __builtin_amdgcn_global_load_lds((const unsigned*)(_u + offA[_i]), \
;         (__attribute__((address_space(3))) unsigned*)((__attribute__((address_space(3))) char*)(P) + tidg * 16 + _i * 8192), 16, 0, 0); } while (0)
; #define STAGE_B(P, half, kt) do { const char* _u = Bb + ((size_t)(half) * 128 * ldb + (size_t)(kt) * BK) * 2; \
;     _Pragma("unroll") for (int _i = 0; _i < 2; ++_i) \
;       __builtin_amdgcn_global_load_lds((const unsigned*)(_u + offB[_i]), \
;         (__attribute__((address_space(3))) unsigned*)((__attribute__((address_space(3))) char*)(P) + tidg * 16 + _i * 8192), 16, 0, 0); } while (0)
; #define LDA(dst, b, h) _Pragma("unroll") for (int m = 0; m < 4; ++m) _Pragma("unroll") for (int k = 0; k < 2; ++k) \
;     dst[m][k] = *reinterpret_cast<const bf16x8*>((const char*)SA(b, h) + lds_byte(wr * 64 + m * 16 + fr, k * 32 + fq * 8))
; #define LDB(dst, b, h) _Pragma("unroll") for (int n = 0; n < 2; ++n) _Pragma("unroll") for (int k = 0; k < 2; ++k) \
;     dst[n][k] = *reinterpret_cast<const bf16x8*>((const char*)SB(b, h) + lds_byte(wc * 32 + n * 16 + fr, k * 32 + fq * 8))
; #define MMA(ai, bj, At_, Bt_) do { __builtin_amdgcn_s_setprio(1); \
;     _Pragma("unroll") for (int m = 0; m < 4; ++m) _Pragma("unroll") for (int n = 0; n < 2; ++n) _Pragma("unroll") for (int k = 0; k < 2; ++k) \
;       acc[ai][bj][m][n] = __builtin_amdgcn_mfma_f32_16x16x32_bf16(Bt_[n][k], At_[m][k], acc[ai][bj][m][n], 0, 0, 0); \
;     __builtin_amdgcn_s_setprio(0); } while (0)
; #define BAR __builtin_amdgcn_s_barrier()
; template <bool PF = true, class Epi, class KRF = KRFull>
; __device__ __forceinline__ void gemm_phase(const u16* __restrict__ A, int lda, const u16* __restrict__ Bt, int ldb, int K, int nM, int nN,
;                                            lds_u16* shm, Epi epi, KRF krf = KRFull(), bool flip = false) {
;     ...
;       STAGE_B(SB(0, 1), 1, t + 2);
;       WAIT_V(6); BAR; MMA(1, 1, At, B1); BAR;
;       LDB(B0, 1, 0); SCHED; LDA(At, 1, 0); STAGE_A(SA(0, 1), 1, t + 2);
;       WAIT_L(8); BAR; WAIT_L(0); MMA(0, 0, At, B0); BAR; SCHED;
;       LDB(B1, 1, 1); STAGE_B(SB(1, 0), 0, t + 3);
;       BAR; WAIT_L(0); MMA(0, 1, At, B1); BAR;
;       LDA(At, 1, 1); STAGE_A(SA(1, 0), 0, t + 3);
	v_add_u32_e32 v157, 0x14000, v144
	v_lshl_add_u64 v[158:159], v[236:237], 0, s[74:75]
	v_add_u32_e32 v157, 0x16000, v144
	s_add_u32 m0, s22, 0x14000
	s_nop 0
	global_load_lds_dwordx4 v[158:159], off
	v_lshl_add_u64 v[158:159], v[238:239], 0, s[74:75]
	s_add_u32 m0, s22, 0x16000
	s_nop 0
	global_load_lds_dwordx4 v[158:159], off
	s_waitcnt vmcnt(6)
	s_barrier
	s_setprio 1
	v_mfma_f32_16x16x32_bf16 v[28:31], v[212:215], v[180:183], v[28:31]
	v_mfma_f32_16x16x32_bf16 v[24:27], v[222:225], v[180:183], v[24:27]
	v_mfma_f32_16x16x32_bf16 v[20:23], v[212:215], v[188:191], v[20:23]
	v_mfma_f32_16x16x32_bf16 v[16:19], v[222:225], v[188:191], v[16:19]
	v_mfma_f32_16x16x32_bf16 v[12:15], v[212:215], v[196:199], v[12:15]
	v_mfma_f32_16x16x32_bf16 v[8:11], v[222:225], v[196:199], v[8:11]
	v_mfma_f32_16x16x32_bf16 v[4:7], v[212:215], v[204:207], v[4:7]
	v_mfma_f32_16x16x32_bf16 v[0:3], v[222:225], v[204:207], v[0:3]
	v_mfma_f32_16x16x32_bf16 v[28:31], v[216:219], v[184:187], v[28:31]
	v_mfma_f32_16x16x32_bf16 v[24:27], v[226:229], v[184:187], v[24:27]
	v_mfma_f32_16x16x32_bf16 v[20:23], v[216:219], v[192:195], v[20:23]
	v_mfma_f32_16x16x32_bf16 v[16:19], v[226:229], v[192:195], v[16:19]
	v_mfma_f32_16x16x32_bf16 v[12:15], v[216:219], v[200:203], v[12:15]
	v_mfma_f32_16x16x32_bf16 v[8:11], v[226:229], v[200:203], v[8:11]
	v_mfma_f32_16x16x32_bf16 v[4:7], v[216:219], v[208:211], v[4:7]
	v_mfma_f32_16x16x32_bf16 v[0:3], v[226:229], v[208:211], v[0:3]
	s_setprio 0
	s_barrier
	ds_read_b128 v[158:161], v145
	ds_read_b128 v[162:165], v145 offset:1024
	ds_read_b128 v[166:169], v145 offset:2048
	ds_read_b128 v[170:173], v145 offset:3072
	v_add_u32_e32 v157, 0x4000, v144
	v_lshl_add_u64 v[212:213], v[174:175], 0, s[74:75]
	v_add_u32_e32 v157, 0x6000, v144
	s_add_u32 m0, s22, 0x4000
	ds_read_b128 v[180:183], v142 offset:32768
	ds_read_b128 v[184:187], v142 offset:33792
	ds_read_b128 v[188:191], v141 offset:32768
	ds_read_b128 v[192:195], v141 offset:33792
	ds_read_b128 v[196:199], v140 offset:32768
	ds_read_b128 v[200:203], v140 offset:33792
	ds_read_b128 v[204:207], v139 offset:32768
	ds_read_b128 v[208:211], v139 offset:33792
	global_load_lds_dwordx4 v[212:213], off
	v_lshl_add_u64 v[212:213], v[234:235], 0, s[74:75]
	s_add_u32 m0, s22, 0x6000
	s_nop 0
	global_load_lds_dwordx4 v[212:213], off
	s_waitcnt lgkmcnt(8)
	s_barrier
	s_waitcnt lgkmcnt(0)
	s_setprio 1
	s_waitcnt lgkmcnt(0)
	v_mfma_f32_16x16x32_bf16 v[124:127], v[158:161], v[180:183], v[124:127]
	v_mfma_f32_16x16x32_bf16 v[120:123], v[166:169], v[180:183], v[120:123]
	v_mfma_f32_16x16x32_bf16 v[116:119], v[158:161], v[188:191], v[116:119]
	v_mfma_f32_16x16x32_bf16 v[112:115], v[166:169], v[188:191], v[112:115]
	v_mfma_f32_16x16x32_bf16 v[108:111], v[158:161], v[196:199], v[108:111]
	v_mfma_f32_16x16x32_bf16 v[104:107], v[166:169], v[196:199], v[104:107]
	v_mfma_f32_16x16x32_bf16 v[100:103], v[158:161], v[204:207], v[100:103]
	v_mfma_f32_16x16x32_bf16 v[96:99], v[166:169], v[204:207], v[96:99]
	v_mfma_f32_16x16x32_bf16 v[124:127], v[162:165], v[184:187], v[124:127]
	v_mfma_f32_16x16x32_bf16 v[120:123], v[170:173], v[184:187], v[120:123]
	v_mfma_f32_16x16x32_bf16 v[116:119], v[162:165], v[192:195], v[116:119]
	v_mfma_f32_16x16x32_bf16 v[112:115], v[170:173], v[192:195], v[112:115]
	v_mfma_f32_16x16x32_bf16 v[108:111], v[162:165], v[200:203], v[108:111]
	v_mfma_f32_16x16x32_bf16 v[104:107], v[170:173], v[200:203], v[104:107]
	v_mfma_f32_16x16x32_bf16 v[100:103], v[162:165], v[208:211], v[100:103]
	v_mfma_f32_16x16x32_bf16 v[96:99], v[170:173], v[208:211], v[96:99]
	s_setprio 0
	s_barrier
	v_lshl_add_u64 v[240:241], v[236:237], 0, s[68:69]
	s_add_u32 m0, s22, 0x18000
	ds_read_b128 v[212:215], v143
	ds_read_b128 v[216:219], v143 offset:1024
	ds_read_b128 v[222:225], v143 offset:2048
	ds_read_b128 v[226:229], v143 offset:3072
	global_load_lds_dwordx4 v[240:241], off
	v_lshl_add_u64 v[240:241], v[238:239], 0, s[68:69]
	s_add_u32 m0, s22, 0x1a000
	s_nop 0
	global_load_lds_dwordx4 v[240:241], off
	s_barrier
	s_waitcnt lgkmcnt(0)
	s_setprio 1
	s_waitcnt lgkmcnt(0)
	v_mfma_f32_16x16x32_bf16 v[92:95], v[212:215], v[180:183], v[92:95]
	v_mfma_f32_16x16x32_bf16 v[88:91], v[222:225], v[180:183], v[88:91]
	v_mfma_f32_16x16x32_bf16 v[84:87], v[212:215], v[188:191], v[84:87]
	v_mfma_f32_16x16x32_bf16 v[80:83], v[222:225], v[188:191], v[80:83]
	v_mfma_f32_16x16x32_bf16 v[76:79], v[212:215], v[196:199], v[76:79]
	v_mfma_f32_16x16x32_bf16 v[72:75], v[222:225], v[196:199], v[72:75]
	v_mfma_f32_16x16x32_bf16 v[68:71], v[212:215], v[204:207], v[68:71]
	v_mfma_f32_16x16x32_bf16 v[64:67], v[222:225], v[204:207], v[64:67]
	v_mfma_f32_16x16x32_bf16 v[92:95], v[216:219], v[184:187], v[92:95]
	v_mfma_f32_16x16x32_bf16 v[88:91], v[226:229], v[184:187], v[88:91]
	v_mfma_f32_16x16x32_bf16 v[84:87], v[216:219], v[192:195], v[84:87]
	v_mfma_f32_16x16x32_bf16 v[80:83], v[226:229], v[192:195], v[80:83]
	v_mfma_f32_16x16x32_bf16 v[76:79], v[216:219], v[200:203], v[76:79]
	v_mfma_f32_16x16x32_bf16 v[72:75], v[226:229], v[200:203], v[72:75]
	v_mfma_f32_16x16x32_bf16 v[68:71], v[216:219], v[208:211], v[68:71]
	v_mfma_f32_16x16x32_bf16 v[64:67], v[226:229], v[208:211], v[64:67]
	s_setprio 0
	v_lshl_add_u64 v[174:175], v[174:175], 0, s[68:69]
	s_add_u32 m0, s22, 0x8000
	s_barrier
	ds_read_b128 v[180:183], v142 offset:49152
	ds_read_b128 v[184:187], v142 offset:50176
	ds_read_b128 v[188:191], v141 offset:49152
	ds_read_b128 v[192:195], v141 offset:50176
	ds_read_b128 v[196:199], v140 offset:49152
	ds_read_b128 v[200:203], v140 offset:50176
	ds_read_b128 v[204:207], v139 offset:49152
	ds_read_b128 v[208:211], v139 offset:50176
	global_load_lds_dwordx4 v[174:175], off
	v_lshl_add_u64 v[174:175], v[234:235], 0, s[68:69]
	s_add_u32 m0, s22, 0xa000
	s_nop 0
	global_load_lds_dwordx4 v[174:175], off
	s_barrier
; #define STAGE_A(P, half, kt) do { const char* _u = Ab + ((size_t)(half) * 128 * lda + (size_t)(kt) * BK) * 2; \
;     _Pragma("unroll") for (int _i = 0; _i < 2; ++_i) \
;       __builtin_amdgcn_global_load_lds((const unsigned*)(_u + offA[_i]), \
;         (__attribute__((address_space(3))) unsigned*)((__attribute__((address_space(3))) char*)(P) + tidg * 16 + _i * 8192), 16, 0, 0); } while (0)
; #define STAGE_B(P, half, kt) do { const char* _u = Bb + ((size_t)(half) * 128 * ldb + (size_t)(kt) * BK) * 2; \
;     _Pragma("unroll") for (int _i = 0; _i < 2; ++_i) \
;       __builtin_amdgcn_global_load_lds((const unsigned*)(_u + offB[_i]), \
;         (__attribute__((address_space(3))) unsigned*)((__attribute__((address_space(3))) char*)(P) + tidg * 16 + _i * 8192), 16, 0, 0); } while (0)
; #define LDA(dst, b, h) _Pragma("unroll") for (int m = 0; m < 4; ++m) _Pragma("unroll") for (int k = 0; k < 2; ++k) \
;     dst[m][k] = *reinterpret_cast<const bf16x8*>((const char*)SA(b, h) + lds_byte(wr * 64 + m * 16 + fr, k * 32 + fq * 8))
; #define LDB(dst, b, h) _Pragma("unroll") for (int n = 0; n < 2; ++n) _Pragma("unroll") for (int k = 0; k < 2; ++k) \
;     dst[n][k] = *reinterpret_cast<const bf16x8*>((const char*)SB(b, h) + lds_byte(wc * 32 + n * 16 + fr, k * 32 + fq * 8))
; #define MMA(ai, bj, At_, Bt_) do { __builtin_amdgcn_s_setprio(1); \
;     _Pragma("unroll") for (int m = 0; m < 4; ++m) _Pragma("unroll") for (int n = 0; n < 2; ++n) _Pragma("unroll") for (int k = 0; k < 2; ++k) \
;       acc[ai][bj][m][n] = __builtin_amdgcn_mfma_f32_16x16x32_bf16(Bt_[n][k], At_[m][k], acc[ai][bj][m][n], 0, 0, 0); \
;     __builtin_amdgcn_s_setprio(0); } while (0)
; #define WAIT_V(n) asm volatile("s_waitcnt vmcnt(" #n ")" ::: "memory")
; template <bool PF = true, class Epi, class KRF = KRFull>
; __device__ __forceinline__ void gemm_phase(const u16* __restrict__ A, int lda, const u16* __restrict__ Bt, int ldb, int K, int nM, int nN,
;                                            lds_u16* shm, Epi epi, KRF krf = KRFull(), bool flip = false) {
;     ...
;       BAR; WAIT_L(0); MMA(1, 0, At, B0); BAR; SCHED;
;       STAGE_B(SB(1, 1), 1, t + 3);
;       WAIT_V(6); BAR; MMA(1, 1, At, B1); BAR;
;     }
;     { LDB(B0, 0, 0); LDA(At, 0, 0); STAGE_A(SA(1, 1), 1, nt - 1);
;       BAR; WAIT_L(0); MMA(0, 0, At, B0); BAR;
;       LDB(B1, 0, 1); BAR; WAIT_L(0); MMA(0, 1, At, B1); BAR;
	s_waitcnt lgkmcnt(0)
	s_setprio 1
	s_waitcnt lgkmcnt(0)
	v_mfma_f32_16x16x32_bf16 v[60:63], v[158:161], v[180:183], v[60:63]
	v_mfma_f32_16x16x32_bf16 v[56:59], v[166:169], v[180:183], v[56:59]
	v_mfma_f32_16x16x32_bf16 v[52:55], v[158:161], v[188:191], v[52:55]
	v_mfma_f32_16x16x32_bf16 v[48:51], v[166:169], v[188:191], v[48:51]
	v_mfma_f32_16x16x32_bf16 v[44:47], v[158:161], v[196:199], v[44:47]
	v_mfma_f32_16x16x32_bf16 v[40:43], v[166:169], v[196:199], v[40:43]
	v_mfma_f32_16x16x32_bf16 v[36:39], v[158:161], v[204:207], v[36:39]
	v_mfma_f32_16x16x32_bf16 v[32:35], v[166:169], v[204:207], v[32:35]
	v_mfma_f32_16x16x32_bf16 v[60:63], v[162:165], v[184:187], v[60:63]
	v_mfma_f32_16x16x32_bf16 v[56:59], v[170:173], v[184:187], v[56:59]
	v_mfma_f32_16x16x32_bf16 v[52:55], v[162:165], v[192:195], v[52:55]
	v_mfma_f32_16x16x32_bf16 v[48:51], v[170:173], v[192:195], v[48:51]
	v_mfma_f32_16x16x32_bf16 v[44:47], v[162:165], v[200:203], v[44:47]
	v_mfma_f32_16x16x32_bf16 v[40:43], v[170:173], v[200:203], v[40:43]
	v_mfma_f32_16x16x32_bf16 v[36:39], v[162:165], v[208:211], v[36:39]
	v_mfma_f32_16x16x32_bf16 v[32:35], v[170:173], v[208:211], v[32:35]
	s_setprio 0
	s_barrier
	v_lshl_add_u64 v[158:159], v[236:237], 0, s[76:77]
	s_add_u32 m0, s22, 0x1c000
	s_nop 0
	global_load_lds_dwordx4 v[158:159], off
	v_lshl_add_u64 v[158:159], v[238:239], 0, s[76:77]
	s_add_u32 m0, s22, 0x1e000
	s_nop 0
	global_load_lds_dwordx4 v[158:159], off
	s_waitcnt vmcnt(6)
	s_barrier
	s_setprio 1
	v_mfma_f32_16x16x32_bf16 v[28:31], v[212:215], v[180:183], v[28:31]
	v_mfma_f32_16x16x32_bf16 v[24:27], v[222:225], v[180:183], v[24:27]
	v_mfma_f32_16x16x32_bf16 v[20:23], v[212:215], v[188:191], v[20:23]
	v_mfma_f32_16x16x32_bf16 v[16:19], v[222:225], v[188:191], v[16:19]
	v_mfma_f32_16x16x32_bf16 v[12:15], v[212:215], v[196:199], v[12:15]
	v_mfma_f32_16x16x32_bf16 v[8:11], v[222:225], v[196:199], v[8:11]
	v_mfma_f32_16x16x32_bf16 v[4:7], v[212:215], v[204:207], v[4:7]
	v_mfma_f32_16x16x32_bf16 v[0:3], v[222:225], v[204:207], v[0:3]
	v_mfma_f32_16x16x32_bf16 v[28:31], v[216:219], v[184:187], v[28:31]
	v_mfma_f32_16x16x32_bf16 v[24:27], v[226:229], v[184:187], v[24:27]
	v_mfma_f32_16x16x32_bf16 v[20:23], v[216:219], v[192:195], v[20:23]
	v_mfma_f32_16x16x32_bf16 v[16:19], v[226:229], v[192:195], v[16:19]
	v_mfma_f32_16x16x32_bf16 v[12:15], v[216:219], v[200:203], v[12:15]
	v_mfma_f32_16x16x32_bf16 v[8:11], v[226:229], v[200:203], v[8:11]
	v_mfma_f32_16x16x32_bf16 v[4:7], v[216:219], v[208:211], v[4:7]
	v_mfma_f32_16x16x32_bf16 v[0:3], v[226:229], v[208:211], v[0:3]
	s_setprio 0
	s_add_i32 s21, s21, 2
	s_add_u32 s12, s12, 0x100
	s_addc_u32 s13, s13, 0
	s_cmpk_gt_u32 s21, 0x53
	s_barrier
	s_cbranch_scc0 .LBB0_2580
	s_add_u32 s12, s6, 0x162b80
	s_addc_u32 s13, s7, 0
	v_readfirstlane_b32 s21, v155
	v_lshl_add_u64 v[150:151], s[12:13], 0, v[178:179]
	s_mov_b32 m0, s21
	v_lshl_add_u64 v[128:129], s[12:13], 0, v[128:129]
	v_readfirstlane_b32 s12, v156
	ds_read_b128 v[130:133], v154
	ds_read_b128 v[134:137], v154 offset:1024
	ds_read_b128 v[146:149], v154 offset:2048
	ds_read_b128 v[158:161], v154 offset:3072
	ds_read_b128 v[162:165], v142
	ds_read_b128 v[166:169], v142 offset:1024
	ds_read_b128 v[170:173], v141
	ds_read_b128 v[180:183], v141 offset:1024
	ds_read_b128 v[184:187], v140
	ds_read_b128 v[188:191], v140 offset:1024
	ds_read_b128 v[192:195], v139
	ds_read_b128 v[196:199], v139 offset:1024
	global_load_lds_dwordx4 v[150:151], off
	s_mov_b32 m0, s12
	s_nop 0
	global_load_lds_dwordx4 v[128:129], off
	s_barrier
	s_waitcnt lgkmcnt(0)
	s_setprio 1
	s_waitcnt lgkmcnt(0)
	v_mfma_f32_16x16x32_bf16 v[124:127], v[130:133], v[162:165], v[124:127]
	v_mfma_f32_16x16x32_bf16 v[120:123], v[146:149], v[162:165], v[120:123]
	v_mfma_f32_16x16x32_bf16 v[116:119], v[130:133], v[170:173], v[116:119]
	v_mfma_f32_16x16x32_bf16 v[112:115], v[146:149], v[170:173], v[112:115]
	v_mfma_f32_16x16x32_bf16 v[108:111], v[130:133], v[184:187], v[108:111]
	v_mfma_f32_16x16x32_bf16 v[104:107], v[146:149], v[184:187], v[104:107]
	v_mfma_f32_16x16x32_bf16 v[100:103], v[130:133], v[192:195], v[100:103]
	v_mfma_f32_16x16x32_bf16 v[96:99], v[146:149], v[192:195], v[96:99]
	v_mfma_f32_16x16x32_bf16 v[124:127], v[134:137], v[166:169], v[124:127]
	v_mfma_f32_16x16x32_bf16 v[120:123], v[158:161], v[166:169], v[120:123]
	v_mfma_f32_16x16x32_bf16 v[116:119], v[134:137], v[180:183], v[116:119]
	v_mfma_f32_16x16x32_bf16 v[112:115], v[158:161], v[180:183], v[112:115]
	v_mfma_f32_16x16x32_bf16 v[108:111], v[134:137], v[188:191], v[108:111]
	v_mfma_f32_16x16x32_bf16 v[104:107], v[158:161], v[188:191], v[104:107]
	v_mfma_f32_16x16x32_bf16 v[100:103], v[134:137], v[196:199], v[100:103]
	v_mfma_f32_16x16x32_bf16 v[96:99], v[158:161], v[196:199], v[96:99]
	s_setprio 0
	s_barrier
	ds_read_b128 v[154:157], v153
	ds_read_b128 v[200:203], v153 offset:1024
	ds_read_b128 v[204:207], v153 offset:2048
	ds_read_b128 v[150:153], v153 offset:3072
	s_barrier
	s_waitcnt lgkmcnt(0)
	s_setprio 1
	s_waitcnt lgkmcnt(0)
	v_mfma_f32_16x16x32_bf16 v[92:95], v[154:157], v[162:165], v[92:95]
	v_mfma_f32_16x16x32_bf16 v[88:91], v[204:207], v[162:165], v[88:91]
	v_mfma_f32_16x16x32_bf16 v[84:87], v[154:157], v[170:173], v[84:87]
	v_mfma_f32_16x16x32_bf16 v[80:83], v[204:207], v[170:173], v[80:83]
	v_mfma_f32_16x16x32_bf16 v[76:79], v[154:157], v[184:187], v[76:79]
	v_mfma_f32_16x16x32_bf16 v[72:75], v[204:207], v[184:187], v[72:75]
	v_mfma_f32_16x16x32_bf16 v[68:71], v[154:157], v[192:195], v[68:71]
	v_mfma_f32_16x16x32_bf16 v[64:67], v[204:207], v[192:195], v[64:67]
	v_mfma_f32_16x16x32_bf16 v[92:95], v[200:203], v[166:169], v[92:95]
	v_mfma_f32_16x16x32_bf16 v[88:91], v[150:153], v[166:169], v[88:91]
	v_mfma_f32_16x16x32_bf16 v[84:87], v[200:203], v[180:183], v[84:87]
	v_mfma_f32_16x16x32_bf16 v[80:83], v[150:153], v[180:183], v[80:83]
	v_mfma_f32_16x16x32_bf16 v[76:79], v[200:203], v[188:191], v[76:79]
	v_mfma_f32_16x16x32_bf16 v[72:75], v[150:153], v[188:191], v[72:75]
	v_mfma_f32_16x16x32_bf16 v[68:71], v[200:203], v[196:199], v[68:71]
	v_mfma_f32_16x16x32_bf16 v[64:67], v[150:153], v[196:199], v[64:67]
	s_setprio 0
	s_barrier
; #define LDA(dst, b, h) _Pragma("unroll") for (int m = 0; m < 4; ++m) _Pragma("unroll") for (int k = 0; k < 2; ++k) \
;     dst[m][k] = *reinterpret_cast<const bf16x8*>((const char*)SA(b, h) + lds_byte(wr * 64 + m * 16 + fr, k * 32 + fq * 8))
; #define LDB(dst, b, h) _Pragma("unroll") for (int n = 0; n < 2; ++n) _Pragma("unroll") for (int k = 0; k < 2; ++k) \
;     dst[n][k] = *reinterpret_cast<const bf16x8*>((const char*)SB(b, h) + lds_byte(wc * 32 + n * 16 + fr, k * 32 + fq * 8))
; #define MMA(ai, bj, At_, Bt_) do { __builtin_amdgcn_s_setprio(1); \
;     _Pragma("unroll") for (int m = 0; m < 4; ++m) _Pragma("unroll") for (int n = 0; n < 2; ++n) _Pragma("unroll") for (int k = 0; k < 2; ++k) \
;       acc[ai][bj][m][n] = __builtin_amdgcn_mfma_f32_16x16x32_bf16(Bt_[n][k], At_[m][k], acc[ai][bj][m][n], 0, 0, 0); \
;     __builtin_amdgcn_s_setprio(0); } while (0)
; #define WAIT_V(n) asm volatile("s_waitcnt vmcnt(" #n ")" ::: "memory")
; #define WAIT_L(n) asm volatile("s_waitcnt lgkmcnt(" #n ")" ::: "memory")
; #define BAR __builtin_amdgcn_s_barrier()
; template <bool PF = true, class Epi, class KRF = KRFull>
; __device__ __forceinline__ void gemm_phase(const u16* __restrict__ A, int lda, const u16* __restrict__ Bt, int ldb, int K, int nM, int nN,
;                                            lds_u16* shm, Epi epi, KRF krf = KRFull(), bool flip = false) {
;     ...
;       LDA(At, 0, 1); WAIT_V(4); BAR; WAIT_L(0); MMA(1, 0, At, B0); MMA(1, 1, At, B1); BAR; }
;     { LDB(B0, 1, 0); LDA(At, 1, 0); WAIT_V(2); BAR; WAIT_L(0); MMA(0, 0, At, B0); BAR;
	ds_read_b128 v[162:165], v142 offset:16384
	ds_read_b128 v[166:169], v142 offset:17408
	ds_read_b128 v[170:173], v141 offset:16384
	ds_read_b128 v[180:183], v141 offset:17408
	ds_read_b128 v[184:187], v140 offset:16384
	ds_read_b128 v[188:191], v140 offset:17408
	ds_read_b128 v[192:195], v139 offset:16384
	ds_read_b128 v[196:199], v139 offset:17408
	s_waitcnt vmcnt(4)
	s_barrier
	s_waitcnt lgkmcnt(0)
	s_setprio 1
	s_waitcnt lgkmcnt(0)
	v_mfma_f32_16x16x32_bf16 v[60:63], v[130:133], v[162:165], v[60:63]
	v_mfma_f32_16x16x32_bf16 v[56:59], v[146:149], v[162:165], v[56:59]
	v_mfma_f32_16x16x32_bf16 v[52:55], v[130:133], v[170:173], v[52:55]
	v_mfma_f32_16x16x32_bf16 v[48:51], v[146:149], v[170:173], v[48:51]
	v_mfma_f32_16x16x32_bf16 v[44:47], v[130:133], v[184:187], v[44:47]
	v_mfma_f32_16x16x32_bf16 v[40:43], v[146:149], v[184:187], v[40:43]
	v_mfma_f32_16x16x32_bf16 v[36:39], v[130:133], v[192:195], v[36:39]
	v_mfma_f32_16x16x32_bf16 v[32:35], v[146:149], v[192:195], v[32:35]
	v_mfma_f32_16x16x32_bf16 v[60:63], v[134:137], v[166:169], v[60:63]
	v_mfma_f32_16x16x32_bf16 v[56:59], v[158:161], v[166:169], v[56:59]
	v_mfma_f32_16x16x32_bf16 v[52:55], v[134:137], v[180:183], v[52:55]
	v_mfma_f32_16x16x32_bf16 v[48:51], v[158:161], v[180:183], v[48:51]
	v_mfma_f32_16x16x32_bf16 v[44:47], v[134:137], v[188:191], v[44:47]
	v_mfma_f32_16x16x32_bf16 v[40:43], v[158:161], v[188:191], v[40:43]
	v_mfma_f32_16x16x32_bf16 v[36:39], v[134:137], v[196:199], v[36:39]
	v_mfma_f32_16x16x32_bf16 v[32:35], v[158:161], v[196:199], v[32:35]
	s_setprio 0
	s_setprio 1
	v_mfma_f32_16x16x32_bf16 v[28:31], v[154:157], v[162:165], v[28:31]
	v_mfma_f32_16x16x32_bf16 v[24:27], v[204:207], v[162:165], v[24:27]
	v_mfma_f32_16x16x32_bf16 v[20:23], v[154:157], v[170:173], v[20:23]
	v_mfma_f32_16x16x32_bf16 v[16:19], v[204:207], v[170:173], v[16:19]
	v_mfma_f32_16x16x32_bf16 v[12:15], v[154:157], v[184:187], v[12:15]
	v_mfma_f32_16x16x32_bf16 v[8:11], v[204:207], v[184:187], v[8:11]
	v_mfma_f32_16x16x32_bf16 v[4:7], v[154:157], v[192:195], v[4:7]
	v_mfma_f32_16x16x32_bf16 v[0:3], v[204:207], v[192:195], v[0:3]
	v_mfma_f32_16x16x32_bf16 v[28:31], v[200:203], v[166:169], v[28:31]
	v_mfma_f32_16x16x32_bf16 v[24:27], v[150:153], v[166:169], v[24:27]
	v_mfma_f32_16x16x32_bf16 v[20:23], v[200:203], v[180:183], v[20:23]
	v_mfma_f32_16x16x32_bf16 v[16:19], v[150:153], v[180:183], v[16:19]
	v_mfma_f32_16x16x32_bf16 v[12:15], v[200:203], v[188:191], v[12:15]
	v_mfma_f32_16x16x32_bf16 v[8:11], v[150:153], v[188:191], v[8:11]
	v_mfma_f32_16x16x32_bf16 v[4:7], v[200:203], v[196:199], v[4:7]
	v_mfma_f32_16x16x32_bf16 v[0:3], v[150:153], v[196:199], v[0:3]
	s_setprio 0
	s_barrier
	ds_read_b128 v[128:131], v145
	ds_read_b128 v[132:135], v145 offset:1024
	ds_read_b128 v[146:149], v145 offset:2048
	ds_read_b128 v[150:153], v145 offset:3072
	ds_read_b128 v[154:157], v142 offset:32768
	ds_read_b128 v[158:161], v142 offset:33792
	ds_read_b128 v[162:165], v141 offset:32768
	ds_read_b128 v[166:169], v141 offset:33792
	ds_read_b128 v[170:173], v140 offset:32768
	ds_read_b128 v[180:183], v140 offset:33792
	ds_read_b128 v[184:187], v139 offset:32768
	ds_read_b128 v[188:191], v139 offset:33792
	s_waitcnt vmcnt(2)
	s_barrier
	s_waitcnt lgkmcnt(0)
	s_setprio 1
	s_waitcnt lgkmcnt(0)
	v_mfma_f32_16x16x32_bf16 v[124:127], v[128:131], v[154:157], v[124:127]
	v_mfma_f32_16x16x32_bf16 v[120:123], v[146:149], v[154:157], v[120:123]
	v_mfma_f32_16x16x32_bf16 v[116:119], v[128:131], v[162:165], v[116:119]
	v_mfma_f32_16x16x32_bf16 v[112:115], v[146:149], v[162:165], v[112:115]
	v_mfma_f32_16x16x32_bf16 v[108:111], v[128:131], v[170:173], v[108:111]
	v_mfma_f32_16x16x32_bf16 v[104:107], v[146:149], v[170:173], v[104:107]
	v_mfma_f32_16x16x32_bf16 v[100:103], v[128:131], v[184:187], v[100:103]
	v_mfma_f32_16x16x32_bf16 v[96:99], v[146:149], v[184:187], v[96:99]
	v_mfma_f32_16x16x32_bf16 v[124:127], v[132:135], v[158:161], v[124:127]
	v_mfma_f32_16x16x32_bf16 v[120:123], v[150:153], v[158:161], v[120:123]
	v_mfma_f32_16x16x32_bf16 v[116:119], v[132:135], v[166:169], v[116:119]
	v_mfma_f32_16x16x32_bf16 v[112:115], v[150:153], v[166:169], v[112:115]
	v_mfma_f32_16x16x32_bf16 v[108:111], v[132:135], v[180:183], v[108:111]
	v_mfma_f32_16x16x32_bf16 v[104:107], v[150:153], v[180:183], v[104:107]
	v_mfma_f32_16x16x32_bf16 v[100:103], v[132:135], v[188:191], v[100:103]
	v_mfma_f32_16x16x32_bf16 v[96:99], v[150:153], v[188:191], v[96:99]
	s_setprio 0
	s_barrier
; #define LDA(dst, b, h) _Pragma("unroll") for (int m = 0; m < 4; ++m) _Pragma("unroll") for (int k = 0; k < 2; ++k) \
;     dst[m][k] = *reinterpret_cast<const bf16x8*>((const char*)SA(b, h) + lds_byte(wr * 64 + m * 16 + fr, k * 32 + fq * 8))
; #define LDB(dst, b, h) _Pragma("unroll") for (int n = 0; n < 2; ++n) _Pragma("unroll") for (int k = 0; k < 2; ++k) \
;     dst[n][k] = *reinterpret_cast<const bf16x8*>((const char*)SB(b, h) + lds_byte(wc * 32 + n * 16 + fr, k * 32 + fq * 8))
; #define MMA(ai, bj, At_, Bt_) do { __builtin_amdgcn_s_setprio(1); \
;     _Pragma("unroll") for (int m = 0; m < 4; ++m) _Pragma("unroll") for (int n = 0; n < 2; ++n) _Pragma("unroll") for (int k = 0; k < 2; ++k) \
;       acc[ai][bj][m][n] = __builtin_amdgcn_mfma_f32_16x16x32_bf16(Bt_[n][k], At_[m][k], acc[ai][bj][m][n], 0, 0, 0); \
;     __builtin_amdgcn_s_setprio(0); } while (0)
; #define WAIT_V(n) asm volatile("s_waitcnt vmcnt(" #n ")" ::: "memory")
; #define WAIT_L(n) asm volatile("s_waitcnt lgkmcnt(" #n ")" ::: "memory")
; #define BAR __builtin_amdgcn_s_barrier()
; template <bool PF = true, class Epi, class KRF = KRFull>
; __device__ __forceinline__ void gemm_phase(const u16* __restrict__ A, int lda, const u16* __restrict__ Bt, int ldb, int K, int nM, int nN,
;                                            lds_u16* shm, Epi epi, KRF krf = KRFull(), bool flip = false) {
;     ...
;       LDB(B1, 1, 1); WAIT_V(0); BAR; WAIT_L(0); MMA(0, 1, At, B1); BAR;
;       LDA(At, 1, 1); BAR; WAIT_L(0); MMA(1, 0, At, B0); MMA(1, 1, At, B1); BAR; }
;     if (wr == 0) BAR;
	ds_read_b128 v[192:195], v143
	ds_read_b128 v[196:199], v143 offset:1024
	ds_read_b128 v[200:203], v143 offset:2048
	ds_read_b128 v[204:207], v143 offset:3072
	s_waitcnt vmcnt(0)
	s_barrier
	s_waitcnt lgkmcnt(0)
	s_setprio 1
	s_waitcnt lgkmcnt(0)
	v_mfma_f32_16x16x32_bf16 v[92:95], v[192:195], v[154:157], v[92:95]
	v_mfma_f32_16x16x32_bf16 v[88:91], v[200:203], v[154:157], v[88:91]
	v_mfma_f32_16x16x32_bf16 v[84:87], v[192:195], v[162:165], v[84:87]
	v_mfma_f32_16x16x32_bf16 v[80:83], v[200:203], v[162:165], v[80:83]
	v_mfma_f32_16x16x32_bf16 v[76:79], v[192:195], v[170:173], v[76:79]
	v_mfma_f32_16x16x32_bf16 v[72:75], v[200:203], v[170:173], v[72:75]
	v_mfma_f32_16x16x32_bf16 v[68:71], v[192:195], v[184:187], v[68:71]
	v_mfma_f32_16x16x32_bf16 v[64:67], v[200:203], v[184:187], v[64:67]
	v_mfma_f32_16x16x32_bf16 v[92:95], v[196:199], v[158:161], v[92:95]
	v_mfma_f32_16x16x32_bf16 v[88:91], v[204:207], v[158:161], v[88:91]
	v_mfma_f32_16x16x32_bf16 v[84:87], v[196:199], v[166:169], v[84:87]
	v_mfma_f32_16x16x32_bf16 v[80:83], v[204:207], v[166:169], v[80:83]
	v_mfma_f32_16x16x32_bf16 v[76:79], v[196:199], v[180:183], v[76:79]
	v_mfma_f32_16x16x32_bf16 v[72:75], v[204:207], v[180:183], v[72:75]
	v_mfma_f32_16x16x32_bf16 v[68:71], v[196:199], v[188:191], v[68:71]
	v_mfma_f32_16x16x32_bf16 v[64:67], v[204:207], v[188:191], v[64:67]
	s_setprio 0
	s_barrier
	ds_read_b128 v[154:157], v142 offset:49152
	ds_read_b128 v[142:145], v142 offset:50176
	ds_read_b128 v[158:161], v141 offset:49152
	ds_read_b128 v[162:165], v141 offset:50176
	ds_read_b128 v[166:169], v140 offset:49152
	ds_read_b128 v[170:173], v140 offset:50176
	ds_read_b128 v[180:183], v139 offset:49152
	ds_read_b128 v[184:187], v139 offset:50176
	s_barrier
	s_waitcnt lgkmcnt(0)
	s_setprio 1
	s_waitcnt lgkmcnt(0)
	v_mfma_f32_16x16x32_bf16 v[60:63], v[128:131], v[154:157], v[60:63]
	v_mfma_f32_16x16x32_bf16 v[56:59], v[146:149], v[154:157], v[56:59]
	v_mfma_f32_16x16x32_bf16 v[52:55], v[128:131], v[158:161], v[52:55]
	v_mfma_f32_16x16x32_bf16 v[48:51], v[146:149], v[158:161], v[48:51]
	v_mfma_f32_16x16x32_bf16 v[44:47], v[128:131], v[166:169], v[44:47]
	v_mfma_f32_16x16x32_bf16 v[40:43], v[146:149], v[166:169], v[40:43]
	v_mfma_f32_16x16x32_bf16 v[36:39], v[128:131], v[180:183], v[36:39]
	v_mfma_f32_16x16x32_bf16 v[32:35], v[146:149], v[180:183], v[32:35]
	v_mfma_f32_16x16x32_bf16 v[60:63], v[132:135], v[142:145], v[60:63]
	v_mfma_f32_16x16x32_bf16 v[56:59], v[150:153], v[142:145], v[56:59]
	v_mfma_f32_16x16x32_bf16 v[52:55], v[132:135], v[162:165], v[52:55]
	v_mfma_f32_16x16x32_bf16 v[48:51], v[150:153], v[162:165], v[48:51]
	v_mfma_f32_16x16x32_bf16 v[44:47], v[132:135], v[170:173], v[44:47]
	v_mfma_f32_16x16x32_bf16 v[40:43], v[150:153], v[170:173], v[40:43]
	v_mfma_f32_16x16x32_bf16 v[36:39], v[132:135], v[184:187], v[36:39]
	v_mfma_f32_16x16x32_bf16 v[32:35], v[150:153], v[184:187], v[32:35]
	s_setprio 0
	s_setprio 1
	v_mfma_f32_16x16x32_bf16 v[28:31], v[192:195], v[154:157], v[28:31]
	v_mfma_f32_16x16x32_bf16 v[24:27], v[200:203], v[154:157], v[24:27]
	v_mfma_f32_16x16x32_bf16 v[20:23], v[192:195], v[158:161], v[20:23]
	v_mfma_f32_16x16x32_bf16 v[16:19], v[200:203], v[158:161], v[16:19]
	v_mfma_f32_16x16x32_bf16 v[12:15], v[192:195], v[166:169], v[12:15]
	v_mfma_f32_16x16x32_bf16 v[8:11], v[200:203], v[166:169], v[8:11]
	v_mfma_f32_16x16x32_bf16 v[4:7], v[192:195], v[180:183], v[4:7]
	v_mfma_f32_16x16x32_bf16 v[0:3], v[200:203], v[180:183], v[0:3]
	v_mfma_f32_16x16x32_bf16 v[28:31], v[196:199], v[142:145], v[28:31]
	v_mfma_f32_16x16x32_bf16 v[24:27], v[204:207], v[142:145], v[24:27]
	v_mfma_f32_16x16x32_bf16 v[20:23], v[196:199], v[162:165], v[20:23]
	v_mfma_f32_16x16x32_bf16 v[16:19], v[204:207], v[162:165], v[16:19]
	v_mfma_f32_16x16x32_bf16 v[12:15], v[196:199], v[170:173], v[12:15]
	v_mfma_f32_16x16x32_bf16 v[8:11], v[204:207], v[170:173], v[8:11]
	v_mfma_f32_16x16x32_bf16 v[4:7], v[196:199], v[184:187], v[4:7]
	v_mfma_f32_16x16x32_bf16 v[0:3], v[204:207], v[184:187], v[0:3]
	s_setprio 0
	v_cmp_gt_u32_e32 vcc, s95, v138
	s_barrier
	s_and_saveexec_b64 s[12:13], vcc
	s_cbranch_execz .LBB0_2583
	s_barrier
